# stack4 plus permutation after first loads and DPP quad reductions in EpiRes epilogues
# speedup vs baseline: 1.0444x; 1.0075x over previous
.LBB0_250:
	ds_read_b128 v[128:131], v173
	ds_read_b128 v[132:135], v173 offset:1024
	ds_read_b128 v[136:139], v173 offset:2048
	ds_read_b128 v[140:143], v173 offset:3072
	ds_read_b128 v[156:159], v174
	ds_read_b128 v[160:163], v174 offset:1024
	ds_read_b128 v[164:167], v174 offset:2048
	ds_read_b128 v[178:181], v174 offset:3072
	s_add_u32 s56, s54, 0x100
	s_addc_u32 s57, s55, 0
	s_cmp_eq_u32 s86, 40
	s_cselect_b32 s61, s5, s57
	s_cselect_b32 s60, s4, s56
	s_cselect_b32 s59, s53, s85
	s_cselect_b32 s58, s52, s84
	v_lshl_add_u64 v[168:169], s[54:55], 0, v[150:151]
	s_add_i32 m0, s67, 0xc000
	ds_read_b128 v[182:185], v175
	ds_read_b128 v[186:189], v175 offset:1024
	ds_read_b128 v[192:195], v175 offset:2048
	ds_read_b128 v[196:199], v175 offset:3072
	ds_read_b128 v[200:203], v175 offset:4096
	ds_read_b128 v[204:207], v175 offset:5120
	ds_read_b128 v[208:211], v175 offset:6144
	ds_read_b128 v[212:215], v175 offset:7168
	global_load_lds_dwordx4 v[168:169], off
	v_lshl_add_u64 v[168:169], s[54:55], 0, v[148:149]
	s_add_i32 m0, s67, 0xe000
	s_nop 0
	global_load_lds_dwordx4 v[168:169], off
	s_waitcnt vmcnt(8)
	s_waitcnt lgkmcnt(0)
	s_barrier
	s_setprio 1
	s_waitcnt lgkmcnt(0)
	v_mfma_f32_16x16x32_bf16 v[124:127], v[128:131], v[182:185], v[124:127]
	v_mfma_f32_16x16x32_bf16 v[120:123], v[136:139], v[182:185], v[120:123]
	v_mfma_f32_16x16x32_bf16 v[108:111], v[128:131], v[192:195], v[108:111]
	v_mfma_f32_16x16x32_bf16 v[104:107], v[136:139], v[192:195], v[104:107]
	v_mfma_f32_16x16x32_bf16 v[92:95], v[128:131], v[200:203], v[92:95]
	v_mfma_f32_16x16x32_bf16 v[88:91], v[136:139], v[200:203], v[88:91]
	v_mfma_f32_16x16x32_bf16 v[76:79], v[128:131], v[208:211], v[76:79]
	v_mfma_f32_16x16x32_bf16 v[72:75], v[136:139], v[208:211], v[72:75]
	v_mfma_f32_16x16x32_bf16 v[124:127], v[132:135], v[186:189], v[124:127]
	v_mfma_f32_16x16x32_bf16 v[120:123], v[140:143], v[186:189], v[120:123]
	v_mfma_f32_16x16x32_bf16 v[108:111], v[132:135], v[196:199], v[108:111]
	v_mfma_f32_16x16x32_bf16 v[104:107], v[140:143], v[196:199], v[104:107]
	v_mfma_f32_16x16x32_bf16 v[92:95], v[132:135], v[204:207], v[92:95]
	v_mfma_f32_16x16x32_bf16 v[88:91], v[140:143], v[204:207], v[88:91]
	v_mfma_f32_16x16x32_bf16 v[76:79], v[132:135], v[212:215], v[76:79]
	v_mfma_f32_16x16x32_bf16 v[72:75], v[140:143], v[212:215], v[72:75]
	s_setprio 0
	s_setprio 1
	v_mfma_f32_16x16x32_bf16 v[116:119], v[156:159], v[182:185], v[116:119]
	v_mfma_f32_16x16x32_bf16 v[112:115], v[164:167], v[182:185], v[112:115]
	v_mfma_f32_16x16x32_bf16 v[100:103], v[156:159], v[192:195], v[100:103]
	v_mfma_f32_16x16x32_bf16 v[96:99], v[164:167], v[192:195], v[96:99]
	v_mfma_f32_16x16x32_bf16 v[84:87], v[156:159], v[200:203], v[84:87]
	v_mfma_f32_16x16x32_bf16 v[80:83], v[164:167], v[200:203], v[80:83]
	v_mfma_f32_16x16x32_bf16 v[68:71], v[156:159], v[208:211], v[68:71]
	v_mfma_f32_16x16x32_bf16 v[64:67], v[164:167], v[208:211], v[64:67]
	v_mfma_f32_16x16x32_bf16 v[116:119], v[160:163], v[186:189], v[116:119]
	v_mfma_f32_16x16x32_bf16 v[112:115], v[178:181], v[186:189], v[112:115]
	v_mfma_f32_16x16x32_bf16 v[100:103], v[160:163], v[196:199], v[100:103]
	v_mfma_f32_16x16x32_bf16 v[96:99], v[178:181], v[196:199], v[96:99]
	v_mfma_f32_16x16x32_bf16 v[84:87], v[160:163], v[204:207], v[84:87]
	v_mfma_f32_16x16x32_bf16 v[80:83], v[178:181], v[204:207], v[80:83]
	v_mfma_f32_16x16x32_bf16 v[68:71], v[160:163], v[212:215], v[68:71]
	v_mfma_f32_16x16x32_bf16 v[64:67], v[178:181], v[212:215], v[64:67]
	s_setprio 0
	s_barrier
	s_add_i32 s54, s79, s66
	v_lshl_add_u64 v[168:169], s[58:59], 0, v[144:145]
	s_mov_b32 m0, s54
	ds_read_b128 v[182:185], v175 offset:16384
	ds_read_b128 v[186:189], v175 offset:17408
	ds_read_b128 v[192:195], v175 offset:18432
	ds_read_b128 v[196:199], v175 offset:19456
	ds_read_b128 v[200:203], v175 offset:20480
	ds_read_b128 v[204:207], v175 offset:21504
	ds_read_b128 v[208:211], v175 offset:22528
	ds_read_b128 v[212:215], v175 offset:23552
	global_load_lds_dwordx4 v[168:169], off
	s_add_i32 m0, s54, 0x2000
	s_add_u32 s54, s58, 0xb0000
	v_lshl_add_u64 v[216:217], s[58:59], 0, v[146:147]
	s_addc_u32 s55, s59, 0
	s_add_i32 s87, s80, s66
	global_load_lds_dwordx4 v[216:217], off
	v_lshl_add_u64 v[218:219], s[54:55], 0, v[144:145]
	s_mov_b32 m0, s87
	v_lshl_add_u64 v[220:221], s[60:61], 0, v[146:147]
	global_load_lds_dwordx4 v[218:219], off
	v_lshl_add_u64 v[218:219], s[54:55], 0, v[146:147]
	s_add_i32 m0, s87, 0x2000
	s_nop 0
	global_load_lds_dwordx4 v[218:219], off
	v_lshl_add_u64 v[218:219], s[60:61], 0, v[144:145]
	s_mov_b32 m0, s67
	s_nop 0
	global_load_lds_dwordx4 v[218:219], off
	s_mov_b32 m0, s68
	s_nop 0
	global_load_lds_dwordx4 v[220:221], off
	s_waitcnt vmcnt(8)
	s_waitcnt lgkmcnt(0)
	s_barrier
	s_setprio 1
	s_waitcnt lgkmcnt(0)
	v_mfma_f32_16x16x32_bf16 v[60:63], v[128:131], v[182:185], v[60:63]
	v_mfma_f32_16x16x32_bf16 v[56:59], v[136:139], v[182:185], v[56:59]
	v_mfma_f32_16x16x32_bf16 v[44:47], v[128:131], v[192:195], v[44:47]
	v_mfma_f32_16x16x32_bf16 v[40:43], v[136:139], v[192:195], v[40:43]
	v_mfma_f32_16x16x32_bf16 v[28:31], v[128:131], v[200:203], v[28:31]
	v_mfma_f32_16x16x32_bf16 v[24:27], v[136:139], v[200:203], v[24:27]
	v_mfma_f32_16x16x32_bf16 v[12:15], v[128:131], v[208:211], v[12:15]
	v_mfma_f32_16x16x32_bf16 v[8:11], v[136:139], v[208:211], v[8:11]
	v_mfma_f32_16x16x32_bf16 v[60:63], v[132:135], v[186:189], v[60:63]
	v_mfma_f32_16x16x32_bf16 v[56:59], v[140:143], v[186:189], v[56:59]
	v_mfma_f32_16x16x32_bf16 v[44:47], v[132:135], v[196:199], v[44:47]
	v_mfma_f32_16x16x32_bf16 v[40:43], v[140:143], v[196:199], v[40:43]
	v_mfma_f32_16x16x32_bf16 v[28:31], v[132:135], v[204:207], v[28:31]
	v_mfma_f32_16x16x32_bf16 v[24:27], v[140:143], v[204:207], v[24:27]
	v_mfma_f32_16x16x32_bf16 v[12:15], v[132:135], v[212:215], v[12:15]
	v_mfma_f32_16x16x32_bf16 v[8:11], v[140:143], v[212:215], v[8:11]
	s_setprio 0
	s_setprio 1
	v_mfma_f32_16x16x32_bf16 v[52:55], v[156:159], v[182:185], v[52:55]
	v_mfma_f32_16x16x32_bf16 v[48:51], v[164:167], v[182:185], v[48:51]
	v_mfma_f32_16x16x32_bf16 v[36:39], v[156:159], v[192:195], v[36:39]
	v_mfma_f32_16x16x32_bf16 v[32:35], v[164:167], v[192:195], v[32:35]
	v_mfma_f32_16x16x32_bf16 v[20:23], v[156:159], v[200:203], v[20:23]
	v_mfma_f32_16x16x32_bf16 v[16:19], v[164:167], v[200:203], v[16:19]
	v_mfma_f32_16x16x32_bf16 v[4:7], v[156:159], v[208:211], v[4:7]
	v_mfma_f32_16x16x32_bf16 v[0:3], v[164:167], v[208:211], v[0:3]
	v_mfma_f32_16x16x32_bf16 v[52:55], v[160:163], v[186:189], v[52:55]
	v_mfma_f32_16x16x32_bf16 v[48:51], v[178:181], v[186:189], v[48:51]
	v_mfma_f32_16x16x32_bf16 v[36:39], v[160:163], v[196:199], v[36:39]
	v_mfma_f32_16x16x32_bf16 v[32:35], v[178:181], v[196:199], v[32:35]
	v_mfma_f32_16x16x32_bf16 v[20:23], v[160:163], v[204:207], v[20:23]
	v_mfma_f32_16x16x32_bf16 v[16:19], v[178:181], v[204:207], v[16:19]
	v_mfma_f32_16x16x32_bf16 v[4:7], v[160:163], v[212:215], v[4:7]
	v_mfma_f32_16x16x32_bf16 v[0:3], v[178:181], v[212:215], v[0:3]
	s_setprio 0
	s_barrier
	s_add_i32 s87, 0, 0x18000
	s_add_i32 s88, 0, 0x1c000
	v_add_u32_e32 v140, s87, v171
	v_add_u32_e32 v177, s88, v171
	ds_read_b128 v[128:131], v140
	ds_read_b128 v[132:135], v140 offset:1024
	ds_read_b128 v[136:139], v140 offset:2048
	ds_read_b128 v[140:143], v140 offset:3072
	ds_read_b128 v[156:159], v177
	ds_read_b128 v[160:163], v177 offset:1024
	ds_read_b128 v[164:167], v177 offset:2048
	ds_read_b128 v[178:181], v177 offset:3072
	s_add_u32 s54, s60, 0xb0000
	s_addc_u32 s55, s61, 0
	s_mov_b32 m0, s69
	v_lshl_add_u64 v[222:223], s[54:55], 0, v[144:145]
	ds_read_b128 v[182:185], v175 offset:32768
	ds_read_b128 v[186:189], v175 offset:33792
	ds_read_b128 v[192:195], v175 offset:34816
	ds_read_b128 v[196:199], v175 offset:35840
	ds_read_b128 v[200:203], v175 offset:36864
	ds_read_b128 v[204:207], v175 offset:37888
	ds_read_b128 v[208:211], v175 offset:38912
	ds_read_b128 v[212:215], v175 offset:39936
	global_load_lds_dwordx4 v[222:223], off
	v_lshl_add_u64 v[222:223], s[54:55], 0, v[146:147]
	s_mov_b32 m0, s70
	s_nop 0
	global_load_lds_dwordx4 v[222:223], off
	s_waitcnt vmcnt(8)
	s_waitcnt lgkmcnt(0)
	s_barrier
	s_setprio 1
	s_waitcnt lgkmcnt(0)
	v_mfma_f32_16x16x32_bf16 v[124:127], v[128:131], v[182:185], v[124:127]
	v_mfma_f32_16x16x32_bf16 v[120:123], v[136:139], v[182:185], v[120:123]
	v_mfma_f32_16x16x32_bf16 v[108:111], v[128:131], v[192:195], v[108:111]
	v_mfma_f32_16x16x32_bf16 v[104:107], v[136:139], v[192:195], v[104:107]
	v_mfma_f32_16x16x32_bf16 v[92:95], v[128:131], v[200:203], v[92:95]
	v_mfma_f32_16x16x32_bf16 v[88:91], v[136:139], v[200:203], v[88:91]
	v_mfma_f32_16x16x32_bf16 v[76:79], v[128:131], v[208:211], v[76:79]
	v_mfma_f32_16x16x32_bf16 v[72:75], v[136:139], v[208:211], v[72:75]
	v_mfma_f32_16x16x32_bf16 v[124:127], v[132:135], v[186:189], v[124:127]
	v_mfma_f32_16x16x32_bf16 v[120:123], v[140:143], v[186:189], v[120:123]
	v_mfma_f32_16x16x32_bf16 v[108:111], v[132:135], v[196:199], v[108:111]
	v_mfma_f32_16x16x32_bf16 v[104:107], v[140:143], v[196:199], v[104:107]
	v_mfma_f32_16x16x32_bf16 v[92:95], v[132:135], v[204:207], v[92:95]
	v_mfma_f32_16x16x32_bf16 v[88:91], v[140:143], v[204:207], v[88:91]
	v_mfma_f32_16x16x32_bf16 v[76:79], v[132:135], v[212:215], v[76:79]
	v_mfma_f32_16x16x32_bf16 v[72:75], v[140:143], v[212:215], v[72:75]
	s_setprio 0
	s_setprio 1
	v_mfma_f32_16x16x32_bf16 v[116:119], v[156:159], v[182:185], v[116:119]
	v_mfma_f32_16x16x32_bf16 v[112:115], v[164:167], v[182:185], v[112:115]
	v_mfma_f32_16x16x32_bf16 v[100:103], v[156:159], v[192:195], v[100:103]
	v_mfma_f32_16x16x32_bf16 v[96:99], v[164:167], v[192:195], v[96:99]
	v_mfma_f32_16x16x32_bf16 v[84:87], v[156:159], v[200:203], v[84:87]
	v_mfma_f32_16x16x32_bf16 v[80:83], v[164:167], v[200:203], v[80:83]
	v_mfma_f32_16x16x32_bf16 v[68:71], v[156:159], v[208:211], v[68:71]
	v_mfma_f32_16x16x32_bf16 v[64:67], v[164:167], v[208:211], v[64:67]
	v_mfma_f32_16x16x32_bf16 v[116:119], v[160:163], v[186:189], v[116:119]
	v_mfma_f32_16x16x32_bf16 v[112:115], v[178:181], v[186:189], v[112:115]
	v_mfma_f32_16x16x32_bf16 v[100:103], v[160:163], v[196:199], v[100:103]
	v_mfma_f32_16x16x32_bf16 v[96:99], v[178:181], v[196:199], v[96:99]
	v_mfma_f32_16x16x32_bf16 v[84:87], v[160:163], v[204:207], v[84:87]
	v_mfma_f32_16x16x32_bf16 v[80:83], v[178:181], v[204:207], v[80:83]
	v_mfma_f32_16x16x32_bf16 v[68:71], v[160:163], v[212:215], v[68:71]
	v_mfma_f32_16x16x32_bf16 v[64:67], v[178:181], v[212:215], v[64:67]
	s_setprio 0
	s_barrier
	s_add_i32 s54, s87, s66
	v_lshl_add_u64 v[168:169], v[168:169], 0, s[30:31]
	s_mov_b32 m0, s54
	ds_read_b128 v[182:185], v175 offset:49152
	ds_read_b128 v[186:189], v175 offset:50176
	ds_read_b128 v[192:195], v175 offset:51200
	ds_read_b128 v[196:199], v175 offset:52224
	ds_read_b128 v[200:203], v175 offset:53248
	ds_read_b128 v[204:207], v175 offset:54272
	ds_read_b128 v[208:211], v175 offset:55296
	ds_read_b128 v[212:215], v175 offset:56320
	global_load_lds_dwordx4 v[168:169], off
	s_add_i32 m0, s54, 0x2000
	s_add_u32 s54, s58, 0xb0080
	v_lshl_add_u64 v[168:169], v[216:217], 0, s[30:31]
	s_addc_u32 s55, s59, 0
	s_add_i32 s58, s88, s66
	global_load_lds_dwordx4 v[168:169], off
	v_lshl_add_u64 v[168:169], s[54:55], 0, v[144:145]
	s_mov_b32 m0, s58
	s_nop 0
	global_load_lds_dwordx4 v[168:169], off
	v_lshl_add_u64 v[168:169], s[54:55], 0, v[146:147]
	s_add_i32 m0, s58, 0x2000
	s_nop 0
	global_load_lds_dwordx4 v[168:169], off
	v_lshl_add_u64 v[168:169], v[218:219], 0, s[30:31]
	s_mov_b32 m0, s72
	s_nop 0
	global_load_lds_dwordx4 v[168:169], off
	v_lshl_add_u64 v[168:169], v[220:221], 0, s[30:31]
	s_mov_b32 m0, s73
	s_nop 0
	global_load_lds_dwordx4 v[168:169], off
	s_waitcnt vmcnt(8)
	s_waitcnt lgkmcnt(0)
	s_barrier
	s_setprio 1
	s_waitcnt lgkmcnt(0)
	v_mfma_f32_16x16x32_bf16 v[60:63], v[128:131], v[182:185], v[60:63]
	v_mfma_f32_16x16x32_bf16 v[56:59], v[136:139], v[182:185], v[56:59]
	v_mfma_f32_16x16x32_bf16 v[44:47], v[128:131], v[192:195], v[44:47]
	v_mfma_f32_16x16x32_bf16 v[40:43], v[136:139], v[192:195], v[40:43]
	v_mfma_f32_16x16x32_bf16 v[28:31], v[128:131], v[200:203], v[28:31]
	v_mfma_f32_16x16x32_bf16 v[24:27], v[136:139], v[200:203], v[24:27]
	v_mfma_f32_16x16x32_bf16 v[12:15], v[128:131], v[208:211], v[12:15]
	v_mfma_f32_16x16x32_bf16 v[8:11], v[136:139], v[208:211], v[8:11]
	v_mfma_f32_16x16x32_bf16 v[60:63], v[132:135], v[186:189], v[60:63]
	v_mfma_f32_16x16x32_bf16 v[56:59], v[140:143], v[186:189], v[56:59]
	v_mfma_f32_16x16x32_bf16 v[44:47], v[132:135], v[196:199], v[44:47]
	v_mfma_f32_16x16x32_bf16 v[40:43], v[140:143], v[196:199], v[40:43]
	v_mfma_f32_16x16x32_bf16 v[28:31], v[132:135], v[204:207], v[28:31]
	v_mfma_f32_16x16x32_bf16 v[24:27], v[140:143], v[204:207], v[24:27]
	v_mfma_f32_16x16x32_bf16 v[12:15], v[132:135], v[212:215], v[12:15]
	v_mfma_f32_16x16x32_bf16 v[8:11], v[140:143], v[212:215], v[8:11]
	s_setprio 0
	s_setprio 1
	v_mfma_f32_16x16x32_bf16 v[52:55], v[156:159], v[182:185], v[52:55]
	v_mfma_f32_16x16x32_bf16 v[48:51], v[164:167], v[182:185], v[48:51]
	v_mfma_f32_16x16x32_bf16 v[36:39], v[156:159], v[192:195], v[36:39]
	v_mfma_f32_16x16x32_bf16 v[32:35], v[164:167], v[192:195], v[32:35]
	v_mfma_f32_16x16x32_bf16 v[20:23], v[156:159], v[200:203], v[20:23]
	v_mfma_f32_16x16x32_bf16 v[16:19], v[164:167], v[200:203], v[16:19]
	v_mfma_f32_16x16x32_bf16 v[4:7], v[156:159], v[208:211], v[4:7]
	v_mfma_f32_16x16x32_bf16 v[0:3], v[164:167], v[208:211], v[0:3]
	v_mfma_f32_16x16x32_bf16 v[52:55], v[160:163], v[186:189], v[52:55]
	v_mfma_f32_16x16x32_bf16 v[48:51], v[178:181], v[186:189], v[48:51]
	v_mfma_f32_16x16x32_bf16 v[36:39], v[160:163], v[196:199], v[36:39]
	v_mfma_f32_16x16x32_bf16 v[32:35], v[178:181], v[196:199], v[32:35]
	v_mfma_f32_16x16x32_bf16 v[20:23], v[160:163], v[204:207], v[20:23]
	v_mfma_f32_16x16x32_bf16 v[16:19], v[178:181], v[204:207], v[16:19]
	v_mfma_f32_16x16x32_bf16 v[4:7], v[160:163], v[212:215], v[4:7]
	v_mfma_f32_16x16x32_bf16 v[0:3], v[178:181], v[212:215], v[0:3]
	s_setprio 0
	s_barrier
	s_add_i32 s86, s86, 2
	s_add_u32 s84, s84, 0x100
	s_addc_u32 s85, s85, 0
	s_cmp_gt_u32 s86, 41
	s_mov_b64 s[54:55], s[56:57]
	s_cbranch_scc0 .LBB0_250
	v_mbcnt_lo_u32_b32 v235, -1, 0
	v_mbcnt_hi_u32_b32 v235, -1, v235
	v_lshrrev_b32_e32 v236, 2, v235
	v_and_b32_e32 v237, 3, v235
	v_lshl_add_u32 v232, v237, 4, v236
	v_lshlrev_b32_e32 v232, 2, v232
	v_and_b32_e32 v233, -16, v170
	v_or_b32_e32 v233, v233, v236
	v_lshlrev_b32_e32 v237, 2, v237
	v_and_b32_e32 v234, -13, v172
	v_or_b32_e32 v234, v234, v237
	v_readlane_b32 s12, v254, 0
	v_lshl_add_u32 v160, s82, 8, v233
	v_lshl_or_b32 v156, s83, 8, v234
	s_cmpk_lt_i32 s82, 0x100
	v_readlane_b32 s13, v254, 1
	v_ashrrev_i32_e32 v161, 31, v160
	s_cselect_b32 s55, s13, s78
	s_cselect_b32 s54, s12, s77
	v_lshlrev_b64 v[192:193], 12, v[160:161]
	v_ashrrev_i32_e32 v157, 31, v156
	v_lshl_add_u64 v[128:129], s[54:55], 0, v[192:193]
	v_lshlrev_b64 v[158:159], 2, v[156:157]
	v_lshl_add_u64 v[128:129], v[128:129], 0, v[158:159]
	global_load_dwordx4 v[166:169], v[128:129], off
	global_load_dwordx4 v[178:181], v[128:129], off offset:64
	global_load_dwordx4 v[182:185], v[128:129], off offset:512
	global_load_dwordx4 v[186:189], v[128:129], off offset:576
	v_or_b32_e32 v162, 16, v160
	v_ashrrev_i32_e32 v163, 31, v162
	v_lshlrev_b64 v[164:165], 12, v[162:163]
	v_lshl_add_u64 v[128:129], s[54:55], 0, v[164:165]
	v_lshl_add_u64 v[128:129], v[128:129], 0, v[158:159]
	global_load_dwordx4 v[140:143], v[128:129], off
	global_load_dwordx4 v[136:139], v[128:129], off offset:64
	global_load_dwordx4 v[132:135], v[128:129], off offset:512
	s_nop 0
	global_load_dwordx4 v[128:131], v[128:129], off offset:576
	v_readlane_b32 s14, v254, 2
	v_readlane_b32 s15, v254, 3
	v_readlane_b32 s16, v254, 4
	v_readlane_b32 s17, v254, 5
	v_readlane_b32 s18, v254, 6
	v_readlane_b32 s19, v254, 7
	v_readlane_b32 s20, v254, 8
	v_readlane_b32 s21, v254, 9
	v_readlane_b32 s22, v254, 10
	v_readlane_b32 s23, v254, 11
	v_readlane_b32 s24, v254, 12
	v_readlane_b32 s25, v254, 13
	v_readlane_b32 s26, v254, 14
	v_readlane_b32 s27, v254, 15
	ds_bpermute_b32 v127, v232, v127
	ds_bpermute_b32 v126, v232, v126
	ds_bpermute_b32 v125, v232, v125
	ds_bpermute_b32 v124, v232, v124
	ds_bpermute_b32 v123, v232, v123
	ds_bpermute_b32 v122, v232, v122
	ds_bpermute_b32 v121, v232, v121
	ds_bpermute_b32 v120, v232, v120
	ds_bpermute_b32 v119, v232, v119
	ds_bpermute_b32 v118, v232, v118
	ds_bpermute_b32 v117, v232, v117
	ds_bpermute_b32 v116, v232, v116
	ds_bpermute_b32 v115, v232, v115
	ds_bpermute_b32 v114, v232, v114
	ds_bpermute_b32 v113, v232, v113
	ds_bpermute_b32 v112, v232, v112
	ds_bpermute_b32 v111, v232, v111
	ds_bpermute_b32 v110, v232, v110
	ds_bpermute_b32 v109, v232, v109
	ds_bpermute_b32 v108, v232, v108
	ds_bpermute_b32 v107, v232, v107
	ds_bpermute_b32 v106, v232, v106
	ds_bpermute_b32 v105, v232, v105
	ds_bpermute_b32 v104, v232, v104
	ds_bpermute_b32 v103, v232, v103
	ds_bpermute_b32 v102, v232, v102
	ds_bpermute_b32 v101, v232, v101
	ds_bpermute_b32 v100, v232, v100
	ds_bpermute_b32 v99, v232, v99
	ds_bpermute_b32 v98, v232, v98
	ds_bpermute_b32 v97, v232, v97
	ds_bpermute_b32 v96, v232, v96
	ds_bpermute_b32 v95, v232, v95
	ds_bpermute_b32 v94, v232, v94
	ds_bpermute_b32 v93, v232, v93
	ds_bpermute_b32 v92, v232, v92
	ds_bpermute_b32 v91, v232, v91
	ds_bpermute_b32 v90, v232, v90
	ds_bpermute_b32 v89, v232, v89
	ds_bpermute_b32 v88, v232, v88
	ds_bpermute_b32 v87, v232, v87
	ds_bpermute_b32 v86, v232, v86
	ds_bpermute_b32 v85, v232, v85
	ds_bpermute_b32 v84, v232, v84
	ds_bpermute_b32 v83, v232, v83
	ds_bpermute_b32 v82, v232, v82
	ds_bpermute_b32 v81, v232, v81
	ds_bpermute_b32 v80, v232, v80
	ds_bpermute_b32 v79, v232, v79
	ds_bpermute_b32 v78, v232, v78
	ds_bpermute_b32 v77, v232, v77
	ds_bpermute_b32 v76, v232, v76
	ds_bpermute_b32 v75, v232, v75
	ds_bpermute_b32 v74, v232, v74
	ds_bpermute_b32 v73, v232, v73
	ds_bpermute_b32 v72, v232, v72
	ds_bpermute_b32 v71, v232, v71
	ds_bpermute_b32 v70, v232, v70
	ds_bpermute_b32 v69, v232, v69
	ds_bpermute_b32 v68, v232, v68
	ds_bpermute_b32 v67, v232, v67
	ds_bpermute_b32 v66, v232, v66
	ds_bpermute_b32 v65, v232, v65
	ds_bpermute_b32 v64, v232, v64
	ds_bpermute_b32 v63, v232, v63
	ds_bpermute_b32 v62, v232, v62
	ds_bpermute_b32 v61, v232, v61
	ds_bpermute_b32 v60, v232, v60
	ds_bpermute_b32 v59, v232, v59
	ds_bpermute_b32 v58, v232, v58
	ds_bpermute_b32 v57, v232, v57
	ds_bpermute_b32 v56, v232, v56
	ds_bpermute_b32 v55, v232, v55
	ds_bpermute_b32 v54, v232, v54
	ds_bpermute_b32 v53, v232, v53
	ds_bpermute_b32 v52, v232, v52
	ds_bpermute_b32 v51, v232, v51
	ds_bpermute_b32 v50, v232, v50
	ds_bpermute_b32 v49, v232, v49
	ds_bpermute_b32 v48, v232, v48
	ds_bpermute_b32 v47, v232, v47
	ds_bpermute_b32 v46, v232, v46
	ds_bpermute_b32 v45, v232, v45
	ds_bpermute_b32 v44, v232, v44
	ds_bpermute_b32 v43, v232, v43
	ds_bpermute_b32 v42, v232, v42
	ds_bpermute_b32 v41, v232, v41
	ds_bpermute_b32 v40, v232, v40
	ds_bpermute_b32 v39, v232, v39
	ds_bpermute_b32 v38, v232, v38
	ds_bpermute_b32 v37, v232, v37
	ds_bpermute_b32 v36, v232, v36
	ds_bpermute_b32 v35, v232, v35
	ds_bpermute_b32 v34, v232, v34
	ds_bpermute_b32 v33, v232, v33
	ds_bpermute_b32 v32, v232, v32
	ds_bpermute_b32 v31, v232, v31
	ds_bpermute_b32 v30, v232, v30
	ds_bpermute_b32 v29, v232, v29
	ds_bpermute_b32 v28, v232, v28
	ds_bpermute_b32 v27, v232, v27
	ds_bpermute_b32 v26, v232, v26
	ds_bpermute_b32 v25, v232, v25
	ds_bpermute_b32 v24, v232, v24
	ds_bpermute_b32 v23, v232, v23
	ds_bpermute_b32 v22, v232, v22
	ds_bpermute_b32 v21, v232, v21
	ds_bpermute_b32 v20, v232, v20
	ds_bpermute_b32 v19, v232, v19
	ds_bpermute_b32 v18, v232, v18
	ds_bpermute_b32 v17, v232, v17
	ds_bpermute_b32 v16, v232, v16
	ds_bpermute_b32 v15, v232, v15
	ds_bpermute_b32 v14, v232, v14
	ds_bpermute_b32 v13, v232, v13
	ds_bpermute_b32 v12, v232, v12
	ds_bpermute_b32 v11, v232, v11
	ds_bpermute_b32 v10, v232, v10
	ds_bpermute_b32 v9, v232, v9
	ds_bpermute_b32 v8, v232, v8
	ds_bpermute_b32 v7, v232, v7
	ds_bpermute_b32 v6, v232, v6
	ds_bpermute_b32 v5, v232, v5
	ds_bpermute_b32 v4, v232, v4
	ds_bpermute_b32 v3, v232, v3
	ds_bpermute_b32 v2, v232, v2
	ds_bpermute_b32 v1, v232, v1
	ds_bpermute_b32 v0, v232, v0
	s_waitcnt lgkmcnt(0)
	s_and_b64 vcc, exec, s[34:35]
	s_cbranch_vccz .LBB0_253
	s_barrier
.LBB0_253:
	s_waitcnt vmcnt(7)
	v_pk_fma_f32 v[126:127], v[126:127], 0.5, v[168:169] op_sel_hi:[1,0,1]
	v_pk_fma_f32 v[124:125], v[124:125], 0.5, v[166:167] op_sel_hi:[1,0,1]
	v_mul_f32_e32 v167, v127, v127
	v_mul_f32_e32 v166, v125, v125
	v_fmac_f32_e32 v166, v124, v124
	v_fmac_f32_e32 v167, v126, v126
	v_add_f32_e32 v177, v166, v167
	v_lshl_add_u64 v[166:167], s[6:7], 0, v[192:193]
	v_lshlrev_b64 v[168:169], 11, v[160:161]
	v_lshl_add_u64 v[166:167], v[166:167], 0, v[158:159]
	v_lshl_add_u64 v[168:169], s[10:11], 0, v[168:169]
	global_store_dwordx4 v[166:167], v[124:127], off
	v_lshl_add_u64 v[168:169], v[156:157], 1, v[168:169]
	s_waitcnt vmcnt(7)
	v_pk_fma_f32 v[120:121], v[120:121], 0.5, v[178:179] op_sel_hi:[1,0,1]
	v_cvt_pk_bf16_f32 v124, v124, v125
	v_cvt_pk_bf16_f32 v125, v126, v127
	global_store_dwordx2 v[168:169], v[124:125], off
	v_pk_fma_f32 v[122:123], v[122:123], 0.5, v[180:181] op_sel_hi:[1,0,1]
	v_mul_f32_e32 v124, v121, v121
	v_fmac_f32_e32 v124, v120, v120
	global_store_dwordx4 v[166:167], v[120:123], off offset:64
	s_waitcnt vmcnt(8)
	v_pk_fma_f32 v[116:117], v[116:117], 0.5, v[182:183] op_sel_hi:[1,0,1]
	v_pk_fma_f32 v[118:119], v[118:119], 0.5, v[184:185] op_sel_hi:[1,0,1]
	v_cvt_pk_bf16_f32 v120, v120, v121
	v_cvt_pk_bf16_f32 v121, v122, v123
	global_store_dwordx2 v[168:169], v[120:121], off offset:32
	v_mul_f32_e32 v120, v117, v117
	v_fmac_f32_e32 v120, v116, v116
	global_store_dwordx4 v[166:167], v[116:119], off offset:512
	s_waitcnt vmcnt(9)
	v_pk_fma_f32 v[112:113], v[112:113], 0.5, v[186:187] op_sel_hi:[1,0,1]
	v_pk_fma_f32 v[114:115], v[114:115], 0.5, v[188:189] op_sel_hi:[1,0,1]
	v_cvt_pk_bf16_f32 v116, v116, v117
	v_cvt_pk_bf16_f32 v117, v118, v119
	global_store_dwordx2 v[168:169], v[116:117], off offset:256
	v_mul_f32_e32 v116, v113, v113
	v_mul_f32_e32 v125, v123, v123
	v_fmac_f32_e32 v116, v112, v112
	global_store_dwordx4 v[166:167], v[112:115], off offset:576
	v_fmac_f32_e32 v125, v122, v122
	v_mul_f32_e32 v121, v119, v119
	v_cvt_pk_bf16_f32 v112, v112, v113
	v_cvt_pk_bf16_f32 v113, v114, v115
	global_store_dwordx2 v[168:169], v[112:113], off offset:288
	v_and_b32_e32 v113, 64, v176
	v_add_f32_e32 v124, v124, v125
	v_fmac_f32_e32 v121, v118, v118
	v_mul_f32_e32 v117, v115, v115
	v_xor_b32_e32 v112, 1, v176
	v_add_u32_e32 v113, 64, v113
	v_add_f32_e32 v124, v177, v124
	v_add_f32_e32 v120, v120, v121
	v_fmac_f32_e32 v117, v114, v114
	v_cmp_lt_i32_e32 vcc, v112, v113
	v_add_f32_e32 v120, v124, v120
	v_add_f32_e32 v116, v116, v117
	v_cndmask_b32_e32 v112, v176, v112, vcc
	v_add_f32_e32 v116, v120, v116
	v_lshlrev_b32_e32 v177, 2, v112
	s_nop 1
	v_mov_b32_dpp v112, v116 quad_perm:[1,0,3,2] row_mask:0xf bank_mask:0xf
	v_xor_b32_e32 v114, 2, v176
	v_cmp_lt_i32_e32 vcc, v114, v113
	s_waitcnt lgkmcnt(0)
	v_add_f32_e32 v112, v116, v112
	v_cndmask_b32_e32 v113, v176, v114, vcc
	v_lshlrev_b32_e32 v178, 2, v113
	s_nop 1
	v_mov_b32_dpp v113, v112 quad_perm:[2,3,0,1] row_mask:0xf bank_mask:0xf
	s_mov_b32 vcc_lo, 0x11111111
	s_mov_b32 vcc_hi, 0x11111111
	s_and_saveexec_b64 s[56:57], vcc
	s_cbranch_execz .LBB0_255
	v_lshl_add_u64 v[114:115], v[160:161], 2, s[90:91]
	s_waitcnt lgkmcnt(0)
	v_add_f32_e32 v112, v112, v113
	global_atomic_add_f32 v[114:115], v112, off
.LBB0_255:
	s_or_b64 exec, exec, s[56:57]
	v_or_b32_e32 v166, 32, v160
	v_ashrrev_i32_e32 v167, 31, v166
	v_lshlrev_b64 v[168:169], 12, v[166:167]
	s_waitcnt lgkmcnt(0)
	v_lshl_add_u64 v[112:113], s[54:55], 0, v[168:169]
	v_lshl_add_u64 v[112:113], v[112:113], 0, v[158:159]
	global_load_dwordx4 v[124:127], v[112:113], off
	global_load_dwordx4 v[120:123], v[112:113], off offset:64
	global_load_dwordx4 v[116:119], v[112:113], off offset:512
	s_nop 0
	global_load_dwordx4 v[112:115], v[112:113], off offset:576
	s_waitcnt vmcnt(15)
	v_pk_fma_f32 v[110:111], v[110:111], 0.5, v[142:143] op_sel_hi:[1,0,1]
	v_pk_fma_f32 v[108:109], v[108:109], 0.5, v[140:141] op_sel_hi:[1,0,1]
	v_mul_f32_e32 v141, v111, v111
	v_mul_f32_e32 v140, v109, v109
	v_fmac_f32_e32 v140, v108, v108
	v_fmac_f32_e32 v141, v110, v110
	v_add_f32_e32 v161, v140, v141
	v_lshl_add_u64 v[140:141], s[6:7], 0, v[164:165]
	v_lshlrev_b64 v[142:143], 11, v[162:163]
	v_lshl_add_u64 v[140:141], v[140:141], 0, v[158:159]
	v_lshl_add_u64 v[142:143], s[10:11], 0, v[142:143]
	global_store_dwordx4 v[140:141], v[108:111], off
	v_lshl_add_u64 v[142:143], v[156:157], 1, v[142:143]
	s_waitcnt vmcnt(15)
	v_pk_fma_f32 v[104:105], v[104:105], 0.5, v[136:137] op_sel_hi:[1,0,1]
	v_cvt_pk_bf16_f32 v108, v108, v109
	v_cvt_pk_bf16_f32 v109, v110, v111
	global_store_dwordx2 v[142:143], v[108:109], off
	v_pk_fma_f32 v[106:107], v[106:107], 0.5, v[138:139] op_sel_hi:[1,0,1]
	v_mul_f32_e32 v108, v105, v105
	v_fmac_f32_e32 v108, v104, v104
	v_mul_f32_e32 v109, v107, v107
	global_store_dwordx4 v[140:141], v[104:107], off offset:64
	s_waitcnt vmcnt(16)
	v_pk_fma_f32 v[102:103], v[102:103], 0.5, v[134:135] op_sel_hi:[1,0,1]
	v_pk_fma_f32 v[100:101], v[100:101], 0.5, v[132:133] op_sel_hi:[1,0,1]
	v_cvt_pk_bf16_f32 v104, v104, v105
	v_cvt_pk_bf16_f32 v105, v106, v107
	v_fmac_f32_e32 v109, v106, v106
	global_store_dwordx2 v[142:143], v[104:105], off offset:32
	v_mul_f32_e32 v104, v101, v101
	v_mul_f32_e32 v105, v103, v103
	v_add_f32_e32 v108, v108, v109
	v_fmac_f32_e32 v104, v100, v100
	v_fmac_f32_e32 v105, v102, v102
	v_add_f32_e32 v108, v161, v108
	v_add_f32_e32 v104, v104, v105
	v_add_f32_e32 v108, v108, v104
	s_waitcnt vmcnt(16)
	v_pk_fma_f32 v[106:107], v[98:99], 0.5, v[130:131] op_sel_hi:[1,0,1]
	v_pk_fma_f32 v[104:105], v[96:97], 0.5, v[128:129] op_sel_hi:[1,0,1]
	v_mul_f32_e32 v97, v107, v107
	v_mul_f32_e32 v96, v105, v105
	v_fmac_f32_e32 v96, v104, v104
	v_fmac_f32_e32 v97, v106, v106
	v_add_f32_e32 v96, v96, v97
	v_add_f32_e32 v98, v108, v96
	s_nop 1
	v_mov_b32_dpp v99, v98 quad_perm:[1,0,3,2] row_mask:0xf bank_mask:0xf
	v_cvt_pk_bf16_f32 v96, v100, v101
	v_cvt_pk_bf16_f32 v97, v102, v103
	global_store_dwordx4 v[140:141], v[100:103], off offset:512
	global_store_dwordx2 v[142:143], v[96:97], off offset:256
	s_waitcnt lgkmcnt(0)
	v_add_f32_e32 v96, v98, v99
	s_nop 1
	v_mov_b32_dpp v97, v96 quad_perm:[2,3,0,1] row_mask:0xf bank_mask:0xf
	v_cvt_pk_bf16_f32 v98, v104, v105
	v_cvt_pk_bf16_f32 v99, v106, v107
	global_store_dwordx4 v[140:141], v[104:107], off offset:576
	global_store_dwordx2 v[142:143], v[98:99], off offset:288
	s_mov_b32 vcc_lo, 0x11111111
	s_mov_b32 vcc_hi, 0x11111111
	s_and_saveexec_b64 s[56:57], vcc
	s_cbranch_execz .LBB0_257
	v_lshl_add_u64 v[98:99], v[162:163], 2, s[90:91]
	s_waitcnt lgkmcnt(0)
	v_add_f32_e32 v96, v96, v97
	global_atomic_add_f32 v[98:99], v96, off
.LBB0_257:
	s_or_b64 exec, exec, s[56:57]
	v_or_b32_e32 v128, 48, v160
	v_ashrrev_i32_e32 v129, 31, v128
	v_lshlrev_b64 v[130:131], 12, v[128:129]
	s_waitcnt lgkmcnt(0)
	v_lshl_add_u64 v[96:97], s[54:55], 0, v[130:131]
	v_lshl_add_u64 v[96:97], v[96:97], 0, v[158:159]
	global_load_dwordx4 v[108:111], v[96:97], off
	global_load_dwordx4 v[104:107], v[96:97], off offset:64
	global_load_dwordx4 v[100:103], v[96:97], off offset:512
	s_nop 0
	global_load_dwordx4 v[96:99], v[96:97], off offset:576
	s_waitcnt vmcnt(15)
	v_pk_fma_f32 v[94:95], v[94:95], 0.5, v[126:127] op_sel_hi:[1,0,1]
	v_pk_fma_f32 v[92:93], v[92:93], 0.5, v[124:125] op_sel_hi:[1,0,1]
	v_mul_f32_e32 v125, v95, v95
	v_mul_f32_e32 v124, v93, v93
	v_fmac_f32_e32 v124, v92, v92
	v_fmac_f32_e32 v125, v94, v94
	v_add_f32_e32 v132, v124, v125
	v_lshl_add_u64 v[124:125], s[6:7], 0, v[168:169]
	v_lshlrev_b64 v[126:127], 11, v[166:167]
	v_lshl_add_u64 v[124:125], v[124:125], 0, v[158:159]
	v_lshl_add_u64 v[126:127], s[10:11], 0, v[126:127]
	global_store_dwordx4 v[124:125], v[92:95], off
	v_lshl_add_u64 v[126:127], v[156:157], 1, v[126:127]
	s_waitcnt vmcnt(15)
	v_pk_fma_f32 v[88:89], v[88:89], 0.5, v[120:121] op_sel_hi:[1,0,1]
	v_cvt_pk_bf16_f32 v92, v92, v93
	v_cvt_pk_bf16_f32 v93, v94, v95
	global_store_dwordx2 v[126:127], v[92:93], off
	v_pk_fma_f32 v[90:91], v[90:91], 0.5, v[122:123] op_sel_hi:[1,0,1]
	v_mul_f32_e32 v92, v89, v89
	v_fmac_f32_e32 v92, v88, v88
	v_mul_f32_e32 v93, v91, v91
	global_store_dwordx4 v[124:125], v[88:91], off offset:64
	s_waitcnt vmcnt(16)
	v_pk_fma_f32 v[86:87], v[86:87], 0.5, v[118:119] op_sel_hi:[1,0,1]
	v_pk_fma_f32 v[84:85], v[84:85], 0.5, v[116:117] op_sel_hi:[1,0,1]
	v_cvt_pk_bf16_f32 v88, v88, v89
	v_cvt_pk_bf16_f32 v89, v90, v91
	v_fmac_f32_e32 v93, v90, v90
	global_store_dwordx2 v[126:127], v[88:89], off offset:32
	v_mul_f32_e32 v88, v85, v85
	v_mul_f32_e32 v89, v87, v87
	v_add_f32_e32 v92, v92, v93
	v_fmac_f32_e32 v88, v84, v84
	v_fmac_f32_e32 v89, v86, v86
	v_add_f32_e32 v92, v132, v92
	v_add_f32_e32 v88, v88, v89
	v_add_f32_e32 v92, v92, v88
	s_waitcnt vmcnt(16)
	v_pk_fma_f32 v[90:91], v[82:83], 0.5, v[114:115] op_sel_hi:[1,0,1]
	v_pk_fma_f32 v[88:89], v[80:81], 0.5, v[112:113] op_sel_hi:[1,0,1]
	v_mul_f32_e32 v81, v91, v91
	v_mul_f32_e32 v80, v89, v89
	v_fmac_f32_e32 v80, v88, v88
	v_fmac_f32_e32 v81, v90, v90
	v_add_f32_e32 v80, v80, v81
	v_add_f32_e32 v82, v92, v80
	s_nop 1
	v_mov_b32_dpp v83, v82 quad_perm:[1,0,3,2] row_mask:0xf bank_mask:0xf
	v_cvt_pk_bf16_f32 v80, v84, v85
	v_cvt_pk_bf16_f32 v81, v86, v87
	global_store_dwordx4 v[124:125], v[84:87], off offset:512
	global_store_dwordx2 v[126:127], v[80:81], off offset:256
	s_waitcnt lgkmcnt(0)
	v_add_f32_e32 v80, v82, v83
	s_nop 1
	v_mov_b32_dpp v81, v80 quad_perm:[2,3,0,1] row_mask:0xf bank_mask:0xf
	v_cvt_pk_bf16_f32 v82, v88, v89
	v_cvt_pk_bf16_f32 v83, v90, v91
	global_store_dwordx4 v[124:125], v[88:91], off offset:576
	global_store_dwordx2 v[126:127], v[82:83], off offset:288
	s_mov_b32 vcc_lo, 0x11111111
	s_mov_b32 vcc_hi, 0x11111111
	s_and_saveexec_b64 s[56:57], vcc
	s_cbranch_execz .LBB0_259
	v_lshl_add_u64 v[82:83], v[166:167], 2, s[90:91]
	s_waitcnt lgkmcnt(0)
	v_add_f32_e32 v80, v80, v81
	global_atomic_add_f32 v[82:83], v80, off
.LBB0_259:
	s_or_b64 exec, exec, s[56:57]
	v_add_u32_e32 v112, 0x80, v160
	v_ashrrev_i32_e32 v113, 31, v112
	v_lshlrev_b64 v[114:115], 12, v[112:113]
	s_waitcnt lgkmcnt(0)
	v_lshl_add_u64 v[80:81], s[54:55], 0, v[114:115]
	v_lshl_add_u64 v[80:81], v[80:81], 0, v[158:159]
	global_load_dwordx4 v[92:95], v[80:81], off
	global_load_dwordx4 v[88:91], v[80:81], off offset:64
	global_load_dwordx4 v[84:87], v[80:81], off offset:512
	s_nop 0
	global_load_dwordx4 v[80:83], v[80:81], off offset:576
	s_waitcnt vmcnt(15)
	v_pk_fma_f32 v[78:79], v[78:79], 0.5, v[110:111] op_sel_hi:[1,0,1]
	v_pk_fma_f32 v[76:77], v[76:77], 0.5, v[108:109] op_sel_hi:[1,0,1]
	v_mul_f32_e32 v109, v79, v79
	v_mul_f32_e32 v108, v77, v77
	v_fmac_f32_e32 v108, v76, v76
	v_fmac_f32_e32 v109, v78, v78
	v_add_f32_e32 v116, v108, v109
	v_lshl_add_u64 v[108:109], s[6:7], 0, v[130:131]
	v_lshlrev_b64 v[110:111], 11, v[128:129]
	v_lshl_add_u64 v[108:109], v[108:109], 0, v[158:159]
	v_lshl_add_u64 v[110:111], s[10:11], 0, v[110:111]
	global_store_dwordx4 v[108:109], v[76:79], off
	v_lshl_add_u64 v[110:111], v[156:157], 1, v[110:111]
	s_waitcnt vmcnt(15)
	v_pk_fma_f32 v[72:73], v[72:73], 0.5, v[104:105] op_sel_hi:[1,0,1]
	v_cvt_pk_bf16_f32 v76, v76, v77
	v_cvt_pk_bf16_f32 v77, v78, v79
	global_store_dwordx2 v[110:111], v[76:77], off
	v_pk_fma_f32 v[74:75], v[74:75], 0.5, v[106:107] op_sel_hi:[1,0,1]
	v_mul_f32_e32 v76, v73, v73
	v_fmac_f32_e32 v76, v72, v72
	v_mul_f32_e32 v77, v75, v75
	global_store_dwordx4 v[108:109], v[72:75], off offset:64
	s_waitcnt vmcnt(16)
	v_pk_fma_f32 v[70:71], v[70:71], 0.5, v[102:103] op_sel_hi:[1,0,1]
	v_pk_fma_f32 v[68:69], v[68:69], 0.5, v[100:101] op_sel_hi:[1,0,1]
	v_cvt_pk_bf16_f32 v72, v72, v73
	v_cvt_pk_bf16_f32 v73, v74, v75
	v_fmac_f32_e32 v77, v74, v74
	global_store_dwordx2 v[110:111], v[72:73], off offset:32
	v_mul_f32_e32 v72, v69, v69
	v_mul_f32_e32 v73, v71, v71
	v_add_f32_e32 v76, v76, v77
	v_fmac_f32_e32 v72, v68, v68
	v_fmac_f32_e32 v73, v70, v70
	v_add_f32_e32 v76, v116, v76
	v_add_f32_e32 v72, v72, v73
	v_add_f32_e32 v76, v76, v72
	s_waitcnt vmcnt(16)
	v_pk_fma_f32 v[74:75], v[66:67], 0.5, v[98:99] op_sel_hi:[1,0,1]
	v_pk_fma_f32 v[72:73], v[64:65], 0.5, v[96:97] op_sel_hi:[1,0,1]
	v_mul_f32_e32 v65, v75, v75
	v_mul_f32_e32 v64, v73, v73
	v_fmac_f32_e32 v64, v72, v72
	v_fmac_f32_e32 v65, v74, v74
	v_add_f32_e32 v64, v64, v65
	v_add_f32_e32 v66, v76, v64
	s_nop 1
	v_mov_b32_dpp v67, v66 quad_perm:[1,0,3,2] row_mask:0xf bank_mask:0xf
	v_cvt_pk_bf16_f32 v64, v68, v69
	v_cvt_pk_bf16_f32 v65, v70, v71
	global_store_dwordx4 v[108:109], v[68:71], off offset:512
	global_store_dwordx2 v[110:111], v[64:65], off offset:256
	s_waitcnt lgkmcnt(0)
	v_add_f32_e32 v64, v66, v67
	s_nop 1
	v_mov_b32_dpp v65, v64 quad_perm:[2,3,0,1] row_mask:0xf bank_mask:0xf
	v_cvt_pk_bf16_f32 v66, v72, v73
	v_cvt_pk_bf16_f32 v67, v74, v75
	global_store_dwordx4 v[108:109], v[72:75], off offset:576
	global_store_dwordx2 v[110:111], v[66:67], off offset:288
	s_mov_b32 vcc_lo, 0x11111111
	s_mov_b32 vcc_hi, 0x11111111
	s_and_saveexec_b64 s[56:57], vcc
	s_cbranch_execz .LBB0_261
	v_lshl_add_u64 v[66:67], v[128:129], 2, s[90:91]
	s_waitcnt lgkmcnt(0)
	v_add_f32_e32 v64, v64, v65
	global_atomic_add_f32 v[66:67], v64, off
.LBB0_261:
	s_or_b64 exec, exec, s[56:57]
	v_or_b32_e32 v96, 16, v112
	v_ashrrev_i32_e32 v97, 31, v96
	v_lshlrev_b64 v[98:99], 12, v[96:97]
	s_waitcnt lgkmcnt(0)
	v_lshl_add_u64 v[64:65], s[54:55], 0, v[98:99]
	v_lshl_add_u64 v[64:65], v[64:65], 0, v[158:159]
	global_load_dwordx4 v[76:79], v[64:65], off
	global_load_dwordx4 v[72:75], v[64:65], off offset:64
	global_load_dwordx4 v[68:71], v[64:65], off offset:512
	s_nop 0
	global_load_dwordx4 v[64:67], v[64:65], off offset:576
	s_waitcnt vmcnt(15)
	v_pk_fma_f32 v[62:63], v[62:63], 0.5, v[94:95] op_sel_hi:[1,0,1]
	v_pk_fma_f32 v[60:61], v[60:61], 0.5, v[92:93] op_sel_hi:[1,0,1]
	v_mul_f32_e32 v93, v63, v63
	v_mul_f32_e32 v92, v61, v61
	v_fmac_f32_e32 v92, v60, v60
	v_fmac_f32_e32 v93, v62, v62
	v_add_f32_e32 v100, v92, v93
	v_lshl_add_u64 v[92:93], s[6:7], 0, v[114:115]
	v_lshlrev_b64 v[94:95], 11, v[112:113]
	v_lshl_add_u64 v[92:93], v[92:93], 0, v[158:159]
	v_lshl_add_u64 v[94:95], s[10:11], 0, v[94:95]
	global_store_dwordx4 v[92:93], v[60:63], off
	v_lshl_add_u64 v[94:95], v[156:157], 1, v[94:95]
	s_waitcnt vmcnt(15)
	v_pk_fma_f32 v[56:57], v[56:57], 0.5, v[88:89] op_sel_hi:[1,0,1]
	v_cvt_pk_bf16_f32 v60, v60, v61
	v_cvt_pk_bf16_f32 v61, v62, v63
	global_store_dwordx2 v[94:95], v[60:61], off
	v_pk_fma_f32 v[58:59], v[58:59], 0.5, v[90:91] op_sel_hi:[1,0,1]
	v_mul_f32_e32 v60, v57, v57
	v_fmac_f32_e32 v60, v56, v56
	v_mul_f32_e32 v61, v59, v59
	global_store_dwordx4 v[92:93], v[56:59], off offset:64
	s_waitcnt vmcnt(16)
	v_pk_fma_f32 v[54:55], v[54:55], 0.5, v[86:87] op_sel_hi:[1,0,1]
	v_pk_fma_f32 v[52:53], v[52:53], 0.5, v[84:85] op_sel_hi:[1,0,1]
	v_cvt_pk_bf16_f32 v56, v56, v57
	v_cvt_pk_bf16_f32 v57, v58, v59
	v_fmac_f32_e32 v61, v58, v58
	global_store_dwordx2 v[94:95], v[56:57], off offset:32
	v_mul_f32_e32 v56, v53, v53
	v_mul_f32_e32 v57, v55, v55
	v_add_f32_e32 v60, v60, v61
	v_fmac_f32_e32 v56, v52, v52
	v_fmac_f32_e32 v57, v54, v54
	v_add_f32_e32 v60, v100, v60
	v_add_f32_e32 v56, v56, v57
	v_add_f32_e32 v60, v60, v56
	s_waitcnt vmcnt(16)
	v_pk_fma_f32 v[58:59], v[50:51], 0.5, v[82:83] op_sel_hi:[1,0,1]
	v_pk_fma_f32 v[56:57], v[48:49], 0.5, v[80:81] op_sel_hi:[1,0,1]
	v_mul_f32_e32 v49, v59, v59
	v_mul_f32_e32 v48, v57, v57
	v_fmac_f32_e32 v48, v56, v56
	v_fmac_f32_e32 v49, v58, v58
	v_add_f32_e32 v48, v48, v49
	v_add_f32_e32 v50, v60, v48
	s_nop 1
	v_mov_b32_dpp v51, v50 quad_perm:[1,0,3,2] row_mask:0xf bank_mask:0xf
	v_cvt_pk_bf16_f32 v48, v52, v53
	v_cvt_pk_bf16_f32 v49, v54, v55
	global_store_dwordx4 v[92:93], v[52:55], off offset:512
	global_store_dwordx2 v[94:95], v[48:49], off offset:256
	s_waitcnt lgkmcnt(0)
	v_add_f32_e32 v48, v50, v51
	s_nop 1
	v_mov_b32_dpp v49, v48 quad_perm:[2,3,0,1] row_mask:0xf bank_mask:0xf
	v_cvt_pk_bf16_f32 v50, v56, v57
	v_cvt_pk_bf16_f32 v51, v58, v59
	global_store_dwordx4 v[92:93], v[56:59], off offset:576
	global_store_dwordx2 v[94:95], v[50:51], off offset:288
	s_mov_b32 vcc_lo, 0x11111111
	s_mov_b32 vcc_hi, 0x11111111
	s_and_saveexec_b64 s[56:57], vcc
	s_cbranch_execz .LBB0_263
	v_lshl_add_u64 v[50:51], v[112:113], 2, s[90:91]
	s_waitcnt lgkmcnt(0)
	v_add_f32_e32 v48, v48, v49
	global_atomic_add_f32 v[50:51], v48, off
.LBB0_263:
	s_or_b64 exec, exec, s[56:57]
	v_or_b32_e32 v80, 32, v112
	v_ashrrev_i32_e32 v81, 31, v80
	v_lshlrev_b64 v[82:83], 12, v[80:81]
	s_waitcnt lgkmcnt(0)
	v_lshl_add_u64 v[48:49], s[54:55], 0, v[82:83]
	v_lshl_add_u64 v[48:49], v[48:49], 0, v[158:159]
	global_load_dwordx4 v[60:63], v[48:49], off
	global_load_dwordx4 v[56:59], v[48:49], off offset:64
	global_load_dwordx4 v[52:55], v[48:49], off offset:512
	s_nop 0
	global_load_dwordx4 v[48:51], v[48:49], off offset:576
	s_waitcnt vmcnt(15)
	v_pk_fma_f32 v[46:47], v[46:47], 0.5, v[78:79] op_sel_hi:[1,0,1]
	v_pk_fma_f32 v[44:45], v[44:45], 0.5, v[76:77] op_sel_hi:[1,0,1]
	v_mul_f32_e32 v77, v47, v47
	v_mul_f32_e32 v76, v45, v45
	v_fmac_f32_e32 v76, v44, v44
	v_fmac_f32_e32 v77, v46, v46
	v_add_f32_e32 v84, v76, v77
	v_lshl_add_u64 v[76:77], s[6:7], 0, v[98:99]
	v_lshlrev_b64 v[78:79], 11, v[96:97]
	v_lshl_add_u64 v[76:77], v[76:77], 0, v[158:159]
	v_lshl_add_u64 v[78:79], s[10:11], 0, v[78:79]
	global_store_dwordx4 v[76:77], v[44:47], off
	v_lshl_add_u64 v[78:79], v[156:157], 1, v[78:79]
	s_waitcnt vmcnt(15)
	v_pk_fma_f32 v[40:41], v[40:41], 0.5, v[72:73] op_sel_hi:[1,0,1]
	v_cvt_pk_bf16_f32 v44, v44, v45
	v_cvt_pk_bf16_f32 v45, v46, v47
	global_store_dwordx2 v[78:79], v[44:45], off
	v_pk_fma_f32 v[42:43], v[42:43], 0.5, v[74:75] op_sel_hi:[1,0,1]
	v_mul_f32_e32 v44, v41, v41
	v_fmac_f32_e32 v44, v40, v40
	v_mul_f32_e32 v45, v43, v43
	global_store_dwordx4 v[76:77], v[40:43], off offset:64
	s_waitcnt vmcnt(16)
	v_pk_fma_f32 v[38:39], v[38:39], 0.5, v[70:71] op_sel_hi:[1,0,1]
	v_pk_fma_f32 v[36:37], v[36:37], 0.5, v[68:69] op_sel_hi:[1,0,1]
	v_cvt_pk_bf16_f32 v40, v40, v41
	v_cvt_pk_bf16_f32 v41, v42, v43
	v_fmac_f32_e32 v45, v42, v42
	global_store_dwordx2 v[78:79], v[40:41], off offset:32
	v_mul_f32_e32 v40, v37, v37
	v_mul_f32_e32 v41, v39, v39
	v_add_f32_e32 v44, v44, v45
	v_fmac_f32_e32 v40, v36, v36
	v_fmac_f32_e32 v41, v38, v38
	v_add_f32_e32 v44, v84, v44
	v_add_f32_e32 v40, v40, v41
	v_add_f32_e32 v44, v44, v40
	s_waitcnt vmcnt(16)
	v_pk_fma_f32 v[42:43], v[34:35], 0.5, v[66:67] op_sel_hi:[1,0,1]
	v_pk_fma_f32 v[40:41], v[32:33], 0.5, v[64:65] op_sel_hi:[1,0,1]
	v_mul_f32_e32 v33, v43, v43
	v_mul_f32_e32 v32, v41, v41
	v_fmac_f32_e32 v32, v40, v40
	v_fmac_f32_e32 v33, v42, v42
	v_add_f32_e32 v32, v32, v33
	v_add_f32_e32 v34, v44, v32
	s_nop 1
	v_mov_b32_dpp v35, v34 quad_perm:[1,0,3,2] row_mask:0xf bank_mask:0xf
	v_cvt_pk_bf16_f32 v32, v36, v37
	v_cvt_pk_bf16_f32 v33, v38, v39
	global_store_dwordx4 v[76:77], v[36:39], off offset:512
	global_store_dwordx2 v[78:79], v[32:33], off offset:256
	s_waitcnt lgkmcnt(0)
	v_add_f32_e32 v32, v34, v35
	s_nop 1
	v_mov_b32_dpp v33, v32 quad_perm:[2,3,0,1] row_mask:0xf bank_mask:0xf
	v_cvt_pk_bf16_f32 v34, v40, v41
	v_cvt_pk_bf16_f32 v35, v42, v43
	global_store_dwordx4 v[76:77], v[40:43], off offset:576
	global_store_dwordx2 v[78:79], v[34:35], off offset:288
	s_mov_b32 vcc_lo, 0x11111111
	s_mov_b32 vcc_hi, 0x11111111
	s_and_saveexec_b64 s[56:57], vcc
	s_cbranch_execz .LBB0_265
	v_lshl_add_u64 v[34:35], v[96:97], 2, s[90:91]
	s_waitcnt lgkmcnt(0)
	v_add_f32_e32 v32, v32, v33
	global_atomic_add_f32 v[34:35], v32, off
.LBB0_265:
	s_or_b64 exec, exec, s[56:57]
	v_or_b32_e32 v64, 48, v112
	v_ashrrev_i32_e32 v65, 31, v64
	v_lshlrev_b64 v[66:67], 12, v[64:65]
	s_waitcnt lgkmcnt(0)
	v_lshl_add_u64 v[32:33], s[54:55], 0, v[66:67]
	v_lshl_add_u64 v[32:33], v[32:33], 0, v[158:159]
	global_load_dwordx4 v[44:47], v[32:33], off
	global_load_dwordx4 v[40:43], v[32:33], off offset:64
	global_load_dwordx4 v[36:39], v[32:33], off offset:512
	s_nop 0
	global_load_dwordx4 v[32:35], v[32:33], off offset:576
	s_waitcnt vmcnt(15)
	v_pk_fma_f32 v[30:31], v[30:31], 0.5, v[62:63] op_sel_hi:[1,0,1]
	v_pk_fma_f32 v[28:29], v[28:29], 0.5, v[60:61] op_sel_hi:[1,0,1]
	v_mul_f32_e32 v61, v31, v31
	v_mul_f32_e32 v60, v29, v29
	v_fmac_f32_e32 v60, v28, v28
	v_fmac_f32_e32 v61, v30, v30
	v_add_f32_e32 v68, v60, v61
	v_lshl_add_u64 v[60:61], s[6:7], 0, v[82:83]
	v_lshlrev_b64 v[62:63], 11, v[80:81]
	v_lshl_add_u64 v[60:61], v[60:61], 0, v[158:159]
	v_lshl_add_u64 v[62:63], s[10:11], 0, v[62:63]
	global_store_dwordx4 v[60:61], v[28:31], off
	v_lshl_add_u64 v[62:63], v[156:157], 1, v[62:63]
	s_waitcnt vmcnt(15)
	v_pk_fma_f32 v[24:25], v[24:25], 0.5, v[56:57] op_sel_hi:[1,0,1]
	v_cvt_pk_bf16_f32 v28, v28, v29
	v_cvt_pk_bf16_f32 v29, v30, v31
	global_store_dwordx2 v[62:63], v[28:29], off
	v_pk_fma_f32 v[26:27], v[26:27], 0.5, v[58:59] op_sel_hi:[1,0,1]
	v_mul_f32_e32 v28, v25, v25
	v_fmac_f32_e32 v28, v24, v24
	v_mul_f32_e32 v29, v27, v27
	global_store_dwordx4 v[60:61], v[24:27], off offset:64
	s_waitcnt vmcnt(16)
	v_pk_fma_f32 v[22:23], v[22:23], 0.5, v[54:55] op_sel_hi:[1,0,1]
	v_pk_fma_f32 v[20:21], v[20:21], 0.5, v[52:53] op_sel_hi:[1,0,1]
	v_cvt_pk_bf16_f32 v24, v24, v25
	v_cvt_pk_bf16_f32 v25, v26, v27
	v_fmac_f32_e32 v29, v26, v26
	global_store_dwordx2 v[62:63], v[24:25], off offset:32
	v_mul_f32_e32 v24, v21, v21
	v_mul_f32_e32 v25, v23, v23
	v_add_f32_e32 v28, v28, v29
	v_fmac_f32_e32 v24, v20, v20
	v_fmac_f32_e32 v25, v22, v22
	v_add_f32_e32 v28, v68, v28
	v_add_f32_e32 v24, v24, v25
	v_add_f32_e32 v28, v28, v24
	s_waitcnt vmcnt(16)
	v_pk_fma_f32 v[26:27], v[18:19], 0.5, v[50:51] op_sel_hi:[1,0,1]
	v_pk_fma_f32 v[24:25], v[16:17], 0.5, v[48:49] op_sel_hi:[1,0,1]
	v_mul_f32_e32 v17, v27, v27
	v_mul_f32_e32 v16, v25, v25
	v_fmac_f32_e32 v16, v24, v24
	v_fmac_f32_e32 v17, v26, v26
	v_add_f32_e32 v16, v16, v17
	v_add_f32_e32 v18, v28, v16
	s_nop 1
	v_mov_b32_dpp v19, v18 quad_perm:[1,0,3,2] row_mask:0xf bank_mask:0xf
	v_cvt_pk_bf16_f32 v16, v20, v21
	v_cvt_pk_bf16_f32 v17, v22, v23
	global_store_dwordx4 v[60:61], v[20:23], off offset:512
	global_store_dwordx2 v[62:63], v[16:17], off offset:256
	s_waitcnt lgkmcnt(0)
	v_add_f32_e32 v16, v18, v19
	s_nop 1
	v_mov_b32_dpp v17, v16 quad_perm:[2,3,0,1] row_mask:0xf bank_mask:0xf
	v_cvt_pk_bf16_f32 v18, v24, v25
	v_cvt_pk_bf16_f32 v19, v26, v27
	global_store_dwordx4 v[60:61], v[24:27], off offset:576
	global_store_dwordx2 v[62:63], v[18:19], off offset:288
	s_mov_b32 vcc_lo, 0x11111111
	s_mov_b32 vcc_hi, 0x11111111
	s_and_saveexec_b64 s[54:55], vcc
	s_cbranch_execz .LBB0_267
	v_lshl_add_u64 v[18:19], v[80:81], 2, s[90:91]
	s_waitcnt lgkmcnt(0)
	v_add_f32_e32 v16, v16, v17
	global_atomic_add_f32 v[18:19], v16, off
.LBB0_267:
	s_or_b64 exec, exec, s[54:55]
	s_waitcnt vmcnt(11)
	v_pk_fma_f32 v[14:15], v[14:15], 0.5, v[46:47] op_sel_hi:[1,0,1]
	v_pk_fma_f32 v[12:13], v[12:13], 0.5, v[44:45] op_sel_hi:[1,0,1]
	s_waitcnt lgkmcnt(0)
	v_mul_f32_e32 v17, v15, v15
	v_mul_f32_e32 v16, v13, v13
	v_fmac_f32_e32 v16, v12, v12
	v_fmac_f32_e32 v17, v14, v14
	v_add_f32_e32 v20, v16, v17
	v_lshl_add_u64 v[16:17], s[6:7], 0, v[66:67]
	v_lshlrev_b64 v[18:19], 11, v[64:65]
	v_lshl_add_u64 v[16:17], v[156:157], 2, v[16:17]
	v_lshl_add_u64 v[18:19], s[10:11], 0, v[18:19]
	global_store_dwordx4 v[16:17], v[12:15], off
	v_lshl_add_u64 v[18:19], v[156:157], 1, v[18:19]
	s_waitcnt vmcnt(11)
	v_pk_fma_f32 v[8:9], v[8:9], 0.5, v[40:41] op_sel_hi:[1,0,1]
	v_cvt_pk_bf16_f32 v12, v12, v13
	v_cvt_pk_bf16_f32 v13, v14, v15
	global_store_dwordx2 v[18:19], v[12:13], off
	v_pk_fma_f32 v[10:11], v[10:11], 0.5, v[42:43] op_sel_hi:[1,0,1]
	v_mul_f32_e32 v12, v9, v9
	v_fmac_f32_e32 v12, v8, v8
	v_mul_f32_e32 v13, v11, v11
	global_store_dwordx4 v[16:17], v[8:11], off offset:64
	s_waitcnt vmcnt(12)
	v_pk_fma_f32 v[6:7], v[6:7], 0.5, v[38:39] op_sel_hi:[1,0,1]
	v_pk_fma_f32 v[4:5], v[4:5], 0.5, v[36:37] op_sel_hi:[1,0,1]
	v_cvt_pk_bf16_f32 v8, v8, v9
	v_cvt_pk_bf16_f32 v9, v10, v11
	v_fmac_f32_e32 v13, v10, v10
	global_store_dwordx2 v[18:19], v[8:9], off offset:32
	v_mul_f32_e32 v8, v5, v5
	v_mul_f32_e32 v9, v7, v7
	v_add_f32_e32 v12, v12, v13
	v_fmac_f32_e32 v8, v4, v4
	v_fmac_f32_e32 v9, v6, v6
	v_add_f32_e32 v12, v20, v12
	v_add_f32_e32 v8, v8, v9
	v_add_f32_e32 v12, v12, v8
	s_waitcnt vmcnt(12)
	v_pk_fma_f32 v[10:11], v[2:3], 0.5, v[34:35] op_sel_hi:[1,0,1]
	v_pk_fma_f32 v[8:9], v[0:1], 0.5, v[32:33] op_sel_hi:[1,0,1]
	v_mul_f32_e32 v1, v11, v11
	v_mul_f32_e32 v0, v9, v9
	v_fmac_f32_e32 v0, v8, v8
	v_fmac_f32_e32 v1, v10, v10
	v_add_f32_e32 v0, v0, v1
	v_add_f32_e32 v2, v12, v0
	s_nop 1
	v_mov_b32_dpp v3, v2 quad_perm:[1,0,3,2] row_mask:0xf bank_mask:0xf
	v_cvt_pk_bf16_f32 v0, v4, v5
	v_cvt_pk_bf16_f32 v1, v6, v7
	global_store_dwordx4 v[16:17], v[4:7], off offset:512
	global_store_dwordx2 v[18:19], v[0:1], off offset:256
	s_waitcnt lgkmcnt(0)
	v_add_f32_e32 v0, v2, v3
	s_nop 1
	v_mov_b32_dpp v1, v0 quad_perm:[2,3,0,1] row_mask:0xf bank_mask:0xf
	v_cvt_pk_bf16_f32 v2, v8, v9
	v_cvt_pk_bf16_f32 v3, v10, v11
	global_store_dwordx4 v[16:17], v[8:11], off offset:576
	global_store_dwordx2 v[18:19], v[2:3], off offset:288
	s_mov_b32 vcc_lo, 0x11111111
	s_mov_b32 vcc_hi, 0x11111111
	s_and_saveexec_b64 s[54:55], vcc
	s_cbranch_execz .LBB0_269
	v_lshl_add_u64 v[2:3], v[64:65], 2, s[90:91]
	s_waitcnt lgkmcnt(0)
	v_add_f32_e32 v0, v0, v1
	global_atomic_add_f32 v[2:3], v0, off

.LBB0_1187:
	ds_read_b128 v[128:131], v171
	ds_read_b128 v[132:135], v171 offset:1024
	ds_read_b128 v[136:139], v171 offset:2048
	ds_read_b128 v[140:143], v171 offset:3072
	ds_read_b128 v[156:159], v172
	ds_read_b128 v[160:163], v172 offset:1024
	ds_read_b128 v[164:167], v172 offset:2048
	ds_read_b128 v[176:179], v172 offset:3072
	s_add_u32 s24, s22, 0x100
	s_addc_u32 s25, s23, 0
	s_cmp_eq_u32 s57, 40
	s_cselect_b32 s31, s5, s25
	s_cselect_b32 s30, s4, s24
	s_cselect_b32 s27, s21, s56
	s_cselect_b32 s26, s20, s55
	v_lshl_add_u64 v[188:189], s[22:23], 0, v[150:151]
	s_add_i32 m0, s38, 0xc000
	ds_read_b128 v[180:183], v173
	ds_read_b128 v[184:187], v173 offset:1024
	ds_read_b128 v[192:195], v173 offset:2048
	ds_read_b128 v[196:199], v173 offset:3072
	ds_read_b128 v[200:203], v173 offset:4096
	ds_read_b128 v[204:207], v173 offset:5120
	ds_read_b128 v[208:211], v173 offset:6144
	ds_read_b128 v[212:215], v173 offset:7168
	global_load_lds_dwordx4 v[188:189], off
	v_lshl_add_u64 v[188:189], s[22:23], 0, v[148:149]
	s_add_i32 m0, s38, 0xe000
	s_nop 0
	global_load_lds_dwordx4 v[188:189], off
	s_waitcnt vmcnt(8)
	s_waitcnt lgkmcnt(0)
	s_barrier
	s_setprio 1
	s_waitcnt lgkmcnt(0)
	v_mfma_f32_16x16x32_bf16 v[124:127], v[128:131], v[180:183], v[124:127]
	v_mfma_f32_16x16x32_bf16 v[120:123], v[136:139], v[180:183], v[120:123]
	v_mfma_f32_16x16x32_bf16 v[108:111], v[128:131], v[192:195], v[108:111]
	v_mfma_f32_16x16x32_bf16 v[104:107], v[136:139], v[192:195], v[104:107]
	v_mfma_f32_16x16x32_bf16 v[92:95], v[128:131], v[200:203], v[92:95]
	v_mfma_f32_16x16x32_bf16 v[88:91], v[136:139], v[200:203], v[88:91]
	v_mfma_f32_16x16x32_bf16 v[76:79], v[128:131], v[208:211], v[76:79]
	v_mfma_f32_16x16x32_bf16 v[72:75], v[136:139], v[208:211], v[72:75]
	v_mfma_f32_16x16x32_bf16 v[124:127], v[132:135], v[184:187], v[124:127]
	v_mfma_f32_16x16x32_bf16 v[120:123], v[140:143], v[184:187], v[120:123]
	v_mfma_f32_16x16x32_bf16 v[108:111], v[132:135], v[196:199], v[108:111]
	v_mfma_f32_16x16x32_bf16 v[104:107], v[140:143], v[196:199], v[104:107]
	v_mfma_f32_16x16x32_bf16 v[92:95], v[132:135], v[204:207], v[92:95]
	v_mfma_f32_16x16x32_bf16 v[88:91], v[140:143], v[204:207], v[88:91]
	v_mfma_f32_16x16x32_bf16 v[76:79], v[132:135], v[212:215], v[76:79]
	v_mfma_f32_16x16x32_bf16 v[72:75], v[140:143], v[212:215], v[72:75]
	s_setprio 0
	s_setprio 1
	v_mfma_f32_16x16x32_bf16 v[116:119], v[156:159], v[180:183], v[116:119]
	v_mfma_f32_16x16x32_bf16 v[112:115], v[164:167], v[180:183], v[112:115]
	v_mfma_f32_16x16x32_bf16 v[100:103], v[156:159], v[192:195], v[100:103]
	v_mfma_f32_16x16x32_bf16 v[96:99], v[164:167], v[192:195], v[96:99]
	v_mfma_f32_16x16x32_bf16 v[84:87], v[156:159], v[200:203], v[84:87]
	v_mfma_f32_16x16x32_bf16 v[80:83], v[164:167], v[200:203], v[80:83]
	v_mfma_f32_16x16x32_bf16 v[68:71], v[156:159], v[208:211], v[68:71]
	v_mfma_f32_16x16x32_bf16 v[64:67], v[164:167], v[208:211], v[64:67]
	v_mfma_f32_16x16x32_bf16 v[116:119], v[160:163], v[184:187], v[116:119]
	v_mfma_f32_16x16x32_bf16 v[112:115], v[176:179], v[184:187], v[112:115]
	v_mfma_f32_16x16x32_bf16 v[100:103], v[160:163], v[196:199], v[100:103]
	v_mfma_f32_16x16x32_bf16 v[96:99], v[176:179], v[196:199], v[96:99]
	v_mfma_f32_16x16x32_bf16 v[84:87], v[160:163], v[204:207], v[84:87]
	v_mfma_f32_16x16x32_bf16 v[80:83], v[176:179], v[204:207], v[80:83]
	v_mfma_f32_16x16x32_bf16 v[68:71], v[160:163], v[212:215], v[68:71]
	v_mfma_f32_16x16x32_bf16 v[64:67], v[176:179], v[212:215], v[64:67]
	s_setprio 0
	s_barrier
	s_add_i32 s22, s49, s37
	v_lshl_add_u64 v[188:189], s[26:27], 0, v[144:145]
	s_mov_b32 m0, s22
	ds_read_b128 v[180:183], v173 offset:16384
	ds_read_b128 v[184:187], v173 offset:17408
	ds_read_b128 v[192:195], v173 offset:18432
	ds_read_b128 v[196:199], v173 offset:19456
	ds_read_b128 v[200:203], v173 offset:20480
	ds_read_b128 v[204:207], v173 offset:21504
	ds_read_b128 v[208:211], v173 offset:22528
	ds_read_b128 v[212:215], v173 offset:23552
	global_load_lds_dwordx4 v[188:189], off
	s_add_i32 m0, s22, 0x2000
	s_add_u32 s22, s26, 0xb0000
	v_lshl_add_u64 v[216:217], s[26:27], 0, v[146:147]
	s_addc_u32 s23, s27, 0
	s_add_i32 s58, s50, s37
	global_load_lds_dwordx4 v[216:217], off
	v_lshl_add_u64 v[218:219], s[22:23], 0, v[144:145]
	s_mov_b32 m0, s58
	v_lshl_add_u64 v[220:221], s[30:31], 0, v[146:147]
	global_load_lds_dwordx4 v[218:219], off
	v_lshl_add_u64 v[218:219], s[22:23], 0, v[146:147]
	s_add_i32 m0, s58, 0x2000
	s_nop 0
	global_load_lds_dwordx4 v[218:219], off
	v_lshl_add_u64 v[218:219], s[30:31], 0, v[144:145]
	s_mov_b32 m0, s38
	s_nop 0
	global_load_lds_dwordx4 v[218:219], off
	s_mov_b32 m0, s39
	s_nop 0
	global_load_lds_dwordx4 v[220:221], off
	s_waitcnt vmcnt(8)
	s_waitcnt lgkmcnt(0)
	s_barrier
	s_setprio 1
	s_waitcnt lgkmcnt(0)
	v_mfma_f32_16x16x32_bf16 v[60:63], v[128:131], v[180:183], v[60:63]
	v_mfma_f32_16x16x32_bf16 v[56:59], v[136:139], v[180:183], v[56:59]
	v_mfma_f32_16x16x32_bf16 v[44:47], v[128:131], v[192:195], v[44:47]
	v_mfma_f32_16x16x32_bf16 v[40:43], v[136:139], v[192:195], v[40:43]
	v_mfma_f32_16x16x32_bf16 v[28:31], v[128:131], v[200:203], v[28:31]
	v_mfma_f32_16x16x32_bf16 v[24:27], v[136:139], v[200:203], v[24:27]
	v_mfma_f32_16x16x32_bf16 v[12:15], v[128:131], v[208:211], v[12:15]
	v_mfma_f32_16x16x32_bf16 v[8:11], v[136:139], v[208:211], v[8:11]
	v_mfma_f32_16x16x32_bf16 v[60:63], v[132:135], v[184:187], v[60:63]
	v_mfma_f32_16x16x32_bf16 v[56:59], v[140:143], v[184:187], v[56:59]
	v_mfma_f32_16x16x32_bf16 v[44:47], v[132:135], v[196:199], v[44:47]
	v_mfma_f32_16x16x32_bf16 v[40:43], v[140:143], v[196:199], v[40:43]
	v_mfma_f32_16x16x32_bf16 v[28:31], v[132:135], v[204:207], v[28:31]
	v_mfma_f32_16x16x32_bf16 v[24:27], v[140:143], v[204:207], v[24:27]
	v_mfma_f32_16x16x32_bf16 v[12:15], v[132:135], v[212:215], v[12:15]
	v_mfma_f32_16x16x32_bf16 v[8:11], v[140:143], v[212:215], v[8:11]
	s_setprio 0
	s_setprio 1
	v_mfma_f32_16x16x32_bf16 v[52:55], v[156:159], v[180:183], v[52:55]
	v_mfma_f32_16x16x32_bf16 v[48:51], v[164:167], v[180:183], v[48:51]
	v_mfma_f32_16x16x32_bf16 v[36:39], v[156:159], v[192:195], v[36:39]
	v_mfma_f32_16x16x32_bf16 v[32:35], v[164:167], v[192:195], v[32:35]
	v_mfma_f32_16x16x32_bf16 v[20:23], v[156:159], v[200:203], v[20:23]
	v_mfma_f32_16x16x32_bf16 v[16:19], v[164:167], v[200:203], v[16:19]
	v_mfma_f32_16x16x32_bf16 v[4:7], v[156:159], v[208:211], v[4:7]
	v_mfma_f32_16x16x32_bf16 v[0:3], v[164:167], v[208:211], v[0:3]
	v_mfma_f32_16x16x32_bf16 v[52:55], v[160:163], v[184:187], v[52:55]
	v_mfma_f32_16x16x32_bf16 v[48:51], v[176:179], v[184:187], v[48:51]
	v_mfma_f32_16x16x32_bf16 v[36:39], v[160:163], v[196:199], v[36:39]
	v_mfma_f32_16x16x32_bf16 v[32:35], v[176:179], v[196:199], v[32:35]
	v_mfma_f32_16x16x32_bf16 v[20:23], v[160:163], v[204:207], v[20:23]
	v_mfma_f32_16x16x32_bf16 v[16:19], v[176:179], v[204:207], v[16:19]
	v_mfma_f32_16x16x32_bf16 v[4:7], v[160:163], v[212:215], v[4:7]
	v_mfma_f32_16x16x32_bf16 v[0:3], v[176:179], v[212:215], v[0:3]
	s_setprio 0
	s_barrier
	s_add_i32 s58, 0, 0x18000
	s_add_i32 s59, 0, 0x1c000
	v_add_u32_e32 v140, s58, v169
	v_add_u32_e32 v175, s59, v169
	ds_read_b128 v[128:131], v140
	ds_read_b128 v[132:135], v140 offset:1024
	ds_read_b128 v[136:139], v140 offset:2048
	ds_read_b128 v[140:143], v140 offset:3072
	ds_read_b128 v[156:159], v175
	ds_read_b128 v[160:163], v175 offset:1024
	ds_read_b128 v[164:167], v175 offset:2048
	ds_read_b128 v[176:179], v175 offset:3072
	s_add_u32 s22, s30, 0xb0000
	s_addc_u32 s23, s31, 0
	s_mov_b32 m0, s40
	v_lshl_add_u64 v[222:223], s[22:23], 0, v[144:145]
	ds_read_b128 v[180:183], v173 offset:32768
	ds_read_b128 v[184:187], v173 offset:33792
	ds_read_b128 v[192:195], v173 offset:34816
	ds_read_b128 v[196:199], v173 offset:35840
	ds_read_b128 v[200:203], v173 offset:36864
	ds_read_b128 v[204:207], v173 offset:37888
	ds_read_b128 v[208:211], v173 offset:38912
	ds_read_b128 v[212:215], v173 offset:39936
	global_load_lds_dwordx4 v[222:223], off
	v_lshl_add_u64 v[222:223], s[22:23], 0, v[146:147]
	s_mov_b32 m0, s41
	s_nop 0
	global_load_lds_dwordx4 v[222:223], off
	s_waitcnt vmcnt(8)
	s_waitcnt lgkmcnt(0)
	s_barrier
	s_setprio 1
	s_waitcnt lgkmcnt(0)
	v_mfma_f32_16x16x32_bf16 v[124:127], v[128:131], v[180:183], v[124:127]
	v_mfma_f32_16x16x32_bf16 v[120:123], v[136:139], v[180:183], v[120:123]
	v_mfma_f32_16x16x32_bf16 v[108:111], v[128:131], v[192:195], v[108:111]
	v_mfma_f32_16x16x32_bf16 v[104:107], v[136:139], v[192:195], v[104:107]
	v_mfma_f32_16x16x32_bf16 v[92:95], v[128:131], v[200:203], v[92:95]
	v_mfma_f32_16x16x32_bf16 v[88:91], v[136:139], v[200:203], v[88:91]
	v_mfma_f32_16x16x32_bf16 v[76:79], v[128:131], v[208:211], v[76:79]
	v_mfma_f32_16x16x32_bf16 v[72:75], v[136:139], v[208:211], v[72:75]
	v_mfma_f32_16x16x32_bf16 v[124:127], v[132:135], v[184:187], v[124:127]
	v_mfma_f32_16x16x32_bf16 v[120:123], v[140:143], v[184:187], v[120:123]
	v_mfma_f32_16x16x32_bf16 v[108:111], v[132:135], v[196:199], v[108:111]
	v_mfma_f32_16x16x32_bf16 v[104:107], v[140:143], v[196:199], v[104:107]
	v_mfma_f32_16x16x32_bf16 v[92:95], v[132:135], v[204:207], v[92:95]
	v_mfma_f32_16x16x32_bf16 v[88:91], v[140:143], v[204:207], v[88:91]
	v_mfma_f32_16x16x32_bf16 v[76:79], v[132:135], v[212:215], v[76:79]
	v_mfma_f32_16x16x32_bf16 v[72:75], v[140:143], v[212:215], v[72:75]
	s_setprio 0
	s_setprio 1
	v_mfma_f32_16x16x32_bf16 v[116:119], v[156:159], v[180:183], v[116:119]
	v_mfma_f32_16x16x32_bf16 v[112:115], v[164:167], v[180:183], v[112:115]
	v_mfma_f32_16x16x32_bf16 v[100:103], v[156:159], v[192:195], v[100:103]
	v_mfma_f32_16x16x32_bf16 v[96:99], v[164:167], v[192:195], v[96:99]
	v_mfma_f32_16x16x32_bf16 v[84:87], v[156:159], v[200:203], v[84:87]
	v_mfma_f32_16x16x32_bf16 v[80:83], v[164:167], v[200:203], v[80:83]
	v_mfma_f32_16x16x32_bf16 v[68:71], v[156:159], v[208:211], v[68:71]
	v_mfma_f32_16x16x32_bf16 v[64:67], v[164:167], v[208:211], v[64:67]
	v_mfma_f32_16x16x32_bf16 v[116:119], v[160:163], v[184:187], v[116:119]
	v_mfma_f32_16x16x32_bf16 v[112:115], v[176:179], v[184:187], v[112:115]
	v_mfma_f32_16x16x32_bf16 v[100:103], v[160:163], v[196:199], v[100:103]
	v_mfma_f32_16x16x32_bf16 v[96:99], v[176:179], v[196:199], v[96:99]
	v_mfma_f32_16x16x32_bf16 v[84:87], v[160:163], v[204:207], v[84:87]
	v_mfma_f32_16x16x32_bf16 v[80:83], v[176:179], v[204:207], v[80:83]
	v_mfma_f32_16x16x32_bf16 v[68:71], v[160:163], v[212:215], v[68:71]
	v_mfma_f32_16x16x32_bf16 v[64:67], v[176:179], v[212:215], v[64:67]
	s_setprio 0
	s_barrier
	s_add_i32 s22, s58, s37
	v_lshl_add_u64 v[188:189], v[188:189], 0, s[16:17]
	s_mov_b32 m0, s22
	ds_read_b128 v[180:183], v173 offset:49152
	ds_read_b128 v[184:187], v173 offset:50176
	ds_read_b128 v[192:195], v173 offset:51200
	ds_read_b128 v[196:199], v173 offset:52224
	ds_read_b128 v[200:203], v173 offset:53248
	ds_read_b128 v[204:207], v173 offset:54272
	ds_read_b128 v[208:211], v173 offset:55296
	ds_read_b128 v[212:215], v173 offset:56320
	global_load_lds_dwordx4 v[188:189], off
	s_add_i32 m0, s22, 0x2000
	s_add_u32 s22, s26, 0xb0080
	v_lshl_add_u64 v[188:189], v[216:217], 0, s[16:17]
	s_addc_u32 s23, s27, 0
	s_add_i32 s26, s59, s37
	global_load_lds_dwordx4 v[188:189], off
	v_lshl_add_u64 v[188:189], s[22:23], 0, v[144:145]
	s_mov_b32 m0, s26
	s_nop 0
	global_load_lds_dwordx4 v[188:189], off
	v_lshl_add_u64 v[188:189], s[22:23], 0, v[146:147]
	s_add_i32 m0, s26, 0x2000
	s_nop 0
	global_load_lds_dwordx4 v[188:189], off
	v_lshl_add_u64 v[188:189], v[218:219], 0, s[16:17]
	s_mov_b32 m0, s43
	s_nop 0
	global_load_lds_dwordx4 v[188:189], off
	v_lshl_add_u64 v[188:189], v[220:221], 0, s[16:17]
	s_mov_b32 m0, s44
	s_nop 0
	global_load_lds_dwordx4 v[188:189], off
	s_waitcnt vmcnt(8)
	s_waitcnt lgkmcnt(0)
	s_barrier
	s_setprio 1
	s_waitcnt lgkmcnt(0)
	v_mfma_f32_16x16x32_bf16 v[60:63], v[128:131], v[180:183], v[60:63]
	v_mfma_f32_16x16x32_bf16 v[56:59], v[136:139], v[180:183], v[56:59]
	v_mfma_f32_16x16x32_bf16 v[44:47], v[128:131], v[192:195], v[44:47]
	v_mfma_f32_16x16x32_bf16 v[40:43], v[136:139], v[192:195], v[40:43]
	v_mfma_f32_16x16x32_bf16 v[28:31], v[128:131], v[200:203], v[28:31]
	v_mfma_f32_16x16x32_bf16 v[24:27], v[136:139], v[200:203], v[24:27]
	v_mfma_f32_16x16x32_bf16 v[12:15], v[128:131], v[208:211], v[12:15]
	v_mfma_f32_16x16x32_bf16 v[8:11], v[136:139], v[208:211], v[8:11]
	v_mfma_f32_16x16x32_bf16 v[60:63], v[132:135], v[184:187], v[60:63]
	v_mfma_f32_16x16x32_bf16 v[56:59], v[140:143], v[184:187], v[56:59]
	v_mfma_f32_16x16x32_bf16 v[44:47], v[132:135], v[196:199], v[44:47]
	v_mfma_f32_16x16x32_bf16 v[40:43], v[140:143], v[196:199], v[40:43]
	v_mfma_f32_16x16x32_bf16 v[28:31], v[132:135], v[204:207], v[28:31]
	v_mfma_f32_16x16x32_bf16 v[24:27], v[140:143], v[204:207], v[24:27]
	v_mfma_f32_16x16x32_bf16 v[12:15], v[132:135], v[212:215], v[12:15]
	v_mfma_f32_16x16x32_bf16 v[8:11], v[140:143], v[212:215], v[8:11]
	s_setprio 0
	s_setprio 1
	v_mfma_f32_16x16x32_bf16 v[52:55], v[156:159], v[180:183], v[52:55]
	v_mfma_f32_16x16x32_bf16 v[48:51], v[164:167], v[180:183], v[48:51]
	v_mfma_f32_16x16x32_bf16 v[36:39], v[156:159], v[192:195], v[36:39]
	v_mfma_f32_16x16x32_bf16 v[32:35], v[164:167], v[192:195], v[32:35]
	v_mfma_f32_16x16x32_bf16 v[20:23], v[156:159], v[200:203], v[20:23]
	v_mfma_f32_16x16x32_bf16 v[16:19], v[164:167], v[200:203], v[16:19]
	v_mfma_f32_16x16x32_bf16 v[4:7], v[156:159], v[208:211], v[4:7]
	v_mfma_f32_16x16x32_bf16 v[0:3], v[164:167], v[208:211], v[0:3]
	v_mfma_f32_16x16x32_bf16 v[52:55], v[160:163], v[184:187], v[52:55]
	v_mfma_f32_16x16x32_bf16 v[48:51], v[176:179], v[184:187], v[48:51]
	v_mfma_f32_16x16x32_bf16 v[36:39], v[160:163], v[196:199], v[36:39]
	v_mfma_f32_16x16x32_bf16 v[32:35], v[176:179], v[196:199], v[32:35]
	v_mfma_f32_16x16x32_bf16 v[20:23], v[160:163], v[204:207], v[20:23]
	v_mfma_f32_16x16x32_bf16 v[16:19], v[176:179], v[204:207], v[16:19]
	v_mfma_f32_16x16x32_bf16 v[4:7], v[160:163], v[212:215], v[4:7]
	v_mfma_f32_16x16x32_bf16 v[0:3], v[176:179], v[212:215], v[0:3]
	s_setprio 0
	s_barrier
	s_add_i32 s57, s57, 2
	s_add_u32 s55, s55, 0x100
	s_addc_u32 s56, s56, 0
	s_cmp_gt_u32 s57, 41
	s_mov_b64 s[22:23], s[24:25]
	s_cbranch_scc0 .LBB0_1187
	v_mbcnt_lo_u32_b32 v235, -1, 0
	v_mbcnt_hi_u32_b32 v235, -1, v235
	v_lshrrev_b32_e32 v236, 2, v235
	v_and_b32_e32 v237, 3, v235
	v_lshl_add_u32 v232, v237, 4, v236
	v_lshlrev_b32_e32 v232, 2, v232
	v_and_b32_e32 v233, -16, v168
	v_or_b32_e32 v233, v233, v236
	v_lshlrev_b32_e32 v237, 2, v237
	v_and_b32_e32 v234, -13, v170
	v_or_b32_e32 v234, v234, v237
	v_lshl_add_u32 v158, s54, 8, v233
	v_lshl_or_b32 v156, s53, 8, v234
	v_ashrrev_i32_e32 v159, 31, v158
	v_lshlrev_b64 v[128:129], 12, v[158:159]
	v_ashrrev_i32_e32 v157, 31, v156
	v_lshl_add_u64 v[128:129], s[8:9], 0, v[128:129]
	v_lshlrev_b64 v[130:131], 2, v[156:157]
	v_lshl_add_u64 v[188:189], v[128:129], 0, v[130:131]
	global_load_dwordx4 v[164:167], v[188:189], off
	global_load_dwordx4 v[176:179], v[188:189], off offset:64
	global_load_dwordx4 v[180:183], v[188:189], off offset:512
	global_load_dwordx4 v[184:187], v[188:189], off offset:576
	v_or_b32_e32 v160, 16, v158
	v_ashrrev_i32_e32 v161, 31, v160
	v_lshlrev_b64 v[128:129], 12, v[160:161]
	v_lshl_add_u64 v[128:129], s[8:9], 0, v[128:129]
	v_lshl_add_u64 v[162:163], v[128:129], 0, v[130:131]
	global_load_dwordx4 v[140:143], v[162:163], off
	global_load_dwordx4 v[136:139], v[162:163], off offset:64
	global_load_dwordx4 v[132:135], v[162:163], off offset:512
	global_load_dwordx4 v[128:131], v[162:163], off offset:576
	v_lshlrev_b64 v[192:193], 11, v[158:159]
	v_lshl_add_u64 v[192:193], s[12:13], 0, v[192:193]
	v_and_b32_e32 v191, 64, v174
	v_lshl_add_u64 v[192:193], v[156:157], 1, v[192:193]
	v_xor_b32_e32 v175, 1, v174
	v_add_u32_e32 v191, 64, v191
	v_cmp_lt_i32_e32 vcc, v175, v191
	v_xor_b32_e32 v194, 2, v174
	ds_bpermute_b32 v127, v232, v127
	ds_bpermute_b32 v126, v232, v126
	ds_bpermute_b32 v125, v232, v125
	ds_bpermute_b32 v124, v232, v124
	ds_bpermute_b32 v123, v232, v123
	ds_bpermute_b32 v122, v232, v122
	ds_bpermute_b32 v121, v232, v121
	ds_bpermute_b32 v120, v232, v120
	ds_bpermute_b32 v119, v232, v119
	ds_bpermute_b32 v118, v232, v118
	ds_bpermute_b32 v117, v232, v117
	ds_bpermute_b32 v116, v232, v116
	ds_bpermute_b32 v115, v232, v115
	ds_bpermute_b32 v114, v232, v114
	ds_bpermute_b32 v113, v232, v113
	ds_bpermute_b32 v112, v232, v112
	ds_bpermute_b32 v111, v232, v111
	ds_bpermute_b32 v110, v232, v110
	ds_bpermute_b32 v109, v232, v109
	ds_bpermute_b32 v108, v232, v108
	ds_bpermute_b32 v107, v232, v107
	ds_bpermute_b32 v106, v232, v106
	ds_bpermute_b32 v105, v232, v105
	ds_bpermute_b32 v104, v232, v104
	ds_bpermute_b32 v103, v232, v103
	ds_bpermute_b32 v102, v232, v102
	ds_bpermute_b32 v101, v232, v101
	ds_bpermute_b32 v100, v232, v100
	ds_bpermute_b32 v99, v232, v99
	ds_bpermute_b32 v98, v232, v98
	ds_bpermute_b32 v97, v232, v97
	ds_bpermute_b32 v96, v232, v96
	ds_bpermute_b32 v95, v232, v95
	ds_bpermute_b32 v94, v232, v94
	ds_bpermute_b32 v93, v232, v93
	ds_bpermute_b32 v92, v232, v92
	ds_bpermute_b32 v91, v232, v91
	ds_bpermute_b32 v90, v232, v90
	ds_bpermute_b32 v89, v232, v89
	ds_bpermute_b32 v88, v232, v88
	ds_bpermute_b32 v87, v232, v87
	ds_bpermute_b32 v86, v232, v86
	ds_bpermute_b32 v85, v232, v85
	ds_bpermute_b32 v84, v232, v84
	ds_bpermute_b32 v83, v232, v83
	ds_bpermute_b32 v82, v232, v82
	ds_bpermute_b32 v81, v232, v81
	ds_bpermute_b32 v80, v232, v80
	ds_bpermute_b32 v79, v232, v79
	ds_bpermute_b32 v78, v232, v78
	ds_bpermute_b32 v77, v232, v77
	ds_bpermute_b32 v76, v232, v76
	ds_bpermute_b32 v75, v232, v75
	ds_bpermute_b32 v74, v232, v74
	ds_bpermute_b32 v73, v232, v73
	ds_bpermute_b32 v72, v232, v72
	ds_bpermute_b32 v71, v232, v71
	ds_bpermute_b32 v70, v232, v70
	ds_bpermute_b32 v69, v232, v69
	ds_bpermute_b32 v68, v232, v68
	ds_bpermute_b32 v67, v232, v67
	ds_bpermute_b32 v66, v232, v66
	ds_bpermute_b32 v65, v232, v65
	ds_bpermute_b32 v64, v232, v64
	ds_bpermute_b32 v63, v232, v63
	ds_bpermute_b32 v62, v232, v62
	ds_bpermute_b32 v61, v232, v61
	ds_bpermute_b32 v60, v232, v60
	ds_bpermute_b32 v59, v232, v59
	ds_bpermute_b32 v58, v232, v58
	ds_bpermute_b32 v57, v232, v57
	ds_bpermute_b32 v56, v232, v56
	ds_bpermute_b32 v55, v232, v55
	ds_bpermute_b32 v54, v232, v54
	ds_bpermute_b32 v53, v232, v53
	ds_bpermute_b32 v52, v232, v52
	ds_bpermute_b32 v51, v232, v51
	ds_bpermute_b32 v50, v232, v50
	ds_bpermute_b32 v49, v232, v49
	ds_bpermute_b32 v48, v232, v48
	ds_bpermute_b32 v47, v232, v47
	ds_bpermute_b32 v46, v232, v46
	ds_bpermute_b32 v45, v232, v45
	ds_bpermute_b32 v44, v232, v44
	ds_bpermute_b32 v43, v232, v43
	ds_bpermute_b32 v42, v232, v42
	ds_bpermute_b32 v41, v232, v41
	ds_bpermute_b32 v40, v232, v40
	ds_bpermute_b32 v39, v232, v39
	ds_bpermute_b32 v38, v232, v38
	ds_bpermute_b32 v37, v232, v37
	ds_bpermute_b32 v36, v232, v36
	ds_bpermute_b32 v35, v232, v35
	ds_bpermute_b32 v34, v232, v34
	ds_bpermute_b32 v33, v232, v33
	ds_bpermute_b32 v32, v232, v32
	ds_bpermute_b32 v31, v232, v31
	ds_bpermute_b32 v30, v232, v30
	ds_bpermute_b32 v29, v232, v29
	ds_bpermute_b32 v28, v232, v28
	ds_bpermute_b32 v27, v232, v27
	ds_bpermute_b32 v26, v232, v26
	ds_bpermute_b32 v25, v232, v25
	ds_bpermute_b32 v24, v232, v24
	ds_bpermute_b32 v23, v232, v23
	ds_bpermute_b32 v22, v232, v22
	ds_bpermute_b32 v21, v232, v21
	ds_bpermute_b32 v20, v232, v20
	ds_bpermute_b32 v19, v232, v19
	ds_bpermute_b32 v18, v232, v18
	ds_bpermute_b32 v17, v232, v17
	ds_bpermute_b32 v16, v232, v16
	ds_bpermute_b32 v15, v232, v15
	ds_bpermute_b32 v14, v232, v14
	ds_bpermute_b32 v13, v232, v13
	ds_bpermute_b32 v12, v232, v12
	ds_bpermute_b32 v11, v232, v11
	ds_bpermute_b32 v10, v232, v10
	ds_bpermute_b32 v9, v232, v9
	ds_bpermute_b32 v8, v232, v8
	ds_bpermute_b32 v7, v232, v7
	ds_bpermute_b32 v6, v232, v6
	ds_bpermute_b32 v5, v232, v5
	ds_bpermute_b32 v4, v232, v4
	ds_bpermute_b32 v3, v232, v3
	ds_bpermute_b32 v2, v232, v2
	ds_bpermute_b32 v1, v232, v1
	ds_bpermute_b32 v0, v232, v0
	s_waitcnt lgkmcnt(0)
	s_waitcnt lgkmcnt(0)
	s_cmp_eq_u64 s[18:19], 0
	s_cbranch_scc1 .LBB0_1190
	s_barrier
.LBB0_1190:
	s_waitcnt vmcnt(7)
	v_pk_fma_f32 v[126:127], v[126:127], 0.5, v[166:167] op_sel_hi:[1,0,1]
	v_pk_fma_f32 v[124:125], v[124:125], 0.5, v[164:165] op_sel_hi:[1,0,1]
	s_waitcnt vmcnt(6)
	v_pk_fma_f32 v[122:123], v[122:123], 0.5, v[178:179] op_sel_hi:[1,0,1]
	v_pk_fma_f32 v[120:121], v[120:121], 0.5, v[176:177] op_sel_hi:[1,0,1]
	s_waitcnt vmcnt(5)
	v_pk_fma_f32 v[118:119], v[118:119], 0.5, v[182:183] op_sel_hi:[1,0,1]
	v_pk_fma_f32 v[116:117], v[116:117], 0.5, v[180:181] op_sel_hi:[1,0,1]
	s_waitcnt vmcnt(4)
	v_pk_fma_f32 v[164:165], v[112:113], 0.5, v[184:185] op_sel_hi:[1,0,1]
	v_mul_f32_e32 v178, v125, v125
	v_mul_f32_e32 v179, v127, v127
	global_store_dwordx4 v[188:189], v[124:127], off
	v_cvt_pk_bf16_f32 v112, v124, v125
	v_cvt_pk_bf16_f32 v113, v126, v127
	v_mul_f32_e32 v125, v121, v121
	v_mul_f32_e32 v127, v123, v123
	v_pk_fma_f32 v[166:167], v[114:115], 0.5, v[186:187] op_sel_hi:[1,0,1]
	v_mul_f32_e32 v180, v117, v117
	v_mul_f32_e32 v181, v119, v119
	v_fmac_f32_e32 v178, v124, v124
	v_fmac_f32_e32 v179, v126, v126
	v_fmac_f32_e32 v125, v120, v120
	v_fmac_f32_e32 v127, v122, v122
	v_mul_f32_e32 v182, v165, v165
	v_mul_f32_e32 v183, v167, v167
	global_store_dwordx2 v[192:193], v[112:113], off
	v_fmac_f32_e32 v180, v116, v116
	v_fmac_f32_e32 v181, v118, v118
	v_add_f32_e32 v112, v178, v179
	v_add_f32_e32 v113, v125, v127
	v_fmac_f32_e32 v182, v164, v164
	v_fmac_f32_e32 v183, v166, v166
	v_add_f32_e32 v124, v180, v181
	v_add_f32_e32 v112, v112, v113
	v_cndmask_b32_e32 v175, v174, v175, vcc
	v_add_f32_e32 v125, v182, v183
	v_add_f32_e32 v112, v112, v124
	v_lshlrev_b32_e32 v175, 2, v175
	v_add_f32_e32 v112, v112, v125
	s_nop 1
	v_mov_b32_dpp v113, v112 quad_perm:[1,0,3,2] row_mask:0xf bank_mask:0xf
	v_cmp_lt_i32_e32 vcc, v194, v191
	v_cvt_pk_bf16_f32 v176, v116, v117
	v_cvt_pk_bf16_f32 v114, v120, v121
	v_cndmask_b32_e32 v191, v174, v194, vcc
	v_cvt_pk_bf16_f32 v115, v122, v123
	v_cvt_pk_bf16_f32 v177, v118, v119
	global_store_dwordx4 v[188:189], v[120:123], off offset:64
	global_store_dwordx2 v[192:193], v[114:115], off offset:32
	global_store_dwordx4 v[188:189], v[116:119], off offset:512
	global_store_dwordx2 v[192:193], v[176:177], off offset:256
	s_waitcnt lgkmcnt(0)
	v_add_f32_e32 v112, v112, v113
	v_lshlrev_b32_e32 v176, 2, v191
	s_nop 1
	v_mov_b32_dpp v113, v112 quad_perm:[2,3,0,1] row_mask:0xf bank_mask:0xf
	v_cvt_pk_bf16_f32 v114, v164, v165
	v_cvt_pk_bf16_f32 v115, v166, v167
	global_store_dwordx4 v[188:189], v[164:167], off offset:576
	global_store_dwordx2 v[192:193], v[114:115], off offset:288
	s_mov_b32 vcc_lo, 0x11111111
	s_mov_b32 vcc_hi, 0x11111111
	s_and_saveexec_b64 s[22:23], vcc
	s_cbranch_execz .LBB0_1192
	v_lshl_add_u64 v[114:115], v[158:159], 2, s[14:15]
	s_waitcnt lgkmcnt(0)
	v_add_f32_e32 v112, v112, v113
	global_atomic_add_f32 v[114:115], v112, off
.LBB0_1192:
	s_or_b64 exec, exec, s[22:23]
	v_or_b32_e32 v164, 32, v158
	v_ashrrev_i32_e32 v165, 31, v164
	s_waitcnt lgkmcnt(0)
	v_lshlrev_b64 v[112:113], 12, v[164:165]
	v_lshl_add_u64 v[112:113], s[8:9], 0, v[112:113]
	v_lshl_add_u64 v[166:167], v[156:157], 2, v[112:113]
	global_load_dwordx4 v[124:127], v[166:167], off
	global_load_dwordx4 v[120:123], v[166:167], off offset:64
	global_load_dwordx4 v[116:119], v[166:167], off offset:512
	global_load_dwordx4 v[112:115], v[166:167], off offset:576
	s_waitcnt vmcnt(15)
	v_pk_fma_f32 v[110:111], v[110:111], 0.5, v[142:143] op_sel_hi:[1,0,1]
	v_pk_fma_f32 v[108:109], v[108:109], 0.5, v[140:141] op_sel_hi:[1,0,1]
	v_mul_f32_e32 v141, v111, v111
	v_mul_f32_e32 v140, v109, v109
	v_fmac_f32_e32 v140, v108, v108
	v_fmac_f32_e32 v141, v110, v110
	v_add_f32_e32 v142, v140, v141
	v_lshlrev_b64 v[140:141], 11, v[160:161]
	v_lshl_add_u64 v[140:141], s[12:13], 0, v[140:141]
	global_store_dwordx4 v[162:163], v[108:111], off
	v_lshl_add_u64 v[140:141], v[156:157], 1, v[140:141]
	s_waitcnt vmcnt(15)
	v_pk_fma_f32 v[104:105], v[104:105], 0.5, v[136:137] op_sel_hi:[1,0,1]
	v_cvt_pk_bf16_f32 v108, v108, v109
	v_cvt_pk_bf16_f32 v109, v110, v111
	global_store_dwordx2 v[140:141], v[108:109], off
	v_pk_fma_f32 v[106:107], v[106:107], 0.5, v[138:139] op_sel_hi:[1,0,1]
	v_mul_f32_e32 v108, v105, v105
	v_fmac_f32_e32 v108, v104, v104
	v_mul_f32_e32 v109, v107, v107
	global_store_dwordx4 v[162:163], v[104:107], off offset:64
	s_waitcnt vmcnt(16)
	v_pk_fma_f32 v[102:103], v[102:103], 0.5, v[134:135] op_sel_hi:[1,0,1]
	v_pk_fma_f32 v[100:101], v[100:101], 0.5, v[132:133] op_sel_hi:[1,0,1]
	v_cvt_pk_bf16_f32 v104, v104, v105
	v_cvt_pk_bf16_f32 v105, v106, v107
	v_fmac_f32_e32 v109, v106, v106
	global_store_dwordx2 v[140:141], v[104:105], off offset:32
	v_mul_f32_e32 v104, v101, v101
	v_mul_f32_e32 v105, v103, v103
	v_add_f32_e32 v108, v108, v109
	v_fmac_f32_e32 v104, v100, v100
	v_fmac_f32_e32 v105, v102, v102
	v_add_f32_e32 v108, v142, v108
	v_add_f32_e32 v104, v104, v105
	v_add_f32_e32 v108, v108, v104
	s_waitcnt vmcnt(16)
	v_pk_fma_f32 v[106:107], v[98:99], 0.5, v[130:131] op_sel_hi:[1,0,1]
	v_pk_fma_f32 v[104:105], v[96:97], 0.5, v[128:129] op_sel_hi:[1,0,1]
	v_mul_f32_e32 v97, v107, v107
	v_mul_f32_e32 v96, v105, v105
	v_fmac_f32_e32 v96, v104, v104
	v_fmac_f32_e32 v97, v106, v106
	v_add_f32_e32 v96, v96, v97
	v_add_f32_e32 v98, v108, v96
	s_nop 1
	v_mov_b32_dpp v99, v98 quad_perm:[1,0,3,2] row_mask:0xf bank_mask:0xf
	v_cvt_pk_bf16_f32 v96, v100, v101
	v_cvt_pk_bf16_f32 v97, v102, v103
	global_store_dwordx4 v[162:163], v[100:103], off offset:512
	global_store_dwordx2 v[140:141], v[96:97], off offset:256
	s_waitcnt lgkmcnt(0)
	v_add_f32_e32 v96, v98, v99
	s_nop 1
	v_mov_b32_dpp v97, v96 quad_perm:[2,3,0,1] row_mask:0xf bank_mask:0xf
	v_cvt_pk_bf16_f32 v98, v104, v105
	v_cvt_pk_bf16_f32 v99, v106, v107
	global_store_dwordx4 v[162:163], v[104:107], off offset:576
	global_store_dwordx2 v[140:141], v[98:99], off offset:288
	s_mov_b32 vcc_lo, 0x11111111
	s_mov_b32 vcc_hi, 0x11111111
	s_and_saveexec_b64 s[22:23], vcc
	s_cbranch_execz .LBB0_1194
	v_lshl_add_u64 v[98:99], v[160:161], 2, s[14:15]
	s_waitcnt lgkmcnt(0)
	v_add_f32_e32 v96, v96, v97
	global_atomic_add_f32 v[98:99], v96, off
.LBB0_1194:
	s_or_b64 exec, exec, s[22:23]
	v_or_b32_e32 v128, 48, v158
	v_ashrrev_i32_e32 v129, 31, v128
	s_waitcnt lgkmcnt(0)
	v_lshlrev_b64 v[96:97], 12, v[128:129]
	v_lshl_add_u64 v[96:97], s[8:9], 0, v[96:97]
	v_lshl_add_u64 v[130:131], v[156:157], 2, v[96:97]
	global_load_dwordx4 v[108:111], v[130:131], off
	global_load_dwordx4 v[104:107], v[130:131], off offset:64
	global_load_dwordx4 v[100:103], v[130:131], off offset:512
	global_load_dwordx4 v[96:99], v[130:131], off offset:576
	s_waitcnt vmcnt(15)
	v_pk_fma_f32 v[94:95], v[94:95], 0.5, v[126:127] op_sel_hi:[1,0,1]
	v_pk_fma_f32 v[92:93], v[92:93], 0.5, v[124:125] op_sel_hi:[1,0,1]
	v_mul_f32_e32 v125, v95, v95
	v_mul_f32_e32 v124, v93, v93
	v_fmac_f32_e32 v124, v92, v92
	v_fmac_f32_e32 v125, v94, v94
	v_add_f32_e32 v126, v124, v125
	v_lshlrev_b64 v[124:125], 11, v[164:165]
	v_lshl_add_u64 v[124:125], s[12:13], 0, v[124:125]
	global_store_dwordx4 v[166:167], v[92:95], off
	v_lshl_add_u64 v[124:125], v[156:157], 1, v[124:125]
	s_waitcnt vmcnt(15)
	v_pk_fma_f32 v[88:89], v[88:89], 0.5, v[120:121] op_sel_hi:[1,0,1]
	v_cvt_pk_bf16_f32 v92, v92, v93
	v_cvt_pk_bf16_f32 v93, v94, v95
	global_store_dwordx2 v[124:125], v[92:93], off
	v_pk_fma_f32 v[90:91], v[90:91], 0.5, v[122:123] op_sel_hi:[1,0,1]
	v_mul_f32_e32 v92, v89, v89
	v_fmac_f32_e32 v92, v88, v88
	v_mul_f32_e32 v93, v91, v91
	global_store_dwordx4 v[166:167], v[88:91], off offset:64
	s_waitcnt vmcnt(16)
	v_pk_fma_f32 v[86:87], v[86:87], 0.5, v[118:119] op_sel_hi:[1,0,1]
	v_pk_fma_f32 v[84:85], v[84:85], 0.5, v[116:117] op_sel_hi:[1,0,1]
	v_cvt_pk_bf16_f32 v88, v88, v89
	v_cvt_pk_bf16_f32 v89, v90, v91
	v_fmac_f32_e32 v93, v90, v90
	global_store_dwordx2 v[124:125], v[88:89], off offset:32
	v_mul_f32_e32 v88, v85, v85
	v_mul_f32_e32 v89, v87, v87
	v_add_f32_e32 v92, v92, v93
	v_fmac_f32_e32 v88, v84, v84
	v_fmac_f32_e32 v89, v86, v86
	v_add_f32_e32 v92, v126, v92
	v_add_f32_e32 v88, v88, v89
	v_add_f32_e32 v92, v92, v88
	s_waitcnt vmcnt(16)
	v_pk_fma_f32 v[90:91], v[82:83], 0.5, v[114:115] op_sel_hi:[1,0,1]
	v_pk_fma_f32 v[88:89], v[80:81], 0.5, v[112:113] op_sel_hi:[1,0,1]
	v_mul_f32_e32 v81, v91, v91
	v_mul_f32_e32 v80, v89, v89
	v_fmac_f32_e32 v80, v88, v88
	v_fmac_f32_e32 v81, v90, v90
	v_add_f32_e32 v80, v80, v81
	v_add_f32_e32 v82, v92, v80
	s_nop 1
	v_mov_b32_dpp v83, v82 quad_perm:[1,0,3,2] row_mask:0xf bank_mask:0xf
	v_cvt_pk_bf16_f32 v80, v84, v85
	v_cvt_pk_bf16_f32 v81, v86, v87
	global_store_dwordx4 v[166:167], v[84:87], off offset:512
	global_store_dwordx2 v[124:125], v[80:81], off offset:256
	s_waitcnt lgkmcnt(0)
	v_add_f32_e32 v80, v82, v83
	s_nop 1
	v_mov_b32_dpp v81, v80 quad_perm:[2,3,0,1] row_mask:0xf bank_mask:0xf
	v_cvt_pk_bf16_f32 v82, v88, v89
	v_cvt_pk_bf16_f32 v83, v90, v91
	global_store_dwordx4 v[166:167], v[88:91], off offset:576
	global_store_dwordx2 v[124:125], v[82:83], off offset:288
	s_mov_b32 vcc_lo, 0x11111111
	s_mov_b32 vcc_hi, 0x11111111
	s_and_saveexec_b64 s[22:23], vcc
	s_cbranch_execz .LBB0_1196
	v_lshl_add_u64 v[82:83], v[164:165], 2, s[14:15]
	s_waitcnt lgkmcnt(0)
	v_add_f32_e32 v80, v80, v81
	global_atomic_add_f32 v[82:83], v80, off
.LBB0_1196:
	s_or_b64 exec, exec, s[22:23]
	v_add_u32_e32 v112, 0x80, v158
	v_ashrrev_i32_e32 v113, 31, v112
	s_waitcnt lgkmcnt(0)
	v_lshlrev_b64 v[80:81], 12, v[112:113]
	v_lshl_add_u64 v[80:81], s[8:9], 0, v[80:81]
	v_lshl_add_u64 v[114:115], v[156:157], 2, v[80:81]
	global_load_dwordx4 v[92:95], v[114:115], off
	global_load_dwordx4 v[88:91], v[114:115], off offset:64
	global_load_dwordx4 v[84:87], v[114:115], off offset:512
	global_load_dwordx4 v[80:83], v[114:115], off offset:576
	s_waitcnt vmcnt(15)
	v_pk_fma_f32 v[78:79], v[78:79], 0.5, v[110:111] op_sel_hi:[1,0,1]
	v_pk_fma_f32 v[76:77], v[76:77], 0.5, v[108:109] op_sel_hi:[1,0,1]
	v_mul_f32_e32 v109, v79, v79
	v_mul_f32_e32 v108, v77, v77
	v_fmac_f32_e32 v108, v76, v76
	v_fmac_f32_e32 v109, v78, v78
	v_add_f32_e32 v110, v108, v109
	v_lshlrev_b64 v[108:109], 11, v[128:129]
	v_lshl_add_u64 v[108:109], s[12:13], 0, v[108:109]
	global_store_dwordx4 v[130:131], v[76:79], off
	v_lshl_add_u64 v[108:109], v[156:157], 1, v[108:109]
	s_waitcnt vmcnt(15)
	v_pk_fma_f32 v[72:73], v[72:73], 0.5, v[104:105] op_sel_hi:[1,0,1]
	v_cvt_pk_bf16_f32 v76, v76, v77
	v_cvt_pk_bf16_f32 v77, v78, v79
	global_store_dwordx2 v[108:109], v[76:77], off
	v_pk_fma_f32 v[74:75], v[74:75], 0.5, v[106:107] op_sel_hi:[1,0,1]
	v_mul_f32_e32 v76, v73, v73
	v_fmac_f32_e32 v76, v72, v72
	v_mul_f32_e32 v77, v75, v75
	global_store_dwordx4 v[130:131], v[72:75], off offset:64
	s_waitcnt vmcnt(16)
	v_pk_fma_f32 v[70:71], v[70:71], 0.5, v[102:103] op_sel_hi:[1,0,1]
	v_pk_fma_f32 v[68:69], v[68:69], 0.5, v[100:101] op_sel_hi:[1,0,1]
	v_cvt_pk_bf16_f32 v72, v72, v73
	v_cvt_pk_bf16_f32 v73, v74, v75
	v_fmac_f32_e32 v77, v74, v74
	global_store_dwordx2 v[108:109], v[72:73], off offset:32
	v_mul_f32_e32 v72, v69, v69
	v_mul_f32_e32 v73, v71, v71
	v_add_f32_e32 v76, v76, v77
	v_fmac_f32_e32 v72, v68, v68
	v_fmac_f32_e32 v73, v70, v70
	v_add_f32_e32 v76, v110, v76
	v_add_f32_e32 v72, v72, v73
	v_add_f32_e32 v76, v76, v72
	s_waitcnt vmcnt(16)
	v_pk_fma_f32 v[74:75], v[66:67], 0.5, v[98:99] op_sel_hi:[1,0,1]
	v_pk_fma_f32 v[72:73], v[64:65], 0.5, v[96:97] op_sel_hi:[1,0,1]
	v_mul_f32_e32 v65, v75, v75
	v_mul_f32_e32 v64, v73, v73
	v_fmac_f32_e32 v64, v72, v72
	v_fmac_f32_e32 v65, v74, v74
	v_add_f32_e32 v64, v64, v65
	v_add_f32_e32 v66, v76, v64
	s_nop 1
	v_mov_b32_dpp v67, v66 quad_perm:[1,0,3,2] row_mask:0xf bank_mask:0xf
	v_cvt_pk_bf16_f32 v64, v68, v69
	v_cvt_pk_bf16_f32 v65, v70, v71
	global_store_dwordx4 v[130:131], v[68:71], off offset:512
	global_store_dwordx2 v[108:109], v[64:65], off offset:256
	s_waitcnt lgkmcnt(0)
	v_add_f32_e32 v64, v66, v67
	s_nop 1
	v_mov_b32_dpp v65, v64 quad_perm:[2,3,0,1] row_mask:0xf bank_mask:0xf
	v_cvt_pk_bf16_f32 v66, v72, v73
	v_cvt_pk_bf16_f32 v67, v74, v75
	global_store_dwordx4 v[130:131], v[72:75], off offset:576
	global_store_dwordx2 v[108:109], v[66:67], off offset:288
	s_mov_b32 vcc_lo, 0x11111111
	s_mov_b32 vcc_hi, 0x11111111
	s_and_saveexec_b64 s[22:23], vcc
	s_cbranch_execz .LBB0_1198
	v_lshl_add_u64 v[66:67], v[128:129], 2, s[14:15]
	s_waitcnt lgkmcnt(0)
	v_add_f32_e32 v64, v64, v65
	global_atomic_add_f32 v[66:67], v64, off
.LBB0_1198:
	s_or_b64 exec, exec, s[22:23]
	v_or_b32_e32 v96, 16, v112
	v_ashrrev_i32_e32 v97, 31, v96
	s_waitcnt lgkmcnt(0)
	v_lshlrev_b64 v[64:65], 12, v[96:97]
	v_lshl_add_u64 v[64:65], s[8:9], 0, v[64:65]
	v_lshl_add_u64 v[98:99], v[156:157], 2, v[64:65]
	global_load_dwordx4 v[76:79], v[98:99], off
	global_load_dwordx4 v[72:75], v[98:99], off offset:64
	global_load_dwordx4 v[68:71], v[98:99], off offset:512
	global_load_dwordx4 v[64:67], v[98:99], off offset:576
	s_waitcnt vmcnt(15)
	v_pk_fma_f32 v[62:63], v[62:63], 0.5, v[94:95] op_sel_hi:[1,0,1]
	v_pk_fma_f32 v[60:61], v[60:61], 0.5, v[92:93] op_sel_hi:[1,0,1]
	v_mul_f32_e32 v93, v63, v63
	v_mul_f32_e32 v92, v61, v61
	v_fmac_f32_e32 v92, v60, v60
	v_fmac_f32_e32 v93, v62, v62
	v_add_f32_e32 v94, v92, v93
	v_lshlrev_b64 v[92:93], 11, v[112:113]
	v_lshl_add_u64 v[92:93], s[12:13], 0, v[92:93]
	global_store_dwordx4 v[114:115], v[60:63], off
	v_lshl_add_u64 v[92:93], v[156:157], 1, v[92:93]
	s_waitcnt vmcnt(15)
	v_pk_fma_f32 v[56:57], v[56:57], 0.5, v[88:89] op_sel_hi:[1,0,1]
	v_cvt_pk_bf16_f32 v60, v60, v61
	v_cvt_pk_bf16_f32 v61, v62, v63
	global_store_dwordx2 v[92:93], v[60:61], off
	v_pk_fma_f32 v[58:59], v[58:59], 0.5, v[90:91] op_sel_hi:[1,0,1]
	v_mul_f32_e32 v60, v57, v57
	v_fmac_f32_e32 v60, v56, v56
	v_mul_f32_e32 v61, v59, v59
	global_store_dwordx4 v[114:115], v[56:59], off offset:64
	s_waitcnt vmcnt(16)
	v_pk_fma_f32 v[54:55], v[54:55], 0.5, v[86:87] op_sel_hi:[1,0,1]
	v_pk_fma_f32 v[52:53], v[52:53], 0.5, v[84:85] op_sel_hi:[1,0,1]
	v_cvt_pk_bf16_f32 v56, v56, v57
	v_cvt_pk_bf16_f32 v57, v58, v59
	v_fmac_f32_e32 v61, v58, v58
	global_store_dwordx2 v[92:93], v[56:57], off offset:32
	v_mul_f32_e32 v56, v53, v53
	v_mul_f32_e32 v57, v55, v55
	v_add_f32_e32 v60, v60, v61
	v_fmac_f32_e32 v56, v52, v52
	v_fmac_f32_e32 v57, v54, v54
	v_add_f32_e32 v60, v94, v60
	v_add_f32_e32 v56, v56, v57
	v_add_f32_e32 v60, v60, v56
	s_waitcnt vmcnt(16)
	v_pk_fma_f32 v[58:59], v[50:51], 0.5, v[82:83] op_sel_hi:[1,0,1]
	v_pk_fma_f32 v[56:57], v[48:49], 0.5, v[80:81] op_sel_hi:[1,0,1]
	v_mul_f32_e32 v49, v59, v59
	v_mul_f32_e32 v48, v57, v57
	v_fmac_f32_e32 v48, v56, v56
	v_fmac_f32_e32 v49, v58, v58
	v_add_f32_e32 v48, v48, v49
	v_add_f32_e32 v50, v60, v48
	s_nop 1
	v_mov_b32_dpp v51, v50 quad_perm:[1,0,3,2] row_mask:0xf bank_mask:0xf
	v_cvt_pk_bf16_f32 v48, v52, v53
	v_cvt_pk_bf16_f32 v49, v54, v55
	global_store_dwordx4 v[114:115], v[52:55], off offset:512
	global_store_dwordx2 v[92:93], v[48:49], off offset:256
	s_waitcnt lgkmcnt(0)
	v_add_f32_e32 v48, v50, v51
	s_nop 1
	v_mov_b32_dpp v49, v48 quad_perm:[2,3,0,1] row_mask:0xf bank_mask:0xf
	v_cvt_pk_bf16_f32 v50, v56, v57
	v_cvt_pk_bf16_f32 v51, v58, v59
	global_store_dwordx4 v[114:115], v[56:59], off offset:576
	global_store_dwordx2 v[92:93], v[50:51], off offset:288
	s_mov_b32 vcc_lo, 0x11111111
	s_mov_b32 vcc_hi, 0x11111111
	s_and_saveexec_b64 s[22:23], vcc
	s_cbranch_execz .LBB0_1200
	v_lshl_add_u64 v[50:51], v[112:113], 2, s[14:15]
	s_waitcnt lgkmcnt(0)
	v_add_f32_e32 v48, v48, v49
	global_atomic_add_f32 v[50:51], v48, off
.LBB0_1200:
	s_or_b64 exec, exec, s[22:23]
	v_or_b32_e32 v80, 32, v112
	v_ashrrev_i32_e32 v81, 31, v80
	s_waitcnt lgkmcnt(0)
	v_lshlrev_b64 v[48:49], 12, v[80:81]
	v_lshl_add_u64 v[48:49], s[8:9], 0, v[48:49]
	v_lshl_add_u64 v[82:83], v[156:157], 2, v[48:49]
	global_load_dwordx4 v[60:63], v[82:83], off
	global_load_dwordx4 v[56:59], v[82:83], off offset:64
	global_load_dwordx4 v[52:55], v[82:83], off offset:512
	global_load_dwordx4 v[48:51], v[82:83], off offset:576
	s_waitcnt vmcnt(15)
	v_pk_fma_f32 v[46:47], v[46:47], 0.5, v[78:79] op_sel_hi:[1,0,1]
	v_pk_fma_f32 v[44:45], v[44:45], 0.5, v[76:77] op_sel_hi:[1,0,1]
	v_mul_f32_e32 v77, v47, v47
	v_mul_f32_e32 v76, v45, v45
	v_fmac_f32_e32 v76, v44, v44
	v_fmac_f32_e32 v77, v46, v46
	v_add_f32_e32 v78, v76, v77
	v_lshlrev_b64 v[76:77], 11, v[96:97]
	v_lshl_add_u64 v[76:77], s[12:13], 0, v[76:77]
	global_store_dwordx4 v[98:99], v[44:47], off
	v_lshl_add_u64 v[76:77], v[156:157], 1, v[76:77]
	s_waitcnt vmcnt(15)
	v_pk_fma_f32 v[40:41], v[40:41], 0.5, v[72:73] op_sel_hi:[1,0,1]
	v_cvt_pk_bf16_f32 v44, v44, v45
	v_cvt_pk_bf16_f32 v45, v46, v47
	global_store_dwordx2 v[76:77], v[44:45], off
	v_pk_fma_f32 v[42:43], v[42:43], 0.5, v[74:75] op_sel_hi:[1,0,1]
	v_mul_f32_e32 v44, v41, v41
	v_fmac_f32_e32 v44, v40, v40
	v_mul_f32_e32 v45, v43, v43
	global_store_dwordx4 v[98:99], v[40:43], off offset:64
	s_waitcnt vmcnt(16)
	v_pk_fma_f32 v[38:39], v[38:39], 0.5, v[70:71] op_sel_hi:[1,0,1]
	v_pk_fma_f32 v[36:37], v[36:37], 0.5, v[68:69] op_sel_hi:[1,0,1]
	v_cvt_pk_bf16_f32 v40, v40, v41
	v_cvt_pk_bf16_f32 v41, v42, v43
	v_fmac_f32_e32 v45, v42, v42
	global_store_dwordx2 v[76:77], v[40:41], off offset:32
	v_mul_f32_e32 v40, v37, v37
	v_mul_f32_e32 v41, v39, v39
	v_add_f32_e32 v44, v44, v45
	v_fmac_f32_e32 v40, v36, v36
	v_fmac_f32_e32 v41, v38, v38
	v_add_f32_e32 v44, v78, v44
	v_add_f32_e32 v40, v40, v41
	v_add_f32_e32 v44, v44, v40
	s_waitcnt vmcnt(16)
	v_pk_fma_f32 v[42:43], v[34:35], 0.5, v[66:67] op_sel_hi:[1,0,1]
	v_pk_fma_f32 v[40:41], v[32:33], 0.5, v[64:65] op_sel_hi:[1,0,1]
	v_mul_f32_e32 v33, v43, v43
	v_mul_f32_e32 v32, v41, v41
	v_fmac_f32_e32 v32, v40, v40
	v_fmac_f32_e32 v33, v42, v42
	v_add_f32_e32 v32, v32, v33
	v_add_f32_e32 v34, v44, v32
	s_nop 1
	v_mov_b32_dpp v35, v34 quad_perm:[1,0,3,2] row_mask:0xf bank_mask:0xf
	v_cvt_pk_bf16_f32 v32, v36, v37
	v_cvt_pk_bf16_f32 v33, v38, v39
	global_store_dwordx4 v[98:99], v[36:39], off offset:512
	global_store_dwordx2 v[76:77], v[32:33], off offset:256
	s_waitcnt lgkmcnt(0)
	v_add_f32_e32 v32, v34, v35
	s_nop 1
	v_mov_b32_dpp v33, v32 quad_perm:[2,3,0,1] row_mask:0xf bank_mask:0xf
	v_cvt_pk_bf16_f32 v34, v40, v41
	v_cvt_pk_bf16_f32 v35, v42, v43
	global_store_dwordx4 v[98:99], v[40:43], off offset:576
	global_store_dwordx2 v[76:77], v[34:35], off offset:288
	s_mov_b32 vcc_lo, 0x11111111
	s_mov_b32 vcc_hi, 0x11111111
	s_and_saveexec_b64 s[22:23], vcc
	s_cbranch_execz .LBB0_1202
	v_lshl_add_u64 v[34:35], v[96:97], 2, s[14:15]
	s_waitcnt lgkmcnt(0)
	v_add_f32_e32 v32, v32, v33
	global_atomic_add_f32 v[34:35], v32, off
.LBB0_1202:
	s_or_b64 exec, exec, s[22:23]
	v_or_b32_e32 v64, 48, v112
	v_ashrrev_i32_e32 v65, 31, v64
	s_waitcnt lgkmcnt(0)
	v_lshlrev_b64 v[32:33], 12, v[64:65]
	v_lshl_add_u64 v[32:33], s[8:9], 0, v[32:33]
	v_lshl_add_u64 v[66:67], v[156:157], 2, v[32:33]
	global_load_dwordx4 v[44:47], v[66:67], off
	global_load_dwordx4 v[40:43], v[66:67], off offset:64
	global_load_dwordx4 v[36:39], v[66:67], off offset:512
	global_load_dwordx4 v[32:35], v[66:67], off offset:576
	s_waitcnt vmcnt(15)
	v_pk_fma_f32 v[30:31], v[30:31], 0.5, v[62:63] op_sel_hi:[1,0,1]
	v_pk_fma_f32 v[28:29], v[28:29], 0.5, v[60:61] op_sel_hi:[1,0,1]
	v_mul_f32_e32 v61, v31, v31
	v_mul_f32_e32 v60, v29, v29
	v_fmac_f32_e32 v60, v28, v28
	v_fmac_f32_e32 v61, v30, v30
	v_add_f32_e32 v62, v60, v61
	v_lshlrev_b64 v[60:61], 11, v[80:81]
	v_lshl_add_u64 v[60:61], s[12:13], 0, v[60:61]
	global_store_dwordx4 v[82:83], v[28:31], off
	v_lshl_add_u64 v[60:61], v[156:157], 1, v[60:61]
	s_waitcnt vmcnt(15)
	v_pk_fma_f32 v[24:25], v[24:25], 0.5, v[56:57] op_sel_hi:[1,0,1]
	v_cvt_pk_bf16_f32 v28, v28, v29
	v_cvt_pk_bf16_f32 v29, v30, v31
	global_store_dwordx2 v[60:61], v[28:29], off
	v_pk_fma_f32 v[26:27], v[26:27], 0.5, v[58:59] op_sel_hi:[1,0,1]
	v_mul_f32_e32 v28, v25, v25
	v_fmac_f32_e32 v28, v24, v24
	v_mul_f32_e32 v29, v27, v27
	global_store_dwordx4 v[82:83], v[24:27], off offset:64
	s_waitcnt vmcnt(16)
	v_pk_fma_f32 v[22:23], v[22:23], 0.5, v[54:55] op_sel_hi:[1,0,1]
	v_pk_fma_f32 v[20:21], v[20:21], 0.5, v[52:53] op_sel_hi:[1,0,1]
	v_cvt_pk_bf16_f32 v24, v24, v25
	v_cvt_pk_bf16_f32 v25, v26, v27
	v_fmac_f32_e32 v29, v26, v26
	global_store_dwordx2 v[60:61], v[24:25], off offset:32
	v_mul_f32_e32 v24, v21, v21
	v_mul_f32_e32 v25, v23, v23
	v_add_f32_e32 v28, v28, v29
	v_fmac_f32_e32 v24, v20, v20
	v_fmac_f32_e32 v25, v22, v22
	v_add_f32_e32 v28, v62, v28
	v_add_f32_e32 v24, v24, v25
	v_add_f32_e32 v28, v28, v24
	s_waitcnt vmcnt(16)
	v_pk_fma_f32 v[26:27], v[18:19], 0.5, v[50:51] op_sel_hi:[1,0,1]
	v_pk_fma_f32 v[24:25], v[16:17], 0.5, v[48:49] op_sel_hi:[1,0,1]
	v_mul_f32_e32 v17, v27, v27
	v_mul_f32_e32 v16, v25, v25
	v_fmac_f32_e32 v16, v24, v24
	v_fmac_f32_e32 v17, v26, v26
	v_add_f32_e32 v16, v16, v17
	v_add_f32_e32 v18, v28, v16
	s_nop 1
	v_mov_b32_dpp v19, v18 quad_perm:[1,0,3,2] row_mask:0xf bank_mask:0xf
	v_cvt_pk_bf16_f32 v16, v20, v21
	v_cvt_pk_bf16_f32 v17, v22, v23
	global_store_dwordx4 v[82:83], v[20:23], off offset:512
	global_store_dwordx2 v[60:61], v[16:17], off offset:256
	s_waitcnt lgkmcnt(0)
	v_add_f32_e32 v16, v18, v19
	s_nop 1
	v_mov_b32_dpp v17, v16 quad_perm:[2,3,0,1] row_mask:0xf bank_mask:0xf
	v_cvt_pk_bf16_f32 v18, v24, v25
	v_cvt_pk_bf16_f32 v19, v26, v27
	global_store_dwordx4 v[82:83], v[24:27], off offset:576
	global_store_dwordx2 v[60:61], v[18:19], off offset:288
	s_mov_b32 vcc_lo, 0x11111111
	s_mov_b32 vcc_hi, 0x11111111
	s_and_saveexec_b64 s[22:23], vcc
	s_cbranch_execz .LBB0_1204
	v_lshl_add_u64 v[18:19], v[80:81], 2, s[14:15]
	s_waitcnt lgkmcnt(0)
	v_add_f32_e32 v16, v16, v17
	global_atomic_add_f32 v[18:19], v16, off
.LBB0_1204:
	s_or_b64 exec, exec, s[22:23]
	s_waitcnt vmcnt(11)
	v_pk_fma_f32 v[14:15], v[14:15], 0.5, v[46:47] op_sel_hi:[1,0,1]
	v_pk_fma_f32 v[12:13], v[12:13], 0.5, v[44:45] op_sel_hi:[1,0,1]
	s_waitcnt lgkmcnt(0)
	v_mul_f32_e32 v17, v15, v15
	v_mul_f32_e32 v16, v13, v13
	v_fmac_f32_e32 v16, v12, v12
	v_fmac_f32_e32 v17, v14, v14
	v_add_f32_e32 v18, v16, v17
	v_lshlrev_b64 v[16:17], 11, v[64:65]
	v_lshl_add_u64 v[16:17], s[12:13], 0, v[16:17]
	global_store_dwordx4 v[66:67], v[12:15], off
	v_lshl_add_u64 v[16:17], v[156:157], 1, v[16:17]
	s_waitcnt vmcnt(11)
	v_pk_fma_f32 v[8:9], v[8:9], 0.5, v[40:41] op_sel_hi:[1,0,1]
	v_cvt_pk_bf16_f32 v12, v12, v13
	v_cvt_pk_bf16_f32 v13, v14, v15
	global_store_dwordx2 v[16:17], v[12:13], off
	v_pk_fma_f32 v[10:11], v[10:11], 0.5, v[42:43] op_sel_hi:[1,0,1]
	v_mul_f32_e32 v12, v9, v9
	v_fmac_f32_e32 v12, v8, v8
	v_mul_f32_e32 v13, v11, v11
	global_store_dwordx4 v[66:67], v[8:11], off offset:64
	s_waitcnt vmcnt(12)
	v_pk_fma_f32 v[6:7], v[6:7], 0.5, v[38:39] op_sel_hi:[1,0,1]
	v_pk_fma_f32 v[4:5], v[4:5], 0.5, v[36:37] op_sel_hi:[1,0,1]
	v_cvt_pk_bf16_f32 v8, v8, v9
	v_cvt_pk_bf16_f32 v9, v10, v11
	v_fmac_f32_e32 v13, v10, v10
	global_store_dwordx2 v[16:17], v[8:9], off offset:32
	v_mul_f32_e32 v8, v5, v5
	v_mul_f32_e32 v9, v7, v7
	v_add_f32_e32 v12, v12, v13
	v_fmac_f32_e32 v8, v4, v4
	v_fmac_f32_e32 v9, v6, v6
	v_add_f32_e32 v12, v18, v12
	v_add_f32_e32 v8, v8, v9
	v_add_f32_e32 v12, v12, v8
	s_waitcnt vmcnt(12)
	v_pk_fma_f32 v[10:11], v[2:3], 0.5, v[34:35] op_sel_hi:[1,0,1]
	v_pk_fma_f32 v[8:9], v[0:1], 0.5, v[32:33] op_sel_hi:[1,0,1]
	v_mul_f32_e32 v1, v11, v11
	v_mul_f32_e32 v0, v9, v9
	v_fmac_f32_e32 v0, v8, v8
	v_fmac_f32_e32 v1, v10, v10
	v_add_f32_e32 v0, v0, v1
	v_add_f32_e32 v2, v12, v0
	s_nop 1
	v_mov_b32_dpp v3, v2 quad_perm:[1,0,3,2] row_mask:0xf bank_mask:0xf
	v_cvt_pk_bf16_f32 v0, v4, v5
	v_cvt_pk_bf16_f32 v1, v6, v7
	global_store_dwordx4 v[66:67], v[4:7], off offset:512
	global_store_dwordx2 v[16:17], v[0:1], off offset:256
	s_waitcnt lgkmcnt(0)
	v_add_f32_e32 v0, v2, v3
	s_nop 1
	v_mov_b32_dpp v1, v0 quad_perm:[2,3,0,1] row_mask:0xf bank_mask:0xf
	v_cvt_pk_bf16_f32 v2, v8, v9
	v_cvt_pk_bf16_f32 v3, v10, v11
	global_store_dwordx4 v[66:67], v[8:11], off offset:576
	global_store_dwordx2 v[16:17], v[2:3], off offset:288
	s_mov_b32 vcc_lo, 0x11111111
	s_mov_b32 vcc_hi, 0x11111111
	s_and_saveexec_b64 s[22:23], vcc
	s_cbranch_execz .LBB0_1206
	v_lshl_add_u64 v[2:3], v[64:65], 2, s[14:15]
	s_waitcnt lgkmcnt(0)
	v_add_f32_e32 v0, v0, v1
	global_atomic_add_f32 v[2:3], v0, off

.LBB0_1307:
	ds_read_b128 v[128:131], v194
	ds_read_b128 v[132:135], v194 offset:1024
	ds_read_b128 v[136:139], v194 offset:2048
	ds_read_b128 v[140:143], v194 offset:3072
	ds_read_b128 v[144:147], v195
	ds_read_b128 v[160:163], v195 offset:1024
	ds_read_b128 v[164:167], v195 offset:2048
	ds_read_b128 v[168:171], v195 offset:3072
	s_add_u32 s36, s0, 0xfffc0080
	s_addc_u32 s37, s1, -1
	s_cmp_eq_u32 s60, 12
	s_cselect_b32 s39, s23, s37
	s_cselect_b32 s38, s33, s36
	s_cselect_b32 s37, s21, s59
	s_cselect_b32 s36, s57, s58
	v_lshl_add_u64 v[188:189], s[0:1], 0, v[154:155]
	s_add_i32 m0, s31, 0xc000
	ds_read_b128 v[172:175], v196
	ds_read_b128 v[176:179], v196 offset:1024
	ds_read_b128 v[180:183], v196 offset:2048
	ds_read_b128 v[184:187], v196 offset:3072
	ds_read_b128 v[200:203], v196 offset:4096
	ds_read_b128 v[204:207], v196 offset:5120
	ds_read_b128 v[208:211], v196 offset:6144
	ds_read_b128 v[212:215], v196 offset:7168
	global_load_lds_dwordx4 v[188:189], off
	v_lshl_add_u64 v[188:189], s[0:1], 0, v[152:153]
	s_add_i32 m0, s31, 0xe000
	s_nop 0
	global_load_lds_dwordx4 v[188:189], off
	s_waitcnt vmcnt(8)
	s_waitcnt lgkmcnt(0)
	s_barrier
	s_setprio 1
	s_waitcnt lgkmcnt(0)
	v_mfma_f32_16x16x32_bf16 v[124:127], v[128:131], v[172:175], v[124:127]
	v_mfma_f32_16x16x32_bf16 v[120:123], v[136:139], v[172:175], v[120:123]
	v_mfma_f32_16x16x32_bf16 v[108:111], v[128:131], v[180:183], v[108:111]
	v_mfma_f32_16x16x32_bf16 v[104:107], v[136:139], v[180:183], v[104:107]
	v_mfma_f32_16x16x32_bf16 v[92:95], v[128:131], v[200:203], v[92:95]
	v_mfma_f32_16x16x32_bf16 v[88:91], v[136:139], v[200:203], v[88:91]
	v_mfma_f32_16x16x32_bf16 v[76:79], v[128:131], v[208:211], v[76:79]
	v_mfma_f32_16x16x32_bf16 v[72:75], v[136:139], v[208:211], v[72:75]
	v_mfma_f32_16x16x32_bf16 v[124:127], v[132:135], v[176:179], v[124:127]
	v_mfma_f32_16x16x32_bf16 v[120:123], v[140:143], v[176:179], v[120:123]
	v_mfma_f32_16x16x32_bf16 v[108:111], v[132:135], v[184:187], v[108:111]
	v_mfma_f32_16x16x32_bf16 v[104:107], v[140:143], v[184:187], v[104:107]
	v_mfma_f32_16x16x32_bf16 v[92:95], v[132:135], v[204:207], v[92:95]
	v_mfma_f32_16x16x32_bf16 v[88:91], v[140:143], v[204:207], v[88:91]
	v_mfma_f32_16x16x32_bf16 v[76:79], v[132:135], v[212:215], v[76:79]
	v_mfma_f32_16x16x32_bf16 v[72:75], v[140:143], v[212:215], v[72:75]
	s_setprio 0
	s_setprio 1
	v_mfma_f32_16x16x32_bf16 v[116:119], v[144:147], v[172:175], v[116:119]
	v_mfma_f32_16x16x32_bf16 v[112:115], v[164:167], v[172:175], v[112:115]
	v_mfma_f32_16x16x32_bf16 v[100:103], v[144:147], v[180:183], v[100:103]
	v_mfma_f32_16x16x32_bf16 v[96:99], v[164:167], v[180:183], v[96:99]
	v_mfma_f32_16x16x32_bf16 v[84:87], v[144:147], v[200:203], v[84:87]
	v_mfma_f32_16x16x32_bf16 v[80:83], v[164:167], v[200:203], v[80:83]
	v_mfma_f32_16x16x32_bf16 v[68:71], v[144:147], v[208:211], v[68:71]
	v_mfma_f32_16x16x32_bf16 v[64:67], v[164:167], v[208:211], v[64:67]
	v_mfma_f32_16x16x32_bf16 v[116:119], v[160:163], v[176:179], v[116:119]
	v_mfma_f32_16x16x32_bf16 v[112:115], v[168:171], v[176:179], v[112:115]
	v_mfma_f32_16x16x32_bf16 v[100:103], v[160:163], v[184:187], v[100:103]
	v_mfma_f32_16x16x32_bf16 v[96:99], v[168:171], v[184:187], v[96:99]
	v_mfma_f32_16x16x32_bf16 v[84:87], v[160:163], v[204:207], v[84:87]
	v_mfma_f32_16x16x32_bf16 v[80:83], v[168:171], v[204:207], v[80:83]
	v_mfma_f32_16x16x32_bf16 v[68:71], v[160:163], v[212:215], v[68:71]
	v_mfma_f32_16x16x32_bf16 v[64:67], v[168:171], v[212:215], v[64:67]
	s_setprio 0
	s_barrier
	s_add_i32 s61, s54, s42
	v_lshl_add_u64 v[188:189], s[36:37], 0, v[148:149]
	s_mov_b32 m0, s61
	ds_read_b128 v[172:175], v196 offset:16384
	ds_read_b128 v[176:179], v196 offset:17408
	ds_read_b128 v[180:183], v196 offset:18432
	ds_read_b128 v[184:187], v196 offset:19456
	ds_read_b128 v[200:203], v196 offset:20480
	ds_read_b128 v[204:207], v196 offset:21504
	ds_read_b128 v[208:211], v196 offset:22528
	ds_read_b128 v[212:215], v196 offset:23552
	global_load_lds_dwordx4 v[188:189], off
	s_add_i32 m0, s61, 0x2000
	s_add_u32 s62, s36, 0x40000
	v_lshl_add_u64 v[216:217], s[36:37], 0, v[150:151]
	s_addc_u32 s63, s37, 0
	s_add_i32 s61, s55, s42
	global_load_lds_dwordx4 v[216:217], off
	v_lshl_add_u64 v[218:219], s[62:63], 0, v[148:149]
	s_mov_b32 m0, s61
	v_lshl_add_u64 v[220:221], s[38:39], 0, v[150:151]
	global_load_lds_dwordx4 v[218:219], off
	v_lshl_add_u64 v[218:219], s[62:63], 0, v[150:151]
	s_add_i32 m0, s61, 0x2000
	s_nop 0
	global_load_lds_dwordx4 v[218:219], off
	v_lshl_add_u64 v[218:219], s[38:39], 0, v[148:149]
	s_mov_b32 m0, s31
	s_nop 0
	global_load_lds_dwordx4 v[218:219], off
	s_mov_b32 m0, s35
	s_nop 0
	global_load_lds_dwordx4 v[220:221], off
	s_waitcnt vmcnt(8)
	s_waitcnt lgkmcnt(0)
	s_barrier
	s_setprio 1
	s_waitcnt lgkmcnt(0)
	v_mfma_f32_16x16x32_bf16 v[60:63], v[128:131], v[172:175], v[60:63]
	v_mfma_f32_16x16x32_bf16 v[56:59], v[136:139], v[172:175], v[56:59]
	v_mfma_f32_16x16x32_bf16 v[44:47], v[128:131], v[180:183], v[44:47]
	v_mfma_f32_16x16x32_bf16 v[40:43], v[136:139], v[180:183], v[40:43]
	v_mfma_f32_16x16x32_bf16 v[28:31], v[128:131], v[200:203], v[28:31]
	v_mfma_f32_16x16x32_bf16 v[24:27], v[136:139], v[200:203], v[24:27]
	v_mfma_f32_16x16x32_bf16 v[12:15], v[128:131], v[208:211], v[12:15]
	v_mfma_f32_16x16x32_bf16 v[8:11], v[136:139], v[208:211], v[8:11]
	v_mfma_f32_16x16x32_bf16 v[60:63], v[132:135], v[176:179], v[60:63]
	v_mfma_f32_16x16x32_bf16 v[56:59], v[140:143], v[176:179], v[56:59]
	v_mfma_f32_16x16x32_bf16 v[44:47], v[132:135], v[184:187], v[44:47]
	v_mfma_f32_16x16x32_bf16 v[40:43], v[140:143], v[184:187], v[40:43]
	v_mfma_f32_16x16x32_bf16 v[28:31], v[132:135], v[204:207], v[28:31]
	v_mfma_f32_16x16x32_bf16 v[24:27], v[140:143], v[204:207], v[24:27]
	v_mfma_f32_16x16x32_bf16 v[12:15], v[132:135], v[212:215], v[12:15]
	v_mfma_f32_16x16x32_bf16 v[8:11], v[140:143], v[212:215], v[8:11]
	s_setprio 0
	s_setprio 1
	v_mfma_f32_16x16x32_bf16 v[52:55], v[144:147], v[172:175], v[52:55]
	v_mfma_f32_16x16x32_bf16 v[48:51], v[164:167], v[172:175], v[48:51]
	v_mfma_f32_16x16x32_bf16 v[36:39], v[144:147], v[180:183], v[36:39]
	v_mfma_f32_16x16x32_bf16 v[32:35], v[164:167], v[180:183], v[32:35]
	v_mfma_f32_16x16x32_bf16 v[20:23], v[144:147], v[200:203], v[20:23]
	v_mfma_f32_16x16x32_bf16 v[16:19], v[164:167], v[200:203], v[16:19]
	v_mfma_f32_16x16x32_bf16 v[4:7], v[144:147], v[208:211], v[4:7]
	v_mfma_f32_16x16x32_bf16 v[0:3], v[164:167], v[208:211], v[0:3]
	v_mfma_f32_16x16x32_bf16 v[52:55], v[160:163], v[176:179], v[52:55]
	v_mfma_f32_16x16x32_bf16 v[48:51], v[168:171], v[176:179], v[48:51]
	v_mfma_f32_16x16x32_bf16 v[36:39], v[160:163], v[184:187], v[36:39]
	v_mfma_f32_16x16x32_bf16 v[32:35], v[168:171], v[184:187], v[32:35]
	v_mfma_f32_16x16x32_bf16 v[20:23], v[160:163], v[204:207], v[20:23]
	v_mfma_f32_16x16x32_bf16 v[16:19], v[168:171], v[204:207], v[16:19]
	v_mfma_f32_16x16x32_bf16 v[4:7], v[160:163], v[212:215], v[4:7]
	v_mfma_f32_16x16x32_bf16 v[0:3], v[168:171], v[212:215], v[0:3]
	s_setprio 0
	s_barrier
	s_add_i32 s61, 0, 0x18000
	s_add_i32 s62, 0, 0x1c000
	v_add_u32_e32 v140, s61, v192
	v_add_u32_e32 v168, s62, v192
	ds_read_b128 v[128:131], v140
	ds_read_b128 v[132:135], v140 offset:1024
	ds_read_b128 v[136:139], v140 offset:2048
	ds_read_b128 v[140:143], v140 offset:3072
	ds_read_b128 v[144:147], v168
	ds_read_b128 v[160:163], v168 offset:1024
	ds_read_b128 v[164:167], v168 offset:2048
	ds_read_b128 v[168:171], v168 offset:3072
	s_add_u32 s38, s38, 0x40000
	s_addc_u32 s39, s39, 0
	s_mov_b32 m0, s45
	v_lshl_add_u64 v[222:223], s[38:39], 0, v[148:149]
	ds_read_b128 v[172:175], v196 offset:32768
	ds_read_b128 v[176:179], v196 offset:33792
	ds_read_b128 v[180:183], v196 offset:34816
	ds_read_b128 v[184:187], v196 offset:35840
	ds_read_b128 v[200:203], v196 offset:36864
	ds_read_b128 v[204:207], v196 offset:37888
	ds_read_b128 v[208:211], v196 offset:38912
	ds_read_b128 v[212:215], v196 offset:39936
	global_load_lds_dwordx4 v[222:223], off
	v_lshl_add_u64 v[222:223], s[38:39], 0, v[150:151]
	s_mov_b32 m0, s46
	s_nop 0
	global_load_lds_dwordx4 v[222:223], off
	s_waitcnt vmcnt(8)
	s_waitcnt lgkmcnt(0)
	s_barrier
	s_setprio 1
	s_waitcnt lgkmcnt(0)
	v_mfma_f32_16x16x32_bf16 v[124:127], v[128:131], v[172:175], v[124:127]
	v_mfma_f32_16x16x32_bf16 v[120:123], v[136:139], v[172:175], v[120:123]
	v_mfma_f32_16x16x32_bf16 v[108:111], v[128:131], v[180:183], v[108:111]
	v_mfma_f32_16x16x32_bf16 v[104:107], v[136:139], v[180:183], v[104:107]
	v_mfma_f32_16x16x32_bf16 v[92:95], v[128:131], v[200:203], v[92:95]
	v_mfma_f32_16x16x32_bf16 v[88:91], v[136:139], v[200:203], v[88:91]
	v_mfma_f32_16x16x32_bf16 v[76:79], v[128:131], v[208:211], v[76:79]
	v_mfma_f32_16x16x32_bf16 v[72:75], v[136:139], v[208:211], v[72:75]
	v_mfma_f32_16x16x32_bf16 v[124:127], v[132:135], v[176:179], v[124:127]
	v_mfma_f32_16x16x32_bf16 v[120:123], v[140:143], v[176:179], v[120:123]
	v_mfma_f32_16x16x32_bf16 v[108:111], v[132:135], v[184:187], v[108:111]
	v_mfma_f32_16x16x32_bf16 v[104:107], v[140:143], v[184:187], v[104:107]
	v_mfma_f32_16x16x32_bf16 v[92:95], v[132:135], v[204:207], v[92:95]
	v_mfma_f32_16x16x32_bf16 v[88:91], v[140:143], v[204:207], v[88:91]
	v_mfma_f32_16x16x32_bf16 v[76:79], v[132:135], v[212:215], v[76:79]
	v_mfma_f32_16x16x32_bf16 v[72:75], v[140:143], v[212:215], v[72:75]
	s_setprio 0
	s_setprio 1
	v_mfma_f32_16x16x32_bf16 v[116:119], v[144:147], v[172:175], v[116:119]
	v_mfma_f32_16x16x32_bf16 v[112:115], v[164:167], v[172:175], v[112:115]
	v_mfma_f32_16x16x32_bf16 v[100:103], v[144:147], v[180:183], v[100:103]
	v_mfma_f32_16x16x32_bf16 v[96:99], v[164:167], v[180:183], v[96:99]
	v_mfma_f32_16x16x32_bf16 v[84:87], v[144:147], v[200:203], v[84:87]
	v_mfma_f32_16x16x32_bf16 v[80:83], v[164:167], v[200:203], v[80:83]
	v_mfma_f32_16x16x32_bf16 v[68:71], v[144:147], v[208:211], v[68:71]
	v_mfma_f32_16x16x32_bf16 v[64:67], v[164:167], v[208:211], v[64:67]
	v_mfma_f32_16x16x32_bf16 v[116:119], v[160:163], v[176:179], v[116:119]
	v_mfma_f32_16x16x32_bf16 v[112:115], v[168:171], v[176:179], v[112:115]
	v_mfma_f32_16x16x32_bf16 v[100:103], v[160:163], v[184:187], v[100:103]
	v_mfma_f32_16x16x32_bf16 v[96:99], v[168:171], v[184:187], v[96:99]
	v_mfma_f32_16x16x32_bf16 v[84:87], v[160:163], v[204:207], v[84:87]
	v_mfma_f32_16x16x32_bf16 v[80:83], v[168:171], v[204:207], v[80:83]
	v_mfma_f32_16x16x32_bf16 v[68:71], v[160:163], v[212:215], v[68:71]
	v_mfma_f32_16x16x32_bf16 v[64:67], v[168:171], v[212:215], v[64:67]
	s_setprio 0
	s_barrier
	s_add_i32 s38, s61, s42
	v_lshl_add_u64 v[188:189], v[188:189], 0, s[16:17]
	s_mov_b32 m0, s38
	ds_read_b128 v[172:175], v196 offset:49152
	ds_read_b128 v[176:179], v196 offset:50176
	ds_read_b128 v[180:183], v196 offset:51200
	ds_read_b128 v[184:187], v196 offset:52224
	ds_read_b128 v[200:203], v196 offset:53248
	ds_read_b128 v[204:207], v196 offset:54272
	ds_read_b128 v[208:211], v196 offset:55296
	ds_read_b128 v[212:215], v196 offset:56320
	global_load_lds_dwordx4 v[188:189], off
	s_add_i32 m0, s38, 0x2000
	s_add_u32 s36, s36, 0x40080
	v_lshl_add_u64 v[188:189], v[216:217], 0, s[16:17]
	s_addc_u32 s37, s37, 0
	s_add_i32 s38, s62, s42
	global_load_lds_dwordx4 v[188:189], off
	v_lshl_add_u64 v[188:189], s[36:37], 0, v[148:149]
	s_mov_b32 m0, s38
	s_nop 0
	global_load_lds_dwordx4 v[188:189], off
	v_lshl_add_u64 v[188:189], s[36:37], 0, v[150:151]
	s_add_i32 m0, s38, 0x2000
	s_nop 0
	global_load_lds_dwordx4 v[188:189], off
	v_lshl_add_u64 v[188:189], v[218:219], 0, s[16:17]
	s_mov_b32 m0, s48
	s_nop 0
	global_load_lds_dwordx4 v[188:189], off
	v_lshl_add_u64 v[188:189], v[220:221], 0, s[16:17]
	s_mov_b32 m0, s49
	s_nop 0
	global_load_lds_dwordx4 v[188:189], off
	s_waitcnt vmcnt(8)
	s_waitcnt lgkmcnt(0)
	s_barrier
	s_setprio 1
	s_waitcnt lgkmcnt(0)
	v_mfma_f32_16x16x32_bf16 v[60:63], v[128:131], v[172:175], v[60:63]
	v_mfma_f32_16x16x32_bf16 v[56:59], v[136:139], v[172:175], v[56:59]
	v_mfma_f32_16x16x32_bf16 v[44:47], v[128:131], v[180:183], v[44:47]
	v_mfma_f32_16x16x32_bf16 v[40:43], v[136:139], v[180:183], v[40:43]
	v_mfma_f32_16x16x32_bf16 v[28:31], v[128:131], v[200:203], v[28:31]
	v_mfma_f32_16x16x32_bf16 v[24:27], v[136:139], v[200:203], v[24:27]
	v_mfma_f32_16x16x32_bf16 v[12:15], v[128:131], v[208:211], v[12:15]
	v_mfma_f32_16x16x32_bf16 v[8:11], v[136:139], v[208:211], v[8:11]
	v_mfma_f32_16x16x32_bf16 v[60:63], v[132:135], v[176:179], v[60:63]
	v_mfma_f32_16x16x32_bf16 v[56:59], v[140:143], v[176:179], v[56:59]
	v_mfma_f32_16x16x32_bf16 v[44:47], v[132:135], v[184:187], v[44:47]
	v_mfma_f32_16x16x32_bf16 v[40:43], v[140:143], v[184:187], v[40:43]
	v_mfma_f32_16x16x32_bf16 v[28:31], v[132:135], v[204:207], v[28:31]
	v_mfma_f32_16x16x32_bf16 v[24:27], v[140:143], v[204:207], v[24:27]
	v_mfma_f32_16x16x32_bf16 v[12:15], v[132:135], v[212:215], v[12:15]
	v_mfma_f32_16x16x32_bf16 v[8:11], v[140:143], v[212:215], v[8:11]
	s_setprio 0
	s_setprio 1
	v_mfma_f32_16x16x32_bf16 v[52:55], v[144:147], v[172:175], v[52:55]
	v_mfma_f32_16x16x32_bf16 v[48:51], v[164:167], v[172:175], v[48:51]
	v_mfma_f32_16x16x32_bf16 v[36:39], v[144:147], v[180:183], v[36:39]
	v_mfma_f32_16x16x32_bf16 v[32:35], v[164:167], v[180:183], v[32:35]
	v_mfma_f32_16x16x32_bf16 v[20:23], v[144:147], v[200:203], v[20:23]
	v_mfma_f32_16x16x32_bf16 v[16:19], v[164:167], v[200:203], v[16:19]
	v_mfma_f32_16x16x32_bf16 v[4:7], v[144:147], v[208:211], v[4:7]
	v_mfma_f32_16x16x32_bf16 v[0:3], v[164:167], v[208:211], v[0:3]
	v_mfma_f32_16x16x32_bf16 v[52:55], v[160:163], v[176:179], v[52:55]
	v_mfma_f32_16x16x32_bf16 v[48:51], v[168:171], v[176:179], v[48:51]
	v_mfma_f32_16x16x32_bf16 v[36:39], v[160:163], v[184:187], v[36:39]
	v_mfma_f32_16x16x32_bf16 v[32:35], v[168:171], v[184:187], v[32:35]
	v_mfma_f32_16x16x32_bf16 v[20:23], v[160:163], v[204:207], v[20:23]
	v_mfma_f32_16x16x32_bf16 v[16:19], v[168:171], v[204:207], v[16:19]
	v_mfma_f32_16x16x32_bf16 v[4:7], v[160:163], v[212:215], v[4:7]
	v_mfma_f32_16x16x32_bf16 v[0:3], v[168:171], v[212:215], v[0:3]
	s_setprio 0
	s_barrier
	s_add_i32 s60, s60, 2
	s_add_u32 s58, s58, 0x100
	s_addc_u32 s59, s59, 0
	s_add_u32 s0, s0, 0x100
	s_addc_u32 s1, s1, 0
	s_cmp_gt_u32 s60, 13
	s_cbranch_scc0 .LBB0_1307
	v_mbcnt_lo_u32_b32 v235, -1, 0
	v_mbcnt_hi_u32_b32 v235, -1, v235
	v_lshrrev_b32_e32 v236, 2, v235
	v_and_b32_e32 v237, 3, v235
	v_lshl_add_u32 v232, v237, 4, v236
	v_lshlrev_b32_e32 v232, 2, v232
	v_and_b32_e32 v233, -16, v191
	v_or_b32_e32 v233, v233, v236
	v_lshlrev_b32_e32 v237, 2, v237
	v_and_b32_e32 v234, -13, v193
	v_or_b32_e32 v234, v234, v237
	v_lshl_add_u32 v164, s30, 8, v233
	v_ashrrev_i32_e32 v165, 31, v164
	v_lshl_add_u64 v[162:163], v[164:165], 2, s[14:15]
	global_load_dword v181, v[162:163], off
	v_lshl_or_b32 v160, s34, 8, v234
	v_lshlrev_b64 v[128:129], 11, v[164:165]
	v_ashrrev_i32_e32 v161, 31, v160
	v_lshl_add_u64 v[128:129], s[8:9], 0, v[128:129]
	v_lshlrev_b64 v[130:131], 1, v[160:161]
	v_lshl_add_u64 v[172:173], v[128:129], 0, v[130:131]
	v_lshlrev_b64 v[128:129], 12, v[164:165]
	v_lshlrev_b64 v[132:133], 2, v[160:161]
	v_lshl_add_u64 v[128:129], s[6:7], 0, v[128:129]
	global_load_dwordx2 v[184:185], v[172:173], off
	global_load_dwordx2 v[188:189], v[172:173], off offset:32
	v_lshl_add_u64 v[176:177], v[128:129], 0, v[132:133]
	global_load_dwordx4 v[200:203], v[176:177], off
	global_load_dwordx4 v[204:207], v[176:177], off offset:64
	v_or_b32_e32 v166, 16, v164
	v_ashrrev_i32_e32 v167, 31, v166
	v_lshl_add_u64 v[136:137], v[166:167], 2, s[14:15]
	global_load_dword v180, v[136:137], off
	global_load_dwordx4 v[208:211], v[176:177], off offset:512
	global_load_dwordx4 v[144:147], v[176:177], off offset:576
	global_load_dwordx2 v[212:213], v[172:173], off offset:256
	global_load_dwordx2 v[214:215], v[172:173], off offset:288
	v_lshlrev_b64 v[128:129], 12, v[166:167]
	v_lshlrev_b64 v[134:135], 11, v[166:167]
	v_lshl_add_u64 v[128:129], s[6:7], 0, v[128:129]
	v_lshl_add_u64 v[134:135], s[8:9], 0, v[134:135]
	v_lshl_add_u64 v[170:171], v[128:129], 0, v[132:133]
	v_lshl_add_u64 v[168:169], v[134:135], 0, v[130:131]
	global_load_dwordx4 v[140:143], v[170:171], off
	global_load_dwordx4 v[136:139], v[170:171], off offset:64
	global_load_dwordx4 v[132:135], v[170:171], off offset:512
	global_load_dwordx4 v[128:131], v[170:171], off offset:576
	global_load_dwordx2 v[186:187], v[168:169], off
	global_load_dwordx2 v[182:183], v[168:169], off offset:32
	global_load_dwordx2 v[178:179], v[168:169], off offset:256
	global_load_dwordx2 v[174:175], v[168:169], off offset:288
	ds_bpermute_b32 v127, v232, v127
	ds_bpermute_b32 v126, v232, v126
	ds_bpermute_b32 v125, v232, v125
	ds_bpermute_b32 v124, v232, v124
	ds_bpermute_b32 v123, v232, v123
	ds_bpermute_b32 v122, v232, v122
	ds_bpermute_b32 v121, v232, v121
	ds_bpermute_b32 v120, v232, v120
	ds_bpermute_b32 v119, v232, v119
	ds_bpermute_b32 v118, v232, v118
	ds_bpermute_b32 v117, v232, v117
	ds_bpermute_b32 v116, v232, v116
	ds_bpermute_b32 v115, v232, v115
	ds_bpermute_b32 v114, v232, v114
	ds_bpermute_b32 v113, v232, v113
	ds_bpermute_b32 v112, v232, v112
	ds_bpermute_b32 v111, v232, v111
	ds_bpermute_b32 v110, v232, v110
	ds_bpermute_b32 v109, v232, v109
	ds_bpermute_b32 v108, v232, v108
	ds_bpermute_b32 v107, v232, v107
	ds_bpermute_b32 v106, v232, v106
	ds_bpermute_b32 v105, v232, v105
	ds_bpermute_b32 v104, v232, v104
	ds_bpermute_b32 v103, v232, v103
	ds_bpermute_b32 v102, v232, v102
	ds_bpermute_b32 v101, v232, v101
	ds_bpermute_b32 v100, v232, v100
	ds_bpermute_b32 v99, v232, v99
	ds_bpermute_b32 v98, v232, v98
	ds_bpermute_b32 v97, v232, v97
	ds_bpermute_b32 v96, v232, v96
	ds_bpermute_b32 v95, v232, v95
	ds_bpermute_b32 v94, v232, v94
	ds_bpermute_b32 v93, v232, v93
	ds_bpermute_b32 v92, v232, v92
	ds_bpermute_b32 v91, v232, v91
	ds_bpermute_b32 v90, v232, v90
	ds_bpermute_b32 v89, v232, v89
	ds_bpermute_b32 v88, v232, v88
	ds_bpermute_b32 v87, v232, v87
	ds_bpermute_b32 v86, v232, v86
	ds_bpermute_b32 v85, v232, v85
	ds_bpermute_b32 v84, v232, v84
	ds_bpermute_b32 v83, v232, v83
	ds_bpermute_b32 v82, v232, v82
	ds_bpermute_b32 v81, v232, v81
	ds_bpermute_b32 v80, v232, v80
	ds_bpermute_b32 v79, v232, v79
	ds_bpermute_b32 v78, v232, v78
	ds_bpermute_b32 v77, v232, v77
	ds_bpermute_b32 v76, v232, v76
	ds_bpermute_b32 v75, v232, v75
	ds_bpermute_b32 v74, v232, v74
	ds_bpermute_b32 v73, v232, v73
	ds_bpermute_b32 v72, v232, v72
	ds_bpermute_b32 v71, v232, v71
	ds_bpermute_b32 v70, v232, v70
	ds_bpermute_b32 v69, v232, v69
	ds_bpermute_b32 v68, v232, v68
	ds_bpermute_b32 v67, v232, v67
	ds_bpermute_b32 v66, v232, v66
	ds_bpermute_b32 v65, v232, v65
	ds_bpermute_b32 v64, v232, v64
	ds_bpermute_b32 v63, v232, v63
	ds_bpermute_b32 v62, v232, v62
	ds_bpermute_b32 v61, v232, v61
	ds_bpermute_b32 v60, v232, v60
	ds_bpermute_b32 v59, v232, v59
	ds_bpermute_b32 v58, v232, v58
	ds_bpermute_b32 v57, v232, v57
	ds_bpermute_b32 v56, v232, v56
	ds_bpermute_b32 v55, v232, v55
	ds_bpermute_b32 v54, v232, v54
	ds_bpermute_b32 v53, v232, v53
	ds_bpermute_b32 v52, v232, v52
	ds_bpermute_b32 v51, v232, v51
	ds_bpermute_b32 v50, v232, v50
	ds_bpermute_b32 v49, v232, v49
	ds_bpermute_b32 v48, v232, v48
	ds_bpermute_b32 v47, v232, v47
	ds_bpermute_b32 v46, v232, v46
	ds_bpermute_b32 v45, v232, v45
	ds_bpermute_b32 v44, v232, v44
	ds_bpermute_b32 v43, v232, v43
	ds_bpermute_b32 v42, v232, v42
	ds_bpermute_b32 v41, v232, v41
	ds_bpermute_b32 v40, v232, v40
	ds_bpermute_b32 v39, v232, v39
	ds_bpermute_b32 v38, v232, v38
	ds_bpermute_b32 v37, v232, v37
	ds_bpermute_b32 v36, v232, v36
	ds_bpermute_b32 v35, v232, v35
	ds_bpermute_b32 v34, v232, v34
	ds_bpermute_b32 v33, v232, v33
	ds_bpermute_b32 v32, v232, v32
	ds_bpermute_b32 v31, v232, v31
	ds_bpermute_b32 v30, v232, v30
	ds_bpermute_b32 v29, v232, v29
	ds_bpermute_b32 v28, v232, v28
	ds_bpermute_b32 v27, v232, v27
	ds_bpermute_b32 v26, v232, v26
	ds_bpermute_b32 v25, v232, v25
	ds_bpermute_b32 v24, v232, v24
	ds_bpermute_b32 v23, v232, v23
	ds_bpermute_b32 v22, v232, v22
	ds_bpermute_b32 v21, v232, v21
	ds_bpermute_b32 v20, v232, v20
	ds_bpermute_b32 v19, v232, v19
	ds_bpermute_b32 v18, v232, v18
	ds_bpermute_b32 v17, v232, v17
	ds_bpermute_b32 v16, v232, v16
	ds_bpermute_b32 v15, v232, v15
	ds_bpermute_b32 v14, v232, v14
	ds_bpermute_b32 v13, v232, v13
	ds_bpermute_b32 v12, v232, v12
	ds_bpermute_b32 v11, v232, v11
	ds_bpermute_b32 v10, v232, v10
	ds_bpermute_b32 v9, v232, v9
	ds_bpermute_b32 v8, v232, v8
	ds_bpermute_b32 v7, v232, v7
	ds_bpermute_b32 v6, v232, v6
	ds_bpermute_b32 v5, v232, v5
	ds_bpermute_b32 v4, v232, v4
	ds_bpermute_b32 v3, v232, v3
	ds_bpermute_b32 v2, v232, v2
	ds_bpermute_b32 v1, v232, v1
	ds_bpermute_b32 v0, v232, v0
	s_waitcnt lgkmcnt(0)
	s_waitcnt lgkmcnt(0)
	s_and_b64 vcc, exec, s[18:19]
	s_cbranch_vccz .LBB0_1310
	s_barrier
.LBB0_1310:
	s_waitcnt vmcnt(17)
	v_fmamk_f32 v181, v181, 0x3a800000, v197
	v_mul_f32_e32 v199, 0x4b800000, v181
	v_cmp_gt_f32_e32 vcc, s56, v181
	s_waitcnt vmcnt(16)
	v_lshlrev_b32_e32 v216, 16, v184
	s_nop 0
	v_cndmask_b32_e32 v181, v181, v199, vcc
	v_rsq_f32_e32 v181, v181
	v_and_b32_e32 v217, 0xffff0000, v184
	v_lshlrev_b32_e32 v184, 16, v185
	v_and_b32_e32 v185, 0xffff0000, v185
	v_mul_f32_e32 v199, 0x45800000, v181
	v_cndmask_b32_e32 v220, v181, v199, vcc
	v_pk_mul_f32 v[126:127], v[126:127], v[220:221] op_sel_hi:[1,0]
	v_pk_mul_f32 v[124:125], v[124:125], v[220:221] op_sel_hi:[1,0]
	v_pk_mul_f32 v[122:123], v[122:123], v[220:221] op_sel_hi:[1,0]
	v_pk_mul_f32 v[120:121], v[120:121], v[220:221] op_sel_hi:[1,0]
	v_mul_f32_e32 v124, 0xbfb8aa3b, v124
	v_mul_f32_e32 v125, 0xbfb8aa3b, v125
	v_mul_f32_e32 v126, 0xbfb8aa3b, v126
	v_mul_f32_e32 v127, 0xbfb8aa3b, v127
	v_mul_f32_e32 v120, 0xbfb8aa3b, v120
	v_mul_f32_e32 v121, 0xbfb8aa3b, v121
	v_mul_f32_e32 v122, 0xbfb8aa3b, v122
	v_mul_f32_e32 v123, 0xbfb8aa3b, v123
	v_exp_f32_e32 v124, v124
	v_exp_f32_e32 v125, v125
	v_exp_f32_e32 v126, v126
	v_exp_f32_e32 v127, v127
	v_exp_f32_e32 v120, v120
	v_exp_f32_e32 v121, v121
	v_exp_f32_e32 v122, v122
	v_exp_f32_e32 v123, v123
	v_add_f32_e32 v124, 1.0, v124
	v_add_f32_e32 v125, 1.0, v125
	v_add_f32_e32 v126, 1.0, v126
	v_add_f32_e32 v127, 1.0, v127
	v_add_f32_e32 v181, 1.0, v120
	v_add_f32_e32 v199, 1.0, v121
	v_add_f32_e32 v221, 1.0, v122
	v_add_f32_e32 v222, 1.0, v123
	v_rcp_f32_e32 v120, v124
	v_rcp_f32_e32 v121, v125
	v_rcp_f32_e32 v122, v126
	v_rcp_f32_e32 v123, v127
	v_rcp_f32_e32 v124, v181
	v_rcp_f32_e32 v125, v199
	v_rcp_f32_e32 v126, v221
	v_rcp_f32_e32 v127, v222
	s_waitcnt vmcnt(14)
	v_pk_fma_f32 v[120:121], v[120:121], v[216:217], v[200:201]
	v_pk_fma_f32 v[122:123], v[122:123], v[184:185], v[202:203]
	v_pk_mul_f32 v[116:117], v[116:117], v[220:221] op_sel_hi:[1,0]
	v_lshlrev_b32_e32 v218, 16, v188
	v_and_b32_e32 v219, 0xffff0000, v188
	v_lshlrev_b32_e32 v188, 16, v189
	v_and_b32_e32 v189, 0xffff0000, v189
	v_pk_mul_f32 v[184:185], v[120:121], v[120:121]
	global_store_dwordx4 v[176:177], v[120:123], off
	v_mul_f32_e32 v116, 0xbfb8aa3b, v116
	s_waitcnt vmcnt(14)
	v_pk_fma_f32 v[124:125], v[124:125], v[218:219], v[204:205]
	v_cvt_pk_bf16_f32 v120, v120, v121
	v_cvt_pk_bf16_f32 v121, v122, v123
	v_pk_fma_f32 v[126:127], v[126:127], v[188:189], v[206:207]
	global_store_dwordx2 v[172:173], v[120:121], off
	global_store_dwordx4 v[176:177], v[124:127], off offset:64
	v_exp_f32_e32 v120, v116
	v_mul_f32_e32 v116, 0xbfb8aa3b, v117
	v_exp_f32_e32 v121, v116
	v_pk_mul_f32 v[116:117], v[118:119], v[220:221] op_sel_hi:[1,0]
	v_add_f32_e32 v118, 1.0, v120
	v_mul_f32_e32 v116, 0xbfb8aa3b, v116
	v_exp_f32_e32 v116, v116
	v_mul_f32_e32 v117, 0xbfb8aa3b, v117
	v_add_f32_e32 v119, 1.0, v121
	v_exp_f32_e32 v117, v117
	v_rcp_f32_e32 v118, v118
	v_rcp_f32_e32 v119, v119
	v_pk_mul_f32 v[188:189], v[122:123], v[122:123]
	v_cvt_pk_bf16_f32 v122, v124, v125
	v_cvt_pk_bf16_f32 v123, v126, v127
	v_add_f32_e32 v116, 1.0, v116
	v_pk_mul_f32 v[112:113], v[112:113], v[220:221] op_sel_hi:[1,0]
	global_store_dwordx2 v[172:173], v[122:123], off offset:32
	s_waitcnt vmcnt(13)
	v_lshlrev_b32_e32 v120, 16, v212
	v_and_b32_e32 v121, 0xffff0000, v212
	v_rcp_f32_e32 v122, v116
	v_add_f32_e32 v116, 1.0, v117
	v_mul_f32_e32 v112, 0xbfb8aa3b, v112
	v_rcp_f32_e32 v123, v116
	v_pk_fma_f32 v[116:117], v[118:119], v[120:121], v[208:209]
	v_exp_f32_e32 v120, v112
	v_mul_f32_e32 v112, 0xbfb8aa3b, v113
	v_exp_f32_e32 v121, v112
	v_pk_mul_f32 v[112:113], v[114:115], v[220:221] op_sel_hi:[1,0]
	v_add_f32_e32 v114, 1.0, v120
	v_mul_f32_e32 v112, 0xbfb8aa3b, v112
	v_mul_f32_e32 v113, 0xbfb8aa3b, v113
	v_exp_f32_e32 v112, v112
	v_exp_f32_e32 v113, v113
	v_add_f32_e32 v115, 1.0, v121
	v_rcp_f32_e32 v114, v114
	v_rcp_f32_e32 v115, v115
	v_add_f32_e32 v112, 1.0, v112
	v_add_f32_e32 v113, 1.0, v113
	v_rcp_f32_e32 v112, v112
	v_rcp_f32_e32 v113, v113
	v_pk_mul_f32 v[200:201], v[124:125], v[124:125]
	v_pk_mul_f32 v[202:203], v[126:127], v[126:127]
	v_lshlrev_b32_e32 v118, 16, v213
	v_and_b32_e32 v119, 0xffff0000, v213
	s_waitcnt vmcnt(12)
	v_lshlrev_b32_e32 v120, 16, v214
	v_and_b32_e32 v121, 0xffff0000, v214
	v_pk_fma_f32 v[118:119], v[122:123], v[118:119], v[210:211]
	v_pk_fma_f32 v[120:121], v[114:115], v[120:121], v[144:145]
	v_lshlrev_b32_e32 v114, 16, v215
	v_and_b32_e32 v115, 0xffff0000, v215
	v_add_f32_e32 v144, v202, v203
	v_add_f32_e32 v145, v200, v201
	v_pk_mul_f32 v[124:125], v[116:117], v[116:117]
	v_pk_mul_f32 v[126:127], v[118:119], v[118:119]
	v_pk_fma_f32 v[122:123], v[112:113], v[114:115], v[146:147]
	v_add_f32_e32 v144, v145, v144
	v_add_f32_e32 v145, v188, v189
	v_add_f32_e32 v146, v184, v185
	v_pk_mul_f32 v[112:113], v[120:121], v[120:121]
	v_pk_mul_f32 v[114:115], v[122:123], v[122:123]
	v_add_f32_e32 v145, v146, v145
	v_add_f32_e32 v126, v126, v127
	v_add_f32_e32 v124, v124, v125
	v_add_f32_e32 v144, v145, v144
	v_add_f32_e32 v124, v124, v126
	v_add_f32_e32 v114, v114, v115
	v_add_f32_e32 v112, v112, v113
	v_add_f32_e32 v124, v124, v144
	v_add_f32_e32 v112, v112, v114
	v_and_b32_e32 v113, 64, v198
	v_add_f32_e32 v114, v112, v124
	v_xor_b32_e32 v112, 1, v198
	v_add_u32_e32 v115, 64, v113
	v_cmp_lt_i32_e32 vcc, v112, v115
	v_cvt_pk_bf16_f32 v113, v118, v119
	global_store_dwordx4 v[176:177], v[116:119], off offset:512
	v_cndmask_b32_e32 v112, v198, v112, vcc
	v_lshlrev_b32_e32 v199, 2, v112
	s_nop 1
	v_mov_b32_dpp v124, v114 quad_perm:[1,0,3,2] row_mask:0xf bank_mask:0xf
	v_cvt_pk_bf16_f32 v112, v116, v117
	global_store_dwordx2 v[172:173], v[112:113], off offset:256
	v_xor_b32_e32 v113, 2, v198
	v_cmp_lt_i32_e32 vcc, v113, v115
	s_waitcnt lgkmcnt(0)
	v_add_f32_e32 v112, v114, v124
	v_cvt_pk_bf16_f32 v114, v120, v121
	v_cndmask_b32_e32 v113, v198, v113, vcc
	v_lshlrev_b32_e32 v200, 2, v113
	s_nop 1
	v_mov_b32_dpp v113, v112 quad_perm:[2,3,0,1] row_mask:0xf bank_mask:0xf
	v_cvt_pk_bf16_f32 v115, v122, v123
	global_store_dwordx4 v[176:177], v[120:123], off offset:576
	global_store_dwordx2 v[172:173], v[114:115], off offset:288
	s_mov_b32 vcc_lo, 0x11111111
	s_mov_b32 vcc_hi, 0x11111111
	s_and_saveexec_b64 s[0:1], vcc
	s_cbranch_execz .LBB0_1312
	v_lshl_add_u64 v[114:115], v[164:165], 2, s[12:13]
	s_waitcnt lgkmcnt(0)
	v_add_f32_e32 v112, v112, v113
	global_atomic_add_f32 v[114:115], v112, off
.LBB0_1312:
	s_or_b64 exec, exec, s[0:1]
	v_fmamk_f32 v112, v180, 0x3a800000, v197
	s_waitcnt lgkmcnt(0)
	v_mul_f32_e32 v113, 0x4b800000, v112
	v_cmp_gt_f32_e32 vcc, s56, v112
	v_or_b32_e32 v144, 32, v164
	v_ashrrev_i32_e32 v145, 31, v144
	v_cndmask_b32_e32 v112, v112, v113, vcc
	v_rsq_f32_e32 v112, v112
	v_lshlrev_b64 v[114:115], 11, v[144:145]
	v_lshl_add_u64 v[114:115], s[8:9], 0, v[114:115]
	v_mul_f32_e32 v113, 0x45800000, v112
	v_cndmask_b32_e32 v202, v112, v113, vcc
	v_lshlrev_b64 v[112:113], 12, v[144:145]
	v_lshl_add_u64 v[112:113], s[6:7], 0, v[112:113]
	v_lshl_add_u64 v[172:173], v[160:161], 2, v[112:113]
	v_lshl_add_u64 v[146:147], v[160:161], 1, v[114:115]
	global_load_dwordx4 v[124:127], v[172:173], off
	global_load_dwordx4 v[120:123], v[172:173], off offset:64
	global_load_dwordx4 v[116:119], v[172:173], off offset:512
	global_load_dwordx4 v[112:115], v[172:173], off offset:576
	global_load_dwordx2 v[188:189], v[146:147], off
	global_load_dwordx2 v[184:185], v[146:147], off offset:32
	global_load_dwordx2 v[180:181], v[146:147], off offset:256
	global_load_dwordx2 v[176:177], v[146:147], off offset:288
	v_lshl_add_u64 v[204:205], v[144:145], 2, s[14:15]
	global_load_dword v165, v[204:205], off
	v_pk_mul_f32 v[108:109], v[108:109], v[202:203] op_sel_hi:[1,0]
	s_waitcnt vmcnt(20)
	v_lshlrev_b32_e32 v204, 16, v186
	v_mul_f32_e32 v108, 0xbfb8aa3b, v108
	v_exp_f32_e32 v201, v108
	v_mul_f32_e32 v108, 0xbfb8aa3b, v109
	v_exp_f32_e32 v203, v108
	v_and_b32_e32 v205, 0xffff0000, v186
	v_pk_mul_f32 v[108:109], v[110:111], v[202:203] op_sel_hi:[1,0]
	s_nop 0
	v_mul_f32_e32 v108, 0xbfb8aa3b, v108
	v_exp_f32_e32 v108, v108
	v_mul_f32_e32 v109, 0xbfb8aa3b, v109
	v_exp_f32_e32 v109, v109
	v_add_f32_e32 v110, 1.0, v201
	v_add_f32_e32 v111, 1.0, v203
	v_add_f32_e32 v108, 1.0, v108
	v_rcp_f32_e32 v110, v110
	v_rcp_f32_e32 v111, v111
	v_rcp_f32_e32 v206, v108
	v_add_f32_e32 v108, 1.0, v109
	v_rcp_f32_e32 v207, v108
	v_pk_fma_f32 v[108:109], v[110:111], v[204:205], v[140:141]
	v_lshlrev_b32_e32 v110, 16, v187
	v_and_b32_e32 v111, 0xffff0000, v187
	v_pk_fma_f32 v[110:111], v[206:207], v[110:111], v[142:143]
	v_pk_mul_f32 v[104:105], v[104:105], v[202:203] op_sel_hi:[1,0]
	v_pk_mul_f32 v[140:141], v[108:109], v[108:109]
	global_store_dwordx4 v[170:171], v[108:111], off
	v_mul_f32_e32 v104, 0xbfb8aa3b, v104
	v_pk_mul_f32 v[142:143], v[110:111], v[110:111]
	v_cvt_pk_bf16_f32 v108, v108, v109
	v_cvt_pk_bf16_f32 v109, v110, v111
	global_store_dwordx2 v[168:169], v[108:109], off
	v_exp_f32_e32 v108, v104
	v_mul_f32_e32 v104, 0xbfb8aa3b, v105
	v_exp_f32_e32 v109, v104
	v_pk_mul_f32 v[104:105], v[106:107], v[202:203] op_sel_hi:[1,0]
	v_add_f32_e32 v106, 1.0, v108
	v_mul_f32_e32 v104, 0xbfb8aa3b, v104
	v_exp_f32_e32 v104, v104
	v_mul_f32_e32 v105, 0xbfb8aa3b, v105
	v_exp_f32_e32 v105, v105
	v_add_f32_e32 v107, 1.0, v109
	v_add_f32_e32 v104, 1.0, v104
	v_rcp_f32_e32 v106, v106
	v_rcp_f32_e32 v107, v107
	v_rcp_f32_e32 v110, v104
	v_add_f32_e32 v104, 1.0, v105
	v_rcp_f32_e32 v111, v104
	s_waitcnt vmcnt(21)
	v_lshlrev_b32_e32 v108, 16, v182
	v_and_b32_e32 v109, 0xffff0000, v182
	v_pk_fma_f32 v[104:105], v[106:107], v[108:109], v[136:137]
	v_lshlrev_b32_e32 v106, 16, v183
	v_and_b32_e32 v107, 0xffff0000, v183
	v_pk_fma_f32 v[106:107], v[110:111], v[106:107], v[138:139]
	v_pk_mul_f32 v[100:101], v[100:101], v[202:203] op_sel_hi:[1,0]
	v_pk_mul_f32 v[108:109], v[104:105], v[104:105]
	global_store_dwordx4 v[170:171], v[104:107], off offset:64
	v_mul_f32_e32 v100, 0xbfb8aa3b, v100
	v_pk_mul_f32 v[96:97], v[96:97], v[202:203] op_sel_hi:[1,0]
	v_cvt_pk_bf16_f32 v104, v104, v105
	v_cvt_pk_bf16_f32 v105, v106, v107
	global_store_dwordx2 v[168:169], v[104:105], off offset:32
	v_exp_f32_e32 v104, v100
	v_mul_f32_e32 v100, 0xbfb8aa3b, v101
	v_exp_f32_e32 v105, v100
	v_pk_mul_f32 v[100:101], v[102:103], v[202:203] op_sel_hi:[1,0]
	v_add_f32_e32 v102, 1.0, v104
	v_mul_f32_e32 v100, 0xbfb8aa3b, v100
	v_exp_f32_e32 v100, v100
	v_mul_f32_e32 v101, 0xbfb8aa3b, v101
	v_add_f32_e32 v103, 1.0, v105
	v_exp_f32_e32 v101, v101
	v_rcp_f32_e32 v102, v102
	v_rcp_f32_e32 v103, v103
	v_add_f32_e32 v100, 1.0, v100
	v_pk_mul_f32 v[110:111], v[106:107], v[106:107]
	s_waitcnt vmcnt(22)
	v_lshlrev_b32_e32 v104, 16, v178
	v_and_b32_e32 v105, 0xffff0000, v178
	v_rcp_f32_e32 v106, v100
	v_add_f32_e32 v100, 1.0, v101
	v_mul_f32_e32 v96, 0xbfb8aa3b, v96
	v_rcp_f32_e32 v107, v100
	v_pk_fma_f32 v[100:101], v[102:103], v[104:105], v[132:133]
	v_exp_f32_e32 v104, v96
	v_mul_f32_e32 v96, 0xbfb8aa3b, v97
	v_exp_f32_e32 v105, v96
	v_pk_mul_f32 v[96:97], v[98:99], v[202:203] op_sel_hi:[1,0]
	v_add_f32_e32 v98, 1.0, v104
	v_mul_f32_e32 v96, 0xbfb8aa3b, v96
	v_mul_f32_e32 v97, 0xbfb8aa3b, v97
	v_exp_f32_e32 v96, v96
	v_exp_f32_e32 v97, v97
	v_add_f32_e32 v99, 1.0, v105
	v_rcp_f32_e32 v98, v98
	v_rcp_f32_e32 v99, v99
	v_add_f32_e32 v96, 1.0, v96
	v_add_f32_e32 v97, 1.0, v97
	v_rcp_f32_e32 v96, v96
	v_rcp_f32_e32 v97, v97
	v_lshlrev_b32_e32 v102, 16, v179
	v_and_b32_e32 v103, 0xffff0000, v179
	s_waitcnt vmcnt(21)
	v_lshlrev_b32_e32 v104, 16, v174
	v_and_b32_e32 v105, 0xffff0000, v174
	v_add_f32_e32 v110, v110, v111
	v_add_f32_e32 v108, v108, v109
	v_pk_fma_f32 v[102:103], v[106:107], v[102:103], v[134:135]
	v_pk_fma_f32 v[104:105], v[98:99], v[104:105], v[128:129]
	v_lshlrev_b32_e32 v98, 16, v175
	v_and_b32_e32 v99, 0xffff0000, v175
	v_add_f32_e32 v108, v108, v110
	v_add_f32_e32 v109, v142, v143
	v_add_f32_e32 v110, v140, v141
	v_pk_mul_f32 v[132:133], v[100:101], v[100:101]
	v_pk_mul_f32 v[134:135], v[102:103], v[102:103]
	v_pk_fma_f32 v[106:107], v[96:97], v[98:99], v[130:131]
	v_add_f32_e32 v109, v110, v109
	v_pk_mul_f32 v[96:97], v[104:105], v[104:105]
	v_pk_mul_f32 v[98:99], v[106:107], v[106:107]
	v_add_f32_e32 v108, v109, v108
	v_add_f32_e32 v109, v134, v135
	v_add_f32_e32 v110, v132, v133
	v_add_f32_e32 v109, v110, v109
	v_add_f32_e32 v98, v98, v99
	v_add_f32_e32 v96, v96, v97
	v_add_f32_e32 v108, v109, v108
	v_add_f32_e32 v96, v96, v98
	v_add_f32_e32 v98, v96, v108
	s_nop 1
	v_mov_b32_dpp v99, v98 quad_perm:[1,0,3,2] row_mask:0xf bank_mask:0xf
	v_cvt_pk_bf16_f32 v96, v100, v101
	v_cvt_pk_bf16_f32 v97, v102, v103
	global_store_dwordx4 v[170:171], v[100:103], off offset:512
	global_store_dwordx2 v[168:169], v[96:97], off offset:256
	s_waitcnt lgkmcnt(0)
	v_add_f32_e32 v96, v98, v99
	s_nop 1
	v_mov_b32_dpp v97, v96 quad_perm:[2,3,0,1] row_mask:0xf bank_mask:0xf
	v_cvt_pk_bf16_f32 v98, v104, v105
	v_cvt_pk_bf16_f32 v99, v106, v107
	global_store_dwordx4 v[170:171], v[104:107], off offset:576
	global_store_dwordx2 v[168:169], v[98:99], off offset:288
	s_mov_b32 vcc_lo, 0x11111111
	s_mov_b32 vcc_hi, 0x11111111
	s_and_saveexec_b64 s[0:1], vcc
	s_cbranch_execz .LBB0_1314
	v_lshl_add_u64 v[98:99], v[166:167], 2, s[12:13]
	s_waitcnt lgkmcnt(0)
	v_add_f32_e32 v96, v96, v97
	global_atomic_add_f32 v[98:99], v96, off
.LBB0_1314:
	s_or_b64 exec, exec, s[0:1]
	s_waitcnt vmcnt(8)
	v_fmamk_f32 v96, v165, 0x3a800000, v197
	s_waitcnt lgkmcnt(0)
	v_mul_f32_e32 v97, 0x4b800000, v96
	v_cmp_gt_f32_e32 vcc, s56, v96
	v_or_b32_e32 v128, 48, v164
	v_ashrrev_i32_e32 v129, 31, v128
	v_cndmask_b32_e32 v96, v96, v97, vcc
	v_rsq_f32_e32 v96, v96
	v_lshlrev_b64 v[98:99], 11, v[128:129]
	v_lshl_add_u64 v[98:99], s[8:9], 0, v[98:99]
	v_mul_f32_e32 v97, 0x45800000, v96
	v_cndmask_b32_e32 v166, v96, v97, vcc
	v_lshlrev_b64 v[96:97], 12, v[128:129]
	v_lshl_add_u64 v[96:97], s[6:7], 0, v[96:97]
	v_lshl_add_u64 v[132:133], v[160:161], 2, v[96:97]
	v_lshl_add_u64 v[130:131], v[160:161], 1, v[98:99]
	global_load_dwordx4 v[108:111], v[132:133], off
	global_load_dwordx4 v[104:107], v[132:133], off offset:64
	global_load_dwordx4 v[100:103], v[132:133], off offset:512
	global_load_dwordx4 v[96:99], v[132:133], off offset:576
	global_load_dwordx2 v[140:141], v[130:131], off
	global_load_dwordx2 v[138:139], v[130:131], off offset:32
	global_load_dwordx2 v[136:137], v[130:131], off offset:256
	global_load_dwordx2 v[134:135], v[130:131], off offset:288
	v_lshl_add_u64 v[142:143], v[128:129], 2, s[14:15]
	global_load_dword v142, v[142:143], off
	v_pk_mul_f32 v[92:93], v[92:93], v[166:167] op_sel_hi:[1,0]
	v_lshlrev_b32_e32 v168, 16, v188
	v_mul_f32_e32 v92, 0xbfb8aa3b, v92
	v_exp_f32_e32 v143, v92
	v_mul_f32_e32 v92, 0xbfb8aa3b, v93
	v_exp_f32_e32 v165, v92
	v_pk_mul_f32 v[92:93], v[94:95], v[166:167] op_sel_hi:[1,0]
	v_add_f32_e32 v94, 1.0, v143
	v_mul_f32_e32 v92, 0xbfb8aa3b, v92
	v_exp_f32_e32 v92, v92
	v_mul_f32_e32 v93, 0xbfb8aa3b, v93
	v_exp_f32_e32 v93, v93
	v_add_f32_e32 v95, 1.0, v165
	v_add_f32_e32 v92, 1.0, v92
	v_rcp_f32_e32 v94, v94
	v_rcp_f32_e32 v95, v95
	v_rcp_f32_e32 v170, v92
	v_add_f32_e32 v92, 1.0, v93
	v_rcp_f32_e32 v171, v92
	v_and_b32_e32 v169, 0xffff0000, v188
	v_pk_fma_f32 v[92:93], v[94:95], v[168:169], v[124:125]
	v_lshlrev_b32_e32 v94, 16, v189
	v_and_b32_e32 v95, 0xffff0000, v189
	v_pk_fma_f32 v[94:95], v[170:171], v[94:95], v[126:127]
	v_pk_mul_f32 v[88:89], v[88:89], v[166:167] op_sel_hi:[1,0]
	v_pk_mul_f32 v[124:125], v[92:93], v[92:93]
	global_store_dwordx4 v[172:173], v[92:95], off
	v_mul_f32_e32 v88, 0xbfb8aa3b, v88
	v_pk_mul_f32 v[126:127], v[94:95], v[94:95]
	v_cvt_pk_bf16_f32 v92, v92, v93
	v_cvt_pk_bf16_f32 v93, v94, v95
	global_store_dwordx2 v[146:147], v[92:93], off
	v_exp_f32_e32 v92, v88
	v_mul_f32_e32 v88, 0xbfb8aa3b, v89
	v_exp_f32_e32 v93, v88
	v_pk_mul_f32 v[88:89], v[90:91], v[166:167] op_sel_hi:[1,0]
	v_add_f32_e32 v90, 1.0, v92
	v_mul_f32_e32 v88, 0xbfb8aa3b, v88
	v_exp_f32_e32 v88, v88
	v_mul_f32_e32 v89, 0xbfb8aa3b, v89
	v_exp_f32_e32 v89, v89
	v_add_f32_e32 v91, 1.0, v93
	v_add_f32_e32 v88, 1.0, v88
	v_rcp_f32_e32 v90, v90
	v_rcp_f32_e32 v91, v91
	v_rcp_f32_e32 v94, v88
	v_add_f32_e32 v88, 1.0, v89
	v_rcp_f32_e32 v95, v88
	v_lshlrev_b32_e32 v92, 16, v184
	v_and_b32_e32 v93, 0xffff0000, v184
	v_pk_fma_f32 v[88:89], v[90:91], v[92:93], v[120:121]
	v_lshlrev_b32_e32 v90, 16, v185
	v_and_b32_e32 v91, 0xffff0000, v185
	v_pk_fma_f32 v[90:91], v[94:95], v[90:91], v[122:123]
	v_pk_mul_f32 v[84:85], v[84:85], v[166:167] op_sel_hi:[1,0]
	v_pk_mul_f32 v[92:93], v[88:89], v[88:89]
	global_store_dwordx4 v[172:173], v[88:91], off offset:64
	v_mul_f32_e32 v84, 0xbfb8aa3b, v84
	v_pk_mul_f32 v[80:81], v[80:81], v[166:167] op_sel_hi:[1,0]
	v_cvt_pk_bf16_f32 v88, v88, v89
	v_cvt_pk_bf16_f32 v89, v90, v91
	global_store_dwordx2 v[146:147], v[88:89], off offset:32
	v_exp_f32_e32 v88, v84
	v_mul_f32_e32 v84, 0xbfb8aa3b, v85
	v_exp_f32_e32 v89, v84
	v_pk_mul_f32 v[84:85], v[86:87], v[166:167] op_sel_hi:[1,0]
	v_add_f32_e32 v86, 1.0, v88
	v_mul_f32_e32 v84, 0xbfb8aa3b, v84
	v_exp_f32_e32 v84, v84
	v_mul_f32_e32 v85, 0xbfb8aa3b, v85
	v_add_f32_e32 v87, 1.0, v89
	v_exp_f32_e32 v85, v85
	v_rcp_f32_e32 v86, v86
	v_rcp_f32_e32 v87, v87
	v_add_f32_e32 v84, 1.0, v84
	v_pk_mul_f32 v[94:95], v[90:91], v[90:91]
	v_lshlrev_b32_e32 v88, 16, v180
	v_and_b32_e32 v89, 0xffff0000, v180
	v_rcp_f32_e32 v90, v84
	v_add_f32_e32 v84, 1.0, v85
	v_mul_f32_e32 v80, 0xbfb8aa3b, v80
	v_rcp_f32_e32 v91, v84
	v_pk_fma_f32 v[84:85], v[86:87], v[88:89], v[116:117]
	v_exp_f32_e32 v88, v80
	v_mul_f32_e32 v80, 0xbfb8aa3b, v81
	v_exp_f32_e32 v89, v80
	v_pk_mul_f32 v[80:81], v[82:83], v[166:167] op_sel_hi:[1,0]
	v_add_f32_e32 v82, 1.0, v88
	v_mul_f32_e32 v80, 0xbfb8aa3b, v80
	v_mul_f32_e32 v81, 0xbfb8aa3b, v81
	v_exp_f32_e32 v80, v80
	v_exp_f32_e32 v81, v81
	v_add_f32_e32 v83, 1.0, v89
	v_rcp_f32_e32 v82, v82
	v_rcp_f32_e32 v83, v83
	v_add_f32_e32 v80, 1.0, v80
	v_add_f32_e32 v81, 1.0, v81
	v_rcp_f32_e32 v80, v80
	v_rcp_f32_e32 v81, v81
	v_lshlrev_b32_e32 v86, 16, v181
	v_and_b32_e32 v87, 0xffff0000, v181
	v_lshlrev_b32_e32 v88, 16, v176
	v_and_b32_e32 v89, 0xffff0000, v176
	v_add_f32_e32 v94, v94, v95
	v_add_f32_e32 v92, v92, v93
	v_pk_fma_f32 v[86:87], v[90:91], v[86:87], v[118:119]
	v_pk_fma_f32 v[88:89], v[82:83], v[88:89], v[112:113]
	v_lshlrev_b32_e32 v82, 16, v177
	v_and_b32_e32 v83, 0xffff0000, v177
	v_add_f32_e32 v92, v92, v94
	v_add_f32_e32 v93, v126, v127
	v_add_f32_e32 v94, v124, v125
	v_pk_mul_f32 v[116:117], v[84:85], v[84:85]
	v_pk_mul_f32 v[118:119], v[86:87], v[86:87]
	v_pk_fma_f32 v[90:91], v[80:81], v[82:83], v[114:115]
	v_add_f32_e32 v93, v94, v93
	v_pk_mul_f32 v[80:81], v[88:89], v[88:89]
	v_pk_mul_f32 v[82:83], v[90:91], v[90:91]
	v_add_f32_e32 v92, v93, v92
	v_add_f32_e32 v93, v118, v119
	v_add_f32_e32 v94, v116, v117
	v_add_f32_e32 v93, v94, v93
	v_add_f32_e32 v82, v82, v83
	v_add_f32_e32 v80, v80, v81
	v_add_f32_e32 v92, v93, v92
	v_add_f32_e32 v80, v80, v82
	v_add_f32_e32 v82, v80, v92
	s_nop 1
	v_mov_b32_dpp v83, v82 quad_perm:[1,0,3,2] row_mask:0xf bank_mask:0xf
	v_cvt_pk_bf16_f32 v80, v84, v85
	v_cvt_pk_bf16_f32 v81, v86, v87
	global_store_dwordx4 v[172:173], v[84:87], off offset:512
	global_store_dwordx2 v[146:147], v[80:81], off offset:256
	s_waitcnt lgkmcnt(0)
	v_add_f32_e32 v80, v82, v83
	s_nop 1
	v_mov_b32_dpp v81, v80 quad_perm:[2,3,0,1] row_mask:0xf bank_mask:0xf
	v_cvt_pk_bf16_f32 v82, v88, v89
	v_cvt_pk_bf16_f32 v83, v90, v91
	global_store_dwordx4 v[172:173], v[88:91], off offset:576
	global_store_dwordx2 v[146:147], v[82:83], off offset:288
	s_mov_b32 vcc_lo, 0x11111111
	s_mov_b32 vcc_hi, 0x11111111
	s_and_saveexec_b64 s[0:1], vcc
	s_cbranch_execz .LBB0_1316
	v_lshl_add_u64 v[82:83], v[144:145], 2, s[12:13]
	s_waitcnt lgkmcnt(0)
	v_add_f32_e32 v80, v80, v81
	global_atomic_add_f32 v[82:83], v80, off
.LBB0_1316:
	s_or_b64 exec, exec, s[0:1]
	s_waitcnt vmcnt(8)
	v_fmamk_f32 v80, v142, 0x3a800000, v197
	s_waitcnt lgkmcnt(0)
	v_mul_f32_e32 v81, 0x4b800000, v80
	v_cmp_gt_f32_e32 vcc, s56, v80
	v_add_u32_e32 v112, 0x80, v164
	v_ashrrev_i32_e32 v113, 31, v112
	v_cndmask_b32_e32 v80, v80, v81, vcc
	v_rsq_f32_e32 v80, v80
	v_lshlrev_b64 v[82:83], 11, v[112:113]
	v_lshl_add_u64 v[82:83], s[8:9], 0, v[82:83]
	v_mul_f32_e32 v81, 0x45800000, v80
	v_cndmask_b32_e32 v142, v80, v81, vcc
	v_lshlrev_b64 v[80:81], 12, v[112:113]
	v_lshl_add_u64 v[80:81], s[6:7], 0, v[80:81]
	v_lshl_add_u64 v[116:117], v[160:161], 2, v[80:81]
	v_lshl_add_u64 v[114:115], v[160:161], 1, v[82:83]
	global_load_dwordx4 v[92:95], v[116:117], off
	global_load_dwordx4 v[88:91], v[116:117], off offset:64
	global_load_dwordx4 v[84:87], v[116:117], off offset:512
	global_load_dwordx4 v[80:83], v[116:117], off offset:576
	global_load_dwordx2 v[124:125], v[114:115], off
	global_load_dwordx2 v[122:123], v[114:115], off offset:32
	global_load_dwordx2 v[120:121], v[114:115], off offset:256
	global_load_dwordx2 v[118:119], v[114:115], off offset:288
	global_load_dword v126, v[162:163], off offset:512
	v_pk_mul_f32 v[76:77], v[76:77], v[142:143] op_sel_hi:[1,0]
	v_lshlrev_b32_e32 v144, 16, v140
	v_mul_f32_e32 v76, 0xbfb8aa3b, v76
	v_exp_f32_e32 v127, v76
	v_mul_f32_e32 v76, 0xbfb8aa3b, v77
	v_exp_f32_e32 v143, v76
	v_and_b32_e32 v145, 0xffff0000, v140
	v_pk_mul_f32 v[76:77], v[78:79], v[142:143] op_sel_hi:[1,0]
	s_nop 0
	v_mul_f32_e32 v76, 0xbfb8aa3b, v76
	v_exp_f32_e32 v76, v76
	v_mul_f32_e32 v77, 0xbfb8aa3b, v77
	v_exp_f32_e32 v77, v77
	v_add_f32_e32 v78, 1.0, v127
	v_add_f32_e32 v79, 1.0, v143
	v_add_f32_e32 v76, 1.0, v76
	v_rcp_f32_e32 v78, v78
	v_rcp_f32_e32 v79, v79
	v_rcp_f32_e32 v146, v76
	v_add_f32_e32 v76, 1.0, v77
	v_rcp_f32_e32 v147, v76
	v_pk_fma_f32 v[76:77], v[78:79], v[144:145], v[108:109]
	v_lshlrev_b32_e32 v78, 16, v141
	v_and_b32_e32 v79, 0xffff0000, v141
	v_pk_fma_f32 v[78:79], v[146:147], v[78:79], v[110:111]
	v_pk_mul_f32 v[72:73], v[72:73], v[142:143] op_sel_hi:[1,0]
	v_pk_mul_f32 v[108:109], v[76:77], v[76:77]
	global_store_dwordx4 v[132:133], v[76:79], off
	v_mul_f32_e32 v72, 0xbfb8aa3b, v72
	v_pk_mul_f32 v[110:111], v[78:79], v[78:79]
	v_cvt_pk_bf16_f32 v76, v76, v77
	v_cvt_pk_bf16_f32 v77, v78, v79
	global_store_dwordx2 v[130:131], v[76:77], off
	v_exp_f32_e32 v76, v72
	v_mul_f32_e32 v72, 0xbfb8aa3b, v73
	v_exp_f32_e32 v77, v72
	v_pk_mul_f32 v[72:73], v[74:75], v[142:143] op_sel_hi:[1,0]
	v_add_f32_e32 v74, 1.0, v76
	v_mul_f32_e32 v72, 0xbfb8aa3b, v72
	v_exp_f32_e32 v72, v72
	v_mul_f32_e32 v73, 0xbfb8aa3b, v73
	v_exp_f32_e32 v73, v73
	v_add_f32_e32 v75, 1.0, v77
	v_add_f32_e32 v72, 1.0, v72
	v_rcp_f32_e32 v74, v74
	v_rcp_f32_e32 v75, v75
	v_rcp_f32_e32 v78, v72
	v_add_f32_e32 v72, 1.0, v73
	v_rcp_f32_e32 v79, v72
	v_lshlrev_b32_e32 v76, 16, v138
	v_and_b32_e32 v77, 0xffff0000, v138
	v_pk_fma_f32 v[72:73], v[74:75], v[76:77], v[104:105]
	v_lshlrev_b32_e32 v74, 16, v139
	v_and_b32_e32 v75, 0xffff0000, v139
	v_pk_fma_f32 v[74:75], v[78:79], v[74:75], v[106:107]
	v_pk_mul_f32 v[68:69], v[68:69], v[142:143] op_sel_hi:[1,0]
	v_pk_mul_f32 v[76:77], v[72:73], v[72:73]
	global_store_dwordx4 v[132:133], v[72:75], off offset:64
	v_mul_f32_e32 v68, 0xbfb8aa3b, v68
	v_pk_mul_f32 v[64:65], v[64:65], v[142:143] op_sel_hi:[1,0]
	v_cvt_pk_bf16_f32 v72, v72, v73
	v_cvt_pk_bf16_f32 v73, v74, v75
	global_store_dwordx2 v[130:131], v[72:73], off offset:32
	v_exp_f32_e32 v72, v68
	v_mul_f32_e32 v68, 0xbfb8aa3b, v69
	v_exp_f32_e32 v73, v68
	v_pk_mul_f32 v[68:69], v[70:71], v[142:143] op_sel_hi:[1,0]
	v_add_f32_e32 v70, 1.0, v72
	v_mul_f32_e32 v68, 0xbfb8aa3b, v68
	v_exp_f32_e32 v68, v68
	v_mul_f32_e32 v69, 0xbfb8aa3b, v69
	v_add_f32_e32 v71, 1.0, v73
	v_exp_f32_e32 v69, v69
	v_rcp_f32_e32 v70, v70
	v_rcp_f32_e32 v71, v71
	v_add_f32_e32 v68, 1.0, v68
	v_pk_mul_f32 v[78:79], v[74:75], v[74:75]
	v_lshlrev_b32_e32 v72, 16, v136
	v_and_b32_e32 v73, 0xffff0000, v136
	v_rcp_f32_e32 v74, v68
	v_add_f32_e32 v68, 1.0, v69
	v_mul_f32_e32 v64, 0xbfb8aa3b, v64
	v_rcp_f32_e32 v75, v68
	v_pk_fma_f32 v[68:69], v[70:71], v[72:73], v[100:101]
	v_exp_f32_e32 v72, v64
	v_mul_f32_e32 v64, 0xbfb8aa3b, v65
	v_exp_f32_e32 v73, v64
	v_pk_mul_f32 v[64:65], v[66:67], v[142:143] op_sel_hi:[1,0]
	v_add_f32_e32 v66, 1.0, v72
	v_mul_f32_e32 v64, 0xbfb8aa3b, v64
	v_mul_f32_e32 v65, 0xbfb8aa3b, v65
	v_exp_f32_e32 v64, v64
	v_exp_f32_e32 v65, v65
	v_add_f32_e32 v67, 1.0, v73
	v_rcp_f32_e32 v66, v66
	v_rcp_f32_e32 v67, v67
	v_add_f32_e32 v64, 1.0, v64
	v_add_f32_e32 v65, 1.0, v65
	v_rcp_f32_e32 v64, v64
	v_rcp_f32_e32 v65, v65
	v_lshlrev_b32_e32 v70, 16, v137
	v_and_b32_e32 v71, 0xffff0000, v137
	v_lshlrev_b32_e32 v72, 16, v134
	v_and_b32_e32 v73, 0xffff0000, v134
	v_add_f32_e32 v78, v78, v79
	v_add_f32_e32 v76, v76, v77
	v_pk_fma_f32 v[70:71], v[74:75], v[70:71], v[102:103]
	v_pk_fma_f32 v[72:73], v[66:67], v[72:73], v[96:97]
	v_lshlrev_b32_e32 v66, 16, v135
	v_and_b32_e32 v67, 0xffff0000, v135
	v_add_f32_e32 v76, v76, v78
	v_add_f32_e32 v77, v110, v111
	v_add_f32_e32 v78, v108, v109
	v_pk_mul_f32 v[100:101], v[68:69], v[68:69]
	v_pk_mul_f32 v[102:103], v[70:71], v[70:71]
	v_pk_fma_f32 v[74:75], v[64:65], v[66:67], v[98:99]
	v_add_f32_e32 v77, v78, v77
	v_pk_mul_f32 v[64:65], v[72:73], v[72:73]
	v_pk_mul_f32 v[66:67], v[74:75], v[74:75]
	v_add_f32_e32 v76, v77, v76
	v_add_f32_e32 v77, v102, v103
	v_add_f32_e32 v78, v100, v101
	v_add_f32_e32 v77, v78, v77
	v_add_f32_e32 v66, v66, v67
	v_add_f32_e32 v64, v64, v65
	v_add_f32_e32 v76, v77, v76
	v_add_f32_e32 v64, v64, v66
	v_add_f32_e32 v66, v64, v76
	s_nop 1
	v_mov_b32_dpp v67, v66 quad_perm:[1,0,3,2] row_mask:0xf bank_mask:0xf
	v_cvt_pk_bf16_f32 v64, v68, v69
	v_cvt_pk_bf16_f32 v65, v70, v71
	global_store_dwordx4 v[132:133], v[68:71], off offset:512
	global_store_dwordx2 v[130:131], v[64:65], off offset:256
	s_waitcnt lgkmcnt(0)
	v_add_f32_e32 v64, v66, v67
	s_nop 1
	v_mov_b32_dpp v65, v64 quad_perm:[2,3,0,1] row_mask:0xf bank_mask:0xf
	v_cvt_pk_bf16_f32 v66, v72, v73
	v_cvt_pk_bf16_f32 v67, v74, v75
	global_store_dwordx4 v[132:133], v[72:75], off offset:576
	global_store_dwordx2 v[130:131], v[66:67], off offset:288
	s_mov_b32 vcc_lo, 0x11111111
	s_mov_b32 vcc_hi, 0x11111111
	s_and_saveexec_b64 s[0:1], vcc
	s_cbranch_execz .LBB0_1318
	v_lshl_add_u64 v[66:67], v[128:129], 2, s[12:13]
	s_waitcnt lgkmcnt(0)
	v_add_f32_e32 v64, v64, v65
	global_atomic_add_f32 v[66:67], v64, off
.LBB0_1318:
	s_or_b64 exec, exec, s[0:1]
	s_waitcnt vmcnt(8)
	v_fmamk_f32 v64, v126, 0x3a800000, v197
	s_waitcnt lgkmcnt(0)
	v_mul_f32_e32 v65, 0x4b800000, v64
	v_cmp_gt_f32_e32 vcc, s56, v64
	v_or_b32_e32 v96, 16, v112
	v_ashrrev_i32_e32 v97, 31, v96
	v_cndmask_b32_e32 v64, v64, v65, vcc
	v_rsq_f32_e32 v64, v64
	v_lshlrev_b64 v[66:67], 11, v[96:97]
	v_lshl_add_u64 v[66:67], s[8:9], 0, v[66:67]
	v_mul_f32_e32 v65, 0x45800000, v64
	v_cndmask_b32_e32 v126, v64, v65, vcc
	v_lshlrev_b64 v[64:65], 12, v[96:97]
	v_lshl_add_u64 v[64:65], s[6:7], 0, v[64:65]
	v_lshl_add_u64 v[100:101], v[160:161], 2, v[64:65]
	v_lshl_add_u64 v[98:99], v[160:161], 1, v[66:67]
	global_load_dwordx4 v[76:79], v[100:101], off
	global_load_dwordx4 v[72:75], v[100:101], off offset:64
	global_load_dwordx4 v[68:71], v[100:101], off offset:512
	global_load_dwordx4 v[64:67], v[100:101], off offset:576
	global_load_dwordx2 v[108:109], v[98:99], off
	global_load_dwordx2 v[106:107], v[98:99], off offset:32
	global_load_dwordx2 v[104:105], v[98:99], off offset:256
	global_load_dwordx2 v[102:103], v[98:99], off offset:288
	v_lshl_add_u64 v[110:111], v[96:97], 2, s[14:15]
	global_load_dword v110, v[110:111], off
	v_pk_mul_f32 v[60:61], v[60:61], v[126:127] op_sel_hi:[1,0]
	v_lshlrev_b32_e32 v128, 16, v124
	v_mul_f32_e32 v60, 0xbfb8aa3b, v60
	v_exp_f32_e32 v111, v60
	v_mul_f32_e32 v60, 0xbfb8aa3b, v61
	v_exp_f32_e32 v127, v60
	v_and_b32_e32 v129, 0xffff0000, v124
	v_pk_mul_f32 v[60:61], v[62:63], v[126:127] op_sel_hi:[1,0]
	s_nop 0
	v_mul_f32_e32 v60, 0xbfb8aa3b, v60
	v_exp_f32_e32 v60, v60
	v_mul_f32_e32 v61, 0xbfb8aa3b, v61
	v_exp_f32_e32 v61, v61
	v_add_f32_e32 v62, 1.0, v111
	v_add_f32_e32 v63, 1.0, v127
	v_add_f32_e32 v60, 1.0, v60
	v_rcp_f32_e32 v62, v62
	v_rcp_f32_e32 v63, v63
	v_rcp_f32_e32 v130, v60
	v_add_f32_e32 v60, 1.0, v61
	v_rcp_f32_e32 v131, v60
	v_pk_fma_f32 v[60:61], v[62:63], v[128:129], v[92:93]
	v_lshlrev_b32_e32 v62, 16, v125
	v_and_b32_e32 v63, 0xffff0000, v125
	v_pk_fma_f32 v[62:63], v[130:131], v[62:63], v[94:95]
	v_pk_mul_f32 v[56:57], v[56:57], v[126:127] op_sel_hi:[1,0]
	v_pk_mul_f32 v[92:93], v[60:61], v[60:61]
	global_store_dwordx4 v[116:117], v[60:63], off
	v_mul_f32_e32 v56, 0xbfb8aa3b, v56
	v_pk_mul_f32 v[94:95], v[62:63], v[62:63]
	v_cvt_pk_bf16_f32 v60, v60, v61
	v_cvt_pk_bf16_f32 v61, v62, v63
	global_store_dwordx2 v[114:115], v[60:61], off
	v_exp_f32_e32 v60, v56
	v_mul_f32_e32 v56, 0xbfb8aa3b, v57
	v_exp_f32_e32 v61, v56
	v_pk_mul_f32 v[56:57], v[58:59], v[126:127] op_sel_hi:[1,0]
	v_add_f32_e32 v58, 1.0, v60
	v_mul_f32_e32 v56, 0xbfb8aa3b, v56
	v_exp_f32_e32 v56, v56
	v_mul_f32_e32 v57, 0xbfb8aa3b, v57
	v_exp_f32_e32 v57, v57
	v_add_f32_e32 v59, 1.0, v61
	v_add_f32_e32 v56, 1.0, v56
	v_rcp_f32_e32 v58, v58
	v_rcp_f32_e32 v59, v59
	v_rcp_f32_e32 v62, v56
	v_add_f32_e32 v56, 1.0, v57
	v_rcp_f32_e32 v63, v56
	v_lshlrev_b32_e32 v60, 16, v122
	v_and_b32_e32 v61, 0xffff0000, v122
	v_pk_fma_f32 v[56:57], v[58:59], v[60:61], v[88:89]
	v_lshlrev_b32_e32 v58, 16, v123
	v_and_b32_e32 v59, 0xffff0000, v123
	v_pk_fma_f32 v[58:59], v[62:63], v[58:59], v[90:91]
	v_pk_mul_f32 v[52:53], v[52:53], v[126:127] op_sel_hi:[1,0]
	v_pk_mul_f32 v[60:61], v[56:57], v[56:57]
	global_store_dwordx4 v[116:117], v[56:59], off offset:64
	v_mul_f32_e32 v52, 0xbfb8aa3b, v52
	v_pk_mul_f32 v[48:49], v[48:49], v[126:127] op_sel_hi:[1,0]
	v_cvt_pk_bf16_f32 v56, v56, v57
	v_cvt_pk_bf16_f32 v57, v58, v59
	global_store_dwordx2 v[114:115], v[56:57], off offset:32
	v_exp_f32_e32 v56, v52
	v_mul_f32_e32 v52, 0xbfb8aa3b, v53
	v_exp_f32_e32 v57, v52
	v_pk_mul_f32 v[52:53], v[54:55], v[126:127] op_sel_hi:[1,0]
	v_add_f32_e32 v54, 1.0, v56
	v_mul_f32_e32 v52, 0xbfb8aa3b, v52
	v_exp_f32_e32 v52, v52
	v_mul_f32_e32 v53, 0xbfb8aa3b, v53
	v_add_f32_e32 v55, 1.0, v57
	v_exp_f32_e32 v53, v53
	v_rcp_f32_e32 v54, v54
	v_rcp_f32_e32 v55, v55
	v_add_f32_e32 v52, 1.0, v52
	v_pk_mul_f32 v[62:63], v[58:59], v[58:59]
	v_lshlrev_b32_e32 v56, 16, v120
	v_and_b32_e32 v57, 0xffff0000, v120
	v_rcp_f32_e32 v58, v52
	v_add_f32_e32 v52, 1.0, v53
	v_mul_f32_e32 v48, 0xbfb8aa3b, v48
	v_rcp_f32_e32 v59, v52
	v_pk_fma_f32 v[52:53], v[54:55], v[56:57], v[84:85]
	v_exp_f32_e32 v56, v48
	v_mul_f32_e32 v48, 0xbfb8aa3b, v49
	v_exp_f32_e32 v57, v48
	v_pk_mul_f32 v[48:49], v[50:51], v[126:127] op_sel_hi:[1,0]
	v_add_f32_e32 v50, 1.0, v56
	v_mul_f32_e32 v48, 0xbfb8aa3b, v48
	v_mul_f32_e32 v49, 0xbfb8aa3b, v49
	v_exp_f32_e32 v48, v48
	v_exp_f32_e32 v49, v49
	v_add_f32_e32 v51, 1.0, v57
	v_rcp_f32_e32 v50, v50
	v_rcp_f32_e32 v51, v51
	v_add_f32_e32 v48, 1.0, v48
	v_add_f32_e32 v49, 1.0, v49
	v_rcp_f32_e32 v48, v48
	v_rcp_f32_e32 v49, v49
	v_lshlrev_b32_e32 v54, 16, v121
	v_and_b32_e32 v55, 0xffff0000, v121
	v_lshlrev_b32_e32 v56, 16, v118
	v_and_b32_e32 v57, 0xffff0000, v118
	v_add_f32_e32 v62, v62, v63
	v_add_f32_e32 v60, v60, v61
	v_pk_fma_f32 v[54:55], v[58:59], v[54:55], v[86:87]
	v_pk_fma_f32 v[56:57], v[50:51], v[56:57], v[80:81]
	v_lshlrev_b32_e32 v50, 16, v119
	v_and_b32_e32 v51, 0xffff0000, v119
	v_add_f32_e32 v60, v60, v62
	v_add_f32_e32 v61, v94, v95
	v_add_f32_e32 v62, v92, v93
	v_pk_mul_f32 v[84:85], v[52:53], v[52:53]
	v_pk_mul_f32 v[86:87], v[54:55], v[54:55]
	v_pk_fma_f32 v[58:59], v[48:49], v[50:51], v[82:83]
	v_add_f32_e32 v61, v62, v61
	v_pk_mul_f32 v[48:49], v[56:57], v[56:57]
	v_pk_mul_f32 v[50:51], v[58:59], v[58:59]
	v_add_f32_e32 v60, v61, v60
	v_add_f32_e32 v61, v86, v87
	v_add_f32_e32 v62, v84, v85
	v_add_f32_e32 v61, v62, v61
	v_add_f32_e32 v50, v50, v51
	v_add_f32_e32 v48, v48, v49
	v_add_f32_e32 v60, v61, v60
	v_add_f32_e32 v48, v48, v50
	v_add_f32_e32 v50, v48, v60
	s_nop 1
	v_mov_b32_dpp v51, v50 quad_perm:[1,0,3,2] row_mask:0xf bank_mask:0xf
	v_cvt_pk_bf16_f32 v48, v52, v53
	v_cvt_pk_bf16_f32 v49, v54, v55
	global_store_dwordx4 v[116:117], v[52:55], off offset:512
	global_store_dwordx2 v[114:115], v[48:49], off offset:256
	s_waitcnt lgkmcnt(0)
	v_add_f32_e32 v48, v50, v51
	s_nop 1
	v_mov_b32_dpp v49, v48 quad_perm:[2,3,0,1] row_mask:0xf bank_mask:0xf
	v_cvt_pk_bf16_f32 v50, v56, v57
	v_cvt_pk_bf16_f32 v51, v58, v59
	global_store_dwordx4 v[116:117], v[56:59], off offset:576
	global_store_dwordx2 v[114:115], v[50:51], off offset:288
	s_mov_b32 vcc_lo, 0x11111111
	s_mov_b32 vcc_hi, 0x11111111
	s_and_saveexec_b64 s[0:1], vcc
	s_cbranch_execz .LBB0_1320
	v_lshl_add_u64 v[50:51], v[112:113], 2, s[12:13]
	s_waitcnt lgkmcnt(0)
	v_add_f32_e32 v48, v48, v49
	global_atomic_add_f32 v[50:51], v48, off
.LBB0_1320:
	s_or_b64 exec, exec, s[0:1]
	s_waitcnt vmcnt(8)
	v_fmamk_f32 v48, v110, 0x3a800000, v197
	s_waitcnt lgkmcnt(0)
	v_mul_f32_e32 v49, 0x4b800000, v48
	v_cmp_gt_f32_e32 vcc, s56, v48
	v_or_b32_e32 v80, 32, v112
	v_ashrrev_i32_e32 v81, 31, v80
	v_cndmask_b32_e32 v48, v48, v49, vcc
	v_rsq_f32_e32 v48, v48
	v_lshlrev_b64 v[50:51], 11, v[80:81]
	v_lshl_add_u64 v[50:51], s[8:9], 0, v[50:51]
	v_mul_f32_e32 v49, 0x45800000, v48
	v_cndmask_b32_e32 v110, v48, v49, vcc
	v_lshlrev_b64 v[48:49], 12, v[80:81]
	v_lshl_add_u64 v[48:49], s[6:7], 0, v[48:49]
	v_lshl_add_u64 v[84:85], v[160:161], 2, v[48:49]
	v_lshl_add_u64 v[82:83], v[160:161], 1, v[50:51]
	global_load_dwordx4 v[60:63], v[84:85], off
	global_load_dwordx4 v[56:59], v[84:85], off offset:64
	global_load_dwordx4 v[52:55], v[84:85], off offset:512
	global_load_dwordx4 v[48:51], v[84:85], off offset:576
	global_load_dwordx2 v[92:93], v[82:83], off
	global_load_dwordx2 v[90:91], v[82:83], off offset:32
	global_load_dwordx2 v[88:89], v[82:83], off offset:256
	global_load_dwordx2 v[86:87], v[82:83], off offset:288
	v_lshl_add_u64 v[94:95], v[80:81], 2, s[14:15]
	global_load_dword v94, v[94:95], off
	v_pk_mul_f32 v[44:45], v[44:45], v[110:111] op_sel_hi:[1,0]
	v_lshlrev_b32_e32 v114, 16, v108
	v_mul_f32_e32 v44, 0xbfb8aa3b, v44
	v_exp_f32_e32 v95, v44
	v_mul_f32_e32 v44, 0xbfb8aa3b, v45
	v_exp_f32_e32 v111, v44
	v_and_b32_e32 v115, 0xffff0000, v108
	v_pk_mul_f32 v[44:45], v[46:47], v[110:111] op_sel_hi:[1,0]
	s_nop 0
	v_mul_f32_e32 v44, 0xbfb8aa3b, v44
	v_exp_f32_e32 v44, v44
	v_mul_f32_e32 v45, 0xbfb8aa3b, v45
	v_exp_f32_e32 v45, v45
	v_add_f32_e32 v46, 1.0, v95
	v_add_f32_e32 v47, 1.0, v111
	v_add_f32_e32 v44, 1.0, v44
	v_rcp_f32_e32 v46, v46
	v_rcp_f32_e32 v47, v47
	v_rcp_f32_e32 v116, v44
	v_add_f32_e32 v44, 1.0, v45
	v_rcp_f32_e32 v117, v44
	v_pk_fma_f32 v[44:45], v[46:47], v[114:115], v[76:77]
	v_lshlrev_b32_e32 v46, 16, v109
	v_and_b32_e32 v47, 0xffff0000, v109
	v_pk_fma_f32 v[46:47], v[116:117], v[46:47], v[78:79]
	v_pk_mul_f32 v[40:41], v[40:41], v[110:111] op_sel_hi:[1,0]
	v_pk_mul_f32 v[76:77], v[44:45], v[44:45]
	global_store_dwordx4 v[100:101], v[44:47], off
	v_mul_f32_e32 v40, 0xbfb8aa3b, v40
	v_pk_mul_f32 v[78:79], v[46:47], v[46:47]
	v_cvt_pk_bf16_f32 v44, v44, v45
	v_cvt_pk_bf16_f32 v45, v46, v47
	global_store_dwordx2 v[98:99], v[44:45], off
	v_exp_f32_e32 v44, v40
	v_mul_f32_e32 v40, 0xbfb8aa3b, v41
	v_exp_f32_e32 v45, v40
	v_pk_mul_f32 v[40:41], v[42:43], v[110:111] op_sel_hi:[1,0]
	v_add_f32_e32 v42, 1.0, v44
	v_mul_f32_e32 v40, 0xbfb8aa3b, v40
	v_exp_f32_e32 v40, v40
	v_mul_f32_e32 v41, 0xbfb8aa3b, v41
	v_exp_f32_e32 v41, v41
	v_add_f32_e32 v43, 1.0, v45
	v_add_f32_e32 v40, 1.0, v40
	v_rcp_f32_e32 v42, v42
	v_rcp_f32_e32 v43, v43
	v_rcp_f32_e32 v46, v40
	v_add_f32_e32 v40, 1.0, v41
	v_rcp_f32_e32 v47, v40
	v_lshlrev_b32_e32 v44, 16, v106
	v_and_b32_e32 v45, 0xffff0000, v106
	v_pk_fma_f32 v[40:41], v[42:43], v[44:45], v[72:73]
	v_lshlrev_b32_e32 v42, 16, v107
	v_and_b32_e32 v43, 0xffff0000, v107
	v_pk_fma_f32 v[42:43], v[46:47], v[42:43], v[74:75]
	v_pk_mul_f32 v[36:37], v[36:37], v[110:111] op_sel_hi:[1,0]
	v_pk_mul_f32 v[44:45], v[40:41], v[40:41]
	global_store_dwordx4 v[100:101], v[40:43], off offset:64
	v_mul_f32_e32 v36, 0xbfb8aa3b, v36
	v_pk_mul_f32 v[32:33], v[32:33], v[110:111] op_sel_hi:[1,0]
	v_cvt_pk_bf16_f32 v40, v40, v41
	v_cvt_pk_bf16_f32 v41, v42, v43
	global_store_dwordx2 v[98:99], v[40:41], off offset:32
	v_exp_f32_e32 v40, v36
	v_mul_f32_e32 v36, 0xbfb8aa3b, v37
	v_exp_f32_e32 v41, v36
	v_pk_mul_f32 v[36:37], v[38:39], v[110:111] op_sel_hi:[1,0]
	v_add_f32_e32 v38, 1.0, v40
	v_mul_f32_e32 v36, 0xbfb8aa3b, v36
	v_exp_f32_e32 v36, v36
	v_mul_f32_e32 v37, 0xbfb8aa3b, v37
	v_add_f32_e32 v39, 1.0, v41
	v_exp_f32_e32 v37, v37
	v_rcp_f32_e32 v38, v38
	v_rcp_f32_e32 v39, v39
	v_add_f32_e32 v36, 1.0, v36
	v_pk_mul_f32 v[46:47], v[42:43], v[42:43]
	v_lshlrev_b32_e32 v40, 16, v104
	v_and_b32_e32 v41, 0xffff0000, v104
	v_rcp_f32_e32 v42, v36
	v_add_f32_e32 v36, 1.0, v37
	v_mul_f32_e32 v32, 0xbfb8aa3b, v32
	v_rcp_f32_e32 v43, v36
	v_pk_fma_f32 v[36:37], v[38:39], v[40:41], v[68:69]
	v_exp_f32_e32 v40, v32
	v_mul_f32_e32 v32, 0xbfb8aa3b, v33
	v_exp_f32_e32 v41, v32
	v_pk_mul_f32 v[32:33], v[34:35], v[110:111] op_sel_hi:[1,0]
	v_add_f32_e32 v34, 1.0, v40
	v_mul_f32_e32 v32, 0xbfb8aa3b, v32
	v_mul_f32_e32 v33, 0xbfb8aa3b, v33
	v_exp_f32_e32 v32, v32
	v_exp_f32_e32 v33, v33
	v_add_f32_e32 v35, 1.0, v41
	v_rcp_f32_e32 v34, v34
	v_rcp_f32_e32 v35, v35
	v_add_f32_e32 v32, 1.0, v32
	v_add_f32_e32 v33, 1.0, v33
	v_rcp_f32_e32 v32, v32
	v_rcp_f32_e32 v33, v33
	v_lshlrev_b32_e32 v38, 16, v105
	v_and_b32_e32 v39, 0xffff0000, v105
	v_lshlrev_b32_e32 v40, 16, v102
	v_and_b32_e32 v41, 0xffff0000, v102
	v_add_f32_e32 v46, v46, v47
	v_add_f32_e32 v44, v44, v45
	v_pk_fma_f32 v[38:39], v[42:43], v[38:39], v[70:71]
	v_pk_fma_f32 v[40:41], v[34:35], v[40:41], v[64:65]
	v_lshlrev_b32_e32 v34, 16, v103
	v_and_b32_e32 v35, 0xffff0000, v103
	v_add_f32_e32 v44, v44, v46
	v_add_f32_e32 v45, v78, v79
	v_add_f32_e32 v46, v76, v77
	v_pk_mul_f32 v[68:69], v[36:37], v[36:37]
	v_pk_mul_f32 v[70:71], v[38:39], v[38:39]
	v_pk_fma_f32 v[42:43], v[32:33], v[34:35], v[66:67]
	v_add_f32_e32 v45, v46, v45
	v_pk_mul_f32 v[32:33], v[40:41], v[40:41]
	v_pk_mul_f32 v[34:35], v[42:43], v[42:43]
	v_add_f32_e32 v44, v45, v44
	v_add_f32_e32 v45, v70, v71
	v_add_f32_e32 v46, v68, v69
	v_add_f32_e32 v45, v46, v45
	v_add_f32_e32 v34, v34, v35
	v_add_f32_e32 v32, v32, v33
	v_add_f32_e32 v44, v45, v44
	v_add_f32_e32 v32, v32, v34
	v_add_f32_e32 v34, v32, v44
	s_nop 1
	v_mov_b32_dpp v35, v34 quad_perm:[1,0,3,2] row_mask:0xf bank_mask:0xf
	v_cvt_pk_bf16_f32 v32, v36, v37
	v_cvt_pk_bf16_f32 v33, v38, v39
	global_store_dwordx4 v[100:101], v[36:39], off offset:512
	global_store_dwordx2 v[98:99], v[32:33], off offset:256
	s_waitcnt lgkmcnt(0)
	v_add_f32_e32 v32, v34, v35
	s_nop 1
	v_mov_b32_dpp v33, v32 quad_perm:[2,3,0,1] row_mask:0xf bank_mask:0xf
	v_cvt_pk_bf16_f32 v34, v40, v41
	v_cvt_pk_bf16_f32 v35, v42, v43
	global_store_dwordx4 v[100:101], v[40:43], off offset:576
	global_store_dwordx2 v[98:99], v[34:35], off offset:288
	s_mov_b32 vcc_lo, 0x11111111
	s_mov_b32 vcc_hi, 0x11111111
	s_and_saveexec_b64 s[0:1], vcc
	s_cbranch_execz .LBB0_1322
	v_lshl_add_u64 v[34:35], v[96:97], 2, s[12:13]
	s_waitcnt lgkmcnt(0)
	v_add_f32_e32 v32, v32, v33
	global_atomic_add_f32 v[34:35], v32, off
.LBB0_1322:
	s_or_b64 exec, exec, s[0:1]
	s_waitcnt vmcnt(8)
	v_fmamk_f32 v32, v94, 0x3a800000, v197
	s_waitcnt lgkmcnt(0)
	v_mul_f32_e32 v33, 0x4b800000, v32
	v_cmp_gt_f32_e32 vcc, s56, v32
	v_or_b32_e32 v64, 48, v112
	v_ashrrev_i32_e32 v65, 31, v64
	v_cndmask_b32_e32 v32, v32, v33, vcc
	v_rsq_f32_e32 v32, v32
	v_lshlrev_b64 v[34:35], 11, v[64:65]
	v_lshl_add_u64 v[34:35], s[8:9], 0, v[34:35]
	v_mul_f32_e32 v33, 0x45800000, v32
	v_cndmask_b32_e32 v94, v32, v33, vcc
	v_lshlrev_b64 v[32:33], 12, v[64:65]
	v_lshl_add_u64 v[32:33], s[6:7], 0, v[32:33]
	v_lshl_add_u64 v[68:69], v[160:161], 2, v[32:33]
	v_lshl_add_u64 v[66:67], v[160:161], 1, v[34:35]
	global_load_dwordx4 v[44:47], v[68:69], off
	global_load_dwordx4 v[40:43], v[68:69], off offset:64
	global_load_dwordx4 v[36:39], v[68:69], off offset:512
	global_load_dwordx4 v[32:35], v[68:69], off offset:576
	global_load_dwordx2 v[76:77], v[66:67], off
	global_load_dwordx2 v[74:75], v[66:67], off offset:32
	global_load_dwordx2 v[72:73], v[66:67], off offset:256
	global_load_dwordx2 v[70:71], v[66:67], off offset:288
	v_lshl_add_u64 v[78:79], v[64:65], 2, s[14:15]
	global_load_dword v78, v[78:79], off
	v_pk_mul_f32 v[28:29], v[28:29], v[94:95] op_sel_hi:[1,0]
	v_lshlrev_b32_e32 v96, 16, v92
	v_mul_f32_e32 v28, 0xbfb8aa3b, v28
	v_exp_f32_e32 v79, v28
	v_mul_f32_e32 v28, 0xbfb8aa3b, v29
	v_exp_f32_e32 v95, v28
	v_and_b32_e32 v97, 0xffff0000, v92
	v_pk_mul_f32 v[28:29], v[30:31], v[94:95] op_sel_hi:[1,0]
	s_nop 0
	v_mul_f32_e32 v28, 0xbfb8aa3b, v28
	v_exp_f32_e32 v28, v28
	v_mul_f32_e32 v29, 0xbfb8aa3b, v29
	v_exp_f32_e32 v29, v29
	v_add_f32_e32 v30, 1.0, v79
	v_add_f32_e32 v31, 1.0, v95
	v_add_f32_e32 v28, 1.0, v28
	v_rcp_f32_e32 v30, v30
	v_rcp_f32_e32 v31, v31
	v_rcp_f32_e32 v98, v28
	v_add_f32_e32 v28, 1.0, v29
	v_rcp_f32_e32 v99, v28
	v_pk_fma_f32 v[28:29], v[30:31], v[96:97], v[60:61]
	v_lshlrev_b32_e32 v30, 16, v93
	v_and_b32_e32 v31, 0xffff0000, v93
	v_pk_fma_f32 v[30:31], v[98:99], v[30:31], v[62:63]
	v_pk_mul_f32 v[24:25], v[24:25], v[94:95] op_sel_hi:[1,0]
	v_pk_mul_f32 v[60:61], v[28:29], v[28:29]
	global_store_dwordx4 v[84:85], v[28:31], off
	v_mul_f32_e32 v24, 0xbfb8aa3b, v24
	v_pk_mul_f32 v[62:63], v[30:31], v[30:31]
	v_cvt_pk_bf16_f32 v28, v28, v29
	v_cvt_pk_bf16_f32 v29, v30, v31
	global_store_dwordx2 v[82:83], v[28:29], off
	v_exp_f32_e32 v28, v24
	v_mul_f32_e32 v24, 0xbfb8aa3b, v25
	v_exp_f32_e32 v29, v24
	v_pk_mul_f32 v[24:25], v[26:27], v[94:95] op_sel_hi:[1,0]
	v_add_f32_e32 v26, 1.0, v28
	v_mul_f32_e32 v24, 0xbfb8aa3b, v24
	v_exp_f32_e32 v24, v24
	v_mul_f32_e32 v25, 0xbfb8aa3b, v25
	v_exp_f32_e32 v25, v25
	v_add_f32_e32 v27, 1.0, v29
	v_add_f32_e32 v24, 1.0, v24
	v_rcp_f32_e32 v26, v26
	v_rcp_f32_e32 v27, v27
	v_rcp_f32_e32 v30, v24
	v_add_f32_e32 v24, 1.0, v25
	v_rcp_f32_e32 v31, v24
	v_lshlrev_b32_e32 v28, 16, v90
	v_and_b32_e32 v29, 0xffff0000, v90
	v_pk_fma_f32 v[24:25], v[26:27], v[28:29], v[56:57]
	v_lshlrev_b32_e32 v26, 16, v91
	v_and_b32_e32 v27, 0xffff0000, v91
	v_pk_fma_f32 v[26:27], v[30:31], v[26:27], v[58:59]
	v_pk_mul_f32 v[20:21], v[20:21], v[94:95] op_sel_hi:[1,0]
	v_pk_mul_f32 v[28:29], v[24:25], v[24:25]
	global_store_dwordx4 v[84:85], v[24:27], off offset:64
	v_mul_f32_e32 v20, 0xbfb8aa3b, v20
	v_pk_mul_f32 v[16:17], v[16:17], v[94:95] op_sel_hi:[1,0]
	v_cvt_pk_bf16_f32 v24, v24, v25
	v_cvt_pk_bf16_f32 v25, v26, v27
	global_store_dwordx2 v[82:83], v[24:25], off offset:32
	v_exp_f32_e32 v24, v20
	v_mul_f32_e32 v20, 0xbfb8aa3b, v21
	v_exp_f32_e32 v25, v20
	v_pk_mul_f32 v[20:21], v[22:23], v[94:95] op_sel_hi:[1,0]
	v_add_f32_e32 v22, 1.0, v24
	v_mul_f32_e32 v20, 0xbfb8aa3b, v20
	v_exp_f32_e32 v20, v20
	v_mul_f32_e32 v21, 0xbfb8aa3b, v21
	v_add_f32_e32 v23, 1.0, v25
	v_exp_f32_e32 v21, v21
	v_rcp_f32_e32 v22, v22
	v_rcp_f32_e32 v23, v23
	v_add_f32_e32 v20, 1.0, v20
	v_pk_mul_f32 v[30:31], v[26:27], v[26:27]
	v_lshlrev_b32_e32 v24, 16, v88
	v_and_b32_e32 v25, 0xffff0000, v88
	v_rcp_f32_e32 v26, v20
	v_add_f32_e32 v20, 1.0, v21
	v_mul_f32_e32 v16, 0xbfb8aa3b, v16
	v_rcp_f32_e32 v27, v20
	v_pk_fma_f32 v[20:21], v[22:23], v[24:25], v[52:53]
	v_exp_f32_e32 v24, v16
	v_mul_f32_e32 v16, 0xbfb8aa3b, v17
	v_exp_f32_e32 v25, v16
	v_pk_mul_f32 v[16:17], v[18:19], v[94:95] op_sel_hi:[1,0]
	v_add_f32_e32 v18, 1.0, v24
	v_mul_f32_e32 v16, 0xbfb8aa3b, v16
	v_mul_f32_e32 v17, 0xbfb8aa3b, v17
	v_exp_f32_e32 v16, v16
	v_exp_f32_e32 v17, v17
	v_add_f32_e32 v19, 1.0, v25
	v_rcp_f32_e32 v18, v18
	v_rcp_f32_e32 v19, v19
	v_add_f32_e32 v16, 1.0, v16
	v_add_f32_e32 v17, 1.0, v17
	v_rcp_f32_e32 v16, v16
	v_rcp_f32_e32 v17, v17
	v_lshlrev_b32_e32 v22, 16, v89
	v_and_b32_e32 v23, 0xffff0000, v89
	v_lshlrev_b32_e32 v24, 16, v86
	v_and_b32_e32 v25, 0xffff0000, v86
	v_add_f32_e32 v30, v30, v31
	v_add_f32_e32 v28, v28, v29
	v_pk_fma_f32 v[22:23], v[26:27], v[22:23], v[54:55]
	v_pk_fma_f32 v[24:25], v[18:19], v[24:25], v[48:49]
	v_lshlrev_b32_e32 v18, 16, v87
	v_and_b32_e32 v19, 0xffff0000, v87
	v_add_f32_e32 v28, v28, v30
	v_add_f32_e32 v29, v62, v63
	v_add_f32_e32 v30, v60, v61
	v_pk_mul_f32 v[52:53], v[20:21], v[20:21]
	v_pk_mul_f32 v[54:55], v[22:23], v[22:23]
	v_pk_fma_f32 v[26:27], v[16:17], v[18:19], v[50:51]
	v_add_f32_e32 v29, v30, v29
	v_pk_mul_f32 v[16:17], v[24:25], v[24:25]
	v_pk_mul_f32 v[18:19], v[26:27], v[26:27]
	v_add_f32_e32 v28, v29, v28
	v_add_f32_e32 v29, v54, v55
	v_add_f32_e32 v30, v52, v53
	v_add_f32_e32 v29, v30, v29
	v_add_f32_e32 v18, v18, v19
	v_add_f32_e32 v16, v16, v17
	v_add_f32_e32 v28, v29, v28
	v_add_f32_e32 v16, v16, v18
	v_add_f32_e32 v18, v16, v28
	s_nop 1
	v_mov_b32_dpp v19, v18 quad_perm:[1,0,3,2] row_mask:0xf bank_mask:0xf
	v_cvt_pk_bf16_f32 v16, v20, v21
	v_cvt_pk_bf16_f32 v17, v22, v23
	global_store_dwordx4 v[84:85], v[20:23], off offset:512
	global_store_dwordx2 v[82:83], v[16:17], off offset:256
	s_waitcnt lgkmcnt(0)
	v_add_f32_e32 v16, v18, v19
	s_nop 1
	v_mov_b32_dpp v17, v16 quad_perm:[2,3,0,1] row_mask:0xf bank_mask:0xf
	v_cvt_pk_bf16_f32 v18, v24, v25
	v_cvt_pk_bf16_f32 v19, v26, v27
	global_store_dwordx4 v[84:85], v[24:27], off offset:576
	global_store_dwordx2 v[82:83], v[18:19], off offset:288
	s_mov_b32 vcc_lo, 0x11111111
	s_mov_b32 vcc_hi, 0x11111111
	s_and_saveexec_b64 s[0:1], vcc
	s_cbranch_execz .LBB0_1324
	v_lshl_add_u64 v[18:19], v[80:81], 2, s[12:13]
	s_waitcnt lgkmcnt(0)
	v_add_f32_e32 v16, v16, v17
	global_atomic_add_f32 v[18:19], v16, off
.LBB0_1324:
	s_or_b64 exec, exec, s[0:1]
	s_waitcnt vmcnt(8)
	v_fmamk_f32 v16, v78, 0x3a800000, v197
	s_waitcnt lgkmcnt(0)
	v_mul_f32_e32 v17, 0x4b800000, v16
	v_cmp_gt_f32_e32 vcc, s56, v16
	v_and_b32_e32 v19, 0xffff0000, v76
	s_nop 0
	v_cndmask_b32_e32 v16, v16, v17, vcc
	v_rsq_f32_e32 v16, v16
	s_nop 0
	v_mul_f32_e32 v17, 0x45800000, v16
	v_cndmask_b32_e32 v16, v16, v17, vcc
	v_pk_mul_f32 v[12:13], v[12:13], v[16:17] op_sel_hi:[1,0]
	s_nop 0
	v_mul_f32_e32 v12, 0xbfb8aa3b, v12
	v_exp_f32_e32 v17, v12
	v_mul_f32_e32 v12, 0xbfb8aa3b, v13
	v_exp_f32_e32 v18, v12
	v_pk_mul_f32 v[12:13], v[14:15], v[16:17] op_sel_hi:[1,0]
	s_nop 0
	v_mul_f32_e32 v12, 0xbfb8aa3b, v12
	v_exp_f32_e32 v12, v12
	v_mul_f32_e32 v13, 0xbfb8aa3b, v13
	v_exp_f32_e32 v13, v13
	v_add_f32_e32 v14, 1.0, v17
	v_add_f32_e32 v15, 1.0, v18
	v_add_f32_e32 v12, 1.0, v12
	v_rcp_f32_e32 v14, v14
	v_rcp_f32_e32 v15, v15
	v_rcp_f32_e32 v20, v12
	v_add_f32_e32 v12, 1.0, v13
	v_rcp_f32_e32 v21, v12
	v_lshlrev_b32_e32 v18, 16, v76
	v_pk_fma_f32 v[12:13], v[14:15], v[18:19], v[44:45]
	v_lshlrev_b32_e32 v14, 16, v77
	v_and_b32_e32 v15, 0xffff0000, v77
	v_pk_fma_f32 v[14:15], v[20:21], v[14:15], v[46:47]
	v_pk_mul_f32 v[8:9], v[8:9], v[16:17] op_sel_hi:[1,0]
	v_pk_mul_f32 v[18:19], v[12:13], v[12:13]
	global_store_dwordx4 v[68:69], v[12:15], off
	v_mul_f32_e32 v8, 0xbfb8aa3b, v8
	v_pk_mul_f32 v[20:21], v[14:15], v[14:15]
	v_cvt_pk_bf16_f32 v12, v12, v13
	v_cvt_pk_bf16_f32 v13, v14, v15
	global_store_dwordx2 v[66:67], v[12:13], off
	v_exp_f32_e32 v12, v8
	v_mul_f32_e32 v8, 0xbfb8aa3b, v9
	v_exp_f32_e32 v13, v8
	v_pk_mul_f32 v[8:9], v[10:11], v[16:17] op_sel_hi:[1,0]
	v_add_f32_e32 v10, 1.0, v12
	v_mul_f32_e32 v8, 0xbfb8aa3b, v8
	v_exp_f32_e32 v8, v8
	v_mul_f32_e32 v9, 0xbfb8aa3b, v9
	v_exp_f32_e32 v9, v9
	v_add_f32_e32 v11, 1.0, v13
	v_add_f32_e32 v8, 1.0, v8
	v_rcp_f32_e32 v10, v10
	v_rcp_f32_e32 v11, v11
	v_rcp_f32_e32 v14, v8
	v_add_f32_e32 v8, 1.0, v9
	v_rcp_f32_e32 v15, v8
	v_lshlrev_b32_e32 v12, 16, v74
	v_and_b32_e32 v13, 0xffff0000, v74
	v_pk_fma_f32 v[8:9], v[10:11], v[12:13], v[40:41]
	v_lshlrev_b32_e32 v10, 16, v75
	v_and_b32_e32 v11, 0xffff0000, v75
	v_pk_fma_f32 v[10:11], v[14:15], v[10:11], v[42:43]
	v_pk_mul_f32 v[4:5], v[4:5], v[16:17] op_sel_hi:[1,0]
	v_pk_mul_f32 v[12:13], v[8:9], v[8:9]
	global_store_dwordx4 v[68:69], v[8:11], off offset:64
	v_mul_f32_e32 v4, 0xbfb8aa3b, v4
	v_pk_mul_f32 v[0:1], v[0:1], v[16:17] op_sel_hi:[1,0]
	v_cvt_pk_bf16_f32 v8, v8, v9
	v_cvt_pk_bf16_f32 v9, v10, v11
	global_store_dwordx2 v[66:67], v[8:9], off offset:32
	v_exp_f32_e32 v8, v4
	v_mul_f32_e32 v4, 0xbfb8aa3b, v5
	v_exp_f32_e32 v9, v4
	v_pk_mul_f32 v[4:5], v[6:7], v[16:17] op_sel_hi:[1,0]
	v_add_f32_e32 v6, 1.0, v8
	v_mul_f32_e32 v4, 0xbfb8aa3b, v4
	v_exp_f32_e32 v4, v4
	v_mul_f32_e32 v5, 0xbfb8aa3b, v5
	v_add_f32_e32 v7, 1.0, v9
	v_exp_f32_e32 v5, v5
	v_rcp_f32_e32 v6, v6
	v_rcp_f32_e32 v7, v7
	v_add_f32_e32 v4, 1.0, v4
	v_pk_mul_f32 v[14:15], v[10:11], v[10:11]
	v_lshlrev_b32_e32 v8, 16, v72
	v_and_b32_e32 v9, 0xffff0000, v72
	v_rcp_f32_e32 v10, v4
	v_add_f32_e32 v4, 1.0, v5
	v_mul_f32_e32 v0, 0xbfb8aa3b, v0
	v_rcp_f32_e32 v11, v4
	v_pk_fma_f32 v[4:5], v[6:7], v[8:9], v[36:37]
	v_exp_f32_e32 v8, v0
	v_mul_f32_e32 v0, 0xbfb8aa3b, v1
	v_exp_f32_e32 v9, v0
	v_pk_mul_f32 v[0:1], v[2:3], v[16:17] op_sel_hi:[1,0]
	v_add_f32_e32 v2, 1.0, v8
	v_mul_f32_e32 v0, 0xbfb8aa3b, v0
	v_mul_f32_e32 v1, 0xbfb8aa3b, v1
	v_exp_f32_e32 v0, v0
	v_exp_f32_e32 v1, v1
	v_add_f32_e32 v3, 1.0, v9
	v_rcp_f32_e32 v2, v2
	v_rcp_f32_e32 v3, v3
	v_add_f32_e32 v0, 1.0, v0
	v_add_f32_e32 v1, 1.0, v1
	v_rcp_f32_e32 v0, v0
	v_rcp_f32_e32 v1, v1
	v_lshlrev_b32_e32 v6, 16, v73
	v_and_b32_e32 v7, 0xffff0000, v73
	v_lshlrev_b32_e32 v8, 16, v70
	v_and_b32_e32 v9, 0xffff0000, v70
	v_add_f32_e32 v14, v14, v15
	v_add_f32_e32 v12, v12, v13
	v_pk_fma_f32 v[6:7], v[10:11], v[6:7], v[38:39]
	v_pk_fma_f32 v[8:9], v[2:3], v[8:9], v[32:33]
	v_lshlrev_b32_e32 v2, 16, v71
	v_and_b32_e32 v3, 0xffff0000, v71
	v_add_f32_e32 v12, v12, v14
	v_add_f32_e32 v13, v20, v21
	v_add_f32_e32 v14, v18, v19
	v_pk_mul_f32 v[22:23], v[4:5], v[4:5]
	v_pk_mul_f32 v[24:25], v[6:7], v[6:7]
	v_pk_fma_f32 v[10:11], v[0:1], v[2:3], v[34:35]
	v_add_f32_e32 v13, v14, v13
	v_pk_mul_f32 v[0:1], v[8:9], v[8:9]
	v_pk_mul_f32 v[2:3], v[10:11], v[10:11]
	v_add_f32_e32 v12, v13, v12
	v_add_f32_e32 v13, v24, v25
	v_add_f32_e32 v14, v22, v23
	v_add_f32_e32 v13, v14, v13
	v_add_f32_e32 v2, v2, v3
	v_add_f32_e32 v0, v0, v1
	v_add_f32_e32 v12, v13, v12
	v_add_f32_e32 v0, v0, v2
	v_add_f32_e32 v2, v0, v12
	s_nop 1
	v_mov_b32_dpp v3, v2 quad_perm:[1,0,3,2] row_mask:0xf bank_mask:0xf
	v_cvt_pk_bf16_f32 v0, v4, v5
	v_cvt_pk_bf16_f32 v1, v6, v7
	global_store_dwordx4 v[68:69], v[4:7], off offset:512
	global_store_dwordx2 v[66:67], v[0:1], off offset:256
	s_waitcnt lgkmcnt(0)
	v_add_f32_e32 v0, v2, v3
	s_nop 1
	v_mov_b32_dpp v1, v0 quad_perm:[2,3,0,1] row_mask:0xf bank_mask:0xf
	v_cvt_pk_bf16_f32 v2, v8, v9
	v_cvt_pk_bf16_f32 v3, v10, v11
	global_store_dwordx4 v[68:69], v[8:11], off offset:576
	global_store_dwordx2 v[66:67], v[2:3], off offset:288
	s_mov_b32 vcc_lo, 0x11111111
	s_mov_b32 vcc_hi, 0x11111111
	s_and_saveexec_b64 s[0:1], vcc
	s_cbranch_execz .LBB0_1326
	v_lshl_add_u64 v[2:3], v[64:65], 2, s[12:13]
	s_waitcnt lgkmcnt(0)
	v_add_f32_e32 v0, v0, v1
	global_atomic_add_f32 v[2:3], v0, off

.LBB0_1497:
	ds_read_b128 v[128:131], v171
	ds_read_b128 v[132:135], v171 offset:1024
	ds_read_b128 v[136:139], v171 offset:2048
	ds_read_b128 v[140:143], v171 offset:3072
	ds_read_b128 v[156:159], v172
	ds_read_b128 v[160:163], v172 offset:1024
	ds_read_b128 v[164:167], v172 offset:2048
	ds_read_b128 v[176:179], v172 offset:3072
	s_add_u32 s26, s24, 0x100
	s_addc_u32 s27, s25, 0
	s_cmp_eq_u32 s55, 40
	s_cselect_b32 s31, s7, s27
	s_cselect_b32 s30, s6, s26
	s_cselect_b32 s29, s23, s54
	s_cselect_b32 s28, s22, s53
	v_lshl_add_u64 v[188:189], s[24:25], 0, v[150:151]
	s_add_i32 m0, s36, 0xc000
	ds_read_b128 v[180:183], v173
	ds_read_b128 v[184:187], v173 offset:1024
	ds_read_b128 v[192:195], v173 offset:2048
	ds_read_b128 v[196:199], v173 offset:3072
	ds_read_b128 v[200:203], v173 offset:4096
	ds_read_b128 v[204:207], v173 offset:5120
	ds_read_b128 v[208:211], v173 offset:6144
	ds_read_b128 v[212:215], v173 offset:7168
	global_load_lds_dwordx4 v[188:189], off
	v_lshl_add_u64 v[188:189], s[24:25], 0, v[148:149]
	s_add_i32 m0, s36, 0xe000
	s_nop 0
	global_load_lds_dwordx4 v[188:189], off
	s_waitcnt vmcnt(8)
	s_waitcnt lgkmcnt(0)
	s_barrier
	s_setprio 1
	s_waitcnt lgkmcnt(0)
	v_mfma_f32_16x16x32_bf16 v[124:127], v[128:131], v[180:183], v[124:127]
	v_mfma_f32_16x16x32_bf16 v[120:123], v[136:139], v[180:183], v[120:123]
	v_mfma_f32_16x16x32_bf16 v[108:111], v[128:131], v[192:195], v[108:111]
	v_mfma_f32_16x16x32_bf16 v[104:107], v[136:139], v[192:195], v[104:107]
	v_mfma_f32_16x16x32_bf16 v[92:95], v[128:131], v[200:203], v[92:95]
	v_mfma_f32_16x16x32_bf16 v[88:91], v[136:139], v[200:203], v[88:91]
	v_mfma_f32_16x16x32_bf16 v[76:79], v[128:131], v[208:211], v[76:79]
	v_mfma_f32_16x16x32_bf16 v[72:75], v[136:139], v[208:211], v[72:75]
	v_mfma_f32_16x16x32_bf16 v[124:127], v[132:135], v[184:187], v[124:127]
	v_mfma_f32_16x16x32_bf16 v[120:123], v[140:143], v[184:187], v[120:123]
	v_mfma_f32_16x16x32_bf16 v[108:111], v[132:135], v[196:199], v[108:111]
	v_mfma_f32_16x16x32_bf16 v[104:107], v[140:143], v[196:199], v[104:107]
	v_mfma_f32_16x16x32_bf16 v[92:95], v[132:135], v[204:207], v[92:95]
	v_mfma_f32_16x16x32_bf16 v[88:91], v[140:143], v[204:207], v[88:91]
	v_mfma_f32_16x16x32_bf16 v[76:79], v[132:135], v[212:215], v[76:79]
	v_mfma_f32_16x16x32_bf16 v[72:75], v[140:143], v[212:215], v[72:75]
	s_setprio 0
	s_setprio 1
	v_mfma_f32_16x16x32_bf16 v[116:119], v[156:159], v[180:183], v[116:119]
	v_mfma_f32_16x16x32_bf16 v[112:115], v[164:167], v[180:183], v[112:115]
	v_mfma_f32_16x16x32_bf16 v[100:103], v[156:159], v[192:195], v[100:103]
	v_mfma_f32_16x16x32_bf16 v[96:99], v[164:167], v[192:195], v[96:99]
	v_mfma_f32_16x16x32_bf16 v[84:87], v[156:159], v[200:203], v[84:87]
	v_mfma_f32_16x16x32_bf16 v[80:83], v[164:167], v[200:203], v[80:83]
	v_mfma_f32_16x16x32_bf16 v[68:71], v[156:159], v[208:211], v[68:71]
	v_mfma_f32_16x16x32_bf16 v[64:67], v[164:167], v[208:211], v[64:67]
	v_mfma_f32_16x16x32_bf16 v[116:119], v[160:163], v[184:187], v[116:119]
	v_mfma_f32_16x16x32_bf16 v[112:115], v[176:179], v[184:187], v[112:115]
	v_mfma_f32_16x16x32_bf16 v[100:103], v[160:163], v[196:199], v[100:103]
	v_mfma_f32_16x16x32_bf16 v[96:99], v[176:179], v[196:199], v[96:99]
	v_mfma_f32_16x16x32_bf16 v[84:87], v[160:163], v[204:207], v[84:87]
	v_mfma_f32_16x16x32_bf16 v[80:83], v[176:179], v[204:207], v[80:83]
	v_mfma_f32_16x16x32_bf16 v[68:71], v[160:163], v[212:215], v[68:71]
	v_mfma_f32_16x16x32_bf16 v[64:67], v[176:179], v[212:215], v[64:67]
	s_setprio 0
	s_barrier
	s_add_i32 s24, s47, s35
	v_lshl_add_u64 v[188:189], s[28:29], 0, v[144:145]
	s_mov_b32 m0, s24
	ds_read_b128 v[180:183], v173 offset:16384
	ds_read_b128 v[184:187], v173 offset:17408
	ds_read_b128 v[192:195], v173 offset:18432
	ds_read_b128 v[196:199], v173 offset:19456
	ds_read_b128 v[200:203], v173 offset:20480
	ds_read_b128 v[204:207], v173 offset:21504
	ds_read_b128 v[208:211], v173 offset:22528
	ds_read_b128 v[212:215], v173 offset:23552
	global_load_lds_dwordx4 v[188:189], off
	s_add_i32 m0, s24, 0x2000
	s_add_u32 s24, s28, 0xb0000
	v_lshl_add_u64 v[216:217], s[28:29], 0, v[146:147]
	s_addc_u32 s25, s29, 0
	s_add_i32 s56, s48, s35
	global_load_lds_dwordx4 v[216:217], off
	v_lshl_add_u64 v[218:219], s[24:25], 0, v[144:145]
	s_mov_b32 m0, s56
	v_lshl_add_u64 v[220:221], s[30:31], 0, v[146:147]
	global_load_lds_dwordx4 v[218:219], off
	v_lshl_add_u64 v[218:219], s[24:25], 0, v[146:147]
	s_add_i32 m0, s56, 0x2000
	s_nop 0
	global_load_lds_dwordx4 v[218:219], off
	v_lshl_add_u64 v[218:219], s[30:31], 0, v[144:145]
	s_mov_b32 m0, s36
	s_nop 0
	global_load_lds_dwordx4 v[218:219], off
	s_mov_b32 m0, s37
	s_nop 0
	global_load_lds_dwordx4 v[220:221], off
	s_waitcnt vmcnt(8)
	s_waitcnt lgkmcnt(0)
	s_barrier
	s_setprio 1
	s_waitcnt lgkmcnt(0)
	v_mfma_f32_16x16x32_bf16 v[60:63], v[128:131], v[180:183], v[60:63]
	v_mfma_f32_16x16x32_bf16 v[56:59], v[136:139], v[180:183], v[56:59]
	v_mfma_f32_16x16x32_bf16 v[44:47], v[128:131], v[192:195], v[44:47]
	v_mfma_f32_16x16x32_bf16 v[40:43], v[136:139], v[192:195], v[40:43]
	v_mfma_f32_16x16x32_bf16 v[28:31], v[128:131], v[200:203], v[28:31]
	v_mfma_f32_16x16x32_bf16 v[24:27], v[136:139], v[200:203], v[24:27]
	v_mfma_f32_16x16x32_bf16 v[12:15], v[128:131], v[208:211], v[12:15]
	v_mfma_f32_16x16x32_bf16 v[8:11], v[136:139], v[208:211], v[8:11]
	v_mfma_f32_16x16x32_bf16 v[60:63], v[132:135], v[184:187], v[60:63]
	v_mfma_f32_16x16x32_bf16 v[56:59], v[140:143], v[184:187], v[56:59]
	v_mfma_f32_16x16x32_bf16 v[44:47], v[132:135], v[196:199], v[44:47]
	v_mfma_f32_16x16x32_bf16 v[40:43], v[140:143], v[196:199], v[40:43]
	v_mfma_f32_16x16x32_bf16 v[28:31], v[132:135], v[204:207], v[28:31]
	v_mfma_f32_16x16x32_bf16 v[24:27], v[140:143], v[204:207], v[24:27]
	v_mfma_f32_16x16x32_bf16 v[12:15], v[132:135], v[212:215], v[12:15]
	v_mfma_f32_16x16x32_bf16 v[8:11], v[140:143], v[212:215], v[8:11]
	s_setprio 0
	s_setprio 1
	v_mfma_f32_16x16x32_bf16 v[52:55], v[156:159], v[180:183], v[52:55]
	v_mfma_f32_16x16x32_bf16 v[48:51], v[164:167], v[180:183], v[48:51]
	v_mfma_f32_16x16x32_bf16 v[36:39], v[156:159], v[192:195], v[36:39]
	v_mfma_f32_16x16x32_bf16 v[32:35], v[164:167], v[192:195], v[32:35]
	v_mfma_f32_16x16x32_bf16 v[20:23], v[156:159], v[200:203], v[20:23]
	v_mfma_f32_16x16x32_bf16 v[16:19], v[164:167], v[200:203], v[16:19]
	v_mfma_f32_16x16x32_bf16 v[4:7], v[156:159], v[208:211], v[4:7]
	v_mfma_f32_16x16x32_bf16 v[0:3], v[164:167], v[208:211], v[0:3]
	v_mfma_f32_16x16x32_bf16 v[52:55], v[160:163], v[184:187], v[52:55]
	v_mfma_f32_16x16x32_bf16 v[48:51], v[176:179], v[184:187], v[48:51]
	v_mfma_f32_16x16x32_bf16 v[36:39], v[160:163], v[196:199], v[36:39]
	v_mfma_f32_16x16x32_bf16 v[32:35], v[176:179], v[196:199], v[32:35]
	v_mfma_f32_16x16x32_bf16 v[20:23], v[160:163], v[204:207], v[20:23]
	v_mfma_f32_16x16x32_bf16 v[16:19], v[176:179], v[204:207], v[16:19]
	v_mfma_f32_16x16x32_bf16 v[4:7], v[160:163], v[212:215], v[4:7]
	v_mfma_f32_16x16x32_bf16 v[0:3], v[176:179], v[212:215], v[0:3]
	s_setprio 0
	s_barrier
	s_add_i32 s56, 0, 0x18000
	s_add_i32 s57, 0, 0x1c000
	v_add_u32_e32 v140, s56, v169
	v_add_u32_e32 v175, s57, v169
	ds_read_b128 v[128:131], v140
	ds_read_b128 v[132:135], v140 offset:1024
	ds_read_b128 v[136:139], v140 offset:2048
	ds_read_b128 v[140:143], v140 offset:3072
	ds_read_b128 v[156:159], v175
	ds_read_b128 v[160:163], v175 offset:1024
	ds_read_b128 v[164:167], v175 offset:2048
	ds_read_b128 v[176:179], v175 offset:3072
	s_add_u32 s24, s30, 0xb0000
	s_addc_u32 s25, s31, 0
	s_mov_b32 m0, s38
	v_lshl_add_u64 v[222:223], s[24:25], 0, v[144:145]
	ds_read_b128 v[180:183], v173 offset:32768
	ds_read_b128 v[184:187], v173 offset:33792
	ds_read_b128 v[192:195], v173 offset:34816
	ds_read_b128 v[196:199], v173 offset:35840
	ds_read_b128 v[200:203], v173 offset:36864
	ds_read_b128 v[204:207], v173 offset:37888
	ds_read_b128 v[208:211], v173 offset:38912
	ds_read_b128 v[212:215], v173 offset:39936
	global_load_lds_dwordx4 v[222:223], off
	v_lshl_add_u64 v[222:223], s[24:25], 0, v[146:147]
	s_mov_b32 m0, s39
	s_nop 0
	global_load_lds_dwordx4 v[222:223], off
	s_waitcnt vmcnt(8)
	s_waitcnt lgkmcnt(0)
	s_barrier
	s_setprio 1
	s_waitcnt lgkmcnt(0)
	v_mfma_f32_16x16x32_bf16 v[124:127], v[128:131], v[180:183], v[124:127]
	v_mfma_f32_16x16x32_bf16 v[120:123], v[136:139], v[180:183], v[120:123]
	v_mfma_f32_16x16x32_bf16 v[108:111], v[128:131], v[192:195], v[108:111]
	v_mfma_f32_16x16x32_bf16 v[104:107], v[136:139], v[192:195], v[104:107]
	v_mfma_f32_16x16x32_bf16 v[92:95], v[128:131], v[200:203], v[92:95]
	v_mfma_f32_16x16x32_bf16 v[88:91], v[136:139], v[200:203], v[88:91]
	v_mfma_f32_16x16x32_bf16 v[76:79], v[128:131], v[208:211], v[76:79]
	v_mfma_f32_16x16x32_bf16 v[72:75], v[136:139], v[208:211], v[72:75]
	v_mfma_f32_16x16x32_bf16 v[124:127], v[132:135], v[184:187], v[124:127]
	v_mfma_f32_16x16x32_bf16 v[120:123], v[140:143], v[184:187], v[120:123]
	v_mfma_f32_16x16x32_bf16 v[108:111], v[132:135], v[196:199], v[108:111]
	v_mfma_f32_16x16x32_bf16 v[104:107], v[140:143], v[196:199], v[104:107]
	v_mfma_f32_16x16x32_bf16 v[92:95], v[132:135], v[204:207], v[92:95]
	v_mfma_f32_16x16x32_bf16 v[88:91], v[140:143], v[204:207], v[88:91]
	v_mfma_f32_16x16x32_bf16 v[76:79], v[132:135], v[212:215], v[76:79]
	v_mfma_f32_16x16x32_bf16 v[72:75], v[140:143], v[212:215], v[72:75]
	s_setprio 0
	s_setprio 1
	v_mfma_f32_16x16x32_bf16 v[116:119], v[156:159], v[180:183], v[116:119]
	v_mfma_f32_16x16x32_bf16 v[112:115], v[164:167], v[180:183], v[112:115]
	v_mfma_f32_16x16x32_bf16 v[100:103], v[156:159], v[192:195], v[100:103]
	v_mfma_f32_16x16x32_bf16 v[96:99], v[164:167], v[192:195], v[96:99]
	v_mfma_f32_16x16x32_bf16 v[84:87], v[156:159], v[200:203], v[84:87]
	v_mfma_f32_16x16x32_bf16 v[80:83], v[164:167], v[200:203], v[80:83]
	v_mfma_f32_16x16x32_bf16 v[68:71], v[156:159], v[208:211], v[68:71]
	v_mfma_f32_16x16x32_bf16 v[64:67], v[164:167], v[208:211], v[64:67]
	v_mfma_f32_16x16x32_bf16 v[116:119], v[160:163], v[184:187], v[116:119]
	v_mfma_f32_16x16x32_bf16 v[112:115], v[176:179], v[184:187], v[112:115]
	v_mfma_f32_16x16x32_bf16 v[100:103], v[160:163], v[196:199], v[100:103]
	v_mfma_f32_16x16x32_bf16 v[96:99], v[176:179], v[196:199], v[96:99]
	v_mfma_f32_16x16x32_bf16 v[84:87], v[160:163], v[204:207], v[84:87]
	v_mfma_f32_16x16x32_bf16 v[80:83], v[176:179], v[204:207], v[80:83]
	v_mfma_f32_16x16x32_bf16 v[68:71], v[160:163], v[212:215], v[68:71]
	v_mfma_f32_16x16x32_bf16 v[64:67], v[176:179], v[212:215], v[64:67]
	s_setprio 0
	s_barrier
	s_add_i32 s24, s56, s35
	v_lshl_add_u64 v[188:189], v[188:189], 0, s[18:19]
	s_mov_b32 m0, s24
	ds_read_b128 v[180:183], v173 offset:49152
	ds_read_b128 v[184:187], v173 offset:50176
	ds_read_b128 v[192:195], v173 offset:51200
	ds_read_b128 v[196:199], v173 offset:52224
	ds_read_b128 v[200:203], v173 offset:53248
	ds_read_b128 v[204:207], v173 offset:54272
	ds_read_b128 v[208:211], v173 offset:55296
	ds_read_b128 v[212:215], v173 offset:56320
	global_load_lds_dwordx4 v[188:189], off
	s_add_i32 m0, s24, 0x2000
	s_add_u32 s24, s28, 0xb0080
	v_lshl_add_u64 v[188:189], v[216:217], 0, s[18:19]
	s_addc_u32 s25, s29, 0
	s_add_i32 s28, s57, s35
	global_load_lds_dwordx4 v[188:189], off
	v_lshl_add_u64 v[188:189], s[24:25], 0, v[144:145]
	s_mov_b32 m0, s28
	s_nop 0
	global_load_lds_dwordx4 v[188:189], off
	v_lshl_add_u64 v[188:189], s[24:25], 0, v[146:147]
	s_add_i32 m0, s28, 0x2000
	s_nop 0
	global_load_lds_dwordx4 v[188:189], off
	v_lshl_add_u64 v[188:189], v[218:219], 0, s[18:19]
	s_mov_b32 m0, s41
	s_nop 0
	global_load_lds_dwordx4 v[188:189], off
	v_lshl_add_u64 v[188:189], v[220:221], 0, s[18:19]
	s_mov_b32 m0, s42
	s_nop 0
	global_load_lds_dwordx4 v[188:189], off
	s_waitcnt vmcnt(8)
	s_waitcnt lgkmcnt(0)
	s_barrier
	s_setprio 1
	s_waitcnt lgkmcnt(0)
	v_mfma_f32_16x16x32_bf16 v[60:63], v[128:131], v[180:183], v[60:63]
	v_mfma_f32_16x16x32_bf16 v[56:59], v[136:139], v[180:183], v[56:59]
	v_mfma_f32_16x16x32_bf16 v[44:47], v[128:131], v[192:195], v[44:47]
	v_mfma_f32_16x16x32_bf16 v[40:43], v[136:139], v[192:195], v[40:43]
	v_mfma_f32_16x16x32_bf16 v[28:31], v[128:131], v[200:203], v[28:31]
	v_mfma_f32_16x16x32_bf16 v[24:27], v[136:139], v[200:203], v[24:27]
	v_mfma_f32_16x16x32_bf16 v[12:15], v[128:131], v[208:211], v[12:15]
	v_mfma_f32_16x16x32_bf16 v[8:11], v[136:139], v[208:211], v[8:11]
	v_mfma_f32_16x16x32_bf16 v[60:63], v[132:135], v[184:187], v[60:63]
	v_mfma_f32_16x16x32_bf16 v[56:59], v[140:143], v[184:187], v[56:59]
	v_mfma_f32_16x16x32_bf16 v[44:47], v[132:135], v[196:199], v[44:47]
	v_mfma_f32_16x16x32_bf16 v[40:43], v[140:143], v[196:199], v[40:43]
	v_mfma_f32_16x16x32_bf16 v[28:31], v[132:135], v[204:207], v[28:31]
	v_mfma_f32_16x16x32_bf16 v[24:27], v[140:143], v[204:207], v[24:27]
	v_mfma_f32_16x16x32_bf16 v[12:15], v[132:135], v[212:215], v[12:15]
	v_mfma_f32_16x16x32_bf16 v[8:11], v[140:143], v[212:215], v[8:11]
	s_setprio 0
	s_setprio 1
	v_mfma_f32_16x16x32_bf16 v[52:55], v[156:159], v[180:183], v[52:55]
	v_mfma_f32_16x16x32_bf16 v[48:51], v[164:167], v[180:183], v[48:51]
	v_mfma_f32_16x16x32_bf16 v[36:39], v[156:159], v[192:195], v[36:39]
	v_mfma_f32_16x16x32_bf16 v[32:35], v[164:167], v[192:195], v[32:35]
	v_mfma_f32_16x16x32_bf16 v[20:23], v[156:159], v[200:203], v[20:23]
	v_mfma_f32_16x16x32_bf16 v[16:19], v[164:167], v[200:203], v[16:19]
	v_mfma_f32_16x16x32_bf16 v[4:7], v[156:159], v[208:211], v[4:7]
	v_mfma_f32_16x16x32_bf16 v[0:3], v[164:167], v[208:211], v[0:3]
	v_mfma_f32_16x16x32_bf16 v[52:55], v[160:163], v[184:187], v[52:55]
	v_mfma_f32_16x16x32_bf16 v[48:51], v[176:179], v[184:187], v[48:51]
	v_mfma_f32_16x16x32_bf16 v[36:39], v[160:163], v[196:199], v[36:39]
	v_mfma_f32_16x16x32_bf16 v[32:35], v[176:179], v[196:199], v[32:35]
	v_mfma_f32_16x16x32_bf16 v[20:23], v[160:163], v[204:207], v[20:23]
	v_mfma_f32_16x16x32_bf16 v[16:19], v[176:179], v[204:207], v[16:19]
	v_mfma_f32_16x16x32_bf16 v[4:7], v[160:163], v[212:215], v[4:7]
	v_mfma_f32_16x16x32_bf16 v[0:3], v[176:179], v[212:215], v[0:3]
	s_setprio 0
	s_barrier
	s_add_i32 s55, s55, 2
	s_add_u32 s53, s53, 0x100
	s_addc_u32 s54, s54, 0
	s_cmp_gt_u32 s55, 41
	s_mov_b64 s[24:25], s[26:27]
	s_cbranch_scc0 .LBB0_1497
	v_mbcnt_lo_u32_b32 v235, -1, 0
	v_mbcnt_hi_u32_b32 v235, -1, v235
	v_lshrrev_b32_e32 v236, 2, v235
	v_and_b32_e32 v237, 3, v235
	v_lshl_add_u32 v232, v237, 4, v236
	v_lshlrev_b32_e32 v232, 2, v232
	v_and_b32_e32 v233, -16, v168
	v_or_b32_e32 v233, v233, v236
	v_lshlrev_b32_e32 v237, 2, v237
	v_and_b32_e32 v234, -13, v170
	v_or_b32_e32 v234, v234, v237
	v_lshl_add_u32 v158, s52, 8, v233
	v_lshl_or_b32 v156, s51, 8, v234
	v_ashrrev_i32_e32 v159, 31, v158
	v_lshlrev_b64 v[128:129], 12, v[158:159]
	v_ashrrev_i32_e32 v157, 31, v156
	v_lshl_add_u64 v[128:129], s[10:11], 0, v[128:129]
	v_lshlrev_b64 v[130:131], 2, v[156:157]
	v_lshl_add_u64 v[188:189], v[128:129], 0, v[130:131]
	global_load_dwordx4 v[164:167], v[188:189], off
	global_load_dwordx4 v[176:179], v[188:189], off offset:64
	global_load_dwordx4 v[180:183], v[188:189], off offset:512
	global_load_dwordx4 v[184:187], v[188:189], off offset:576
	v_or_b32_e32 v160, 16, v158
	v_ashrrev_i32_e32 v161, 31, v160
	v_lshlrev_b64 v[128:129], 12, v[160:161]
	v_lshl_add_u64 v[128:129], s[10:11], 0, v[128:129]
	v_lshl_add_u64 v[162:163], v[128:129], 0, v[130:131]
	global_load_dwordx4 v[140:143], v[162:163], off
	global_load_dwordx4 v[136:139], v[162:163], off offset:64
	global_load_dwordx4 v[132:135], v[162:163], off offset:512
	global_load_dwordx4 v[128:131], v[162:163], off offset:576
	v_lshlrev_b64 v[192:193], 11, v[158:159]
	v_lshl_add_u64 v[192:193], s[14:15], 0, v[192:193]
	v_and_b32_e32 v191, 64, v174
	v_lshl_add_u64 v[192:193], v[156:157], 1, v[192:193]
	v_xor_b32_e32 v175, 1, v174
	v_add_u32_e32 v191, 64, v191
	v_cmp_lt_i32_e32 vcc, v175, v191
	v_xor_b32_e32 v194, 2, v174
	ds_bpermute_b32 v127, v232, v127
	ds_bpermute_b32 v126, v232, v126
	ds_bpermute_b32 v125, v232, v125
	ds_bpermute_b32 v124, v232, v124
	ds_bpermute_b32 v123, v232, v123
	ds_bpermute_b32 v122, v232, v122
	ds_bpermute_b32 v121, v232, v121
	ds_bpermute_b32 v120, v232, v120
	ds_bpermute_b32 v119, v232, v119
	ds_bpermute_b32 v118, v232, v118
	ds_bpermute_b32 v117, v232, v117
	ds_bpermute_b32 v116, v232, v116
	ds_bpermute_b32 v115, v232, v115
	ds_bpermute_b32 v114, v232, v114
	ds_bpermute_b32 v113, v232, v113
	ds_bpermute_b32 v112, v232, v112
	ds_bpermute_b32 v111, v232, v111
	ds_bpermute_b32 v110, v232, v110
	ds_bpermute_b32 v109, v232, v109
	ds_bpermute_b32 v108, v232, v108
	ds_bpermute_b32 v107, v232, v107
	ds_bpermute_b32 v106, v232, v106
	ds_bpermute_b32 v105, v232, v105
	ds_bpermute_b32 v104, v232, v104
	ds_bpermute_b32 v103, v232, v103
	ds_bpermute_b32 v102, v232, v102
	ds_bpermute_b32 v101, v232, v101
	ds_bpermute_b32 v100, v232, v100
	ds_bpermute_b32 v99, v232, v99
	ds_bpermute_b32 v98, v232, v98
	ds_bpermute_b32 v97, v232, v97
	ds_bpermute_b32 v96, v232, v96
	ds_bpermute_b32 v95, v232, v95
	ds_bpermute_b32 v94, v232, v94
	ds_bpermute_b32 v93, v232, v93
	ds_bpermute_b32 v92, v232, v92
	ds_bpermute_b32 v91, v232, v91
	ds_bpermute_b32 v90, v232, v90
	ds_bpermute_b32 v89, v232, v89
	ds_bpermute_b32 v88, v232, v88
	ds_bpermute_b32 v87, v232, v87
	ds_bpermute_b32 v86, v232, v86
	ds_bpermute_b32 v85, v232, v85
	ds_bpermute_b32 v84, v232, v84
	ds_bpermute_b32 v83, v232, v83
	ds_bpermute_b32 v82, v232, v82
	ds_bpermute_b32 v81, v232, v81
	ds_bpermute_b32 v80, v232, v80
	ds_bpermute_b32 v79, v232, v79
	ds_bpermute_b32 v78, v232, v78
	ds_bpermute_b32 v77, v232, v77
	ds_bpermute_b32 v76, v232, v76
	ds_bpermute_b32 v75, v232, v75
	ds_bpermute_b32 v74, v232, v74
	ds_bpermute_b32 v73, v232, v73
	ds_bpermute_b32 v72, v232, v72
	ds_bpermute_b32 v71, v232, v71
	ds_bpermute_b32 v70, v232, v70
	ds_bpermute_b32 v69, v232, v69
	ds_bpermute_b32 v68, v232, v68
	ds_bpermute_b32 v67, v232, v67
	ds_bpermute_b32 v66, v232, v66
	ds_bpermute_b32 v65, v232, v65
	ds_bpermute_b32 v64, v232, v64
	ds_bpermute_b32 v63, v232, v63
	ds_bpermute_b32 v62, v232, v62
	ds_bpermute_b32 v61, v232, v61
	ds_bpermute_b32 v60, v232, v60
	ds_bpermute_b32 v59, v232, v59
	ds_bpermute_b32 v58, v232, v58
	ds_bpermute_b32 v57, v232, v57
	ds_bpermute_b32 v56, v232, v56
	ds_bpermute_b32 v55, v232, v55
	ds_bpermute_b32 v54, v232, v54
	ds_bpermute_b32 v53, v232, v53
	ds_bpermute_b32 v52, v232, v52
	ds_bpermute_b32 v51, v232, v51
	ds_bpermute_b32 v50, v232, v50
	ds_bpermute_b32 v49, v232, v49
	ds_bpermute_b32 v48, v232, v48
	ds_bpermute_b32 v47, v232, v47
	ds_bpermute_b32 v46, v232, v46
	ds_bpermute_b32 v45, v232, v45
	ds_bpermute_b32 v44, v232, v44
	ds_bpermute_b32 v43, v232, v43
	ds_bpermute_b32 v42, v232, v42
	ds_bpermute_b32 v41, v232, v41
	ds_bpermute_b32 v40, v232, v40
	ds_bpermute_b32 v39, v232, v39
	ds_bpermute_b32 v38, v232, v38
	ds_bpermute_b32 v37, v232, v37
	ds_bpermute_b32 v36, v232, v36
	ds_bpermute_b32 v35, v232, v35
	ds_bpermute_b32 v34, v232, v34
	ds_bpermute_b32 v33, v232, v33
	ds_bpermute_b32 v32, v232, v32
	ds_bpermute_b32 v31, v232, v31
	ds_bpermute_b32 v30, v232, v30
	ds_bpermute_b32 v29, v232, v29
	ds_bpermute_b32 v28, v232, v28
	ds_bpermute_b32 v27, v232, v27
	ds_bpermute_b32 v26, v232, v26
	ds_bpermute_b32 v25, v232, v25
	ds_bpermute_b32 v24, v232, v24
	ds_bpermute_b32 v23, v232, v23
	ds_bpermute_b32 v22, v232, v22
	ds_bpermute_b32 v21, v232, v21
	ds_bpermute_b32 v20, v232, v20
	ds_bpermute_b32 v19, v232, v19
	ds_bpermute_b32 v18, v232, v18
	ds_bpermute_b32 v17, v232, v17
	ds_bpermute_b32 v16, v232, v16
	ds_bpermute_b32 v15, v232, v15
	ds_bpermute_b32 v14, v232, v14
	ds_bpermute_b32 v13, v232, v13
	ds_bpermute_b32 v12, v232, v12
	ds_bpermute_b32 v11, v232, v11
	ds_bpermute_b32 v10, v232, v10
	ds_bpermute_b32 v9, v232, v9
	ds_bpermute_b32 v8, v232, v8
	ds_bpermute_b32 v7, v232, v7
	ds_bpermute_b32 v6, v232, v6
	ds_bpermute_b32 v5, v232, v5
	ds_bpermute_b32 v4, v232, v4
	ds_bpermute_b32 v3, v232, v3
	ds_bpermute_b32 v2, v232, v2
	ds_bpermute_b32 v1, v232, v1
	ds_bpermute_b32 v0, v232, v0
	s_waitcnt lgkmcnt(0)
	s_waitcnt lgkmcnt(0)
	s_cmp_eq_u64 s[20:21], 0
	s_cbranch_scc1 .LBB0_1500
	s_barrier
.LBB0_1500:
	s_waitcnt vmcnt(7)
	v_pk_fma_f32 v[126:127], v[126:127], 0.5, v[166:167] op_sel_hi:[1,0,1]
	v_pk_fma_f32 v[124:125], v[124:125], 0.5, v[164:165] op_sel_hi:[1,0,1]
	s_waitcnt vmcnt(6)
	v_pk_fma_f32 v[122:123], v[122:123], 0.5, v[178:179] op_sel_hi:[1,0,1]
	v_pk_fma_f32 v[120:121], v[120:121], 0.5, v[176:177] op_sel_hi:[1,0,1]
	s_waitcnt vmcnt(5)
	v_pk_fma_f32 v[118:119], v[118:119], 0.5, v[182:183] op_sel_hi:[1,0,1]
	v_pk_fma_f32 v[116:117], v[116:117], 0.5, v[180:181] op_sel_hi:[1,0,1]
	s_waitcnt vmcnt(4)
	v_pk_fma_f32 v[164:165], v[112:113], 0.5, v[184:185] op_sel_hi:[1,0,1]
	v_mul_f32_e32 v178, v125, v125
	v_mul_f32_e32 v179, v127, v127
	global_store_dwordx4 v[188:189], v[124:127], off
	v_cvt_pk_bf16_f32 v112, v124, v125
	v_cvt_pk_bf16_f32 v113, v126, v127
	v_mul_f32_e32 v125, v121, v121
	v_mul_f32_e32 v127, v123, v123
	v_pk_fma_f32 v[166:167], v[114:115], 0.5, v[186:187] op_sel_hi:[1,0,1]
	v_mul_f32_e32 v180, v117, v117
	v_mul_f32_e32 v181, v119, v119
	v_fmac_f32_e32 v178, v124, v124
	v_fmac_f32_e32 v179, v126, v126
	v_fmac_f32_e32 v125, v120, v120
	v_fmac_f32_e32 v127, v122, v122
	v_mul_f32_e32 v182, v165, v165
	v_mul_f32_e32 v183, v167, v167
	global_store_dwordx2 v[192:193], v[112:113], off
	v_fmac_f32_e32 v180, v116, v116
	v_fmac_f32_e32 v181, v118, v118
	v_add_f32_e32 v112, v178, v179
	v_add_f32_e32 v113, v125, v127
	v_fmac_f32_e32 v182, v164, v164
	v_fmac_f32_e32 v183, v166, v166
	v_add_f32_e32 v124, v180, v181
	v_add_f32_e32 v112, v112, v113
	v_cndmask_b32_e32 v175, v174, v175, vcc
	v_add_f32_e32 v125, v182, v183
	v_add_f32_e32 v112, v112, v124
	v_lshlrev_b32_e32 v175, 2, v175
	v_add_f32_e32 v112, v112, v125
	s_nop 1
	v_mov_b32_dpp v113, v112 quad_perm:[1,0,3,2] row_mask:0xf bank_mask:0xf
	v_cmp_lt_i32_e32 vcc, v194, v191
	v_cvt_pk_bf16_f32 v176, v116, v117
	v_cvt_pk_bf16_f32 v114, v120, v121
	v_cndmask_b32_e32 v191, v174, v194, vcc
	v_cvt_pk_bf16_f32 v115, v122, v123
	v_cvt_pk_bf16_f32 v177, v118, v119
	global_store_dwordx4 v[188:189], v[120:123], off offset:64
	global_store_dwordx2 v[192:193], v[114:115], off offset:32
	global_store_dwordx4 v[188:189], v[116:119], off offset:512
	global_store_dwordx2 v[192:193], v[176:177], off offset:256
	s_waitcnt lgkmcnt(0)
	v_add_f32_e32 v112, v112, v113
	v_lshlrev_b32_e32 v176, 2, v191
	s_nop 1
	v_mov_b32_dpp v113, v112 quad_perm:[2,3,0,1] row_mask:0xf bank_mask:0xf
	v_cvt_pk_bf16_f32 v114, v164, v165
	v_cvt_pk_bf16_f32 v115, v166, v167
	global_store_dwordx4 v[188:189], v[164:167], off offset:576
	global_store_dwordx2 v[192:193], v[114:115], off offset:288
	s_mov_b32 vcc_lo, 0x11111111
	s_mov_b32 vcc_hi, 0x11111111
	s_and_saveexec_b64 s[24:25], vcc
	s_cbranch_execz .LBB0_1502
	v_lshl_add_u64 v[114:115], v[158:159], 2, s[16:17]
	s_waitcnt lgkmcnt(0)
	v_add_f32_e32 v112, v112, v113
	global_atomic_add_f32 v[114:115], v112, off
.LBB0_1502:
	s_or_b64 exec, exec, s[24:25]
	v_or_b32_e32 v164, 32, v158
	v_ashrrev_i32_e32 v165, 31, v164
	s_waitcnt lgkmcnt(0)
	v_lshlrev_b64 v[112:113], 12, v[164:165]
	v_lshl_add_u64 v[112:113], s[10:11], 0, v[112:113]
	v_lshl_add_u64 v[166:167], v[156:157], 2, v[112:113]
	global_load_dwordx4 v[124:127], v[166:167], off
	global_load_dwordx4 v[120:123], v[166:167], off offset:64
	global_load_dwordx4 v[116:119], v[166:167], off offset:512
	global_load_dwordx4 v[112:115], v[166:167], off offset:576
	s_waitcnt vmcnt(15)
	v_pk_fma_f32 v[110:111], v[110:111], 0.5, v[142:143] op_sel_hi:[1,0,1]
	v_pk_fma_f32 v[108:109], v[108:109], 0.5, v[140:141] op_sel_hi:[1,0,1]
	v_mul_f32_e32 v141, v111, v111
	v_mul_f32_e32 v140, v109, v109
	v_fmac_f32_e32 v140, v108, v108
	v_fmac_f32_e32 v141, v110, v110
	v_add_f32_e32 v142, v140, v141
	v_lshlrev_b64 v[140:141], 11, v[160:161]
	v_lshl_add_u64 v[140:141], s[14:15], 0, v[140:141]
	global_store_dwordx4 v[162:163], v[108:111], off
	v_lshl_add_u64 v[140:141], v[156:157], 1, v[140:141]
	s_waitcnt vmcnt(15)
	v_pk_fma_f32 v[104:105], v[104:105], 0.5, v[136:137] op_sel_hi:[1,0,1]
	v_cvt_pk_bf16_f32 v108, v108, v109
	v_cvt_pk_bf16_f32 v109, v110, v111
	global_store_dwordx2 v[140:141], v[108:109], off
	v_pk_fma_f32 v[106:107], v[106:107], 0.5, v[138:139] op_sel_hi:[1,0,1]
	v_mul_f32_e32 v108, v105, v105
	v_fmac_f32_e32 v108, v104, v104
	v_mul_f32_e32 v109, v107, v107
	global_store_dwordx4 v[162:163], v[104:107], off offset:64
	s_waitcnt vmcnt(16)
	v_pk_fma_f32 v[102:103], v[102:103], 0.5, v[134:135] op_sel_hi:[1,0,1]
	v_pk_fma_f32 v[100:101], v[100:101], 0.5, v[132:133] op_sel_hi:[1,0,1]
	v_cvt_pk_bf16_f32 v104, v104, v105
	v_cvt_pk_bf16_f32 v105, v106, v107
	v_fmac_f32_e32 v109, v106, v106
	global_store_dwordx2 v[140:141], v[104:105], off offset:32
	v_mul_f32_e32 v104, v101, v101
	v_mul_f32_e32 v105, v103, v103
	v_add_f32_e32 v108, v108, v109
	v_fmac_f32_e32 v104, v100, v100
	v_fmac_f32_e32 v105, v102, v102
	v_add_f32_e32 v108, v142, v108
	v_add_f32_e32 v104, v104, v105
	v_add_f32_e32 v108, v108, v104
	s_waitcnt vmcnt(16)
	v_pk_fma_f32 v[106:107], v[98:99], 0.5, v[130:131] op_sel_hi:[1,0,1]
	v_pk_fma_f32 v[104:105], v[96:97], 0.5, v[128:129] op_sel_hi:[1,0,1]
	v_mul_f32_e32 v97, v107, v107
	v_mul_f32_e32 v96, v105, v105
	v_fmac_f32_e32 v96, v104, v104
	v_fmac_f32_e32 v97, v106, v106
	v_add_f32_e32 v96, v96, v97
	v_add_f32_e32 v98, v108, v96
	s_nop 1
	v_mov_b32_dpp v99, v98 quad_perm:[1,0,3,2] row_mask:0xf bank_mask:0xf
	v_cvt_pk_bf16_f32 v96, v100, v101
	v_cvt_pk_bf16_f32 v97, v102, v103
	global_store_dwordx4 v[162:163], v[100:103], off offset:512
	global_store_dwordx2 v[140:141], v[96:97], off offset:256
	s_waitcnt lgkmcnt(0)
	v_add_f32_e32 v96, v98, v99
	s_nop 1
	v_mov_b32_dpp v97, v96 quad_perm:[2,3,0,1] row_mask:0xf bank_mask:0xf
	v_cvt_pk_bf16_f32 v98, v104, v105
	v_cvt_pk_bf16_f32 v99, v106, v107
	global_store_dwordx4 v[162:163], v[104:107], off offset:576
	global_store_dwordx2 v[140:141], v[98:99], off offset:288
	s_mov_b32 vcc_lo, 0x11111111
	s_mov_b32 vcc_hi, 0x11111111
	s_and_saveexec_b64 s[24:25], vcc
	s_cbranch_execz .LBB0_1504
	v_lshl_add_u64 v[98:99], v[160:161], 2, s[16:17]
	s_waitcnt lgkmcnt(0)
	v_add_f32_e32 v96, v96, v97
	global_atomic_add_f32 v[98:99], v96, off
.LBB0_1504:
	s_or_b64 exec, exec, s[24:25]
	v_or_b32_e32 v128, 48, v158
	v_ashrrev_i32_e32 v129, 31, v128
	s_waitcnt lgkmcnt(0)
	v_lshlrev_b64 v[96:97], 12, v[128:129]
	v_lshl_add_u64 v[96:97], s[10:11], 0, v[96:97]
	v_lshl_add_u64 v[130:131], v[156:157], 2, v[96:97]
	global_load_dwordx4 v[108:111], v[130:131], off
	global_load_dwordx4 v[104:107], v[130:131], off offset:64
	global_load_dwordx4 v[100:103], v[130:131], off offset:512
	global_load_dwordx4 v[96:99], v[130:131], off offset:576
	s_waitcnt vmcnt(15)
	v_pk_fma_f32 v[94:95], v[94:95], 0.5, v[126:127] op_sel_hi:[1,0,1]
	v_pk_fma_f32 v[92:93], v[92:93], 0.5, v[124:125] op_sel_hi:[1,0,1]
	v_mul_f32_e32 v125, v95, v95
	v_mul_f32_e32 v124, v93, v93
	v_fmac_f32_e32 v124, v92, v92
	v_fmac_f32_e32 v125, v94, v94
	v_add_f32_e32 v126, v124, v125
	v_lshlrev_b64 v[124:125], 11, v[164:165]
	v_lshl_add_u64 v[124:125], s[14:15], 0, v[124:125]
	global_store_dwordx4 v[166:167], v[92:95], off
	v_lshl_add_u64 v[124:125], v[156:157], 1, v[124:125]
	s_waitcnt vmcnt(15)
	v_pk_fma_f32 v[88:89], v[88:89], 0.5, v[120:121] op_sel_hi:[1,0,1]
	v_cvt_pk_bf16_f32 v92, v92, v93
	v_cvt_pk_bf16_f32 v93, v94, v95
	global_store_dwordx2 v[124:125], v[92:93], off
	v_pk_fma_f32 v[90:91], v[90:91], 0.5, v[122:123] op_sel_hi:[1,0,1]
	v_mul_f32_e32 v92, v89, v89
	v_fmac_f32_e32 v92, v88, v88
	v_mul_f32_e32 v93, v91, v91
	global_store_dwordx4 v[166:167], v[88:91], off offset:64
	s_waitcnt vmcnt(16)
	v_pk_fma_f32 v[86:87], v[86:87], 0.5, v[118:119] op_sel_hi:[1,0,1]
	v_pk_fma_f32 v[84:85], v[84:85], 0.5, v[116:117] op_sel_hi:[1,0,1]
	v_cvt_pk_bf16_f32 v88, v88, v89
	v_cvt_pk_bf16_f32 v89, v90, v91
	v_fmac_f32_e32 v93, v90, v90
	global_store_dwordx2 v[124:125], v[88:89], off offset:32
	v_mul_f32_e32 v88, v85, v85
	v_mul_f32_e32 v89, v87, v87
	v_add_f32_e32 v92, v92, v93
	v_fmac_f32_e32 v88, v84, v84
	v_fmac_f32_e32 v89, v86, v86
	v_add_f32_e32 v92, v126, v92
	v_add_f32_e32 v88, v88, v89
	v_add_f32_e32 v92, v92, v88
	s_waitcnt vmcnt(16)
	v_pk_fma_f32 v[90:91], v[82:83], 0.5, v[114:115] op_sel_hi:[1,0,1]
	v_pk_fma_f32 v[88:89], v[80:81], 0.5, v[112:113] op_sel_hi:[1,0,1]
	v_mul_f32_e32 v81, v91, v91
	v_mul_f32_e32 v80, v89, v89
	v_fmac_f32_e32 v80, v88, v88
	v_fmac_f32_e32 v81, v90, v90
	v_add_f32_e32 v80, v80, v81
	v_add_f32_e32 v82, v92, v80
	s_nop 1
	v_mov_b32_dpp v83, v82 quad_perm:[1,0,3,2] row_mask:0xf bank_mask:0xf
	v_cvt_pk_bf16_f32 v80, v84, v85
	v_cvt_pk_bf16_f32 v81, v86, v87
	global_store_dwordx4 v[166:167], v[84:87], off offset:512
	global_store_dwordx2 v[124:125], v[80:81], off offset:256
	s_waitcnt lgkmcnt(0)
	v_add_f32_e32 v80, v82, v83
	s_nop 1
	v_mov_b32_dpp v81, v80 quad_perm:[2,3,0,1] row_mask:0xf bank_mask:0xf
	v_cvt_pk_bf16_f32 v82, v88, v89
	v_cvt_pk_bf16_f32 v83, v90, v91
	global_store_dwordx4 v[166:167], v[88:91], off offset:576
	global_store_dwordx2 v[124:125], v[82:83], off offset:288
	s_mov_b32 vcc_lo, 0x11111111
	s_mov_b32 vcc_hi, 0x11111111
	s_and_saveexec_b64 s[24:25], vcc
	s_cbranch_execz .LBB0_1506
	v_lshl_add_u64 v[82:83], v[164:165], 2, s[16:17]
	s_waitcnt lgkmcnt(0)
	v_add_f32_e32 v80, v80, v81
	global_atomic_add_f32 v[82:83], v80, off
.LBB0_1506:
	s_or_b64 exec, exec, s[24:25]
	v_add_u32_e32 v112, 0x80, v158
	v_ashrrev_i32_e32 v113, 31, v112
	s_waitcnt lgkmcnt(0)
	v_lshlrev_b64 v[80:81], 12, v[112:113]
	v_lshl_add_u64 v[80:81], s[10:11], 0, v[80:81]
	v_lshl_add_u64 v[114:115], v[156:157], 2, v[80:81]
	global_load_dwordx4 v[92:95], v[114:115], off
	global_load_dwordx4 v[88:91], v[114:115], off offset:64
	global_load_dwordx4 v[84:87], v[114:115], off offset:512
	global_load_dwordx4 v[80:83], v[114:115], off offset:576
	s_waitcnt vmcnt(15)
	v_pk_fma_f32 v[78:79], v[78:79], 0.5, v[110:111] op_sel_hi:[1,0,1]
	v_pk_fma_f32 v[76:77], v[76:77], 0.5, v[108:109] op_sel_hi:[1,0,1]
	v_mul_f32_e32 v109, v79, v79
	v_mul_f32_e32 v108, v77, v77
	v_fmac_f32_e32 v108, v76, v76
	v_fmac_f32_e32 v109, v78, v78
	v_add_f32_e32 v110, v108, v109
	v_lshlrev_b64 v[108:109], 11, v[128:129]
	v_lshl_add_u64 v[108:109], s[14:15], 0, v[108:109]
	global_store_dwordx4 v[130:131], v[76:79], off
	v_lshl_add_u64 v[108:109], v[156:157], 1, v[108:109]
	s_waitcnt vmcnt(15)
	v_pk_fma_f32 v[72:73], v[72:73], 0.5, v[104:105] op_sel_hi:[1,0,1]
	v_cvt_pk_bf16_f32 v76, v76, v77
	v_cvt_pk_bf16_f32 v77, v78, v79
	global_store_dwordx2 v[108:109], v[76:77], off
	v_pk_fma_f32 v[74:75], v[74:75], 0.5, v[106:107] op_sel_hi:[1,0,1]
	v_mul_f32_e32 v76, v73, v73
	v_fmac_f32_e32 v76, v72, v72
	v_mul_f32_e32 v77, v75, v75
	global_store_dwordx4 v[130:131], v[72:75], off offset:64
	s_waitcnt vmcnt(16)
	v_pk_fma_f32 v[70:71], v[70:71], 0.5, v[102:103] op_sel_hi:[1,0,1]
	v_pk_fma_f32 v[68:69], v[68:69], 0.5, v[100:101] op_sel_hi:[1,0,1]
	v_cvt_pk_bf16_f32 v72, v72, v73
	v_cvt_pk_bf16_f32 v73, v74, v75
	v_fmac_f32_e32 v77, v74, v74
	global_store_dwordx2 v[108:109], v[72:73], off offset:32
	v_mul_f32_e32 v72, v69, v69
	v_mul_f32_e32 v73, v71, v71
	v_add_f32_e32 v76, v76, v77
	v_fmac_f32_e32 v72, v68, v68
	v_fmac_f32_e32 v73, v70, v70
	v_add_f32_e32 v76, v110, v76
	v_add_f32_e32 v72, v72, v73
	v_add_f32_e32 v76, v76, v72
	s_waitcnt vmcnt(16)
	v_pk_fma_f32 v[74:75], v[66:67], 0.5, v[98:99] op_sel_hi:[1,0,1]
	v_pk_fma_f32 v[72:73], v[64:65], 0.5, v[96:97] op_sel_hi:[1,0,1]
	v_mul_f32_e32 v65, v75, v75
	v_mul_f32_e32 v64, v73, v73
	v_fmac_f32_e32 v64, v72, v72
	v_fmac_f32_e32 v65, v74, v74
	v_add_f32_e32 v64, v64, v65
	v_add_f32_e32 v66, v76, v64
	s_nop 1
	v_mov_b32_dpp v67, v66 quad_perm:[1,0,3,2] row_mask:0xf bank_mask:0xf
	v_cvt_pk_bf16_f32 v64, v68, v69
	v_cvt_pk_bf16_f32 v65, v70, v71
	global_store_dwordx4 v[130:131], v[68:71], off offset:512
	global_store_dwordx2 v[108:109], v[64:65], off offset:256
	s_waitcnt lgkmcnt(0)
	v_add_f32_e32 v64, v66, v67
	s_nop 1
	v_mov_b32_dpp v65, v64 quad_perm:[2,3,0,1] row_mask:0xf bank_mask:0xf
	v_cvt_pk_bf16_f32 v66, v72, v73
	v_cvt_pk_bf16_f32 v67, v74, v75
	global_store_dwordx4 v[130:131], v[72:75], off offset:576
	global_store_dwordx2 v[108:109], v[66:67], off offset:288
	s_mov_b32 vcc_lo, 0x11111111
	s_mov_b32 vcc_hi, 0x11111111
	s_and_saveexec_b64 s[24:25], vcc
	s_cbranch_execz .LBB0_1508
	v_lshl_add_u64 v[66:67], v[128:129], 2, s[16:17]
	s_waitcnt lgkmcnt(0)
	v_add_f32_e32 v64, v64, v65
	global_atomic_add_f32 v[66:67], v64, off
.LBB0_1508:
	s_or_b64 exec, exec, s[24:25]
	v_or_b32_e32 v96, 16, v112
	v_ashrrev_i32_e32 v97, 31, v96
	s_waitcnt lgkmcnt(0)
	v_lshlrev_b64 v[64:65], 12, v[96:97]
	v_lshl_add_u64 v[64:65], s[10:11], 0, v[64:65]
	v_lshl_add_u64 v[98:99], v[156:157], 2, v[64:65]
	global_load_dwordx4 v[76:79], v[98:99], off
	global_load_dwordx4 v[72:75], v[98:99], off offset:64
	global_load_dwordx4 v[68:71], v[98:99], off offset:512
	global_load_dwordx4 v[64:67], v[98:99], off offset:576
	s_waitcnt vmcnt(15)
	v_pk_fma_f32 v[62:63], v[62:63], 0.5, v[94:95] op_sel_hi:[1,0,1]
	v_pk_fma_f32 v[60:61], v[60:61], 0.5, v[92:93] op_sel_hi:[1,0,1]
	v_mul_f32_e32 v93, v63, v63
	v_mul_f32_e32 v92, v61, v61
	v_fmac_f32_e32 v92, v60, v60
	v_fmac_f32_e32 v93, v62, v62
	v_add_f32_e32 v94, v92, v93
	v_lshlrev_b64 v[92:93], 11, v[112:113]
	v_lshl_add_u64 v[92:93], s[14:15], 0, v[92:93]
	global_store_dwordx4 v[114:115], v[60:63], off
	v_lshl_add_u64 v[92:93], v[156:157], 1, v[92:93]
	s_waitcnt vmcnt(15)
	v_pk_fma_f32 v[56:57], v[56:57], 0.5, v[88:89] op_sel_hi:[1,0,1]
	v_cvt_pk_bf16_f32 v60, v60, v61
	v_cvt_pk_bf16_f32 v61, v62, v63
	global_store_dwordx2 v[92:93], v[60:61], off
	v_pk_fma_f32 v[58:59], v[58:59], 0.5, v[90:91] op_sel_hi:[1,0,1]
	v_mul_f32_e32 v60, v57, v57
	v_fmac_f32_e32 v60, v56, v56
	v_mul_f32_e32 v61, v59, v59
	global_store_dwordx4 v[114:115], v[56:59], off offset:64
	s_waitcnt vmcnt(16)
	v_pk_fma_f32 v[54:55], v[54:55], 0.5, v[86:87] op_sel_hi:[1,0,1]
	v_pk_fma_f32 v[52:53], v[52:53], 0.5, v[84:85] op_sel_hi:[1,0,1]
	v_cvt_pk_bf16_f32 v56, v56, v57
	v_cvt_pk_bf16_f32 v57, v58, v59
	v_fmac_f32_e32 v61, v58, v58
	global_store_dwordx2 v[92:93], v[56:57], off offset:32
	v_mul_f32_e32 v56, v53, v53
	v_mul_f32_e32 v57, v55, v55
	v_add_f32_e32 v60, v60, v61
	v_fmac_f32_e32 v56, v52, v52
	v_fmac_f32_e32 v57, v54, v54
	v_add_f32_e32 v60, v94, v60
	v_add_f32_e32 v56, v56, v57
	v_add_f32_e32 v60, v60, v56
	s_waitcnt vmcnt(16)
	v_pk_fma_f32 v[58:59], v[50:51], 0.5, v[82:83] op_sel_hi:[1,0,1]
	v_pk_fma_f32 v[56:57], v[48:49], 0.5, v[80:81] op_sel_hi:[1,0,1]
	v_mul_f32_e32 v49, v59, v59
	v_mul_f32_e32 v48, v57, v57
	v_fmac_f32_e32 v48, v56, v56
	v_fmac_f32_e32 v49, v58, v58
	v_add_f32_e32 v48, v48, v49
	v_add_f32_e32 v50, v60, v48
	s_nop 1
	v_mov_b32_dpp v51, v50 quad_perm:[1,0,3,2] row_mask:0xf bank_mask:0xf
	v_cvt_pk_bf16_f32 v48, v52, v53
	v_cvt_pk_bf16_f32 v49, v54, v55
	global_store_dwordx4 v[114:115], v[52:55], off offset:512
	global_store_dwordx2 v[92:93], v[48:49], off offset:256
	s_waitcnt lgkmcnt(0)
	v_add_f32_e32 v48, v50, v51
	s_nop 1
	v_mov_b32_dpp v49, v48 quad_perm:[2,3,0,1] row_mask:0xf bank_mask:0xf
	v_cvt_pk_bf16_f32 v50, v56, v57
	v_cvt_pk_bf16_f32 v51, v58, v59
	global_store_dwordx4 v[114:115], v[56:59], off offset:576
	global_store_dwordx2 v[92:93], v[50:51], off offset:288
	s_mov_b32 vcc_lo, 0x11111111
	s_mov_b32 vcc_hi, 0x11111111
	s_and_saveexec_b64 s[24:25], vcc
	s_cbranch_execz .LBB0_1510
	v_lshl_add_u64 v[50:51], v[112:113], 2, s[16:17]
	s_waitcnt lgkmcnt(0)
	v_add_f32_e32 v48, v48, v49
	global_atomic_add_f32 v[50:51], v48, off
.LBB0_1510:
	s_or_b64 exec, exec, s[24:25]
	v_or_b32_e32 v80, 32, v112
	v_ashrrev_i32_e32 v81, 31, v80
	s_waitcnt lgkmcnt(0)
	v_lshlrev_b64 v[48:49], 12, v[80:81]
	v_lshl_add_u64 v[48:49], s[10:11], 0, v[48:49]
	v_lshl_add_u64 v[82:83], v[156:157], 2, v[48:49]
	global_load_dwordx4 v[60:63], v[82:83], off
	global_load_dwordx4 v[56:59], v[82:83], off offset:64
	global_load_dwordx4 v[52:55], v[82:83], off offset:512
	global_load_dwordx4 v[48:51], v[82:83], off offset:576
	s_waitcnt vmcnt(15)
	v_pk_fma_f32 v[46:47], v[46:47], 0.5, v[78:79] op_sel_hi:[1,0,1]
	v_pk_fma_f32 v[44:45], v[44:45], 0.5, v[76:77] op_sel_hi:[1,0,1]
	v_mul_f32_e32 v77, v47, v47
	v_mul_f32_e32 v76, v45, v45
	v_fmac_f32_e32 v76, v44, v44
	v_fmac_f32_e32 v77, v46, v46
	v_add_f32_e32 v78, v76, v77
	v_lshlrev_b64 v[76:77], 11, v[96:97]
	v_lshl_add_u64 v[76:77], s[14:15], 0, v[76:77]
	global_store_dwordx4 v[98:99], v[44:47], off
	v_lshl_add_u64 v[76:77], v[156:157], 1, v[76:77]
	s_waitcnt vmcnt(15)
	v_pk_fma_f32 v[40:41], v[40:41], 0.5, v[72:73] op_sel_hi:[1,0,1]
	v_cvt_pk_bf16_f32 v44, v44, v45
	v_cvt_pk_bf16_f32 v45, v46, v47
	global_store_dwordx2 v[76:77], v[44:45], off
	v_pk_fma_f32 v[42:43], v[42:43], 0.5, v[74:75] op_sel_hi:[1,0,1]
	v_mul_f32_e32 v44, v41, v41
	v_fmac_f32_e32 v44, v40, v40
	v_mul_f32_e32 v45, v43, v43
	global_store_dwordx4 v[98:99], v[40:43], off offset:64
	s_waitcnt vmcnt(16)
	v_pk_fma_f32 v[38:39], v[38:39], 0.5, v[70:71] op_sel_hi:[1,0,1]
	v_pk_fma_f32 v[36:37], v[36:37], 0.5, v[68:69] op_sel_hi:[1,0,1]
	v_cvt_pk_bf16_f32 v40, v40, v41
	v_cvt_pk_bf16_f32 v41, v42, v43
	v_fmac_f32_e32 v45, v42, v42
	global_store_dwordx2 v[76:77], v[40:41], off offset:32
	v_mul_f32_e32 v40, v37, v37
	v_mul_f32_e32 v41, v39, v39
	v_add_f32_e32 v44, v44, v45
	v_fmac_f32_e32 v40, v36, v36
	v_fmac_f32_e32 v41, v38, v38
	v_add_f32_e32 v44, v78, v44
	v_add_f32_e32 v40, v40, v41
	v_add_f32_e32 v44, v44, v40
	s_waitcnt vmcnt(16)
	v_pk_fma_f32 v[42:43], v[34:35], 0.5, v[66:67] op_sel_hi:[1,0,1]
	v_pk_fma_f32 v[40:41], v[32:33], 0.5, v[64:65] op_sel_hi:[1,0,1]
	v_mul_f32_e32 v33, v43, v43
	v_mul_f32_e32 v32, v41, v41
	v_fmac_f32_e32 v32, v40, v40
	v_fmac_f32_e32 v33, v42, v42
	v_add_f32_e32 v32, v32, v33
	v_add_f32_e32 v34, v44, v32
	s_nop 1
	v_mov_b32_dpp v35, v34 quad_perm:[1,0,3,2] row_mask:0xf bank_mask:0xf
	v_cvt_pk_bf16_f32 v32, v36, v37
	v_cvt_pk_bf16_f32 v33, v38, v39
	global_store_dwordx4 v[98:99], v[36:39], off offset:512
	global_store_dwordx2 v[76:77], v[32:33], off offset:256
	s_waitcnt lgkmcnt(0)
	v_add_f32_e32 v32, v34, v35
	s_nop 1
	v_mov_b32_dpp v33, v32 quad_perm:[2,3,0,1] row_mask:0xf bank_mask:0xf
	v_cvt_pk_bf16_f32 v34, v40, v41
	v_cvt_pk_bf16_f32 v35, v42, v43
	global_store_dwordx4 v[98:99], v[40:43], off offset:576
	global_store_dwordx2 v[76:77], v[34:35], off offset:288
	s_mov_b32 vcc_lo, 0x11111111
	s_mov_b32 vcc_hi, 0x11111111
	s_and_saveexec_b64 s[24:25], vcc
	s_cbranch_execz .LBB0_1512
	v_lshl_add_u64 v[34:35], v[96:97], 2, s[16:17]
	s_waitcnt lgkmcnt(0)
	v_add_f32_e32 v32, v32, v33
	global_atomic_add_f32 v[34:35], v32, off
.LBB0_1512:
	s_or_b64 exec, exec, s[24:25]
	v_or_b32_e32 v64, 48, v112
	v_ashrrev_i32_e32 v65, 31, v64
	s_waitcnt lgkmcnt(0)
	v_lshlrev_b64 v[32:33], 12, v[64:65]
	v_lshl_add_u64 v[32:33], s[10:11], 0, v[32:33]
	v_lshl_add_u64 v[66:67], v[156:157], 2, v[32:33]
	global_load_dwordx4 v[44:47], v[66:67], off
	global_load_dwordx4 v[40:43], v[66:67], off offset:64
	global_load_dwordx4 v[36:39], v[66:67], off offset:512
	global_load_dwordx4 v[32:35], v[66:67], off offset:576
	s_waitcnt vmcnt(15)
	v_pk_fma_f32 v[30:31], v[30:31], 0.5, v[62:63] op_sel_hi:[1,0,1]
	v_pk_fma_f32 v[28:29], v[28:29], 0.5, v[60:61] op_sel_hi:[1,0,1]
	v_mul_f32_e32 v61, v31, v31
	v_mul_f32_e32 v60, v29, v29
	v_fmac_f32_e32 v60, v28, v28
	v_fmac_f32_e32 v61, v30, v30
	v_add_f32_e32 v62, v60, v61
	v_lshlrev_b64 v[60:61], 11, v[80:81]
	v_lshl_add_u64 v[60:61], s[14:15], 0, v[60:61]
	global_store_dwordx4 v[82:83], v[28:31], off
	v_lshl_add_u64 v[60:61], v[156:157], 1, v[60:61]
	s_waitcnt vmcnt(15)
	v_pk_fma_f32 v[24:25], v[24:25], 0.5, v[56:57] op_sel_hi:[1,0,1]
	v_cvt_pk_bf16_f32 v28, v28, v29
	v_cvt_pk_bf16_f32 v29, v30, v31
	global_store_dwordx2 v[60:61], v[28:29], off
	v_pk_fma_f32 v[26:27], v[26:27], 0.5, v[58:59] op_sel_hi:[1,0,1]
	v_mul_f32_e32 v28, v25, v25
	v_fmac_f32_e32 v28, v24, v24
	v_mul_f32_e32 v29, v27, v27
	global_store_dwordx4 v[82:83], v[24:27], off offset:64
	s_waitcnt vmcnt(16)
	v_pk_fma_f32 v[22:23], v[22:23], 0.5, v[54:55] op_sel_hi:[1,0,1]
	v_pk_fma_f32 v[20:21], v[20:21], 0.5, v[52:53] op_sel_hi:[1,0,1]
	v_cvt_pk_bf16_f32 v24, v24, v25
	v_cvt_pk_bf16_f32 v25, v26, v27
	v_fmac_f32_e32 v29, v26, v26
	global_store_dwordx2 v[60:61], v[24:25], off offset:32
	v_mul_f32_e32 v24, v21, v21
	v_mul_f32_e32 v25, v23, v23
	v_add_f32_e32 v28, v28, v29
	v_fmac_f32_e32 v24, v20, v20
	v_fmac_f32_e32 v25, v22, v22
	v_add_f32_e32 v28, v62, v28
	v_add_f32_e32 v24, v24, v25
	v_add_f32_e32 v28, v28, v24
	s_waitcnt vmcnt(16)
	v_pk_fma_f32 v[26:27], v[18:19], 0.5, v[50:51] op_sel_hi:[1,0,1]
	v_pk_fma_f32 v[24:25], v[16:17], 0.5, v[48:49] op_sel_hi:[1,0,1]
	v_mul_f32_e32 v17, v27, v27
	v_mul_f32_e32 v16, v25, v25
	v_fmac_f32_e32 v16, v24, v24
	v_fmac_f32_e32 v17, v26, v26
	v_add_f32_e32 v16, v16, v17
	v_add_f32_e32 v18, v28, v16
	s_nop 1
	v_mov_b32_dpp v19, v18 quad_perm:[1,0,3,2] row_mask:0xf bank_mask:0xf
	v_cvt_pk_bf16_f32 v16, v20, v21
	v_cvt_pk_bf16_f32 v17, v22, v23
	global_store_dwordx4 v[82:83], v[20:23], off offset:512
	global_store_dwordx2 v[60:61], v[16:17], off offset:256
	s_waitcnt lgkmcnt(0)
	v_add_f32_e32 v16, v18, v19
	s_nop 1
	v_mov_b32_dpp v17, v16 quad_perm:[2,3,0,1] row_mask:0xf bank_mask:0xf
	v_cvt_pk_bf16_f32 v18, v24, v25
	v_cvt_pk_bf16_f32 v19, v26, v27
	global_store_dwordx4 v[82:83], v[24:27], off offset:576
	global_store_dwordx2 v[60:61], v[18:19], off offset:288
	s_mov_b32 vcc_lo, 0x11111111
	s_mov_b32 vcc_hi, 0x11111111
	s_and_saveexec_b64 s[24:25], vcc
	s_cbranch_execz .LBB0_1514
	v_lshl_add_u64 v[18:19], v[80:81], 2, s[16:17]
	s_waitcnt lgkmcnt(0)
	v_add_f32_e32 v16, v16, v17
	global_atomic_add_f32 v[18:19], v16, off
.LBB0_1514:
	s_or_b64 exec, exec, s[24:25]
	s_waitcnt vmcnt(11)
	v_pk_fma_f32 v[14:15], v[14:15], 0.5, v[46:47] op_sel_hi:[1,0,1]
	v_pk_fma_f32 v[12:13], v[12:13], 0.5, v[44:45] op_sel_hi:[1,0,1]
	s_waitcnt lgkmcnt(0)
	v_mul_f32_e32 v17, v15, v15
	v_mul_f32_e32 v16, v13, v13
	v_fmac_f32_e32 v16, v12, v12
	v_fmac_f32_e32 v17, v14, v14
	v_add_f32_e32 v18, v16, v17
	v_lshlrev_b64 v[16:17], 11, v[64:65]
	v_lshl_add_u64 v[16:17], s[14:15], 0, v[16:17]
	global_store_dwordx4 v[66:67], v[12:15], off
	v_lshl_add_u64 v[16:17], v[156:157], 1, v[16:17]
	s_waitcnt vmcnt(11)
	v_pk_fma_f32 v[8:9], v[8:9], 0.5, v[40:41] op_sel_hi:[1,0,1]
	v_cvt_pk_bf16_f32 v12, v12, v13
	v_cvt_pk_bf16_f32 v13, v14, v15
	global_store_dwordx2 v[16:17], v[12:13], off
	v_pk_fma_f32 v[10:11], v[10:11], 0.5, v[42:43] op_sel_hi:[1,0,1]
	v_mul_f32_e32 v12, v9, v9
	v_fmac_f32_e32 v12, v8, v8
	v_mul_f32_e32 v13, v11, v11
	global_store_dwordx4 v[66:67], v[8:11], off offset:64
	s_waitcnt vmcnt(12)
	v_pk_fma_f32 v[6:7], v[6:7], 0.5, v[38:39] op_sel_hi:[1,0,1]
	v_pk_fma_f32 v[4:5], v[4:5], 0.5, v[36:37] op_sel_hi:[1,0,1]
	v_cvt_pk_bf16_f32 v8, v8, v9
	v_cvt_pk_bf16_f32 v9, v10, v11
	v_fmac_f32_e32 v13, v10, v10
	global_store_dwordx2 v[16:17], v[8:9], off offset:32
	v_mul_f32_e32 v8, v5, v5
	v_mul_f32_e32 v9, v7, v7
	v_add_f32_e32 v12, v12, v13
	v_fmac_f32_e32 v8, v4, v4
	v_fmac_f32_e32 v9, v6, v6
	v_add_f32_e32 v12, v18, v12
	v_add_f32_e32 v8, v8, v9
	v_add_f32_e32 v12, v12, v8
	s_waitcnt vmcnt(12)
	v_pk_fma_f32 v[10:11], v[2:3], 0.5, v[34:35] op_sel_hi:[1,0,1]
	v_pk_fma_f32 v[8:9], v[0:1], 0.5, v[32:33] op_sel_hi:[1,0,1]
	v_mul_f32_e32 v1, v11, v11
	v_mul_f32_e32 v0, v9, v9
	v_fmac_f32_e32 v0, v8, v8
	v_fmac_f32_e32 v1, v10, v10
	v_add_f32_e32 v0, v0, v1
	v_add_f32_e32 v2, v12, v0
	s_nop 1
	v_mov_b32_dpp v3, v2 quad_perm:[1,0,3,2] row_mask:0xf bank_mask:0xf
	v_cvt_pk_bf16_f32 v0, v4, v5
	v_cvt_pk_bf16_f32 v1, v6, v7
	global_store_dwordx4 v[66:67], v[4:7], off offset:512
	global_store_dwordx2 v[16:17], v[0:1], off offset:256
	s_waitcnt lgkmcnt(0)
	v_add_f32_e32 v0, v2, v3
	s_nop 1
	v_mov_b32_dpp v1, v0 quad_perm:[2,3,0,1] row_mask:0xf bank_mask:0xf
	v_cvt_pk_bf16_f32 v2, v8, v9
	v_cvt_pk_bf16_f32 v3, v10, v11
	global_store_dwordx4 v[66:67], v[8:11], off offset:576
	global_store_dwordx2 v[16:17], v[2:3], off offset:288
	s_mov_b32 vcc_lo, 0x11111111
	s_mov_b32 vcc_hi, 0x11111111
	s_and_saveexec_b64 s[24:25], vcc
	s_cbranch_execz .LBB0_1516
	v_lshl_add_u64 v[2:3], v[64:65], 2, s[16:17]
	s_waitcnt lgkmcnt(0)
	v_add_f32_e32 v0, v0, v1
	global_atomic_add_f32 v[2:3], v0, off

.LBB0_1810:
	ds_read_b128 v[128:131], v171
	ds_read_b128 v[132:135], v171 offset:1024
	ds_read_b128 v[136:139], v171 offset:2048
	ds_read_b128 v[140:143], v171 offset:3072
	ds_read_b128 v[156:159], v172
	ds_read_b128 v[160:163], v172 offset:1024
	ds_read_b128 v[164:167], v172 offset:2048
	ds_read_b128 v[176:179], v172 offset:3072
	s_add_u32 s30, s28, 0x100
	s_addc_u32 s31, s29, 0
	s_cmp_eq_u32 s57, 12
	s_cselect_b32 s37, s19, s31
	s_cselect_b32 s36, s25, s30
	s_cselect_b32 s35, s17, s56
	s_cselect_b32 s34, s54, s55
	v_lshl_add_u64 v[188:189], s[28:29], 0, v[150:151]
	s_add_i32 m0, s27, 0xc000
	ds_read_b128 v[180:183], v173
	ds_read_b128 v[184:187], v173 offset:1024
	ds_read_b128 v[192:195], v173 offset:2048
	ds_read_b128 v[196:199], v173 offset:3072
	ds_read_b128 v[200:203], v173 offset:4096
	ds_read_b128 v[204:207], v173 offset:5120
	ds_read_b128 v[208:211], v173 offset:6144
	ds_read_b128 v[212:215], v173 offset:7168
	global_load_lds_dwordx4 v[188:189], off
	v_lshl_add_u64 v[188:189], s[28:29], 0, v[148:149]
	s_add_i32 m0, s27, 0xe000
	s_nop 0
	global_load_lds_dwordx4 v[188:189], off
	s_waitcnt vmcnt(8)
	s_waitcnt lgkmcnt(0)
	s_barrier
	s_setprio 1
	s_waitcnt lgkmcnt(0)
	v_mfma_f32_16x16x32_bf16 v[124:127], v[128:131], v[180:183], v[124:127]
	v_mfma_f32_16x16x32_bf16 v[120:123], v[136:139], v[180:183], v[120:123]
	v_mfma_f32_16x16x32_bf16 v[108:111], v[128:131], v[192:195], v[108:111]
	v_mfma_f32_16x16x32_bf16 v[104:107], v[136:139], v[192:195], v[104:107]
	v_mfma_f32_16x16x32_bf16 v[92:95], v[128:131], v[200:203], v[92:95]
	v_mfma_f32_16x16x32_bf16 v[88:91], v[136:139], v[200:203], v[88:91]
	v_mfma_f32_16x16x32_bf16 v[76:79], v[128:131], v[208:211], v[76:79]
	v_mfma_f32_16x16x32_bf16 v[72:75], v[136:139], v[208:211], v[72:75]
	v_mfma_f32_16x16x32_bf16 v[124:127], v[132:135], v[184:187], v[124:127]
	v_mfma_f32_16x16x32_bf16 v[120:123], v[140:143], v[184:187], v[120:123]
	v_mfma_f32_16x16x32_bf16 v[108:111], v[132:135], v[196:199], v[108:111]
	v_mfma_f32_16x16x32_bf16 v[104:107], v[140:143], v[196:199], v[104:107]
	v_mfma_f32_16x16x32_bf16 v[92:95], v[132:135], v[204:207], v[92:95]
	v_mfma_f32_16x16x32_bf16 v[88:91], v[140:143], v[204:207], v[88:91]
	v_mfma_f32_16x16x32_bf16 v[76:79], v[132:135], v[212:215], v[76:79]
	v_mfma_f32_16x16x32_bf16 v[72:75], v[140:143], v[212:215], v[72:75]
	s_setprio 0
	s_setprio 1
	v_mfma_f32_16x16x32_bf16 v[116:119], v[156:159], v[180:183], v[116:119]
	v_mfma_f32_16x16x32_bf16 v[112:115], v[164:167], v[180:183], v[112:115]
	v_mfma_f32_16x16x32_bf16 v[100:103], v[156:159], v[192:195], v[100:103]
	v_mfma_f32_16x16x32_bf16 v[96:99], v[164:167], v[192:195], v[96:99]
	v_mfma_f32_16x16x32_bf16 v[84:87], v[156:159], v[200:203], v[84:87]
	v_mfma_f32_16x16x32_bf16 v[80:83], v[164:167], v[200:203], v[80:83]
	v_mfma_f32_16x16x32_bf16 v[68:71], v[156:159], v[208:211], v[68:71]
	v_mfma_f32_16x16x32_bf16 v[64:67], v[164:167], v[208:211], v[64:67]
	v_mfma_f32_16x16x32_bf16 v[116:119], v[160:163], v[184:187], v[116:119]
	v_mfma_f32_16x16x32_bf16 v[112:115], v[176:179], v[184:187], v[112:115]
	v_mfma_f32_16x16x32_bf16 v[100:103], v[160:163], v[196:199], v[100:103]
	v_mfma_f32_16x16x32_bf16 v[96:99], v[176:179], v[196:199], v[96:99]
	v_mfma_f32_16x16x32_bf16 v[84:87], v[160:163], v[204:207], v[84:87]
	v_mfma_f32_16x16x32_bf16 v[80:83], v[176:179], v[204:207], v[80:83]
	v_mfma_f32_16x16x32_bf16 v[68:71], v[160:163], v[212:215], v[68:71]
	v_mfma_f32_16x16x32_bf16 v[64:67], v[176:179], v[212:215], v[64:67]
	s_setprio 0
	s_barrier
	s_add_i32 s28, s52, s41
	v_lshl_add_u64 v[188:189], s[34:35], 0, v[144:145]
	s_mov_b32 m0, s28
	ds_read_b128 v[180:183], v173 offset:16384
	ds_read_b128 v[184:187], v173 offset:17408
	ds_read_b128 v[192:195], v173 offset:18432
	ds_read_b128 v[196:199], v173 offset:19456
	ds_read_b128 v[200:203], v173 offset:20480
	ds_read_b128 v[204:207], v173 offset:21504
	ds_read_b128 v[208:211], v173 offset:22528
	ds_read_b128 v[212:215], v173 offset:23552
	global_load_lds_dwordx4 v[188:189], off
	s_add_i32 m0, s28, 0x2000
	s_add_u32 s28, s34, 0x40000
	v_lshl_add_u64 v[216:217], s[34:35], 0, v[146:147]
	s_addc_u32 s29, s35, 0
	s_add_i32 s58, s53, s41
	global_load_lds_dwordx4 v[216:217], off
	v_lshl_add_u64 v[218:219], s[28:29], 0, v[144:145]
	s_mov_b32 m0, s58
	v_lshl_add_u64 v[220:221], s[36:37], 0, v[146:147]
	global_load_lds_dwordx4 v[218:219], off
	v_lshl_add_u64 v[218:219], s[28:29], 0, v[146:147]
	s_add_i32 m0, s58, 0x2000
	s_nop 0
	global_load_lds_dwordx4 v[218:219], off
	v_lshl_add_u64 v[218:219], s[36:37], 0, v[144:145]
	s_mov_b32 m0, s27
	s_nop 0
	global_load_lds_dwordx4 v[218:219], off
	s_mov_b32 m0, s42
	s_nop 0
	global_load_lds_dwordx4 v[220:221], off
	s_waitcnt vmcnt(8)
	s_waitcnt lgkmcnt(0)
	s_barrier
	s_setprio 1
	s_waitcnt lgkmcnt(0)
	v_mfma_f32_16x16x32_bf16 v[60:63], v[128:131], v[180:183], v[60:63]
	v_mfma_f32_16x16x32_bf16 v[56:59], v[136:139], v[180:183], v[56:59]
	v_mfma_f32_16x16x32_bf16 v[44:47], v[128:131], v[192:195], v[44:47]
	v_mfma_f32_16x16x32_bf16 v[40:43], v[136:139], v[192:195], v[40:43]
	v_mfma_f32_16x16x32_bf16 v[28:31], v[128:131], v[200:203], v[28:31]
	v_mfma_f32_16x16x32_bf16 v[24:27], v[136:139], v[200:203], v[24:27]
	v_mfma_f32_16x16x32_bf16 v[12:15], v[128:131], v[208:211], v[12:15]
	v_mfma_f32_16x16x32_bf16 v[8:11], v[136:139], v[208:211], v[8:11]
	v_mfma_f32_16x16x32_bf16 v[60:63], v[132:135], v[184:187], v[60:63]
	v_mfma_f32_16x16x32_bf16 v[56:59], v[140:143], v[184:187], v[56:59]
	v_mfma_f32_16x16x32_bf16 v[44:47], v[132:135], v[196:199], v[44:47]
	v_mfma_f32_16x16x32_bf16 v[40:43], v[140:143], v[196:199], v[40:43]
	v_mfma_f32_16x16x32_bf16 v[28:31], v[132:135], v[204:207], v[28:31]
	v_mfma_f32_16x16x32_bf16 v[24:27], v[140:143], v[204:207], v[24:27]
	v_mfma_f32_16x16x32_bf16 v[12:15], v[132:135], v[212:215], v[12:15]
	v_mfma_f32_16x16x32_bf16 v[8:11], v[140:143], v[212:215], v[8:11]
	s_setprio 0
	s_setprio 1
	v_mfma_f32_16x16x32_bf16 v[52:55], v[156:159], v[180:183], v[52:55]
	v_mfma_f32_16x16x32_bf16 v[48:51], v[164:167], v[180:183], v[48:51]
	v_mfma_f32_16x16x32_bf16 v[36:39], v[156:159], v[192:195], v[36:39]
	v_mfma_f32_16x16x32_bf16 v[32:35], v[164:167], v[192:195], v[32:35]
	v_mfma_f32_16x16x32_bf16 v[20:23], v[156:159], v[200:203], v[20:23]
	v_mfma_f32_16x16x32_bf16 v[16:19], v[164:167], v[200:203], v[16:19]
	v_mfma_f32_16x16x32_bf16 v[4:7], v[156:159], v[208:211], v[4:7]
	v_mfma_f32_16x16x32_bf16 v[0:3], v[164:167], v[208:211], v[0:3]
	v_mfma_f32_16x16x32_bf16 v[52:55], v[160:163], v[184:187], v[52:55]
	v_mfma_f32_16x16x32_bf16 v[48:51], v[176:179], v[184:187], v[48:51]
	v_mfma_f32_16x16x32_bf16 v[36:39], v[160:163], v[196:199], v[36:39]
	v_mfma_f32_16x16x32_bf16 v[32:35], v[176:179], v[196:199], v[32:35]
	v_mfma_f32_16x16x32_bf16 v[20:23], v[160:163], v[204:207], v[20:23]
	v_mfma_f32_16x16x32_bf16 v[16:19], v[176:179], v[204:207], v[16:19]
	v_mfma_f32_16x16x32_bf16 v[4:7], v[160:163], v[212:215], v[4:7]
	v_mfma_f32_16x16x32_bf16 v[0:3], v[176:179], v[212:215], v[0:3]
	s_setprio 0
	s_barrier
	s_add_i32 s58, 0, 0x18000
	s_add_i32 s59, 0, 0x1c000
	v_add_u32_e32 v140, s58, v169
	v_add_u32_e32 v175, s59, v169
	ds_read_b128 v[128:131], v140
	ds_read_b128 v[132:135], v140 offset:1024
	ds_read_b128 v[136:139], v140 offset:2048
	ds_read_b128 v[140:143], v140 offset:3072
	ds_read_b128 v[156:159], v175
	ds_read_b128 v[160:163], v175 offset:1024
	ds_read_b128 v[164:167], v175 offset:2048
	ds_read_b128 v[176:179], v175 offset:3072
	s_add_u32 s28, s36, 0x40000
	s_addc_u32 s29, s37, 0
	s_mov_b32 m0, s43
	v_lshl_add_u64 v[222:223], s[28:29], 0, v[144:145]
	ds_read_b128 v[180:183], v173 offset:32768
	ds_read_b128 v[184:187], v173 offset:33792
	ds_read_b128 v[192:195], v173 offset:34816
	ds_read_b128 v[196:199], v173 offset:35840
	ds_read_b128 v[200:203], v173 offset:36864
	ds_read_b128 v[204:207], v173 offset:37888
	ds_read_b128 v[208:211], v173 offset:38912
	ds_read_b128 v[212:215], v173 offset:39936
	global_load_lds_dwordx4 v[222:223], off
	v_lshl_add_u64 v[222:223], s[28:29], 0, v[146:147]
	s_mov_b32 m0, s44
	s_nop 0
	global_load_lds_dwordx4 v[222:223], off
	s_waitcnt vmcnt(8)
	s_waitcnt lgkmcnt(0)
	s_barrier
	s_setprio 1
	s_waitcnt lgkmcnt(0)
	v_mfma_f32_16x16x32_bf16 v[124:127], v[128:131], v[180:183], v[124:127]
	v_mfma_f32_16x16x32_bf16 v[120:123], v[136:139], v[180:183], v[120:123]
	v_mfma_f32_16x16x32_bf16 v[108:111], v[128:131], v[192:195], v[108:111]
	v_mfma_f32_16x16x32_bf16 v[104:107], v[136:139], v[192:195], v[104:107]
	v_mfma_f32_16x16x32_bf16 v[92:95], v[128:131], v[200:203], v[92:95]
	v_mfma_f32_16x16x32_bf16 v[88:91], v[136:139], v[200:203], v[88:91]
	v_mfma_f32_16x16x32_bf16 v[76:79], v[128:131], v[208:211], v[76:79]
	v_mfma_f32_16x16x32_bf16 v[72:75], v[136:139], v[208:211], v[72:75]
	v_mfma_f32_16x16x32_bf16 v[124:127], v[132:135], v[184:187], v[124:127]
	v_mfma_f32_16x16x32_bf16 v[120:123], v[140:143], v[184:187], v[120:123]
	v_mfma_f32_16x16x32_bf16 v[108:111], v[132:135], v[196:199], v[108:111]
	v_mfma_f32_16x16x32_bf16 v[104:107], v[140:143], v[196:199], v[104:107]
	v_mfma_f32_16x16x32_bf16 v[92:95], v[132:135], v[204:207], v[92:95]
	v_mfma_f32_16x16x32_bf16 v[88:91], v[140:143], v[204:207], v[88:91]
	v_mfma_f32_16x16x32_bf16 v[76:79], v[132:135], v[212:215], v[76:79]
	v_mfma_f32_16x16x32_bf16 v[72:75], v[140:143], v[212:215], v[72:75]
	s_setprio 0
	s_setprio 1
	v_mfma_f32_16x16x32_bf16 v[116:119], v[156:159], v[180:183], v[116:119]
	v_mfma_f32_16x16x32_bf16 v[112:115], v[164:167], v[180:183], v[112:115]
	v_mfma_f32_16x16x32_bf16 v[100:103], v[156:159], v[192:195], v[100:103]
	v_mfma_f32_16x16x32_bf16 v[96:99], v[164:167], v[192:195], v[96:99]
	v_mfma_f32_16x16x32_bf16 v[84:87], v[156:159], v[200:203], v[84:87]
	v_mfma_f32_16x16x32_bf16 v[80:83], v[164:167], v[200:203], v[80:83]
	v_mfma_f32_16x16x32_bf16 v[68:71], v[156:159], v[208:211], v[68:71]
	v_mfma_f32_16x16x32_bf16 v[64:67], v[164:167], v[208:211], v[64:67]
	v_mfma_f32_16x16x32_bf16 v[116:119], v[160:163], v[184:187], v[116:119]
	v_mfma_f32_16x16x32_bf16 v[112:115], v[176:179], v[184:187], v[112:115]
	v_mfma_f32_16x16x32_bf16 v[100:103], v[160:163], v[196:199], v[100:103]
	v_mfma_f32_16x16x32_bf16 v[96:99], v[176:179], v[196:199], v[96:99]
	v_mfma_f32_16x16x32_bf16 v[84:87], v[160:163], v[204:207], v[84:87]
	v_mfma_f32_16x16x32_bf16 v[80:83], v[176:179], v[204:207], v[80:83]
	v_mfma_f32_16x16x32_bf16 v[68:71], v[160:163], v[212:215], v[68:71]
	v_mfma_f32_16x16x32_bf16 v[64:67], v[176:179], v[212:215], v[64:67]
	s_setprio 0
	s_barrier
	s_add_i32 s28, s58, s41
	v_lshl_add_u64 v[188:189], v[188:189], 0, s[12:13]
	s_mov_b32 m0, s28
	ds_read_b128 v[180:183], v173 offset:49152
	ds_read_b128 v[184:187], v173 offset:50176
	ds_read_b128 v[192:195], v173 offset:51200
	ds_read_b128 v[196:199], v173 offset:52224
	ds_read_b128 v[200:203], v173 offset:53248
	ds_read_b128 v[204:207], v173 offset:54272
	ds_read_b128 v[208:211], v173 offset:55296
	ds_read_b128 v[212:215], v173 offset:56320
	global_load_lds_dwordx4 v[188:189], off
	s_add_i32 m0, s28, 0x2000
	s_add_u32 s28, s34, 0x40080
	v_lshl_add_u64 v[188:189], v[216:217], 0, s[12:13]
	s_addc_u32 s29, s35, 0
	s_add_i32 s34, s59, s41
	global_load_lds_dwordx4 v[188:189], off
	v_lshl_add_u64 v[188:189], s[28:29], 0, v[144:145]
	s_mov_b32 m0, s34
	s_nop 0
	global_load_lds_dwordx4 v[188:189], off
	v_lshl_add_u64 v[188:189], s[28:29], 0, v[146:147]
	s_add_i32 m0, s34, 0x2000
	s_nop 0
	global_load_lds_dwordx4 v[188:189], off
	v_lshl_add_u64 v[188:189], v[218:219], 0, s[12:13]
	s_mov_b32 m0, s46
	s_nop 0
	global_load_lds_dwordx4 v[188:189], off
	v_lshl_add_u64 v[188:189], v[220:221], 0, s[12:13]
	s_mov_b32 m0, s47
	s_nop 0
	global_load_lds_dwordx4 v[188:189], off
	s_waitcnt vmcnt(8)
	s_waitcnt lgkmcnt(0)
	s_barrier
	s_setprio 1
	s_waitcnt lgkmcnt(0)
	v_mfma_f32_16x16x32_bf16 v[60:63], v[128:131], v[180:183], v[60:63]
	v_mfma_f32_16x16x32_bf16 v[56:59], v[136:139], v[180:183], v[56:59]
	v_mfma_f32_16x16x32_bf16 v[44:47], v[128:131], v[192:195], v[44:47]
	v_mfma_f32_16x16x32_bf16 v[40:43], v[136:139], v[192:195], v[40:43]
	v_mfma_f32_16x16x32_bf16 v[28:31], v[128:131], v[200:203], v[28:31]
	v_mfma_f32_16x16x32_bf16 v[24:27], v[136:139], v[200:203], v[24:27]
	v_mfma_f32_16x16x32_bf16 v[12:15], v[128:131], v[208:211], v[12:15]
	v_mfma_f32_16x16x32_bf16 v[8:11], v[136:139], v[208:211], v[8:11]
	v_mfma_f32_16x16x32_bf16 v[60:63], v[132:135], v[184:187], v[60:63]
	v_mfma_f32_16x16x32_bf16 v[56:59], v[140:143], v[184:187], v[56:59]
	v_mfma_f32_16x16x32_bf16 v[44:47], v[132:135], v[196:199], v[44:47]
	v_mfma_f32_16x16x32_bf16 v[40:43], v[140:143], v[196:199], v[40:43]
	v_mfma_f32_16x16x32_bf16 v[28:31], v[132:135], v[204:207], v[28:31]
	v_mfma_f32_16x16x32_bf16 v[24:27], v[140:143], v[204:207], v[24:27]
	v_mfma_f32_16x16x32_bf16 v[12:15], v[132:135], v[212:215], v[12:15]
	v_mfma_f32_16x16x32_bf16 v[8:11], v[140:143], v[212:215], v[8:11]
	s_setprio 0
	s_setprio 1
	v_mfma_f32_16x16x32_bf16 v[52:55], v[156:159], v[180:183], v[52:55]
	v_mfma_f32_16x16x32_bf16 v[48:51], v[164:167], v[180:183], v[48:51]
	v_mfma_f32_16x16x32_bf16 v[36:39], v[156:159], v[192:195], v[36:39]
	v_mfma_f32_16x16x32_bf16 v[32:35], v[164:167], v[192:195], v[32:35]
	v_mfma_f32_16x16x32_bf16 v[20:23], v[156:159], v[200:203], v[20:23]
	v_mfma_f32_16x16x32_bf16 v[16:19], v[164:167], v[200:203], v[16:19]
	v_mfma_f32_16x16x32_bf16 v[4:7], v[156:159], v[208:211], v[4:7]
	v_mfma_f32_16x16x32_bf16 v[0:3], v[164:167], v[208:211], v[0:3]
	v_mfma_f32_16x16x32_bf16 v[52:55], v[160:163], v[184:187], v[52:55]
	v_mfma_f32_16x16x32_bf16 v[48:51], v[176:179], v[184:187], v[48:51]
	v_mfma_f32_16x16x32_bf16 v[36:39], v[160:163], v[196:199], v[36:39]
	v_mfma_f32_16x16x32_bf16 v[32:35], v[176:179], v[196:199], v[32:35]
	v_mfma_f32_16x16x32_bf16 v[20:23], v[160:163], v[204:207], v[20:23]
	v_mfma_f32_16x16x32_bf16 v[16:19], v[176:179], v[204:207], v[16:19]
	v_mfma_f32_16x16x32_bf16 v[4:7], v[160:163], v[212:215], v[4:7]
	v_mfma_f32_16x16x32_bf16 v[0:3], v[176:179], v[212:215], v[0:3]
	s_setprio 0
	s_barrier
	s_add_i32 s57, s57, 2
	s_add_u32 s55, s55, 0x100
	s_addc_u32 s56, s56, 0
	s_cmp_gt_u32 s57, 13
	s_mov_b64 s[28:29], s[30:31]
	s_cbranch_scc0 .LBB0_1810
	v_mbcnt_lo_u32_b32 v235, -1, 0
	v_mbcnt_hi_u32_b32 v235, -1, v235
	v_lshrrev_b32_e32 v236, 2, v235
	v_and_b32_e32 v237, 3, v235
	v_lshl_add_u32 v232, v237, 4, v236
	v_lshlrev_b32_e32 v232, 2, v232
	v_and_b32_e32 v233, -16, v168
	v_or_b32_e32 v233, v233, v236
	v_lshlrev_b32_e32 v237, 2, v237
	v_and_b32_e32 v234, -13, v170
	v_or_b32_e32 v234, v234, v237
	v_lshl_add_u32 v158, s24, 8, v233
	v_lshl_or_b32 v156, s26, 8, v234
	v_ashrrev_i32_e32 v159, 31, v158
	v_lshlrev_b64 v[128:129], 12, v[158:159]
	v_ashrrev_i32_e32 v157, 31, v156
	v_lshl_add_u64 v[128:129], s[0:1], 0, v[128:129]
	v_lshlrev_b64 v[130:131], 2, v[156:157]
	v_lshl_add_u64 v[188:189], v[128:129], 0, v[130:131]
	global_load_dwordx4 v[164:167], v[188:189], off
	global_load_dwordx4 v[176:179], v[188:189], off offset:64
	global_load_dwordx4 v[180:183], v[188:189], off offset:512
	global_load_dwordx4 v[184:187], v[188:189], off offset:576
	v_or_b32_e32 v160, 16, v158
	v_ashrrev_i32_e32 v161, 31, v160
	v_lshlrev_b64 v[128:129], 12, v[160:161]
	v_lshl_add_u64 v[128:129], s[0:1], 0, v[128:129]
	v_lshl_add_u64 v[162:163], v[128:129], 0, v[130:131]
	global_load_dwordx4 v[140:143], v[162:163], off
	global_load_dwordx4 v[136:139], v[162:163], off offset:64
	global_load_dwordx4 v[132:135], v[162:163], off offset:512
	global_load_dwordx4 v[128:131], v[162:163], off offset:576
	v_lshlrev_b64 v[192:193], 11, v[158:159]
	v_lshl_add_u64 v[192:193], s[8:9], 0, v[192:193]
	v_and_b32_e32 v191, 64, v174
	v_lshl_add_u64 v[192:193], v[156:157], 1, v[192:193]
	v_xor_b32_e32 v175, 1, v174
	v_add_u32_e32 v191, 64, v191
	v_cmp_lt_i32_e32 vcc, v175, v191
	v_xor_b32_e32 v194, 2, v174
	ds_bpermute_b32 v127, v232, v127
	ds_bpermute_b32 v126, v232, v126
	ds_bpermute_b32 v125, v232, v125
	ds_bpermute_b32 v124, v232, v124
	ds_bpermute_b32 v123, v232, v123
	ds_bpermute_b32 v122, v232, v122
	ds_bpermute_b32 v121, v232, v121
	ds_bpermute_b32 v120, v232, v120
	ds_bpermute_b32 v119, v232, v119
	ds_bpermute_b32 v118, v232, v118
	ds_bpermute_b32 v117, v232, v117
	ds_bpermute_b32 v116, v232, v116
	ds_bpermute_b32 v115, v232, v115
	ds_bpermute_b32 v114, v232, v114
	ds_bpermute_b32 v113, v232, v113
	ds_bpermute_b32 v112, v232, v112
	ds_bpermute_b32 v111, v232, v111
	ds_bpermute_b32 v110, v232, v110
	ds_bpermute_b32 v109, v232, v109
	ds_bpermute_b32 v108, v232, v108
	ds_bpermute_b32 v107, v232, v107
	ds_bpermute_b32 v106, v232, v106
	ds_bpermute_b32 v105, v232, v105
	ds_bpermute_b32 v104, v232, v104
	ds_bpermute_b32 v103, v232, v103
	ds_bpermute_b32 v102, v232, v102
	ds_bpermute_b32 v101, v232, v101
	ds_bpermute_b32 v100, v232, v100
	ds_bpermute_b32 v99, v232, v99
	ds_bpermute_b32 v98, v232, v98
	ds_bpermute_b32 v97, v232, v97
	ds_bpermute_b32 v96, v232, v96
	ds_bpermute_b32 v95, v232, v95
	ds_bpermute_b32 v94, v232, v94
	ds_bpermute_b32 v93, v232, v93
	ds_bpermute_b32 v92, v232, v92
	ds_bpermute_b32 v91, v232, v91
	ds_bpermute_b32 v90, v232, v90
	ds_bpermute_b32 v89, v232, v89
	ds_bpermute_b32 v88, v232, v88
	ds_bpermute_b32 v87, v232, v87
	ds_bpermute_b32 v86, v232, v86
	ds_bpermute_b32 v85, v232, v85
	ds_bpermute_b32 v84, v232, v84
	ds_bpermute_b32 v83, v232, v83
	ds_bpermute_b32 v82, v232, v82
	ds_bpermute_b32 v81, v232, v81
	ds_bpermute_b32 v80, v232, v80
	ds_bpermute_b32 v79, v232, v79
	ds_bpermute_b32 v78, v232, v78
	ds_bpermute_b32 v77, v232, v77
	ds_bpermute_b32 v76, v232, v76
	ds_bpermute_b32 v75, v232, v75
	ds_bpermute_b32 v74, v232, v74
	ds_bpermute_b32 v73, v232, v73
	ds_bpermute_b32 v72, v232, v72
	ds_bpermute_b32 v71, v232, v71
	ds_bpermute_b32 v70, v232, v70
	ds_bpermute_b32 v69, v232, v69
	ds_bpermute_b32 v68, v232, v68
	ds_bpermute_b32 v67, v232, v67
	ds_bpermute_b32 v66, v232, v66
	ds_bpermute_b32 v65, v232, v65
	ds_bpermute_b32 v64, v232, v64
	ds_bpermute_b32 v63, v232, v63
	ds_bpermute_b32 v62, v232, v62
	ds_bpermute_b32 v61, v232, v61
	ds_bpermute_b32 v60, v232, v60
	ds_bpermute_b32 v59, v232, v59
	ds_bpermute_b32 v58, v232, v58
	ds_bpermute_b32 v57, v232, v57
	ds_bpermute_b32 v56, v232, v56
	ds_bpermute_b32 v55, v232, v55
	ds_bpermute_b32 v54, v232, v54
	ds_bpermute_b32 v53, v232, v53
	ds_bpermute_b32 v52, v232, v52
	ds_bpermute_b32 v51, v232, v51
	ds_bpermute_b32 v50, v232, v50
	ds_bpermute_b32 v49, v232, v49
	ds_bpermute_b32 v48, v232, v48
	ds_bpermute_b32 v47, v232, v47
	ds_bpermute_b32 v46, v232, v46
	ds_bpermute_b32 v45, v232, v45
	ds_bpermute_b32 v44, v232, v44
	ds_bpermute_b32 v43, v232, v43
	ds_bpermute_b32 v42, v232, v42
	ds_bpermute_b32 v41, v232, v41
	ds_bpermute_b32 v40, v232, v40
	ds_bpermute_b32 v39, v232, v39
	ds_bpermute_b32 v38, v232, v38
	ds_bpermute_b32 v37, v232, v37
	ds_bpermute_b32 v36, v232, v36
	ds_bpermute_b32 v35, v232, v35
	ds_bpermute_b32 v34, v232, v34
	ds_bpermute_b32 v33, v232, v33
	ds_bpermute_b32 v32, v232, v32
	ds_bpermute_b32 v31, v232, v31
	ds_bpermute_b32 v30, v232, v30
	ds_bpermute_b32 v29, v232, v29
	ds_bpermute_b32 v28, v232, v28
	ds_bpermute_b32 v27, v232, v27
	ds_bpermute_b32 v26, v232, v26
	ds_bpermute_b32 v25, v232, v25
	ds_bpermute_b32 v24, v232, v24
	ds_bpermute_b32 v23, v232, v23
	ds_bpermute_b32 v22, v232, v22
	ds_bpermute_b32 v21, v232, v21
	ds_bpermute_b32 v20, v232, v20
	ds_bpermute_b32 v19, v232, v19
	ds_bpermute_b32 v18, v232, v18
	ds_bpermute_b32 v17, v232, v17
	ds_bpermute_b32 v16, v232, v16
	ds_bpermute_b32 v15, v232, v15
	ds_bpermute_b32 v14, v232, v14
	ds_bpermute_b32 v13, v232, v13
	ds_bpermute_b32 v12, v232, v12
	ds_bpermute_b32 v11, v232, v11
	ds_bpermute_b32 v10, v232, v10
	ds_bpermute_b32 v9, v232, v9
	ds_bpermute_b32 v8, v232, v8
	ds_bpermute_b32 v7, v232, v7
	ds_bpermute_b32 v6, v232, v6
	ds_bpermute_b32 v5, v232, v5
	ds_bpermute_b32 v4, v232, v4
	ds_bpermute_b32 v3, v232, v3
	ds_bpermute_b32 v2, v232, v2
	ds_bpermute_b32 v1, v232, v1
	ds_bpermute_b32 v0, v232, v0
	s_waitcnt lgkmcnt(0)
	s_waitcnt lgkmcnt(0)
	s_cmp_eq_u64 s[14:15], 0
	s_cbranch_scc1 .LBB0_1813
	s_barrier
.LBB0_1813:
	s_waitcnt vmcnt(7)
	v_pk_add_f32 v[126:127], v[126:127], v[166:167]
	v_pk_add_f32 v[124:125], v[124:125], v[164:165]
	s_waitcnt vmcnt(6)
	v_pk_add_f32 v[122:123], v[122:123], v[178:179]
	v_pk_add_f32 v[120:121], v[120:121], v[176:177]
	s_waitcnt vmcnt(5)
	v_pk_add_f32 v[118:119], v[118:119], v[182:183]
	v_pk_add_f32 v[116:117], v[116:117], v[180:181]
	s_waitcnt vmcnt(4)
	v_pk_add_f32 v[164:165], v[112:113], v[184:185]
	v_mul_f32_e32 v178, v125, v125
	v_mul_f32_e32 v179, v127, v127
	global_store_dwordx4 v[188:189], v[124:127], off
	v_cvt_pk_bf16_f32 v112, v124, v125
	v_cvt_pk_bf16_f32 v113, v126, v127
	v_mul_f32_e32 v125, v121, v121
	v_mul_f32_e32 v127, v123, v123
	v_pk_add_f32 v[166:167], v[114:115], v[186:187]
	v_mul_f32_e32 v180, v117, v117
	v_mul_f32_e32 v181, v119, v119
	v_fmac_f32_e32 v178, v124, v124
	v_fmac_f32_e32 v179, v126, v126
	v_fmac_f32_e32 v125, v120, v120
	v_fmac_f32_e32 v127, v122, v122
	v_mul_f32_e32 v182, v165, v165
	v_mul_f32_e32 v183, v167, v167
	global_store_dwordx2 v[192:193], v[112:113], off
	v_fmac_f32_e32 v180, v116, v116
	v_fmac_f32_e32 v181, v118, v118
	v_add_f32_e32 v112, v178, v179
	v_add_f32_e32 v113, v125, v127
	v_fmac_f32_e32 v182, v164, v164
	v_fmac_f32_e32 v183, v166, v166
	v_add_f32_e32 v124, v180, v181
	v_add_f32_e32 v112, v112, v113
	v_cndmask_b32_e32 v175, v174, v175, vcc
	v_add_f32_e32 v125, v182, v183
	v_add_f32_e32 v112, v112, v124
	v_lshlrev_b32_e32 v175, 2, v175
	v_add_f32_e32 v112, v112, v125
	s_nop 1
	v_mov_b32_dpp v113, v112 quad_perm:[1,0,3,2] row_mask:0xf bank_mask:0xf
	v_cmp_lt_i32_e32 vcc, v194, v191
	v_cvt_pk_bf16_f32 v176, v116, v117
	v_cvt_pk_bf16_f32 v114, v120, v121
	v_cndmask_b32_e32 v191, v174, v194, vcc
	v_cvt_pk_bf16_f32 v115, v122, v123
	v_cvt_pk_bf16_f32 v177, v118, v119
	global_store_dwordx4 v[188:189], v[120:123], off offset:64
	global_store_dwordx2 v[192:193], v[114:115], off offset:32
	global_store_dwordx4 v[188:189], v[116:119], off offset:512
	global_store_dwordx2 v[192:193], v[176:177], off offset:256
	s_waitcnt lgkmcnt(0)
	v_add_f32_e32 v112, v112, v113
	v_lshlrev_b32_e32 v176, 2, v191
	s_nop 1
	v_mov_b32_dpp v113, v112 quad_perm:[2,3,0,1] row_mask:0xf bank_mask:0xf
	v_cvt_pk_bf16_f32 v114, v164, v165
	v_cvt_pk_bf16_f32 v115, v166, v167
	global_store_dwordx4 v[188:189], v[164:167], off offset:576
	global_store_dwordx2 v[192:193], v[114:115], off offset:288
	s_mov_b32 vcc_lo, 0x11111111
	s_mov_b32 vcc_hi, 0x11111111
	s_and_saveexec_b64 s[24:25], vcc
	s_cbranch_execz .LBB0_1815
	v_lshl_add_u64 v[114:115], v[158:159], 2, s[10:11]
	s_waitcnt lgkmcnt(0)
	v_add_f32_e32 v112, v112, v113
	global_atomic_add_f32 v[114:115], v112, off
.LBB0_1815:
	s_or_b64 exec, exec, s[24:25]
	v_or_b32_e32 v164, 32, v158
	v_ashrrev_i32_e32 v165, 31, v164
	s_waitcnt lgkmcnt(0)
	v_lshlrev_b64 v[112:113], 12, v[164:165]
	v_lshl_add_u64 v[112:113], s[0:1], 0, v[112:113]
	v_lshl_add_u64 v[166:167], v[156:157], 2, v[112:113]
	global_load_dwordx4 v[124:127], v[166:167], off
	global_load_dwordx4 v[120:123], v[166:167], off offset:64
	global_load_dwordx4 v[116:119], v[166:167], off offset:512
	global_load_dwordx4 v[112:115], v[166:167], off offset:576
	s_waitcnt vmcnt(15)
	v_pk_add_f32 v[110:111], v[110:111], v[142:143]
	v_pk_add_f32 v[108:109], v[108:109], v[140:141]
	v_mul_f32_e32 v141, v111, v111
	v_mul_f32_e32 v140, v109, v109
	v_fmac_f32_e32 v140, v108, v108
	v_fmac_f32_e32 v141, v110, v110
	v_add_f32_e32 v142, v140, v141
	v_lshlrev_b64 v[140:141], 11, v[160:161]
	v_lshl_add_u64 v[140:141], s[8:9], 0, v[140:141]
	global_store_dwordx4 v[162:163], v[108:111], off
	v_lshl_add_u64 v[140:141], v[156:157], 1, v[140:141]
	s_waitcnt vmcnt(15)
	v_pk_add_f32 v[104:105], v[104:105], v[136:137]
	v_cvt_pk_bf16_f32 v108, v108, v109
	v_cvt_pk_bf16_f32 v109, v110, v111
	global_store_dwordx2 v[140:141], v[108:109], off
	v_pk_add_f32 v[106:107], v[106:107], v[138:139]
	v_mul_f32_e32 v108, v105, v105
	v_fmac_f32_e32 v108, v104, v104
	v_mul_f32_e32 v109, v107, v107
	global_store_dwordx4 v[162:163], v[104:107], off offset:64
	s_waitcnt vmcnt(16)
	v_pk_add_f32 v[102:103], v[102:103], v[134:135]
	v_pk_add_f32 v[100:101], v[100:101], v[132:133]
	v_cvt_pk_bf16_f32 v104, v104, v105
	v_cvt_pk_bf16_f32 v105, v106, v107
	v_fmac_f32_e32 v109, v106, v106
	global_store_dwordx2 v[140:141], v[104:105], off offset:32
	v_mul_f32_e32 v104, v101, v101
	v_mul_f32_e32 v105, v103, v103
	v_add_f32_e32 v108, v108, v109
	v_fmac_f32_e32 v104, v100, v100
	v_fmac_f32_e32 v105, v102, v102
	v_add_f32_e32 v108, v142, v108
	v_add_f32_e32 v104, v104, v105
	v_add_f32_e32 v108, v108, v104
	s_waitcnt vmcnt(16)
	v_pk_add_f32 v[106:107], v[98:99], v[130:131]
	v_pk_add_f32 v[104:105], v[96:97], v[128:129]
	v_mul_f32_e32 v97, v107, v107
	v_mul_f32_e32 v96, v105, v105
	v_fmac_f32_e32 v96, v104, v104
	v_fmac_f32_e32 v97, v106, v106
	v_add_f32_e32 v96, v96, v97
	v_add_f32_e32 v98, v108, v96
	s_nop 1
	v_mov_b32_dpp v99, v98 quad_perm:[1,0,3,2] row_mask:0xf bank_mask:0xf
	v_cvt_pk_bf16_f32 v96, v100, v101
	v_cvt_pk_bf16_f32 v97, v102, v103
	global_store_dwordx4 v[162:163], v[100:103], off offset:512
	global_store_dwordx2 v[140:141], v[96:97], off offset:256
	s_waitcnt lgkmcnt(0)
	v_add_f32_e32 v96, v98, v99
	s_nop 1
	v_mov_b32_dpp v97, v96 quad_perm:[2,3,0,1] row_mask:0xf bank_mask:0xf
	v_cvt_pk_bf16_f32 v98, v104, v105
	v_cvt_pk_bf16_f32 v99, v106, v107
	global_store_dwordx4 v[162:163], v[104:107], off offset:576
	global_store_dwordx2 v[140:141], v[98:99], off offset:288
	s_mov_b32 vcc_lo, 0x11111111
	s_mov_b32 vcc_hi, 0x11111111
	s_and_saveexec_b64 s[24:25], vcc
	s_cbranch_execz .LBB0_1817
	v_lshl_add_u64 v[98:99], v[160:161], 2, s[10:11]
	s_waitcnt lgkmcnt(0)
	v_add_f32_e32 v96, v96, v97
	global_atomic_add_f32 v[98:99], v96, off
.LBB0_1817:
	s_or_b64 exec, exec, s[24:25]
	v_or_b32_e32 v128, 48, v158
	v_ashrrev_i32_e32 v129, 31, v128
	s_waitcnt lgkmcnt(0)
	v_lshlrev_b64 v[96:97], 12, v[128:129]
	v_lshl_add_u64 v[96:97], s[0:1], 0, v[96:97]
	v_lshl_add_u64 v[130:131], v[156:157], 2, v[96:97]
	global_load_dwordx4 v[108:111], v[130:131], off
	global_load_dwordx4 v[104:107], v[130:131], off offset:64
	global_load_dwordx4 v[100:103], v[130:131], off offset:512
	global_load_dwordx4 v[96:99], v[130:131], off offset:576
	s_waitcnt vmcnt(15)
	v_pk_add_f32 v[94:95], v[94:95], v[126:127]
	v_pk_add_f32 v[92:93], v[92:93], v[124:125]
	v_mul_f32_e32 v125, v95, v95
	v_mul_f32_e32 v124, v93, v93
	v_fmac_f32_e32 v124, v92, v92
	v_fmac_f32_e32 v125, v94, v94
	v_add_f32_e32 v126, v124, v125
	v_lshlrev_b64 v[124:125], 11, v[164:165]
	v_lshl_add_u64 v[124:125], s[8:9], 0, v[124:125]
	global_store_dwordx4 v[166:167], v[92:95], off
	v_lshl_add_u64 v[124:125], v[156:157], 1, v[124:125]
	s_waitcnt vmcnt(15)
	v_pk_add_f32 v[88:89], v[88:89], v[120:121]
	v_cvt_pk_bf16_f32 v92, v92, v93
	v_cvt_pk_bf16_f32 v93, v94, v95
	global_store_dwordx2 v[124:125], v[92:93], off
	v_pk_add_f32 v[90:91], v[90:91], v[122:123]
	v_mul_f32_e32 v92, v89, v89
	v_fmac_f32_e32 v92, v88, v88
	v_mul_f32_e32 v93, v91, v91
	global_store_dwordx4 v[166:167], v[88:91], off offset:64
	s_waitcnt vmcnt(16)
	v_pk_add_f32 v[86:87], v[86:87], v[118:119]
	v_pk_add_f32 v[84:85], v[84:85], v[116:117]
	v_cvt_pk_bf16_f32 v88, v88, v89
	v_cvt_pk_bf16_f32 v89, v90, v91
	v_fmac_f32_e32 v93, v90, v90
	global_store_dwordx2 v[124:125], v[88:89], off offset:32
	v_mul_f32_e32 v88, v85, v85
	v_mul_f32_e32 v89, v87, v87
	v_add_f32_e32 v92, v92, v93
	v_fmac_f32_e32 v88, v84, v84
	v_fmac_f32_e32 v89, v86, v86
	v_add_f32_e32 v92, v126, v92
	v_add_f32_e32 v88, v88, v89
	v_add_f32_e32 v92, v92, v88
	s_waitcnt vmcnt(16)
	v_pk_add_f32 v[90:91], v[82:83], v[114:115]
	v_pk_add_f32 v[88:89], v[80:81], v[112:113]
	v_mul_f32_e32 v81, v91, v91
	v_mul_f32_e32 v80, v89, v89
	v_fmac_f32_e32 v80, v88, v88
	v_fmac_f32_e32 v81, v90, v90
	v_add_f32_e32 v80, v80, v81
	v_add_f32_e32 v82, v92, v80
	s_nop 1
	v_mov_b32_dpp v83, v82 quad_perm:[1,0,3,2] row_mask:0xf bank_mask:0xf
	v_cvt_pk_bf16_f32 v80, v84, v85
	v_cvt_pk_bf16_f32 v81, v86, v87
	global_store_dwordx4 v[166:167], v[84:87], off offset:512
	global_store_dwordx2 v[124:125], v[80:81], off offset:256
	s_waitcnt lgkmcnt(0)
	v_add_f32_e32 v80, v82, v83
	s_nop 1
	v_mov_b32_dpp v81, v80 quad_perm:[2,3,0,1] row_mask:0xf bank_mask:0xf
	v_cvt_pk_bf16_f32 v82, v88, v89
	v_cvt_pk_bf16_f32 v83, v90, v91
	global_store_dwordx4 v[166:167], v[88:91], off offset:576
	global_store_dwordx2 v[124:125], v[82:83], off offset:288
	s_mov_b32 vcc_lo, 0x11111111
	s_mov_b32 vcc_hi, 0x11111111
	s_and_saveexec_b64 s[24:25], vcc
	s_cbranch_execz .LBB0_1819
	v_lshl_add_u64 v[82:83], v[164:165], 2, s[10:11]
	s_waitcnt lgkmcnt(0)
	v_add_f32_e32 v80, v80, v81
	global_atomic_add_f32 v[82:83], v80, off
.LBB0_1819:
	s_or_b64 exec, exec, s[24:25]
	v_add_u32_e32 v112, 0x80, v158
	v_ashrrev_i32_e32 v113, 31, v112
	s_waitcnt lgkmcnt(0)
	v_lshlrev_b64 v[80:81], 12, v[112:113]
	v_lshl_add_u64 v[80:81], s[0:1], 0, v[80:81]
	v_lshl_add_u64 v[114:115], v[156:157], 2, v[80:81]
	global_load_dwordx4 v[92:95], v[114:115], off
	global_load_dwordx4 v[88:91], v[114:115], off offset:64
	global_load_dwordx4 v[84:87], v[114:115], off offset:512
	global_load_dwordx4 v[80:83], v[114:115], off offset:576
	s_waitcnt vmcnt(15)
	v_pk_add_f32 v[78:79], v[78:79], v[110:111]
	v_pk_add_f32 v[76:77], v[76:77], v[108:109]
	v_mul_f32_e32 v109, v79, v79
	v_mul_f32_e32 v108, v77, v77
	v_fmac_f32_e32 v108, v76, v76
	v_fmac_f32_e32 v109, v78, v78
	v_add_f32_e32 v110, v108, v109
	v_lshlrev_b64 v[108:109], 11, v[128:129]
	v_lshl_add_u64 v[108:109], s[8:9], 0, v[108:109]
	global_store_dwordx4 v[130:131], v[76:79], off
	v_lshl_add_u64 v[108:109], v[156:157], 1, v[108:109]
	s_waitcnt vmcnt(15)
	v_pk_add_f32 v[72:73], v[72:73], v[104:105]
	v_cvt_pk_bf16_f32 v76, v76, v77
	v_cvt_pk_bf16_f32 v77, v78, v79
	global_store_dwordx2 v[108:109], v[76:77], off
	v_pk_add_f32 v[74:75], v[74:75], v[106:107]
	v_mul_f32_e32 v76, v73, v73
	v_fmac_f32_e32 v76, v72, v72
	v_mul_f32_e32 v77, v75, v75
	global_store_dwordx4 v[130:131], v[72:75], off offset:64
	s_waitcnt vmcnt(16)
	v_pk_add_f32 v[70:71], v[70:71], v[102:103]
	v_pk_add_f32 v[68:69], v[68:69], v[100:101]
	v_cvt_pk_bf16_f32 v72, v72, v73
	v_cvt_pk_bf16_f32 v73, v74, v75
	v_fmac_f32_e32 v77, v74, v74
	global_store_dwordx2 v[108:109], v[72:73], off offset:32
	v_mul_f32_e32 v72, v69, v69
	v_mul_f32_e32 v73, v71, v71
	v_add_f32_e32 v76, v76, v77
	v_fmac_f32_e32 v72, v68, v68
	v_fmac_f32_e32 v73, v70, v70
	v_add_f32_e32 v76, v110, v76
	v_add_f32_e32 v72, v72, v73
	v_add_f32_e32 v76, v76, v72
	s_waitcnt vmcnt(16)
	v_pk_add_f32 v[74:75], v[66:67], v[98:99]
	v_pk_add_f32 v[72:73], v[64:65], v[96:97]
	v_mul_f32_e32 v65, v75, v75
	v_mul_f32_e32 v64, v73, v73
	v_fmac_f32_e32 v64, v72, v72
	v_fmac_f32_e32 v65, v74, v74
	v_add_f32_e32 v64, v64, v65
	v_add_f32_e32 v66, v76, v64
	s_nop 1
	v_mov_b32_dpp v67, v66 quad_perm:[1,0,3,2] row_mask:0xf bank_mask:0xf
	v_cvt_pk_bf16_f32 v64, v68, v69
	v_cvt_pk_bf16_f32 v65, v70, v71
	global_store_dwordx4 v[130:131], v[68:71], off offset:512
	global_store_dwordx2 v[108:109], v[64:65], off offset:256
	s_waitcnt lgkmcnt(0)
	v_add_f32_e32 v64, v66, v67
	s_nop 1
	v_mov_b32_dpp v65, v64 quad_perm:[2,3,0,1] row_mask:0xf bank_mask:0xf
	v_cvt_pk_bf16_f32 v66, v72, v73
	v_cvt_pk_bf16_f32 v67, v74, v75
	global_store_dwordx4 v[130:131], v[72:75], off offset:576
	global_store_dwordx2 v[108:109], v[66:67], off offset:288
	s_mov_b32 vcc_lo, 0x11111111
	s_mov_b32 vcc_hi, 0x11111111
	s_and_saveexec_b64 s[24:25], vcc
	s_cbranch_execz .LBB0_1821
	v_lshl_add_u64 v[66:67], v[128:129], 2, s[10:11]
	s_waitcnt lgkmcnt(0)
	v_add_f32_e32 v64, v64, v65
	global_atomic_add_f32 v[66:67], v64, off
.LBB0_1821:
	s_or_b64 exec, exec, s[24:25]
	v_or_b32_e32 v96, 16, v112
	v_ashrrev_i32_e32 v97, 31, v96
	s_waitcnt lgkmcnt(0)
	v_lshlrev_b64 v[64:65], 12, v[96:97]
	v_lshl_add_u64 v[64:65], s[0:1], 0, v[64:65]
	v_lshl_add_u64 v[98:99], v[156:157], 2, v[64:65]
	global_load_dwordx4 v[76:79], v[98:99], off
	global_load_dwordx4 v[72:75], v[98:99], off offset:64
	global_load_dwordx4 v[68:71], v[98:99], off offset:512
	global_load_dwordx4 v[64:67], v[98:99], off offset:576
	s_waitcnt vmcnt(15)
	v_pk_add_f32 v[62:63], v[62:63], v[94:95]
	v_pk_add_f32 v[60:61], v[60:61], v[92:93]
	v_mul_f32_e32 v93, v63, v63
	v_mul_f32_e32 v92, v61, v61
	v_fmac_f32_e32 v92, v60, v60
	v_fmac_f32_e32 v93, v62, v62
	v_add_f32_e32 v94, v92, v93
	v_lshlrev_b64 v[92:93], 11, v[112:113]
	v_lshl_add_u64 v[92:93], s[8:9], 0, v[92:93]
	global_store_dwordx4 v[114:115], v[60:63], off
	v_lshl_add_u64 v[92:93], v[156:157], 1, v[92:93]
	s_waitcnt vmcnt(15)
	v_pk_add_f32 v[56:57], v[56:57], v[88:89]
	v_cvt_pk_bf16_f32 v60, v60, v61
	v_cvt_pk_bf16_f32 v61, v62, v63
	global_store_dwordx2 v[92:93], v[60:61], off
	v_pk_add_f32 v[58:59], v[58:59], v[90:91]
	v_mul_f32_e32 v60, v57, v57
	v_fmac_f32_e32 v60, v56, v56
	v_mul_f32_e32 v61, v59, v59
	global_store_dwordx4 v[114:115], v[56:59], off offset:64
	s_waitcnt vmcnt(16)
	v_pk_add_f32 v[54:55], v[54:55], v[86:87]
	v_pk_add_f32 v[52:53], v[52:53], v[84:85]
	v_cvt_pk_bf16_f32 v56, v56, v57
	v_cvt_pk_bf16_f32 v57, v58, v59
	v_fmac_f32_e32 v61, v58, v58
	global_store_dwordx2 v[92:93], v[56:57], off offset:32
	v_mul_f32_e32 v56, v53, v53
	v_mul_f32_e32 v57, v55, v55
	v_add_f32_e32 v60, v60, v61
	v_fmac_f32_e32 v56, v52, v52
	v_fmac_f32_e32 v57, v54, v54
	v_add_f32_e32 v60, v94, v60
	v_add_f32_e32 v56, v56, v57
	v_add_f32_e32 v60, v60, v56
	s_waitcnt vmcnt(16)
	v_pk_add_f32 v[58:59], v[50:51], v[82:83]
	v_pk_add_f32 v[56:57], v[48:49], v[80:81]
	v_mul_f32_e32 v49, v59, v59
	v_mul_f32_e32 v48, v57, v57
	v_fmac_f32_e32 v48, v56, v56
	v_fmac_f32_e32 v49, v58, v58
	v_add_f32_e32 v48, v48, v49
	v_add_f32_e32 v50, v60, v48
	s_nop 1
	v_mov_b32_dpp v51, v50 quad_perm:[1,0,3,2] row_mask:0xf bank_mask:0xf
	v_cvt_pk_bf16_f32 v48, v52, v53
	v_cvt_pk_bf16_f32 v49, v54, v55
	global_store_dwordx4 v[114:115], v[52:55], off offset:512
	global_store_dwordx2 v[92:93], v[48:49], off offset:256
	s_waitcnt lgkmcnt(0)
	v_add_f32_e32 v48, v50, v51
	s_nop 1
	v_mov_b32_dpp v49, v48 quad_perm:[2,3,0,1] row_mask:0xf bank_mask:0xf
	v_cvt_pk_bf16_f32 v50, v56, v57
	v_cvt_pk_bf16_f32 v51, v58, v59
	global_store_dwordx4 v[114:115], v[56:59], off offset:576
	global_store_dwordx2 v[92:93], v[50:51], off offset:288
	s_mov_b32 vcc_lo, 0x11111111
	s_mov_b32 vcc_hi, 0x11111111
	s_and_saveexec_b64 s[24:25], vcc
	s_cbranch_execz .LBB0_1823
	v_lshl_add_u64 v[50:51], v[112:113], 2, s[10:11]
	s_waitcnt lgkmcnt(0)
	v_add_f32_e32 v48, v48, v49
	global_atomic_add_f32 v[50:51], v48, off
.LBB0_1823:
	s_or_b64 exec, exec, s[24:25]
	v_or_b32_e32 v80, 32, v112
	v_ashrrev_i32_e32 v81, 31, v80
	s_waitcnt lgkmcnt(0)
	v_lshlrev_b64 v[48:49], 12, v[80:81]
	v_lshl_add_u64 v[48:49], s[0:1], 0, v[48:49]
	v_lshl_add_u64 v[82:83], v[156:157], 2, v[48:49]
	global_load_dwordx4 v[60:63], v[82:83], off
	global_load_dwordx4 v[56:59], v[82:83], off offset:64
	global_load_dwordx4 v[52:55], v[82:83], off offset:512
	global_load_dwordx4 v[48:51], v[82:83], off offset:576
	s_waitcnt vmcnt(15)
	v_pk_add_f32 v[46:47], v[46:47], v[78:79]
	v_pk_add_f32 v[44:45], v[44:45], v[76:77]
	v_mul_f32_e32 v77, v47, v47
	v_mul_f32_e32 v76, v45, v45
	v_fmac_f32_e32 v76, v44, v44
	v_fmac_f32_e32 v77, v46, v46
	v_add_f32_e32 v78, v76, v77
	v_lshlrev_b64 v[76:77], 11, v[96:97]
	v_lshl_add_u64 v[76:77], s[8:9], 0, v[76:77]
	global_store_dwordx4 v[98:99], v[44:47], off
	v_lshl_add_u64 v[76:77], v[156:157], 1, v[76:77]
	s_waitcnt vmcnt(15)
	v_pk_add_f32 v[40:41], v[40:41], v[72:73]
	v_cvt_pk_bf16_f32 v44, v44, v45
	v_cvt_pk_bf16_f32 v45, v46, v47
	global_store_dwordx2 v[76:77], v[44:45], off
	v_pk_add_f32 v[42:43], v[42:43], v[74:75]
	v_mul_f32_e32 v44, v41, v41
	v_fmac_f32_e32 v44, v40, v40
	v_mul_f32_e32 v45, v43, v43
	global_store_dwordx4 v[98:99], v[40:43], off offset:64
	s_waitcnt vmcnt(16)
	v_pk_add_f32 v[38:39], v[38:39], v[70:71]
	v_pk_add_f32 v[36:37], v[36:37], v[68:69]
	v_cvt_pk_bf16_f32 v40, v40, v41
	v_cvt_pk_bf16_f32 v41, v42, v43
	v_fmac_f32_e32 v45, v42, v42
	global_store_dwordx2 v[76:77], v[40:41], off offset:32
	v_mul_f32_e32 v40, v37, v37
	v_mul_f32_e32 v41, v39, v39
	v_add_f32_e32 v44, v44, v45
	v_fmac_f32_e32 v40, v36, v36
	v_fmac_f32_e32 v41, v38, v38
	v_add_f32_e32 v44, v78, v44
	v_add_f32_e32 v40, v40, v41
	v_add_f32_e32 v44, v44, v40
	s_waitcnt vmcnt(16)
	v_pk_add_f32 v[42:43], v[34:35], v[66:67]
	v_pk_add_f32 v[40:41], v[32:33], v[64:65]
	v_mul_f32_e32 v33, v43, v43
	v_mul_f32_e32 v32, v41, v41
	v_fmac_f32_e32 v32, v40, v40
	v_fmac_f32_e32 v33, v42, v42
	v_add_f32_e32 v32, v32, v33
	v_add_f32_e32 v34, v44, v32
	s_nop 1
	v_mov_b32_dpp v35, v34 quad_perm:[1,0,3,2] row_mask:0xf bank_mask:0xf
	v_cvt_pk_bf16_f32 v32, v36, v37
	v_cvt_pk_bf16_f32 v33, v38, v39
	global_store_dwordx4 v[98:99], v[36:39], off offset:512
	global_store_dwordx2 v[76:77], v[32:33], off offset:256
	s_waitcnt lgkmcnt(0)
	v_add_f32_e32 v32, v34, v35
	s_nop 1
	v_mov_b32_dpp v33, v32 quad_perm:[2,3,0,1] row_mask:0xf bank_mask:0xf
	v_cvt_pk_bf16_f32 v34, v40, v41
	v_cvt_pk_bf16_f32 v35, v42, v43
	global_store_dwordx4 v[98:99], v[40:43], off offset:576
	global_store_dwordx2 v[76:77], v[34:35], off offset:288
	s_mov_b32 vcc_lo, 0x11111111
	s_mov_b32 vcc_hi, 0x11111111
	s_and_saveexec_b64 s[24:25], vcc
	s_cbranch_execz .LBB0_1825
	v_lshl_add_u64 v[34:35], v[96:97], 2, s[10:11]
	s_waitcnt lgkmcnt(0)
	v_add_f32_e32 v32, v32, v33
	global_atomic_add_f32 v[34:35], v32, off
.LBB0_1825:
	s_or_b64 exec, exec, s[24:25]
	v_or_b32_e32 v64, 48, v112
	v_ashrrev_i32_e32 v65, 31, v64
	s_waitcnt lgkmcnt(0)
	v_lshlrev_b64 v[32:33], 12, v[64:65]
	v_lshl_add_u64 v[32:33], s[0:1], 0, v[32:33]
	v_lshl_add_u64 v[66:67], v[156:157], 2, v[32:33]
	global_load_dwordx4 v[44:47], v[66:67], off
	global_load_dwordx4 v[40:43], v[66:67], off offset:64
	global_load_dwordx4 v[36:39], v[66:67], off offset:512
	global_load_dwordx4 v[32:35], v[66:67], off offset:576
	s_waitcnt vmcnt(15)
	v_pk_add_f32 v[30:31], v[30:31], v[62:63]
	v_pk_add_f32 v[28:29], v[28:29], v[60:61]
	v_mul_f32_e32 v61, v31, v31
	v_mul_f32_e32 v60, v29, v29
	v_fmac_f32_e32 v60, v28, v28
	v_fmac_f32_e32 v61, v30, v30
	v_add_f32_e32 v62, v60, v61
	v_lshlrev_b64 v[60:61], 11, v[80:81]
	v_lshl_add_u64 v[60:61], s[8:9], 0, v[60:61]
	global_store_dwordx4 v[82:83], v[28:31], off
	v_lshl_add_u64 v[60:61], v[156:157], 1, v[60:61]
	s_waitcnt vmcnt(15)
	v_pk_add_f32 v[24:25], v[24:25], v[56:57]
	v_cvt_pk_bf16_f32 v28, v28, v29
	v_cvt_pk_bf16_f32 v29, v30, v31
	global_store_dwordx2 v[60:61], v[28:29], off
	v_pk_add_f32 v[26:27], v[26:27], v[58:59]
	v_mul_f32_e32 v28, v25, v25
	v_fmac_f32_e32 v28, v24, v24
	v_mul_f32_e32 v29, v27, v27
	global_store_dwordx4 v[82:83], v[24:27], off offset:64
	s_waitcnt vmcnt(16)
	v_pk_add_f32 v[22:23], v[22:23], v[54:55]
	v_pk_add_f32 v[20:21], v[20:21], v[52:53]
	v_cvt_pk_bf16_f32 v24, v24, v25
	v_cvt_pk_bf16_f32 v25, v26, v27
	v_fmac_f32_e32 v29, v26, v26
	global_store_dwordx2 v[60:61], v[24:25], off offset:32
	v_mul_f32_e32 v24, v21, v21
	v_mul_f32_e32 v25, v23, v23
	v_add_f32_e32 v28, v28, v29
	v_fmac_f32_e32 v24, v20, v20
	v_fmac_f32_e32 v25, v22, v22
	v_add_f32_e32 v28, v62, v28
	v_add_f32_e32 v24, v24, v25
	v_add_f32_e32 v28, v28, v24
	s_waitcnt vmcnt(16)
	v_pk_add_f32 v[26:27], v[18:19], v[50:51]
	v_pk_add_f32 v[24:25], v[16:17], v[48:49]
	v_mul_f32_e32 v17, v27, v27
	v_mul_f32_e32 v16, v25, v25
	v_fmac_f32_e32 v16, v24, v24
	v_fmac_f32_e32 v17, v26, v26
	v_add_f32_e32 v16, v16, v17
	v_add_f32_e32 v18, v28, v16
	s_nop 1
	v_mov_b32_dpp v19, v18 quad_perm:[1,0,3,2] row_mask:0xf bank_mask:0xf
	v_cvt_pk_bf16_f32 v16, v20, v21
	v_cvt_pk_bf16_f32 v17, v22, v23
	global_store_dwordx4 v[82:83], v[20:23], off offset:512
	global_store_dwordx2 v[60:61], v[16:17], off offset:256
	s_waitcnt lgkmcnt(0)
	v_add_f32_e32 v16, v18, v19
	s_nop 1
	v_mov_b32_dpp v17, v16 quad_perm:[2,3,0,1] row_mask:0xf bank_mask:0xf
	v_cvt_pk_bf16_f32 v18, v24, v25
	v_cvt_pk_bf16_f32 v19, v26, v27
	global_store_dwordx4 v[82:83], v[24:27], off offset:576
	global_store_dwordx2 v[60:61], v[18:19], off offset:288
	s_mov_b32 vcc_lo, 0x11111111
	s_mov_b32 vcc_hi, 0x11111111
	s_and_saveexec_b64 s[24:25], vcc
	s_cbranch_execz .LBB0_1827
	v_lshl_add_u64 v[18:19], v[80:81], 2, s[10:11]
	s_waitcnt lgkmcnt(0)
	v_add_f32_e32 v16, v16, v17
	global_atomic_add_f32 v[18:19], v16, off
.LBB0_1827:
	s_or_b64 exec, exec, s[24:25]
	s_waitcnt vmcnt(11)
	v_pk_add_f32 v[14:15], v[14:15], v[46:47]
	v_pk_add_f32 v[12:13], v[12:13], v[44:45]
	s_waitcnt lgkmcnt(0)
	v_mul_f32_e32 v17, v15, v15
	v_mul_f32_e32 v16, v13, v13
	v_fmac_f32_e32 v16, v12, v12
	v_fmac_f32_e32 v17, v14, v14
	v_add_f32_e32 v18, v16, v17
	v_lshlrev_b64 v[16:17], 11, v[64:65]
	v_lshl_add_u64 v[16:17], s[8:9], 0, v[16:17]
	global_store_dwordx4 v[66:67], v[12:15], off
	v_lshl_add_u64 v[16:17], v[156:157], 1, v[16:17]
	s_waitcnt vmcnt(11)
	v_pk_add_f32 v[8:9], v[8:9], v[40:41]
	v_cvt_pk_bf16_f32 v12, v12, v13
	v_cvt_pk_bf16_f32 v13, v14, v15
	global_store_dwordx2 v[16:17], v[12:13], off
	v_pk_add_f32 v[10:11], v[10:11], v[42:43]
	v_mul_f32_e32 v12, v9, v9
	v_fmac_f32_e32 v12, v8, v8
	v_mul_f32_e32 v13, v11, v11
	global_store_dwordx4 v[66:67], v[8:11], off offset:64
	s_waitcnt vmcnt(12)
	v_pk_add_f32 v[6:7], v[6:7], v[38:39]
	v_pk_add_f32 v[4:5], v[4:5], v[36:37]
	v_cvt_pk_bf16_f32 v8, v8, v9
	v_cvt_pk_bf16_f32 v9, v10, v11
	v_fmac_f32_e32 v13, v10, v10
	global_store_dwordx2 v[16:17], v[8:9], off offset:32
	v_mul_f32_e32 v8, v5, v5
	v_mul_f32_e32 v9, v7, v7
	v_add_f32_e32 v12, v12, v13
	v_fmac_f32_e32 v8, v4, v4
	v_fmac_f32_e32 v9, v6, v6
	v_add_f32_e32 v12, v18, v12
	v_add_f32_e32 v8, v8, v9
	v_add_f32_e32 v12, v12, v8
	s_waitcnt vmcnt(12)
	v_pk_add_f32 v[10:11], v[2:3], v[34:35]
	v_pk_add_f32 v[8:9], v[0:1], v[32:33]
	v_mul_f32_e32 v1, v11, v11
	v_mul_f32_e32 v0, v9, v9
	v_fmac_f32_e32 v0, v8, v8
	v_fmac_f32_e32 v1, v10, v10
	v_add_f32_e32 v0, v0, v1
	v_add_f32_e32 v2, v12, v0
	s_nop 1
	v_mov_b32_dpp v3, v2 quad_perm:[1,0,3,2] row_mask:0xf bank_mask:0xf
	v_cvt_pk_bf16_f32 v0, v4, v5
	v_cvt_pk_bf16_f32 v1, v6, v7
	global_store_dwordx4 v[66:67], v[4:7], off offset:512
	global_store_dwordx2 v[16:17], v[0:1], off offset:256
	s_waitcnt lgkmcnt(0)
	v_add_f32_e32 v0, v2, v3
	s_nop 1
	v_mov_b32_dpp v1, v0 quad_perm:[2,3,0,1] row_mask:0xf bank_mask:0xf
	v_cvt_pk_bf16_f32 v2, v8, v9
	v_cvt_pk_bf16_f32 v3, v10, v11
	global_store_dwordx4 v[66:67], v[8:11], off offset:576
	global_store_dwordx2 v[16:17], v[2:3], off offset:288
	s_mov_b32 vcc_lo, 0x11111111
	s_mov_b32 vcc_hi, 0x11111111
	s_and_saveexec_b64 s[24:25], vcc
	s_cbranch_execz .LBB0_1829
	v_lshl_add_u64 v[2:3], v[64:65], 2, s[10:11]
	s_waitcnt lgkmcnt(0)
	v_add_f32_e32 v0, v0, v1
	global_atomic_add_f32 v[2:3], v0, off

.LBB0_1998:
	ds_read_b128 v[128:131], v171
	ds_read_b128 v[132:135], v171 offset:1024
	ds_read_b128 v[136:139], v171 offset:2048
	ds_read_b128 v[140:143], v171 offset:3072
	ds_read_b128 v[156:159], v172
	ds_read_b128 v[160:163], v172 offset:1024
	ds_read_b128 v[164:167], v172 offset:2048
	ds_read_b128 v[176:179], v172 offset:3072
	s_add_u32 s24, s22, 0x100
	s_addc_u32 s25, s23, 0
	s_cmp_eq_u32 s55, 40
	s_cselect_b32 s29, s7, s25
	s_cselect_b32 s28, s6, s24
	s_cselect_b32 s27, s21, s54
	s_cselect_b32 s26, s20, s53
	v_lshl_add_u64 v[188:189], s[22:23], 0, v[150:151]
	s_add_i32 m0, s36, 0xc000
	ds_read_b128 v[180:183], v173
	ds_read_b128 v[184:187], v173 offset:1024
	ds_read_b128 v[192:195], v173 offset:2048
	ds_read_b128 v[196:199], v173 offset:3072
	ds_read_b128 v[200:203], v173 offset:4096
	ds_read_b128 v[204:207], v173 offset:5120
	ds_read_b128 v[208:211], v173 offset:6144
	ds_read_b128 v[212:215], v173 offset:7168
	global_load_lds_dwordx4 v[188:189], off
	v_lshl_add_u64 v[188:189], s[22:23], 0, v[148:149]
	s_add_i32 m0, s36, 0xe000
	s_nop 0
	global_load_lds_dwordx4 v[188:189], off
	s_waitcnt vmcnt(8)
	s_waitcnt lgkmcnt(0)
	s_barrier
	s_setprio 1
	s_waitcnt lgkmcnt(0)
	v_mfma_f32_16x16x32_bf16 v[124:127], v[128:131], v[180:183], v[124:127]
	v_mfma_f32_16x16x32_bf16 v[120:123], v[136:139], v[180:183], v[120:123]
	v_mfma_f32_16x16x32_bf16 v[108:111], v[128:131], v[192:195], v[108:111]
	v_mfma_f32_16x16x32_bf16 v[104:107], v[136:139], v[192:195], v[104:107]
	v_mfma_f32_16x16x32_bf16 v[92:95], v[128:131], v[200:203], v[92:95]
	v_mfma_f32_16x16x32_bf16 v[88:91], v[136:139], v[200:203], v[88:91]
	v_mfma_f32_16x16x32_bf16 v[76:79], v[128:131], v[208:211], v[76:79]
	v_mfma_f32_16x16x32_bf16 v[72:75], v[136:139], v[208:211], v[72:75]
	v_mfma_f32_16x16x32_bf16 v[124:127], v[132:135], v[184:187], v[124:127]
	v_mfma_f32_16x16x32_bf16 v[120:123], v[140:143], v[184:187], v[120:123]
	v_mfma_f32_16x16x32_bf16 v[108:111], v[132:135], v[196:199], v[108:111]
	v_mfma_f32_16x16x32_bf16 v[104:107], v[140:143], v[196:199], v[104:107]
	v_mfma_f32_16x16x32_bf16 v[92:95], v[132:135], v[204:207], v[92:95]
	v_mfma_f32_16x16x32_bf16 v[88:91], v[140:143], v[204:207], v[88:91]
	v_mfma_f32_16x16x32_bf16 v[76:79], v[132:135], v[212:215], v[76:79]
	v_mfma_f32_16x16x32_bf16 v[72:75], v[140:143], v[212:215], v[72:75]
	s_setprio 0
	s_setprio 1
	v_mfma_f32_16x16x32_bf16 v[116:119], v[156:159], v[180:183], v[116:119]
	v_mfma_f32_16x16x32_bf16 v[112:115], v[164:167], v[180:183], v[112:115]
	v_mfma_f32_16x16x32_bf16 v[100:103], v[156:159], v[192:195], v[100:103]
	v_mfma_f32_16x16x32_bf16 v[96:99], v[164:167], v[192:195], v[96:99]
	v_mfma_f32_16x16x32_bf16 v[84:87], v[156:159], v[200:203], v[84:87]
	v_mfma_f32_16x16x32_bf16 v[80:83], v[164:167], v[200:203], v[80:83]
	v_mfma_f32_16x16x32_bf16 v[68:71], v[156:159], v[208:211], v[68:71]
	v_mfma_f32_16x16x32_bf16 v[64:67], v[164:167], v[208:211], v[64:67]
	v_mfma_f32_16x16x32_bf16 v[116:119], v[160:163], v[184:187], v[116:119]
	v_mfma_f32_16x16x32_bf16 v[112:115], v[176:179], v[184:187], v[112:115]
	v_mfma_f32_16x16x32_bf16 v[100:103], v[160:163], v[196:199], v[100:103]
	v_mfma_f32_16x16x32_bf16 v[96:99], v[176:179], v[196:199], v[96:99]
	v_mfma_f32_16x16x32_bf16 v[84:87], v[160:163], v[204:207], v[84:87]
	v_mfma_f32_16x16x32_bf16 v[80:83], v[176:179], v[204:207], v[80:83]
	v_mfma_f32_16x16x32_bf16 v[68:71], v[160:163], v[212:215], v[68:71]
	v_mfma_f32_16x16x32_bf16 v[64:67], v[176:179], v[212:215], v[64:67]
	s_setprio 0
	s_barrier
	s_add_i32 s22, s47, s35
	v_lshl_add_u64 v[188:189], s[26:27], 0, v[144:145]
	s_mov_b32 m0, s22
	ds_read_b128 v[180:183], v173 offset:16384
	ds_read_b128 v[184:187], v173 offset:17408
	ds_read_b128 v[192:195], v173 offset:18432
	ds_read_b128 v[196:199], v173 offset:19456
	ds_read_b128 v[200:203], v173 offset:20480
	ds_read_b128 v[204:207], v173 offset:21504
	ds_read_b128 v[208:211], v173 offset:22528
	ds_read_b128 v[212:215], v173 offset:23552
	global_load_lds_dwordx4 v[188:189], off
	s_add_i32 m0, s22, 0x2000
	s_add_u32 s22, s26, 0xb0000
	v_lshl_add_u64 v[216:217], s[26:27], 0, v[146:147]
	s_addc_u32 s23, s27, 0
	s_add_i32 s56, s48, s35
	global_load_lds_dwordx4 v[216:217], off
	v_lshl_add_u64 v[218:219], s[22:23], 0, v[144:145]
	s_mov_b32 m0, s56
	v_lshl_add_u64 v[220:221], s[28:29], 0, v[146:147]
	global_load_lds_dwordx4 v[218:219], off
	v_lshl_add_u64 v[218:219], s[22:23], 0, v[146:147]
	s_add_i32 m0, s56, 0x2000
	s_nop 0
	global_load_lds_dwordx4 v[218:219], off
	v_lshl_add_u64 v[218:219], s[28:29], 0, v[144:145]
	s_mov_b32 m0, s36
	s_nop 0
	global_load_lds_dwordx4 v[218:219], off
	s_mov_b32 m0, s37
	s_nop 0
	global_load_lds_dwordx4 v[220:221], off
	s_waitcnt vmcnt(8)
	s_waitcnt lgkmcnt(0)
	s_barrier
	s_setprio 1
	s_waitcnt lgkmcnt(0)
	v_mfma_f32_16x16x32_bf16 v[60:63], v[128:131], v[180:183], v[60:63]
	v_mfma_f32_16x16x32_bf16 v[56:59], v[136:139], v[180:183], v[56:59]
	v_mfma_f32_16x16x32_bf16 v[44:47], v[128:131], v[192:195], v[44:47]
	v_mfma_f32_16x16x32_bf16 v[40:43], v[136:139], v[192:195], v[40:43]
	v_mfma_f32_16x16x32_bf16 v[28:31], v[128:131], v[200:203], v[28:31]
	v_mfma_f32_16x16x32_bf16 v[24:27], v[136:139], v[200:203], v[24:27]
	v_mfma_f32_16x16x32_bf16 v[12:15], v[128:131], v[208:211], v[12:15]
	v_mfma_f32_16x16x32_bf16 v[8:11], v[136:139], v[208:211], v[8:11]
	v_mfma_f32_16x16x32_bf16 v[60:63], v[132:135], v[184:187], v[60:63]
	v_mfma_f32_16x16x32_bf16 v[56:59], v[140:143], v[184:187], v[56:59]
	v_mfma_f32_16x16x32_bf16 v[44:47], v[132:135], v[196:199], v[44:47]
	v_mfma_f32_16x16x32_bf16 v[40:43], v[140:143], v[196:199], v[40:43]
	v_mfma_f32_16x16x32_bf16 v[28:31], v[132:135], v[204:207], v[28:31]
	v_mfma_f32_16x16x32_bf16 v[24:27], v[140:143], v[204:207], v[24:27]
	v_mfma_f32_16x16x32_bf16 v[12:15], v[132:135], v[212:215], v[12:15]
	v_mfma_f32_16x16x32_bf16 v[8:11], v[140:143], v[212:215], v[8:11]
	s_setprio 0
	s_setprio 1
	v_mfma_f32_16x16x32_bf16 v[52:55], v[156:159], v[180:183], v[52:55]
	v_mfma_f32_16x16x32_bf16 v[48:51], v[164:167], v[180:183], v[48:51]
	v_mfma_f32_16x16x32_bf16 v[36:39], v[156:159], v[192:195], v[36:39]
	v_mfma_f32_16x16x32_bf16 v[32:35], v[164:167], v[192:195], v[32:35]
	v_mfma_f32_16x16x32_bf16 v[20:23], v[156:159], v[200:203], v[20:23]
	v_mfma_f32_16x16x32_bf16 v[16:19], v[164:167], v[200:203], v[16:19]
	v_mfma_f32_16x16x32_bf16 v[4:7], v[156:159], v[208:211], v[4:7]
	v_mfma_f32_16x16x32_bf16 v[0:3], v[164:167], v[208:211], v[0:3]
	v_mfma_f32_16x16x32_bf16 v[52:55], v[160:163], v[184:187], v[52:55]
	v_mfma_f32_16x16x32_bf16 v[48:51], v[176:179], v[184:187], v[48:51]
	v_mfma_f32_16x16x32_bf16 v[36:39], v[160:163], v[196:199], v[36:39]
	v_mfma_f32_16x16x32_bf16 v[32:35], v[176:179], v[196:199], v[32:35]
	v_mfma_f32_16x16x32_bf16 v[20:23], v[160:163], v[204:207], v[20:23]
	v_mfma_f32_16x16x32_bf16 v[16:19], v[176:179], v[204:207], v[16:19]
	v_mfma_f32_16x16x32_bf16 v[4:7], v[160:163], v[212:215], v[4:7]
	v_mfma_f32_16x16x32_bf16 v[0:3], v[176:179], v[212:215], v[0:3]
	s_setprio 0
	s_barrier
	s_add_i32 s56, 0, 0x18000
	s_add_i32 s57, 0, 0x1c000
	v_add_u32_e32 v140, s56, v169
	v_add_u32_e32 v175, s57, v169
	ds_read_b128 v[128:131], v140
	ds_read_b128 v[132:135], v140 offset:1024
	ds_read_b128 v[136:139], v140 offset:2048
	ds_read_b128 v[140:143], v140 offset:3072
	ds_read_b128 v[156:159], v175
	ds_read_b128 v[160:163], v175 offset:1024
	ds_read_b128 v[164:167], v175 offset:2048
	ds_read_b128 v[176:179], v175 offset:3072
	s_add_u32 s22, s28, 0xb0000
	s_addc_u32 s23, s29, 0
	s_mov_b32 m0, s38
	v_lshl_add_u64 v[222:223], s[22:23], 0, v[144:145]
	ds_read_b128 v[180:183], v173 offset:32768
	ds_read_b128 v[184:187], v173 offset:33792
	ds_read_b128 v[192:195], v173 offset:34816
	ds_read_b128 v[196:199], v173 offset:35840
	ds_read_b128 v[200:203], v173 offset:36864
	ds_read_b128 v[204:207], v173 offset:37888
	ds_read_b128 v[208:211], v173 offset:38912
	ds_read_b128 v[212:215], v173 offset:39936
	global_load_lds_dwordx4 v[222:223], off
	v_lshl_add_u64 v[222:223], s[22:23], 0, v[146:147]
	s_mov_b32 m0, s39
	s_nop 0
	global_load_lds_dwordx4 v[222:223], off
	s_waitcnt vmcnt(8)
	s_waitcnt lgkmcnt(0)
	s_barrier
	s_setprio 1
	s_waitcnt lgkmcnt(0)
	v_mfma_f32_16x16x32_bf16 v[124:127], v[128:131], v[180:183], v[124:127]
	v_mfma_f32_16x16x32_bf16 v[120:123], v[136:139], v[180:183], v[120:123]
	v_mfma_f32_16x16x32_bf16 v[108:111], v[128:131], v[192:195], v[108:111]
	v_mfma_f32_16x16x32_bf16 v[104:107], v[136:139], v[192:195], v[104:107]
	v_mfma_f32_16x16x32_bf16 v[92:95], v[128:131], v[200:203], v[92:95]
	v_mfma_f32_16x16x32_bf16 v[88:91], v[136:139], v[200:203], v[88:91]
	v_mfma_f32_16x16x32_bf16 v[76:79], v[128:131], v[208:211], v[76:79]
	v_mfma_f32_16x16x32_bf16 v[72:75], v[136:139], v[208:211], v[72:75]
	v_mfma_f32_16x16x32_bf16 v[124:127], v[132:135], v[184:187], v[124:127]
	v_mfma_f32_16x16x32_bf16 v[120:123], v[140:143], v[184:187], v[120:123]
	v_mfma_f32_16x16x32_bf16 v[108:111], v[132:135], v[196:199], v[108:111]
	v_mfma_f32_16x16x32_bf16 v[104:107], v[140:143], v[196:199], v[104:107]
	v_mfma_f32_16x16x32_bf16 v[92:95], v[132:135], v[204:207], v[92:95]
	v_mfma_f32_16x16x32_bf16 v[88:91], v[140:143], v[204:207], v[88:91]
	v_mfma_f32_16x16x32_bf16 v[76:79], v[132:135], v[212:215], v[76:79]
	v_mfma_f32_16x16x32_bf16 v[72:75], v[140:143], v[212:215], v[72:75]
	s_setprio 0
	s_setprio 1
	v_mfma_f32_16x16x32_bf16 v[116:119], v[156:159], v[180:183], v[116:119]
	v_mfma_f32_16x16x32_bf16 v[112:115], v[164:167], v[180:183], v[112:115]
	v_mfma_f32_16x16x32_bf16 v[100:103], v[156:159], v[192:195], v[100:103]
	v_mfma_f32_16x16x32_bf16 v[96:99], v[164:167], v[192:195], v[96:99]
	v_mfma_f32_16x16x32_bf16 v[84:87], v[156:159], v[200:203], v[84:87]
	v_mfma_f32_16x16x32_bf16 v[80:83], v[164:167], v[200:203], v[80:83]
	v_mfma_f32_16x16x32_bf16 v[68:71], v[156:159], v[208:211], v[68:71]
	v_mfma_f32_16x16x32_bf16 v[64:67], v[164:167], v[208:211], v[64:67]
	v_mfma_f32_16x16x32_bf16 v[116:119], v[160:163], v[184:187], v[116:119]
	v_mfma_f32_16x16x32_bf16 v[112:115], v[176:179], v[184:187], v[112:115]
	v_mfma_f32_16x16x32_bf16 v[100:103], v[160:163], v[196:199], v[100:103]
	v_mfma_f32_16x16x32_bf16 v[96:99], v[176:179], v[196:199], v[96:99]
	v_mfma_f32_16x16x32_bf16 v[84:87], v[160:163], v[204:207], v[84:87]
	v_mfma_f32_16x16x32_bf16 v[80:83], v[176:179], v[204:207], v[80:83]
	v_mfma_f32_16x16x32_bf16 v[68:71], v[160:163], v[212:215], v[68:71]
	v_mfma_f32_16x16x32_bf16 v[64:67], v[176:179], v[212:215], v[64:67]
	s_setprio 0
	s_barrier
	s_add_i32 s22, s56, s35
	v_lshl_add_u64 v[188:189], v[188:189], 0, s[16:17]
	s_mov_b32 m0, s22
	ds_read_b128 v[180:183], v173 offset:49152
	ds_read_b128 v[184:187], v173 offset:50176
	ds_read_b128 v[192:195], v173 offset:51200
	ds_read_b128 v[196:199], v173 offset:52224
	ds_read_b128 v[200:203], v173 offset:53248
	ds_read_b128 v[204:207], v173 offset:54272
	ds_read_b128 v[208:211], v173 offset:55296
	ds_read_b128 v[212:215], v173 offset:56320
	global_load_lds_dwordx4 v[188:189], off
	s_add_i32 m0, s22, 0x2000
	s_add_u32 s22, s26, 0xb0080
	v_lshl_add_u64 v[188:189], v[216:217], 0, s[16:17]
	s_addc_u32 s23, s27, 0
	s_add_i32 s26, s57, s35
	global_load_lds_dwordx4 v[188:189], off
	v_lshl_add_u64 v[188:189], s[22:23], 0, v[144:145]
	s_mov_b32 m0, s26
	s_nop 0
	global_load_lds_dwordx4 v[188:189], off
	v_lshl_add_u64 v[188:189], s[22:23], 0, v[146:147]
	s_add_i32 m0, s26, 0x2000
	s_nop 0
	global_load_lds_dwordx4 v[188:189], off
	v_lshl_add_u64 v[188:189], v[218:219], 0, s[16:17]
	s_mov_b32 m0, s41
	s_nop 0
	global_load_lds_dwordx4 v[188:189], off
	v_lshl_add_u64 v[188:189], v[220:221], 0, s[16:17]
	s_mov_b32 m0, s42
	s_nop 0
	global_load_lds_dwordx4 v[188:189], off
	s_waitcnt vmcnt(8)
	s_waitcnt lgkmcnt(0)
	s_barrier
	s_setprio 1
	s_waitcnt lgkmcnt(0)
	v_mfma_f32_16x16x32_bf16 v[60:63], v[128:131], v[180:183], v[60:63]
	v_mfma_f32_16x16x32_bf16 v[56:59], v[136:139], v[180:183], v[56:59]
	v_mfma_f32_16x16x32_bf16 v[44:47], v[128:131], v[192:195], v[44:47]
	v_mfma_f32_16x16x32_bf16 v[40:43], v[136:139], v[192:195], v[40:43]
	v_mfma_f32_16x16x32_bf16 v[28:31], v[128:131], v[200:203], v[28:31]
	v_mfma_f32_16x16x32_bf16 v[24:27], v[136:139], v[200:203], v[24:27]
	v_mfma_f32_16x16x32_bf16 v[12:15], v[128:131], v[208:211], v[12:15]
	v_mfma_f32_16x16x32_bf16 v[8:11], v[136:139], v[208:211], v[8:11]
	v_mfma_f32_16x16x32_bf16 v[60:63], v[132:135], v[184:187], v[60:63]
	v_mfma_f32_16x16x32_bf16 v[56:59], v[140:143], v[184:187], v[56:59]
	v_mfma_f32_16x16x32_bf16 v[44:47], v[132:135], v[196:199], v[44:47]
	v_mfma_f32_16x16x32_bf16 v[40:43], v[140:143], v[196:199], v[40:43]
	v_mfma_f32_16x16x32_bf16 v[28:31], v[132:135], v[204:207], v[28:31]
	v_mfma_f32_16x16x32_bf16 v[24:27], v[140:143], v[204:207], v[24:27]
	v_mfma_f32_16x16x32_bf16 v[12:15], v[132:135], v[212:215], v[12:15]
	v_mfma_f32_16x16x32_bf16 v[8:11], v[140:143], v[212:215], v[8:11]
	s_setprio 0
	s_setprio 1
	v_mfma_f32_16x16x32_bf16 v[52:55], v[156:159], v[180:183], v[52:55]
	v_mfma_f32_16x16x32_bf16 v[48:51], v[164:167], v[180:183], v[48:51]
	v_mfma_f32_16x16x32_bf16 v[36:39], v[156:159], v[192:195], v[36:39]
	v_mfma_f32_16x16x32_bf16 v[32:35], v[164:167], v[192:195], v[32:35]
	v_mfma_f32_16x16x32_bf16 v[20:23], v[156:159], v[200:203], v[20:23]
	v_mfma_f32_16x16x32_bf16 v[16:19], v[164:167], v[200:203], v[16:19]
	v_mfma_f32_16x16x32_bf16 v[4:7], v[156:159], v[208:211], v[4:7]
	v_mfma_f32_16x16x32_bf16 v[0:3], v[164:167], v[208:211], v[0:3]
	v_mfma_f32_16x16x32_bf16 v[52:55], v[160:163], v[184:187], v[52:55]
	v_mfma_f32_16x16x32_bf16 v[48:51], v[176:179], v[184:187], v[48:51]
	v_mfma_f32_16x16x32_bf16 v[36:39], v[160:163], v[196:199], v[36:39]
	v_mfma_f32_16x16x32_bf16 v[32:35], v[176:179], v[196:199], v[32:35]
	v_mfma_f32_16x16x32_bf16 v[20:23], v[160:163], v[204:207], v[20:23]
	v_mfma_f32_16x16x32_bf16 v[16:19], v[176:179], v[204:207], v[16:19]
	v_mfma_f32_16x16x32_bf16 v[4:7], v[160:163], v[212:215], v[4:7]
	v_mfma_f32_16x16x32_bf16 v[0:3], v[176:179], v[212:215], v[0:3]
	s_setprio 0
	s_barrier
	s_add_i32 s55, s55, 2
	s_add_u32 s53, s53, 0x100
	s_addc_u32 s54, s54, 0
	s_cmp_gt_u32 s55, 41
	s_mov_b64 s[22:23], s[24:25]
	s_cbranch_scc0 .LBB0_1998
	v_mbcnt_lo_u32_b32 v235, -1, 0
	v_mbcnt_hi_u32_b32 v235, -1, v235
	v_lshrrev_b32_e32 v236, 2, v235
	v_and_b32_e32 v237, 3, v235
	v_lshl_add_u32 v232, v237, 4, v236
	v_lshlrev_b32_e32 v232, 2, v232
	v_and_b32_e32 v233, -16, v168
	v_or_b32_e32 v233, v233, v236
	v_lshlrev_b32_e32 v237, 2, v237
	v_and_b32_e32 v234, -13, v170
	v_or_b32_e32 v234, v234, v237
	v_lshl_add_u32 v158, s52, 8, v233
	v_lshl_or_b32 v156, s51, 8, v234
	v_ashrrev_i32_e32 v159, 31, v158
	v_lshlrev_b64 v[128:129], 12, v[158:159]
	v_ashrrev_i32_e32 v157, 31, v156
	v_lshl_add_u64 v[128:129], s[8:9], 0, v[128:129]
	v_lshlrev_b64 v[130:131], 2, v[156:157]
	v_lshl_add_u64 v[188:189], v[128:129], 0, v[130:131]
	global_load_dwordx4 v[164:167], v[188:189], off
	global_load_dwordx4 v[176:179], v[188:189], off offset:64
	global_load_dwordx4 v[180:183], v[188:189], off offset:512
	global_load_dwordx4 v[184:187], v[188:189], off offset:576
	v_or_b32_e32 v160, 16, v158
	v_ashrrev_i32_e32 v161, 31, v160
	v_lshlrev_b64 v[128:129], 12, v[160:161]
	v_lshl_add_u64 v[128:129], s[8:9], 0, v[128:129]
	v_lshl_add_u64 v[162:163], v[128:129], 0, v[130:131]
	global_load_dwordx4 v[140:143], v[162:163], off
	global_load_dwordx4 v[136:139], v[162:163], off offset:64
	global_load_dwordx4 v[132:135], v[162:163], off offset:512
	global_load_dwordx4 v[128:131], v[162:163], off offset:576
	v_lshlrev_b64 v[192:193], 11, v[158:159]
	v_lshl_add_u64 v[192:193], s[12:13], 0, v[192:193]
	v_and_b32_e32 v191, 64, v174
	v_lshl_add_u64 v[192:193], v[156:157], 1, v[192:193]
	v_xor_b32_e32 v175, 1, v174
	v_add_u32_e32 v191, 64, v191
	v_cmp_lt_i32_e32 vcc, v175, v191
	v_xor_b32_e32 v194, 2, v174
	ds_bpermute_b32 v127, v232, v127
	ds_bpermute_b32 v126, v232, v126
	ds_bpermute_b32 v125, v232, v125
	ds_bpermute_b32 v124, v232, v124
	ds_bpermute_b32 v123, v232, v123
	ds_bpermute_b32 v122, v232, v122
	ds_bpermute_b32 v121, v232, v121
	ds_bpermute_b32 v120, v232, v120
	ds_bpermute_b32 v119, v232, v119
	ds_bpermute_b32 v118, v232, v118
	ds_bpermute_b32 v117, v232, v117
	ds_bpermute_b32 v116, v232, v116
	ds_bpermute_b32 v115, v232, v115
	ds_bpermute_b32 v114, v232, v114
	ds_bpermute_b32 v113, v232, v113
	ds_bpermute_b32 v112, v232, v112
	ds_bpermute_b32 v111, v232, v111
	ds_bpermute_b32 v110, v232, v110
	ds_bpermute_b32 v109, v232, v109
	ds_bpermute_b32 v108, v232, v108
	ds_bpermute_b32 v107, v232, v107
	ds_bpermute_b32 v106, v232, v106
	ds_bpermute_b32 v105, v232, v105
	ds_bpermute_b32 v104, v232, v104
	ds_bpermute_b32 v103, v232, v103
	ds_bpermute_b32 v102, v232, v102
	ds_bpermute_b32 v101, v232, v101
	ds_bpermute_b32 v100, v232, v100
	ds_bpermute_b32 v99, v232, v99
	ds_bpermute_b32 v98, v232, v98
	ds_bpermute_b32 v97, v232, v97
	ds_bpermute_b32 v96, v232, v96
	ds_bpermute_b32 v95, v232, v95
	ds_bpermute_b32 v94, v232, v94
	ds_bpermute_b32 v93, v232, v93
	ds_bpermute_b32 v92, v232, v92
	ds_bpermute_b32 v91, v232, v91
	ds_bpermute_b32 v90, v232, v90
	ds_bpermute_b32 v89, v232, v89
	ds_bpermute_b32 v88, v232, v88
	ds_bpermute_b32 v87, v232, v87
	ds_bpermute_b32 v86, v232, v86
	ds_bpermute_b32 v85, v232, v85
	ds_bpermute_b32 v84, v232, v84
	ds_bpermute_b32 v83, v232, v83
	ds_bpermute_b32 v82, v232, v82
	ds_bpermute_b32 v81, v232, v81
	ds_bpermute_b32 v80, v232, v80
	ds_bpermute_b32 v79, v232, v79
	ds_bpermute_b32 v78, v232, v78
	ds_bpermute_b32 v77, v232, v77
	ds_bpermute_b32 v76, v232, v76
	ds_bpermute_b32 v75, v232, v75
	ds_bpermute_b32 v74, v232, v74
	ds_bpermute_b32 v73, v232, v73
	ds_bpermute_b32 v72, v232, v72
	ds_bpermute_b32 v71, v232, v71
	ds_bpermute_b32 v70, v232, v70
	ds_bpermute_b32 v69, v232, v69
	ds_bpermute_b32 v68, v232, v68
	ds_bpermute_b32 v67, v232, v67
	ds_bpermute_b32 v66, v232, v66
	ds_bpermute_b32 v65, v232, v65
	ds_bpermute_b32 v64, v232, v64
	ds_bpermute_b32 v63, v232, v63
	ds_bpermute_b32 v62, v232, v62
	ds_bpermute_b32 v61, v232, v61
	ds_bpermute_b32 v60, v232, v60
	ds_bpermute_b32 v59, v232, v59
	ds_bpermute_b32 v58, v232, v58
	ds_bpermute_b32 v57, v232, v57
	ds_bpermute_b32 v56, v232, v56
	ds_bpermute_b32 v55, v232, v55
	ds_bpermute_b32 v54, v232, v54
	ds_bpermute_b32 v53, v232, v53
	ds_bpermute_b32 v52, v232, v52
	ds_bpermute_b32 v51, v232, v51
	ds_bpermute_b32 v50, v232, v50
	ds_bpermute_b32 v49, v232, v49
	ds_bpermute_b32 v48, v232, v48
	ds_bpermute_b32 v47, v232, v47
	ds_bpermute_b32 v46, v232, v46
	ds_bpermute_b32 v45, v232, v45
	ds_bpermute_b32 v44, v232, v44
	ds_bpermute_b32 v43, v232, v43
	ds_bpermute_b32 v42, v232, v42
	ds_bpermute_b32 v41, v232, v41
	ds_bpermute_b32 v40, v232, v40
	ds_bpermute_b32 v39, v232, v39
	ds_bpermute_b32 v38, v232, v38
	ds_bpermute_b32 v37, v232, v37
	ds_bpermute_b32 v36, v232, v36
	ds_bpermute_b32 v35, v232, v35
	ds_bpermute_b32 v34, v232, v34
	ds_bpermute_b32 v33, v232, v33
	ds_bpermute_b32 v32, v232, v32
	ds_bpermute_b32 v31, v232, v31
	ds_bpermute_b32 v30, v232, v30
	ds_bpermute_b32 v29, v232, v29
	ds_bpermute_b32 v28, v232, v28
	ds_bpermute_b32 v27, v232, v27
	ds_bpermute_b32 v26, v232, v26
	ds_bpermute_b32 v25, v232, v25
	ds_bpermute_b32 v24, v232, v24
	ds_bpermute_b32 v23, v232, v23
	ds_bpermute_b32 v22, v232, v22
	ds_bpermute_b32 v21, v232, v21
	ds_bpermute_b32 v20, v232, v20
	ds_bpermute_b32 v19, v232, v19
	ds_bpermute_b32 v18, v232, v18
	ds_bpermute_b32 v17, v232, v17
	ds_bpermute_b32 v16, v232, v16
	ds_bpermute_b32 v15, v232, v15
	ds_bpermute_b32 v14, v232, v14
	ds_bpermute_b32 v13, v232, v13
	ds_bpermute_b32 v12, v232, v12
	ds_bpermute_b32 v11, v232, v11
	ds_bpermute_b32 v10, v232, v10
	ds_bpermute_b32 v9, v232, v9
	ds_bpermute_b32 v8, v232, v8
	ds_bpermute_b32 v7, v232, v7
	ds_bpermute_b32 v6, v232, v6
	ds_bpermute_b32 v5, v232, v5
	ds_bpermute_b32 v4, v232, v4
	ds_bpermute_b32 v3, v232, v3
	ds_bpermute_b32 v2, v232, v2
	ds_bpermute_b32 v1, v232, v1
	ds_bpermute_b32 v0, v232, v0
	s_waitcnt lgkmcnt(0)
	s_waitcnt lgkmcnt(0)
	s_cmp_eq_u64 s[18:19], 0
	s_cbranch_scc1 .LBB0_2001
	s_barrier

.LBB0_2118:
	ds_read_b128 v[128:131], v189
	ds_read_b128 v[132:135], v189 offset:1024
	ds_read_b128 v[136:139], v189 offset:2048
	ds_read_b128 v[140:143], v189 offset:3072
	ds_read_b128 v[156:159], v191
	ds_read_b128 v[160:163], v191 offset:1024
	ds_read_b128 v[164:167], v191 offset:2048
	ds_read_b128 v[168:171], v191 offset:3072
	s_add_u32 s34, s30, 0xfffc0080
	s_addc_u32 s35, s31, -1
	s_cmp_eq_u32 s58, 12
	s_cselect_b32 s37, s21, s35
	s_cselect_b32 s36, s27, s34
	s_cselect_b32 s35, s19, s57
	s_cselect_b32 s34, s33, s56
	v_lshl_add_u64 v[184:185], s[30:31], 0, v[150:151]
	s_add_i32 m0, s29, 0xc000
	ds_read_b128 v[172:175], v192
	ds_read_b128 v[176:179], v192 offset:1024
	ds_read_b128 v[180:183], v192 offset:2048
	ds_read_b128 v[196:199], v192 offset:3072
	ds_read_b128 v[200:203], v192 offset:4096
	ds_read_b128 v[204:207], v192 offset:5120
	ds_read_b128 v[208:211], v192 offset:6144
	ds_read_b128 v[212:215], v192 offset:7168
	global_load_lds_dwordx4 v[184:185], off
	v_lshl_add_u64 v[184:185], s[30:31], 0, v[148:149]
	s_add_i32 m0, s29, 0xe000
	s_nop 0
	global_load_lds_dwordx4 v[184:185], off
	s_waitcnt vmcnt(8)
	s_waitcnt lgkmcnt(0)
	s_barrier
	s_setprio 1
	s_waitcnt lgkmcnt(0)
	v_mfma_f32_16x16x32_bf16 v[124:127], v[128:131], v[172:175], v[124:127]
	v_mfma_f32_16x16x32_bf16 v[120:123], v[136:139], v[172:175], v[120:123]
	v_mfma_f32_16x16x32_bf16 v[108:111], v[128:131], v[180:183], v[108:111]
	v_mfma_f32_16x16x32_bf16 v[104:107], v[136:139], v[180:183], v[104:107]
	v_mfma_f32_16x16x32_bf16 v[92:95], v[128:131], v[200:203], v[92:95]
	v_mfma_f32_16x16x32_bf16 v[88:91], v[136:139], v[200:203], v[88:91]
	v_mfma_f32_16x16x32_bf16 v[76:79], v[128:131], v[208:211], v[76:79]
	v_mfma_f32_16x16x32_bf16 v[72:75], v[136:139], v[208:211], v[72:75]
	v_mfma_f32_16x16x32_bf16 v[124:127], v[132:135], v[176:179], v[124:127]
	v_mfma_f32_16x16x32_bf16 v[120:123], v[140:143], v[176:179], v[120:123]
	v_mfma_f32_16x16x32_bf16 v[108:111], v[132:135], v[196:199], v[108:111]
	v_mfma_f32_16x16x32_bf16 v[104:107], v[140:143], v[196:199], v[104:107]
	v_mfma_f32_16x16x32_bf16 v[92:95], v[132:135], v[204:207], v[92:95]
	v_mfma_f32_16x16x32_bf16 v[88:91], v[140:143], v[204:207], v[88:91]
	v_mfma_f32_16x16x32_bf16 v[76:79], v[132:135], v[212:215], v[76:79]
	v_mfma_f32_16x16x32_bf16 v[72:75], v[140:143], v[212:215], v[72:75]
	s_setprio 0
	s_setprio 1
	v_mfma_f32_16x16x32_bf16 v[116:119], v[156:159], v[172:175], v[116:119]
	v_mfma_f32_16x16x32_bf16 v[112:115], v[164:167], v[172:175], v[112:115]
	v_mfma_f32_16x16x32_bf16 v[100:103], v[156:159], v[180:183], v[100:103]
	v_mfma_f32_16x16x32_bf16 v[96:99], v[164:167], v[180:183], v[96:99]
	v_mfma_f32_16x16x32_bf16 v[84:87], v[156:159], v[200:203], v[84:87]
	v_mfma_f32_16x16x32_bf16 v[80:83], v[164:167], v[200:203], v[80:83]
	v_mfma_f32_16x16x32_bf16 v[68:71], v[156:159], v[208:211], v[68:71]
	v_mfma_f32_16x16x32_bf16 v[64:67], v[164:167], v[208:211], v[64:67]
	v_mfma_f32_16x16x32_bf16 v[116:119], v[160:163], v[176:179], v[116:119]
	v_mfma_f32_16x16x32_bf16 v[112:115], v[168:171], v[176:179], v[112:115]
	v_mfma_f32_16x16x32_bf16 v[100:103], v[160:163], v[196:199], v[100:103]
	v_mfma_f32_16x16x32_bf16 v[96:99], v[168:171], v[196:199], v[96:99]
	v_mfma_f32_16x16x32_bf16 v[84:87], v[160:163], v[204:207], v[84:87]
	v_mfma_f32_16x16x32_bf16 v[80:83], v[168:171], v[204:207], v[80:83]
	v_mfma_f32_16x16x32_bf16 v[68:71], v[160:163], v[212:215], v[68:71]
	v_mfma_f32_16x16x32_bf16 v[64:67], v[168:171], v[212:215], v[64:67]
	s_setprio 0
	s_barrier
	s_add_i32 s59, s53, s40
	v_lshl_add_u64 v[184:185], s[34:35], 0, v[144:145]
	s_mov_b32 m0, s59
	ds_read_b128 v[172:175], v192 offset:16384
	ds_read_b128 v[176:179], v192 offset:17408
	ds_read_b128 v[180:183], v192 offset:18432
	ds_read_b128 v[196:199], v192 offset:19456
	ds_read_b128 v[200:203], v192 offset:20480
	ds_read_b128 v[204:207], v192 offset:21504
	ds_read_b128 v[208:211], v192 offset:22528
	ds_read_b128 v[212:215], v192 offset:23552
	global_load_lds_dwordx4 v[184:185], off
	s_add_i32 m0, s59, 0x2000
	s_add_u32 s60, s34, 0x40000
	v_lshl_add_u64 v[216:217], s[34:35], 0, v[146:147]
	s_addc_u32 s61, s35, 0
	s_add_i32 s59, s54, s40
	global_load_lds_dwordx4 v[216:217], off
	v_lshl_add_u64 v[218:219], s[60:61], 0, v[144:145]
	s_mov_b32 m0, s59
	v_lshl_add_u64 v[220:221], s[36:37], 0, v[146:147]
	global_load_lds_dwordx4 v[218:219], off
	v_lshl_add_u64 v[218:219], s[60:61], 0, v[146:147]
	s_add_i32 m0, s59, 0x2000
	s_nop 0
	global_load_lds_dwordx4 v[218:219], off
	v_lshl_add_u64 v[218:219], s[36:37], 0, v[144:145]
	s_mov_b32 m0, s29
	s_nop 0
	global_load_lds_dwordx4 v[218:219], off
	s_mov_b32 m0, s43
	s_nop 0
	global_load_lds_dwordx4 v[220:221], off
	s_waitcnt vmcnt(8)
	s_waitcnt lgkmcnt(0)
	s_barrier
	s_setprio 1
	s_waitcnt lgkmcnt(0)
	v_mfma_f32_16x16x32_bf16 v[60:63], v[128:131], v[172:175], v[60:63]
	v_mfma_f32_16x16x32_bf16 v[56:59], v[136:139], v[172:175], v[56:59]
	v_mfma_f32_16x16x32_bf16 v[44:47], v[128:131], v[180:183], v[44:47]
	v_mfma_f32_16x16x32_bf16 v[40:43], v[136:139], v[180:183], v[40:43]
	v_mfma_f32_16x16x32_bf16 v[28:31], v[128:131], v[200:203], v[28:31]
	v_mfma_f32_16x16x32_bf16 v[24:27], v[136:139], v[200:203], v[24:27]
	v_mfma_f32_16x16x32_bf16 v[12:15], v[128:131], v[208:211], v[12:15]
	v_mfma_f32_16x16x32_bf16 v[8:11], v[136:139], v[208:211], v[8:11]
	v_mfma_f32_16x16x32_bf16 v[60:63], v[132:135], v[176:179], v[60:63]
	v_mfma_f32_16x16x32_bf16 v[56:59], v[140:143], v[176:179], v[56:59]
	v_mfma_f32_16x16x32_bf16 v[44:47], v[132:135], v[196:199], v[44:47]
	v_mfma_f32_16x16x32_bf16 v[40:43], v[140:143], v[196:199], v[40:43]
	v_mfma_f32_16x16x32_bf16 v[28:31], v[132:135], v[204:207], v[28:31]
	v_mfma_f32_16x16x32_bf16 v[24:27], v[140:143], v[204:207], v[24:27]
	v_mfma_f32_16x16x32_bf16 v[12:15], v[132:135], v[212:215], v[12:15]
	v_mfma_f32_16x16x32_bf16 v[8:11], v[140:143], v[212:215], v[8:11]
	s_setprio 0
	s_setprio 1
	v_mfma_f32_16x16x32_bf16 v[52:55], v[156:159], v[172:175], v[52:55]
	v_mfma_f32_16x16x32_bf16 v[48:51], v[164:167], v[172:175], v[48:51]
	v_mfma_f32_16x16x32_bf16 v[36:39], v[156:159], v[180:183], v[36:39]
	v_mfma_f32_16x16x32_bf16 v[32:35], v[164:167], v[180:183], v[32:35]
	v_mfma_f32_16x16x32_bf16 v[20:23], v[156:159], v[200:203], v[20:23]
	v_mfma_f32_16x16x32_bf16 v[16:19], v[164:167], v[200:203], v[16:19]
	v_mfma_f32_16x16x32_bf16 v[4:7], v[156:159], v[208:211], v[4:7]
	v_mfma_f32_16x16x32_bf16 v[0:3], v[164:167], v[208:211], v[0:3]
	v_mfma_f32_16x16x32_bf16 v[52:55], v[160:163], v[176:179], v[52:55]
	v_mfma_f32_16x16x32_bf16 v[48:51], v[168:171], v[176:179], v[48:51]
	v_mfma_f32_16x16x32_bf16 v[36:39], v[160:163], v[196:199], v[36:39]
	v_mfma_f32_16x16x32_bf16 v[32:35], v[168:171], v[196:199], v[32:35]
	v_mfma_f32_16x16x32_bf16 v[20:23], v[160:163], v[204:207], v[20:23]
	v_mfma_f32_16x16x32_bf16 v[16:19], v[168:171], v[204:207], v[16:19]
	v_mfma_f32_16x16x32_bf16 v[4:7], v[160:163], v[212:215], v[4:7]
	v_mfma_f32_16x16x32_bf16 v[0:3], v[168:171], v[212:215], v[0:3]
	s_setprio 0
	s_barrier
	s_add_i32 s59, 0, 0x18000
	s_add_i32 s60, 0, 0x1c000
	v_add_u32_e32 v140, s59, v187
	v_add_u32_e32 v168, s60, v187
	ds_read_b128 v[128:131], v140
	ds_read_b128 v[132:135], v140 offset:1024
	ds_read_b128 v[136:139], v140 offset:2048
	ds_read_b128 v[140:143], v140 offset:3072
	ds_read_b128 v[156:159], v168
	ds_read_b128 v[160:163], v168 offset:1024
	ds_read_b128 v[164:167], v168 offset:2048
	ds_read_b128 v[168:171], v168 offset:3072
	s_add_u32 s36, s36, 0x40000
	s_addc_u32 s37, s37, 0
	s_mov_b32 m0, s44
	v_lshl_add_u64 v[222:223], s[36:37], 0, v[144:145]
	ds_read_b128 v[172:175], v192 offset:32768
	ds_read_b128 v[176:179], v192 offset:33792
	ds_read_b128 v[180:183], v192 offset:34816
	ds_read_b128 v[196:199], v192 offset:35840
	ds_read_b128 v[200:203], v192 offset:36864
	ds_read_b128 v[204:207], v192 offset:37888
	ds_read_b128 v[208:211], v192 offset:38912
	ds_read_b128 v[212:215], v192 offset:39936
	global_load_lds_dwordx4 v[222:223], off
	v_lshl_add_u64 v[222:223], s[36:37], 0, v[146:147]
	s_mov_b32 m0, s45
	s_nop 0
	global_load_lds_dwordx4 v[222:223], off
	s_waitcnt vmcnt(8)
	s_waitcnt lgkmcnt(0)
	s_barrier
	s_setprio 1
	s_waitcnt lgkmcnt(0)
	v_mfma_f32_16x16x32_bf16 v[124:127], v[128:131], v[172:175], v[124:127]
	v_mfma_f32_16x16x32_bf16 v[120:123], v[136:139], v[172:175], v[120:123]
	v_mfma_f32_16x16x32_bf16 v[108:111], v[128:131], v[180:183], v[108:111]
	v_mfma_f32_16x16x32_bf16 v[104:107], v[136:139], v[180:183], v[104:107]
	v_mfma_f32_16x16x32_bf16 v[92:95], v[128:131], v[200:203], v[92:95]
	v_mfma_f32_16x16x32_bf16 v[88:91], v[136:139], v[200:203], v[88:91]
	v_mfma_f32_16x16x32_bf16 v[76:79], v[128:131], v[208:211], v[76:79]
	v_mfma_f32_16x16x32_bf16 v[72:75], v[136:139], v[208:211], v[72:75]
	v_mfma_f32_16x16x32_bf16 v[124:127], v[132:135], v[176:179], v[124:127]
	v_mfma_f32_16x16x32_bf16 v[120:123], v[140:143], v[176:179], v[120:123]
	v_mfma_f32_16x16x32_bf16 v[108:111], v[132:135], v[196:199], v[108:111]
	v_mfma_f32_16x16x32_bf16 v[104:107], v[140:143], v[196:199], v[104:107]
	v_mfma_f32_16x16x32_bf16 v[92:95], v[132:135], v[204:207], v[92:95]
	v_mfma_f32_16x16x32_bf16 v[88:91], v[140:143], v[204:207], v[88:91]
	v_mfma_f32_16x16x32_bf16 v[76:79], v[132:135], v[212:215], v[76:79]
	v_mfma_f32_16x16x32_bf16 v[72:75], v[140:143], v[212:215], v[72:75]
	s_setprio 0
	s_setprio 1
	v_mfma_f32_16x16x32_bf16 v[116:119], v[156:159], v[172:175], v[116:119]
	v_mfma_f32_16x16x32_bf16 v[112:115], v[164:167], v[172:175], v[112:115]
	v_mfma_f32_16x16x32_bf16 v[100:103], v[156:159], v[180:183], v[100:103]
	v_mfma_f32_16x16x32_bf16 v[96:99], v[164:167], v[180:183], v[96:99]
	v_mfma_f32_16x16x32_bf16 v[84:87], v[156:159], v[200:203], v[84:87]
	v_mfma_f32_16x16x32_bf16 v[80:83], v[164:167], v[200:203], v[80:83]
	v_mfma_f32_16x16x32_bf16 v[68:71], v[156:159], v[208:211], v[68:71]
	v_mfma_f32_16x16x32_bf16 v[64:67], v[164:167], v[208:211], v[64:67]
	v_mfma_f32_16x16x32_bf16 v[116:119], v[160:163], v[176:179], v[116:119]
	v_mfma_f32_16x16x32_bf16 v[112:115], v[168:171], v[176:179], v[112:115]
	v_mfma_f32_16x16x32_bf16 v[100:103], v[160:163], v[196:199], v[100:103]
	v_mfma_f32_16x16x32_bf16 v[96:99], v[168:171], v[196:199], v[96:99]
	v_mfma_f32_16x16x32_bf16 v[84:87], v[160:163], v[204:207], v[84:87]
	v_mfma_f32_16x16x32_bf16 v[80:83], v[168:171], v[204:207], v[80:83]
	v_mfma_f32_16x16x32_bf16 v[68:71], v[160:163], v[212:215], v[68:71]
	v_mfma_f32_16x16x32_bf16 v[64:67], v[168:171], v[212:215], v[64:67]
	s_setprio 0
	s_barrier
	s_add_i32 s36, s59, s40
	v_lshl_add_u64 v[184:185], v[184:185], 0, s[14:15]
	s_mov_b32 m0, s36
	ds_read_b128 v[172:175], v192 offset:49152
	ds_read_b128 v[176:179], v192 offset:50176
	ds_read_b128 v[180:183], v192 offset:51200
	ds_read_b128 v[196:199], v192 offset:52224
	ds_read_b128 v[200:203], v192 offset:53248
	ds_read_b128 v[204:207], v192 offset:54272
	ds_read_b128 v[208:211], v192 offset:55296
	ds_read_b128 v[212:215], v192 offset:56320
	global_load_lds_dwordx4 v[184:185], off
	s_add_i32 m0, s36, 0x2000
	s_add_u32 s34, s34, 0x40080
	v_lshl_add_u64 v[184:185], v[216:217], 0, s[14:15]
	s_addc_u32 s35, s35, 0
	s_add_i32 s36, s60, s40
	global_load_lds_dwordx4 v[184:185], off
	v_lshl_add_u64 v[184:185], s[34:35], 0, v[144:145]
	s_mov_b32 m0, s36
	s_nop 0
	global_load_lds_dwordx4 v[184:185], off
	v_lshl_add_u64 v[184:185], s[34:35], 0, v[146:147]
	s_add_i32 m0, s36, 0x2000
	s_nop 0
	global_load_lds_dwordx4 v[184:185], off
	v_lshl_add_u64 v[184:185], v[218:219], 0, s[14:15]
	s_mov_b32 m0, s47
	s_nop 0
	global_load_lds_dwordx4 v[184:185], off
	v_lshl_add_u64 v[184:185], v[220:221], 0, s[14:15]
	s_mov_b32 m0, s48
	s_nop 0
	global_load_lds_dwordx4 v[184:185], off
	s_waitcnt vmcnt(8)
	s_waitcnt lgkmcnt(0)
	s_barrier
	s_setprio 1
	s_waitcnt lgkmcnt(0)
	v_mfma_f32_16x16x32_bf16 v[60:63], v[128:131], v[172:175], v[60:63]
	v_mfma_f32_16x16x32_bf16 v[56:59], v[136:139], v[172:175], v[56:59]
	v_mfma_f32_16x16x32_bf16 v[44:47], v[128:131], v[180:183], v[44:47]
	v_mfma_f32_16x16x32_bf16 v[40:43], v[136:139], v[180:183], v[40:43]
	v_mfma_f32_16x16x32_bf16 v[28:31], v[128:131], v[200:203], v[28:31]
	v_mfma_f32_16x16x32_bf16 v[24:27], v[136:139], v[200:203], v[24:27]
	v_mfma_f32_16x16x32_bf16 v[12:15], v[128:131], v[208:211], v[12:15]
	v_mfma_f32_16x16x32_bf16 v[8:11], v[136:139], v[208:211], v[8:11]
	v_mfma_f32_16x16x32_bf16 v[60:63], v[132:135], v[176:179], v[60:63]
	v_mfma_f32_16x16x32_bf16 v[56:59], v[140:143], v[176:179], v[56:59]
	v_mfma_f32_16x16x32_bf16 v[44:47], v[132:135], v[196:199], v[44:47]
	v_mfma_f32_16x16x32_bf16 v[40:43], v[140:143], v[196:199], v[40:43]
	v_mfma_f32_16x16x32_bf16 v[28:31], v[132:135], v[204:207], v[28:31]
	v_mfma_f32_16x16x32_bf16 v[24:27], v[140:143], v[204:207], v[24:27]
	v_mfma_f32_16x16x32_bf16 v[12:15], v[132:135], v[212:215], v[12:15]
	v_mfma_f32_16x16x32_bf16 v[8:11], v[140:143], v[212:215], v[8:11]
	s_setprio 0
	s_setprio 1
	v_mfma_f32_16x16x32_bf16 v[52:55], v[156:159], v[172:175], v[52:55]
	v_mfma_f32_16x16x32_bf16 v[48:51], v[164:167], v[172:175], v[48:51]
	v_mfma_f32_16x16x32_bf16 v[36:39], v[156:159], v[180:183], v[36:39]
	v_mfma_f32_16x16x32_bf16 v[32:35], v[164:167], v[180:183], v[32:35]
	v_mfma_f32_16x16x32_bf16 v[20:23], v[156:159], v[200:203], v[20:23]
	v_mfma_f32_16x16x32_bf16 v[16:19], v[164:167], v[200:203], v[16:19]
	v_mfma_f32_16x16x32_bf16 v[4:7], v[156:159], v[208:211], v[4:7]
	v_mfma_f32_16x16x32_bf16 v[0:3], v[164:167], v[208:211], v[0:3]
	v_mfma_f32_16x16x32_bf16 v[52:55], v[160:163], v[176:179], v[52:55]
	v_mfma_f32_16x16x32_bf16 v[48:51], v[168:171], v[176:179], v[48:51]
	v_mfma_f32_16x16x32_bf16 v[36:39], v[160:163], v[196:199], v[36:39]
	v_mfma_f32_16x16x32_bf16 v[32:35], v[168:171], v[196:199], v[32:35]
	v_mfma_f32_16x16x32_bf16 v[20:23], v[160:163], v[204:207], v[20:23]
	v_mfma_f32_16x16x32_bf16 v[16:19], v[168:171], v[204:207], v[16:19]
	v_mfma_f32_16x16x32_bf16 v[4:7], v[160:163], v[212:215], v[4:7]
	v_mfma_f32_16x16x32_bf16 v[0:3], v[168:171], v[212:215], v[0:3]
	s_setprio 0
	s_barrier
	s_add_i32 s58, s58, 2
	s_add_u32 s56, s56, 0x100
	s_addc_u32 s57, s57, 0
	s_add_u32 s30, s30, 0x100
	s_addc_u32 s31, s31, 0
	s_cmp_gt_u32 s58, 13
	s_cbranch_scc0 .LBB0_2118
	v_mbcnt_lo_u32_b32 v235, -1, 0
	v_mbcnt_hi_u32_b32 v235, -1, v235
	v_lshrrev_b32_e32 v236, 2, v235
	v_and_b32_e32 v237, 3, v235
	v_lshl_add_u32 v232, v237, 4, v236
	v_lshlrev_b32_e32 v232, 2, v232
	v_and_b32_e32 v233, -16, v186
	v_or_b32_e32 v233, v233, v236
	v_lshlrev_b32_e32 v237, 2, v237
	v_and_b32_e32 v234, -13, v188
	v_or_b32_e32 v234, v234, v237
	v_lshl_add_u32 v160, s26, 8, v233
	v_ashrrev_i32_e32 v161, 31, v160
	v_lshl_add_u64 v[158:159], v[160:161], 2, s[12:13]
	global_load_dword v169, v[158:159], off
	v_lshl_or_b32 v156, s28, 8, v234
	v_lshlrev_b64 v[128:129], 11, v[160:161]
	v_ashrrev_i32_e32 v157, 31, v156
	v_lshlrev_b64 v[132:133], 12, v[160:161]
	v_lshl_add_u64 v[128:129], s[6:7], 0, v[128:129]
	v_lshlrev_b64 v[130:131], 1, v[156:157]
	v_lshlrev_b64 v[134:135], 2, v[156:157]
	v_lshl_add_u64 v[132:133], s[4:5], 0, v[132:133]
	v_lshl_add_u64 v[128:129], v[128:129], 0, v[130:131]
	v_lshl_add_u64 v[166:167], v[132:133], 0, v[134:135]
	global_load_dwordx2 v[172:173], v[128:129], off
	global_load_dwordx2 v[176:177], v[128:129], off offset:32
	global_load_dwordx4 v[196:199], v[166:167], off
	global_load_dwordx4 v[200:203], v[166:167], off offset:64
	v_or_b32_e32 v162, 16, v160
	v_ashrrev_i32_e32 v163, 31, v162
	v_lshl_add_u64 v[138:139], v[162:163], 2, s[12:13]
	global_load_dword v168, v[138:139], off
	global_load_dwordx4 v[204:207], v[166:167], off offset:512
	global_load_dwordx4 v[208:211], v[166:167], off offset:576
	global_load_dwordx2 v[180:181], v[128:129], off offset:256
	global_load_dwordx2 v[184:185], v[128:129], off offset:288
	v_lshlrev_b64 v[132:133], 12, v[162:163]
	v_lshlrev_b64 v[136:137], 11, v[162:163]
	v_lshl_add_u64 v[132:133], s[4:5], 0, v[132:133]
	v_lshl_add_u64 v[136:137], s[6:7], 0, v[136:137]
	v_lshl_add_u64 v[164:165], v[132:133], 0, v[134:135]
	v_lshl_add_u64 v[170:171], v[136:137], 0, v[130:131]
	global_load_dwordx4 v[140:143], v[164:165], off
	global_load_dwordx4 v[136:139], v[164:165], off offset:64
	global_load_dwordx4 v[132:135], v[164:165], off offset:512
	global_load_dwordx4 v[128:131], v[164:165], off offset:576
	global_load_dwordx2 v[182:183], v[170:171], off
	global_load_dwordx2 v[178:179], v[170:171], off offset:32
	global_load_dwordx2 v[174:175], v[170:171], off offset:256
	s_nop 0
	global_load_dwordx2 v[170:171], v[170:171], off offset:288
	ds_bpermute_b32 v127, v232, v127
	ds_bpermute_b32 v126, v232, v126
	ds_bpermute_b32 v125, v232, v125
	ds_bpermute_b32 v124, v232, v124
	ds_bpermute_b32 v123, v232, v123
	ds_bpermute_b32 v122, v232, v122
	ds_bpermute_b32 v121, v232, v121
	ds_bpermute_b32 v120, v232, v120
	ds_bpermute_b32 v119, v232, v119
	ds_bpermute_b32 v118, v232, v118
	ds_bpermute_b32 v117, v232, v117
	ds_bpermute_b32 v116, v232, v116
	ds_bpermute_b32 v115, v232, v115
	ds_bpermute_b32 v114, v232, v114
	ds_bpermute_b32 v113, v232, v113
	ds_bpermute_b32 v112, v232, v112
	ds_bpermute_b32 v111, v232, v111
	ds_bpermute_b32 v110, v232, v110
	ds_bpermute_b32 v109, v232, v109
	ds_bpermute_b32 v108, v232, v108
	ds_bpermute_b32 v107, v232, v107
	ds_bpermute_b32 v106, v232, v106
	ds_bpermute_b32 v105, v232, v105
	ds_bpermute_b32 v104, v232, v104
	ds_bpermute_b32 v103, v232, v103
	ds_bpermute_b32 v102, v232, v102
	ds_bpermute_b32 v101, v232, v101
	ds_bpermute_b32 v100, v232, v100
	ds_bpermute_b32 v99, v232, v99
	ds_bpermute_b32 v98, v232, v98
	ds_bpermute_b32 v97, v232, v97
	ds_bpermute_b32 v96, v232, v96
	ds_bpermute_b32 v95, v232, v95
	ds_bpermute_b32 v94, v232, v94
	ds_bpermute_b32 v93, v232, v93
	ds_bpermute_b32 v92, v232, v92
	ds_bpermute_b32 v91, v232, v91
	ds_bpermute_b32 v90, v232, v90
	ds_bpermute_b32 v89, v232, v89
	ds_bpermute_b32 v88, v232, v88
	ds_bpermute_b32 v87, v232, v87
	ds_bpermute_b32 v86, v232, v86
	ds_bpermute_b32 v85, v232, v85
	ds_bpermute_b32 v84, v232, v84
	ds_bpermute_b32 v83, v232, v83
	ds_bpermute_b32 v82, v232, v82
	ds_bpermute_b32 v81, v232, v81
	ds_bpermute_b32 v80, v232, v80
	ds_bpermute_b32 v79, v232, v79
	ds_bpermute_b32 v78, v232, v78
	ds_bpermute_b32 v77, v232, v77
	ds_bpermute_b32 v76, v232, v76
	ds_bpermute_b32 v75, v232, v75
	ds_bpermute_b32 v74, v232, v74
	ds_bpermute_b32 v73, v232, v73
	ds_bpermute_b32 v72, v232, v72
	ds_bpermute_b32 v71, v232, v71
	ds_bpermute_b32 v70, v232, v70
	ds_bpermute_b32 v69, v232, v69
	ds_bpermute_b32 v68, v232, v68
	ds_bpermute_b32 v67, v232, v67
	ds_bpermute_b32 v66, v232, v66
	ds_bpermute_b32 v65, v232, v65
	ds_bpermute_b32 v64, v232, v64
	ds_bpermute_b32 v63, v232, v63
	ds_bpermute_b32 v62, v232, v62
	ds_bpermute_b32 v61, v232, v61
	ds_bpermute_b32 v60, v232, v60
	ds_bpermute_b32 v59, v232, v59
	ds_bpermute_b32 v58, v232, v58
	ds_bpermute_b32 v57, v232, v57
	ds_bpermute_b32 v56, v232, v56
	ds_bpermute_b32 v55, v232, v55
	ds_bpermute_b32 v54, v232, v54
	ds_bpermute_b32 v53, v232, v53
	ds_bpermute_b32 v52, v232, v52
	ds_bpermute_b32 v51, v232, v51
	ds_bpermute_b32 v50, v232, v50
	ds_bpermute_b32 v49, v232, v49
	ds_bpermute_b32 v48, v232, v48
	ds_bpermute_b32 v47, v232, v47
	ds_bpermute_b32 v46, v232, v46
	ds_bpermute_b32 v45, v232, v45
	ds_bpermute_b32 v44, v232, v44
	ds_bpermute_b32 v43, v232, v43
	ds_bpermute_b32 v42, v232, v42
	ds_bpermute_b32 v41, v232, v41
	ds_bpermute_b32 v40, v232, v40
	ds_bpermute_b32 v39, v232, v39
	ds_bpermute_b32 v38, v232, v38
	ds_bpermute_b32 v37, v232, v37
	ds_bpermute_b32 v36, v232, v36
	ds_bpermute_b32 v35, v232, v35
	ds_bpermute_b32 v34, v232, v34
	ds_bpermute_b32 v33, v232, v33
	ds_bpermute_b32 v32, v232, v32
	ds_bpermute_b32 v31, v232, v31
	ds_bpermute_b32 v30, v232, v30
	ds_bpermute_b32 v29, v232, v29
	ds_bpermute_b32 v28, v232, v28
	ds_bpermute_b32 v27, v232, v27
	ds_bpermute_b32 v26, v232, v26
	ds_bpermute_b32 v25, v232, v25
	ds_bpermute_b32 v24, v232, v24
	ds_bpermute_b32 v23, v232, v23
	ds_bpermute_b32 v22, v232, v22
	ds_bpermute_b32 v21, v232, v21
	ds_bpermute_b32 v20, v232, v20
	ds_bpermute_b32 v19, v232, v19
	ds_bpermute_b32 v18, v232, v18
	ds_bpermute_b32 v17, v232, v17
	ds_bpermute_b32 v16, v232, v16
	ds_bpermute_b32 v15, v232, v15
	ds_bpermute_b32 v14, v232, v14
	ds_bpermute_b32 v13, v232, v13
	ds_bpermute_b32 v12, v232, v12
	ds_bpermute_b32 v11, v232, v11
	ds_bpermute_b32 v10, v232, v10
	ds_bpermute_b32 v9, v232, v9
	ds_bpermute_b32 v8, v232, v8
	ds_bpermute_b32 v7, v232, v7
	ds_bpermute_b32 v6, v232, v6
	ds_bpermute_b32 v5, v232, v5
	ds_bpermute_b32 v4, v232, v4
	ds_bpermute_b32 v3, v232, v3
	ds_bpermute_b32 v2, v232, v2
	ds_bpermute_b32 v1, v232, v1
	ds_bpermute_b32 v0, v232, v0
	s_waitcnt lgkmcnt(0)
	s_waitcnt lgkmcnt(0)
	s_and_b64 vcc, exec, s[16:17]
	s_cbranch_vccz .LBB0_2121
	s_barrier
.LBB0_2121:
	s_waitcnt vmcnt(17)
	v_fmamk_f32 v169, v169, 0x3a800000, v193
	v_mul_f32_e32 v195, 0x4b800000, v169
	v_cmp_gt_f32_e32 vcc, s55, v169
	s_waitcnt vmcnt(16)
	v_lshlrev_b32_e32 v212, 16, v172
	s_nop 0
	v_cndmask_b32_e32 v169, v169, v195, vcc
	v_rsq_f32_e32 v169, v169
	v_and_b32_e32 v213, 0xffff0000, v172
	v_lshlrev_b32_e32 v172, 16, v173
	v_and_b32_e32 v173, 0xffff0000, v173
	v_mul_f32_e32 v195, 0x45800000, v169
	v_cndmask_b32_e32 v216, v169, v195, vcc
	v_pk_mul_f32 v[126:127], v[126:127], v[216:217] op_sel_hi:[1,0]
	v_pk_mul_f32 v[124:125], v[124:125], v[216:217] op_sel_hi:[1,0]
	v_pk_mul_f32 v[116:117], v[116:117], v[216:217] op_sel_hi:[1,0]
	v_pk_mul_f32 v[218:219], v[118:119], v[216:217] op_sel_hi:[1,0]
	v_mul_f32_e32 v119, 0xbfb8aa3b, v125
	v_mul_f32_e32 v125, 0xbfb8aa3b, v127
	v_mul_f32_e32 v117, 0xbfb8aa3b, v117
	v_mul_f32_e32 v118, 0xbfb8aa3b, v124
	v_mul_f32_e32 v124, 0xbfb8aa3b, v126
	v_exp_f32_e32 v119, v119
	v_exp_f32_e32 v125, v125
	v_exp_f32_e32 v127, v117
	v_exp_f32_e32 v118, v118
	v_exp_f32_e32 v124, v124
	v_mul_f32_e32 v116, 0xbfb8aa3b, v116
	v_add_f32_e32 v117, 1.0, v119
	v_add_f32_e32 v119, 1.0, v125
	v_add_f32_e32 v125, 1.0, v127
	v_mul_f32_e32 v127, 0xbfb8aa3b, v218
	v_exp_f32_e32 v126, v116
	v_add_f32_e32 v116, 1.0, v118
	v_add_f32_e32 v118, 1.0, v124
	v_exp_f32_e32 v169, v127
	v_mul_f32_e32 v127, 0xbfb8aa3b, v219
	v_rcp_f32_e32 v118, v118
	v_rcp_f32_e32 v119, v119
	v_exp_f32_e32 v195, v127
	v_add_f32_e32 v169, 1.0, v169
	v_pk_mul_f32 v[112:113], v[112:113], v[216:217] op_sel_hi:[1,0]
	s_waitcnt vmcnt(14)
	v_pk_fma_f32 v[118:119], v[118:119], v[172:173], v[198:199]
	v_rcp_f32_e32 v198, v169
	v_add_f32_e32 v169, 1.0, v195
	v_mul_f32_e32 v112, 0xbfb8aa3b, v112
	v_rcp_f32_e32 v199, v169
	v_exp_f32_e32 v169, v112
	v_mul_f32_e32 v112, 0xbfb8aa3b, v113
	v_pk_mul_f32 v[122:123], v[122:123], v[216:217] op_sel_hi:[1,0]
	v_pk_mul_f32 v[120:121], v[120:121], v[216:217] op_sel_hi:[1,0]
	v_exp_f32_e32 v195, v112
	v_pk_mul_f32 v[112:113], v[114:115], v[216:217] op_sel_hi:[1,0]
	v_mul_f32_e32 v120, 0xbfb8aa3b, v120
	v_mul_f32_e32 v121, 0xbfb8aa3b, v121
	v_mul_f32_e32 v122, 0xbfb8aa3b, v122
	v_mul_f32_e32 v123, 0xbfb8aa3b, v123
	v_mul_f32_e32 v112, 0xbfb8aa3b, v112
	v_mul_f32_e32 v113, 0xbfb8aa3b, v113
	v_exp_f32_e32 v120, v120
	v_exp_f32_e32 v121, v121
	v_exp_f32_e32 v122, v122
	v_exp_f32_e32 v123, v123
	v_exp_f32_e32 v112, v112
	v_exp_f32_e32 v113, v113
	v_add_f32_e32 v124, 1.0, v126
	v_rcp_f32_e32 v124, v124
	v_rcp_f32_e32 v125, v125
	v_add_f32_e32 v114, 1.0, v169
	v_add_f32_e32 v115, 1.0, v195
	v_add_f32_e32 v120, 1.0, v120
	v_add_f32_e32 v121, 1.0, v121
	v_add_f32_e32 v122, 1.0, v122
	v_add_f32_e32 v123, 1.0, v123
	v_rcp_f32_e32 v114, v114
	v_rcp_f32_e32 v115, v115
	v_add_f32_e32 v112, 1.0, v112
	v_add_f32_e32 v113, 1.0, v113
	v_rcp_f32_e32 v116, v116
	v_rcp_f32_e32 v117, v117
	v_rcp_f32_e32 v120, v120
	v_rcp_f32_e32 v121, v121
	v_rcp_f32_e32 v122, v122
	v_rcp_f32_e32 v123, v123
	s_waitcnt vmcnt(9)
	v_lshlrev_b32_e32 v126, 16, v180
	v_and_b32_e32 v127, 0xffff0000, v180
	v_rcp_f32_e32 v112, v112
	v_rcp_f32_e32 v113, v113
	v_pk_fma_f32 v[124:125], v[124:125], v[126:127], v[204:205]
	v_lshlrev_b32_e32 v126, 16, v181
	v_and_b32_e32 v127, 0xffff0000, v181
	v_pk_fma_f32 v[126:127], v[198:199], v[126:127], v[206:207]
	s_waitcnt vmcnt(8)
	v_lshlrev_b32_e32 v198, 16, v184
	v_and_b32_e32 v199, 0xffff0000, v184
	v_lshlrev_b32_e32 v214, 16, v176
	v_and_b32_e32 v215, 0xffff0000, v176
	v_lshlrev_b32_e32 v176, 16, v177
	v_and_b32_e32 v177, 0xffff0000, v177
	v_pk_fma_f32 v[198:199], v[114:115], v[198:199], v[208:209]
	v_lshlrev_b32_e32 v114, 16, v185
	v_and_b32_e32 v115, 0xffff0000, v185
	v_pk_fma_f32 v[116:117], v[116:117], v[212:213], v[196:197]
	v_pk_fma_f32 v[120:121], v[120:121], v[214:215], v[200:201]
	v_pk_fma_f32 v[122:123], v[122:123], v[176:177], v[202:203]
	v_pk_fma_f32 v[200:201], v[112:113], v[114:115], v[210:211]
	v_pk_mul_f32 v[172:173], v[116:117], v[116:117]
	v_pk_mul_f32 v[176:177], v[118:119], v[118:119]
	v_pk_mul_f32 v[196:197], v[120:121], v[120:121]
	v_pk_mul_f32 v[202:203], v[122:123], v[122:123]
	v_pk_mul_f32 v[112:113], v[198:199], v[198:199]
	v_pk_mul_f32 v[114:115], v[200:201], v[200:201]
	v_add_f32_e32 v169, v202, v203
	v_add_f32_e32 v184, v196, v197
	v_add_f32_e32 v176, v176, v177
	v_add_f32_e32 v172, v172, v173
	v_add_f32_e32 v114, v114, v115
	v_add_f32_e32 v112, v112, v113
	v_pk_mul_f32 v[180:181], v[124:125], v[124:125]
	v_pk_mul_f32 v[204:205], v[126:127], v[126:127]
	v_add_f32_e32 v169, v184, v169
	v_add_f32_e32 v172, v172, v176
	v_add_f32_e32 v112, v112, v114
	v_and_b32_e32 v114, 64, v194
	v_add_f32_e32 v169, v172, v169
	v_add_f32_e32 v172, v204, v205
	v_add_f32_e32 v173, v180, v181
	v_xor_b32_e32 v113, 1, v194
	v_add_u32_e32 v114, 64, v114
	v_add_f32_e32 v172, v173, v172
	v_cmp_lt_i32_e32 vcc, v113, v114
	v_add_f32_e32 v169, v172, v169
	v_add_f32_e32 v112, v112, v169
	v_cndmask_b32_e32 v113, v194, v113, vcc
	v_lshlrev_b32_e32 v195, 2, v113
	s_nop 1
	v_mov_b32_dpp v113, v112 quad_perm:[1,0,3,2] row_mask:0xf bank_mask:0xf
	global_store_dwordx4 v[166:167], v[116:119], off
	global_store_dwordx4 v[166:167], v[120:123], off offset:64
	global_store_dwordx4 v[166:167], v[124:127], off offset:512
	global_store_dwordx4 v[166:167], v[198:201], off offset:576
	s_waitcnt lgkmcnt(0)
	v_add_f32_e32 v112, v112, v113
	v_xor_b32_e32 v113, 2, v194
	v_cmp_lt_i32_e32 vcc, v113, v114
	s_nop 1
	v_cndmask_b32_e32 v113, v194, v113, vcc
	v_lshlrev_b32_e32 v196, 2, v113
	s_nop 1
	v_mov_b32_dpp v113, v112 quad_perm:[2,3,0,1] row_mask:0xf bank_mask:0xf
	s_mov_b32 vcc_lo, 0x11111111
	s_mov_b32 vcc_hi, 0x11111111
	s_and_saveexec_b64 s[26:27], vcc
	s_cbranch_execz .LBB0_2123
	v_lshl_add_u64 v[114:115], v[160:161], 2, s[10:11]
	s_waitcnt lgkmcnt(0)
	v_add_f32_e32 v112, v112, v113
	global_atomic_add_f32 v[114:115], v112, off
.LBB0_2123:
	s_or_b64 exec, exec, s[26:27]
	v_fmamk_f32 v112, v168, 0x3a800000, v193
	s_waitcnt lgkmcnt(0)
	v_mul_f32_e32 v113, 0x4b800000, v112
	v_cmp_gt_f32_e32 vcc, s55, v112
	v_or_b32_e32 v166, 32, v160
	v_ashrrev_i32_e32 v167, 31, v166
	v_cndmask_b32_e32 v112, v112, v113, vcc
	v_rsq_f32_e32 v112, v112
	v_lshlrev_b64 v[114:115], 11, v[166:167]
	v_lshl_add_u64 v[114:115], s[6:7], 0, v[114:115]
	v_mul_f32_e32 v113, 0x45800000, v112
	v_cndmask_b32_e32 v198, v112, v113, vcc
	v_lshlrev_b64 v[112:113], 12, v[166:167]
	v_lshl_add_u64 v[112:113], s[4:5], 0, v[112:113]
	v_lshl_add_u64 v[168:169], v[156:157], 2, v[112:113]
	v_lshl_add_u64 v[172:173], v[156:157], 1, v[114:115]
	global_load_dwordx4 v[124:127], v[168:169], off
	global_load_dwordx4 v[120:123], v[168:169], off offset:64
	global_load_dwordx4 v[116:119], v[168:169], off offset:512
	global_load_dwordx4 v[112:115], v[168:169], off offset:576
	global_load_dwordx2 v[184:185], v[172:173], off
	global_load_dwordx2 v[180:181], v[172:173], off offset:32
	global_load_dwordx2 v[176:177], v[172:173], off offset:256
	s_nop 0
	global_load_dwordx2 v[172:173], v[172:173], off offset:288
	v_lshl_add_u64 v[200:201], v[166:167], 2, s[12:13]
	global_load_dword v161, v[200:201], off
	v_pk_mul_f32 v[108:109], v[108:109], v[198:199] op_sel_hi:[1,0]
	s_waitcnt vmcnt(16)
	v_lshlrev_b32_e32 v200, 16, v182
	v_mul_f32_e32 v108, 0xbfb8aa3b, v108
	v_exp_f32_e32 v197, v108
	v_mul_f32_e32 v108, 0xbfb8aa3b, v109
	v_exp_f32_e32 v199, v108
	v_and_b32_e32 v201, 0xffff0000, v182
	v_pk_mul_f32 v[108:109], v[110:111], v[198:199] op_sel_hi:[1,0]
	s_nop 0
	v_mul_f32_e32 v108, 0xbfb8aa3b, v108
	v_exp_f32_e32 v108, v108
	v_mul_f32_e32 v109, 0xbfb8aa3b, v109
	v_add_f32_e32 v110, 1.0, v197
	v_add_f32_e32 v111, 1.0, v199
	v_exp_f32_e32 v109, v109
	v_rcp_f32_e32 v110, v110
	v_rcp_f32_e32 v111, v111
	v_pk_mul_f32 v[104:105], v[104:105], v[198:199] op_sel_hi:[1,0]
	v_add_f32_e32 v108, 1.0, v108
	v_mul_f32_e32 v104, 0xbfb8aa3b, v104
	v_rcp_f32_e32 v202, v108
	v_add_f32_e32 v108, 1.0, v109
	v_exp_f32_e32 v182, v104
	v_mul_f32_e32 v104, 0xbfb8aa3b, v105
	v_rcp_f32_e32 v203, v108
	v_pk_fma_f32 v[108:109], v[110:111], v[200:201], v[140:141]
	v_lshlrev_b32_e32 v110, 16, v183
	v_and_b32_e32 v111, 0xffff0000, v183
	v_exp_f32_e32 v183, v104
	v_pk_mul_f32 v[104:105], v[106:107], v[198:199] op_sel_hi:[1,0]
	v_add_f32_e32 v106, 1.0, v182
	v_mul_f32_e32 v104, 0xbfb8aa3b, v104
	v_exp_f32_e32 v104, v104
	v_mul_f32_e32 v105, 0xbfb8aa3b, v105
	v_add_f32_e32 v107, 1.0, v183
	v_exp_f32_e32 v105, v105
	v_rcp_f32_e32 v106, v106
	v_rcp_f32_e32 v107, v107
	v_pk_mul_f32 v[100:101], v[100:101], v[198:199] op_sel_hi:[1,0]
	v_add_f32_e32 v104, 1.0, v104
	v_mul_f32_e32 v100, 0xbfb8aa3b, v100
	s_waitcnt vmcnt(15)
	v_lshlrev_b32_e32 v182, 16, v178
	v_and_b32_e32 v183, 0xffff0000, v178
	v_rcp_f32_e32 v200, v104
	v_add_f32_e32 v104, 1.0, v105
	v_exp_f32_e32 v178, v100
	v_mul_f32_e32 v100, 0xbfb8aa3b, v101
	v_rcp_f32_e32 v201, v104
	v_pk_fma_f32 v[104:105], v[106:107], v[182:183], v[136:137]
	v_lshlrev_b32_e32 v106, 16, v179
	v_and_b32_e32 v107, 0xffff0000, v179
	v_exp_f32_e32 v179, v100
	v_pk_mul_f32 v[100:101], v[102:103], v[198:199] op_sel_hi:[1,0]
	v_add_f32_e32 v102, 1.0, v178
	v_mul_f32_e32 v100, 0xbfb8aa3b, v100
	v_exp_f32_e32 v100, v100
	v_mul_f32_e32 v101, 0xbfb8aa3b, v101
	v_add_f32_e32 v103, 1.0, v179
	v_exp_f32_e32 v101, v101
	v_rcp_f32_e32 v102, v102
	v_rcp_f32_e32 v103, v103
	v_pk_mul_f32 v[96:97], v[96:97], v[198:199] op_sel_hi:[1,0]
	v_add_f32_e32 v100, 1.0, v100
	v_mul_f32_e32 v96, 0xbfb8aa3b, v96
	s_waitcnt vmcnt(14)
	v_lshlrev_b32_e32 v178, 16, v174
	v_and_b32_e32 v179, 0xffff0000, v174
	v_rcp_f32_e32 v182, v100
	v_add_f32_e32 v100, 1.0, v101
	v_exp_f32_e32 v174, v96
	v_mul_f32_e32 v96, 0xbfb8aa3b, v97
	v_rcp_f32_e32 v183, v100
	v_pk_fma_f32 v[100:101], v[102:103], v[178:179], v[132:133]
	v_lshlrev_b32_e32 v102, 16, v175
	v_and_b32_e32 v103, 0xffff0000, v175
	v_exp_f32_e32 v175, v96
	v_pk_mul_f32 v[96:97], v[98:99], v[198:199] op_sel_hi:[1,0]
	v_add_f32_e32 v98, 1.0, v174
	v_mul_f32_e32 v96, 0xbfb8aa3b, v96
	v_mul_f32_e32 v97, 0xbfb8aa3b, v97
	v_exp_f32_e32 v96, v96
	v_exp_f32_e32 v97, v97
	v_add_f32_e32 v99, 1.0, v175
	v_rcp_f32_e32 v98, v98
	v_rcp_f32_e32 v99, v99
	v_add_f32_e32 v96, 1.0, v96
	v_add_f32_e32 v97, 1.0, v97
	v_rcp_f32_e32 v96, v96
	v_rcp_f32_e32 v97, v97
	v_pk_fma_f32 v[106:107], v[200:201], v[106:107], v[138:139]
	v_pk_fma_f32 v[110:111], v[202:203], v[110:111], v[142:143]
	v_pk_mul_f32 v[136:137], v[104:105], v[104:105]
	v_pk_mul_f32 v[138:139], v[106:107], v[106:107]
	s_waitcnt vmcnt(13)
	v_lshlrev_b32_e32 v174, 16, v170
	v_and_b32_e32 v175, 0xffff0000, v170
	v_pk_mul_f32 v[140:141], v[108:109], v[108:109]
	v_pk_mul_f32 v[142:143], v[110:111], v[110:111]
	v_pk_fma_f32 v[102:103], v[182:183], v[102:103], v[134:135]
	v_pk_fma_f32 v[128:129], v[98:99], v[174:175], v[128:129]
	v_lshlrev_b32_e32 v98, 16, v171
	v_and_b32_e32 v99, 0xffff0000, v171
	v_add_f32_e32 v138, v138, v139
	v_add_f32_e32 v136, v136, v137
	v_pk_mul_f32 v[132:133], v[100:101], v[100:101]
	v_pk_mul_f32 v[134:135], v[102:103], v[102:103]
	v_pk_fma_f32 v[130:131], v[96:97], v[98:99], v[130:131]
	v_add_f32_e32 v136, v136, v138
	v_add_f32_e32 v137, v142, v143
	v_add_f32_e32 v138, v140, v141
	v_pk_mul_f32 v[96:97], v[128:129], v[128:129]
	v_pk_mul_f32 v[98:99], v[130:131], v[130:131]
	v_add_f32_e32 v137, v138, v137
	v_add_f32_e32 v134, v134, v135
	v_add_f32_e32 v132, v132, v133
	v_add_f32_e32 v136, v137, v136
	v_add_f32_e32 v132, v132, v134
	v_add_f32_e32 v98, v98, v99
	v_add_f32_e32 v96, v96, v97
	v_add_f32_e32 v132, v132, v136
	v_add_f32_e32 v96, v96, v98
	v_add_f32_e32 v96, v96, v132
	s_nop 1
	v_mov_b32_dpp v97, v96 quad_perm:[1,0,3,2] row_mask:0xf bank_mask:0xf
	global_store_dwordx4 v[164:165], v[108:111], off
	global_store_dwordx4 v[164:165], v[104:107], off offset:64
	global_store_dwordx4 v[164:165], v[100:103], off offset:512
	global_store_dwordx4 v[164:165], v[128:131], off offset:576
	s_waitcnt lgkmcnt(0)
	v_add_f32_e32 v96, v96, v97
	s_nop 1
	v_mov_b32_dpp v97, v96 quad_perm:[2,3,0,1] row_mask:0xf bank_mask:0xf
	s_mov_b32 vcc_lo, 0x11111111
	s_mov_b32 vcc_hi, 0x11111111
	s_and_saveexec_b64 s[26:27], vcc
	s_cbranch_execz .LBB0_2125
	v_lshl_add_u64 v[98:99], v[162:163], 2, s[10:11]
	s_waitcnt lgkmcnt(0)
	v_add_f32_e32 v96, v96, v97
	global_atomic_add_f32 v[98:99], v96, off
.LBB0_2125:
	s_or_b64 exec, exec, s[26:27]
	s_waitcnt vmcnt(4)
	v_fmamk_f32 v96, v161, 0x3a800000, v193
	s_waitcnt lgkmcnt(0)
	v_mul_f32_e32 v97, 0x4b800000, v96
	v_cmp_gt_f32_e32 vcc, s55, v96
	v_or_b32_e32 v128, 48, v160
	v_ashrrev_i32_e32 v129, 31, v128
	v_cndmask_b32_e32 v96, v96, v97, vcc
	v_rsq_f32_e32 v96, v96
	v_lshlrev_b64 v[98:99], 11, v[128:129]
	v_lshl_add_u64 v[98:99], s[6:7], 0, v[98:99]
	v_mul_f32_e32 v97, 0x45800000, v96
	v_cndmask_b32_e32 v142, v96, v97, vcc
	v_lshlrev_b64 v[96:97], 12, v[128:129]
	v_lshl_add_u64 v[96:97], s[4:5], 0, v[96:97]
	v_lshl_add_u64 v[130:131], v[156:157], 2, v[96:97]
	v_lshl_add_u64 v[132:133], v[156:157], 1, v[98:99]
	global_load_dwordx4 v[108:111], v[130:131], off
	global_load_dwordx4 v[104:107], v[130:131], off offset:64
	global_load_dwordx4 v[100:103], v[130:131], off offset:512
	global_load_dwordx4 v[96:99], v[130:131], off offset:576
	global_load_dwordx2 v[138:139], v[132:133], off
	global_load_dwordx2 v[136:137], v[132:133], off offset:32
	global_load_dwordx2 v[134:135], v[132:133], off offset:256
	s_nop 0
	global_load_dwordx2 v[132:133], v[132:133], off offset:288
	v_lshl_add_u64 v[140:141], v[128:129], 2, s[12:13]
	global_load_dword v140, v[140:141], off
	v_pk_mul_f32 v[92:93], v[92:93], v[142:143] op_sel_hi:[1,0]
	v_lshlrev_b32_e32 v162, 16, v184
	v_mul_f32_e32 v92, 0xbfb8aa3b, v92
	v_exp_f32_e32 v141, v92
	v_mul_f32_e32 v92, 0xbfb8aa3b, v93
	v_exp_f32_e32 v143, v92
	v_and_b32_e32 v163, 0xffff0000, v184
	v_pk_mul_f32 v[88:89], v[88:89], v[142:143] op_sel_hi:[1,0]
	s_nop 0
	v_mul_f32_e32 v88, 0xbfb8aa3b, v88
	v_pk_mul_f32 v[92:93], v[94:95], v[142:143] op_sel_hi:[1,0]
	v_add_f32_e32 v94, 1.0, v141
	v_exp_f32_e32 v141, v88
	v_mul_f32_e32 v88, 0xbfb8aa3b, v89
	v_add_f32_e32 v95, 1.0, v143
	v_exp_f32_e32 v143, v88
	v_mul_f32_e32 v92, 0xbfb8aa3b, v92
	v_exp_f32_e32 v92, v92
	v_mul_f32_e32 v93, 0xbfb8aa3b, v93
	v_pk_mul_f32 v[84:85], v[84:85], v[142:143] op_sel_hi:[1,0]
	v_pk_mul_f32 v[88:89], v[90:91], v[142:143] op_sel_hi:[1,0]
	v_mul_f32_e32 v84, 0xbfb8aa3b, v84
	v_add_f32_e32 v90, 1.0, v141
	v_exp_f32_e32 v141, v84
	v_mul_f32_e32 v84, 0xbfb8aa3b, v85
	v_add_f32_e32 v91, 1.0, v143
	v_exp_f32_e32 v143, v84
	v_exp_f32_e32 v93, v93
	v_add_f32_e32 v92, 1.0, v92
	v_mul_f32_e32 v88, 0xbfb8aa3b, v88
	v_pk_mul_f32 v[80:81], v[80:81], v[142:143] op_sel_hi:[1,0]
	v_rcp_f32_e32 v94, v94
	v_mul_f32_e32 v80, 0xbfb8aa3b, v80
	v_rcp_f32_e32 v95, v95
	v_rcp_f32_e32 v164, v92
	v_add_f32_e32 v92, 1.0, v93
	v_exp_f32_e32 v88, v88
	v_mul_f32_e32 v89, 0xbfb8aa3b, v89
	v_pk_mul_f32 v[84:85], v[86:87], v[142:143] op_sel_hi:[1,0]
	v_add_f32_e32 v86, 1.0, v141
	v_exp_f32_e32 v141, v80
	v_mul_f32_e32 v80, 0xbfb8aa3b, v81
	v_rcp_f32_e32 v165, v92
	v_exp_f32_e32 v89, v89
	v_add_f32_e32 v87, 1.0, v143
	v_exp_f32_e32 v143, v80
	v_pk_fma_f32 v[92:93], v[94:95], v[162:163], v[124:125]
	v_lshlrev_b32_e32 v94, 16, v185
	v_and_b32_e32 v95, 0xffff0000, v185
	v_add_f32_e32 v88, 1.0, v88
	v_mul_f32_e32 v84, 0xbfb8aa3b, v84
	v_pk_fma_f32 v[94:95], v[164:165], v[94:95], v[126:127]
	v_rcp_f32_e32 v90, v90
	v_rcp_f32_e32 v91, v91
	v_rcp_f32_e32 v164, v88
	v_add_f32_e32 v88, 1.0, v89
	v_exp_f32_e32 v84, v84
	v_mul_f32_e32 v85, 0xbfb8aa3b, v85
	v_pk_mul_f32 v[80:81], v[82:83], v[142:143] op_sel_hi:[1,0]
	v_rcp_f32_e32 v165, v88
	v_exp_f32_e32 v85, v85
	v_mul_f32_e32 v80, 0xbfb8aa3b, v80
	v_mul_f32_e32 v81, 0xbfb8aa3b, v81
	v_exp_f32_e32 v80, v80
	v_exp_f32_e32 v81, v81
	v_lshlrev_b32_e32 v162, 16, v180
	v_and_b32_e32 v163, 0xffff0000, v180
	v_pk_fma_f32 v[88:89], v[90:91], v[162:163], v[120:121]
	v_lshlrev_b32_e32 v90, 16, v181
	v_and_b32_e32 v91, 0xffff0000, v181
	v_add_f32_e32 v84, 1.0, v84
	v_pk_fma_f32 v[90:91], v[164:165], v[90:91], v[122:123]
	v_rcp_f32_e32 v86, v86
	v_rcp_f32_e32 v87, v87
	v_rcp_f32_e32 v164, v84
	v_add_f32_e32 v84, 1.0, v85
	v_add_f32_e32 v82, 1.0, v141
	v_add_f32_e32 v83, 1.0, v143
	v_rcp_f32_e32 v165, v84
	v_rcp_f32_e32 v82, v82
	v_rcp_f32_e32 v83, v83
	v_add_f32_e32 v80, 1.0, v80
	v_add_f32_e32 v81, 1.0, v81
	v_rcp_f32_e32 v80, v80
	v_rcp_f32_e32 v81, v81
	v_lshlrev_b32_e32 v162, 16, v176
	v_and_b32_e32 v163, 0xffff0000, v176
	v_pk_mul_f32 v[120:121], v[88:89], v[88:89]
	v_pk_mul_f32 v[122:123], v[90:91], v[90:91]
	v_pk_fma_f32 v[84:85], v[86:87], v[162:163], v[116:117]
	v_lshlrev_b32_e32 v86, 16, v177
	v_and_b32_e32 v87, 0xffff0000, v177
	v_lshlrev_b32_e32 v142, 16, v172
	v_and_b32_e32 v143, 0xffff0000, v172
	v_pk_mul_f32 v[124:125], v[92:93], v[92:93]
	v_pk_mul_f32 v[126:127], v[94:95], v[94:95]
	v_pk_fma_f32 v[86:87], v[164:165], v[86:87], v[118:119]
	v_pk_fma_f32 v[112:113], v[82:83], v[142:143], v[112:113]
	v_lshlrev_b32_e32 v82, 16, v173
	v_and_b32_e32 v83, 0xffff0000, v173
	v_add_f32_e32 v122, v122, v123
	v_add_f32_e32 v120, v120, v121
	v_pk_mul_f32 v[116:117], v[84:85], v[84:85]
	v_pk_mul_f32 v[118:119], v[86:87], v[86:87]
	v_pk_fma_f32 v[114:115], v[80:81], v[82:83], v[114:115]
	v_add_f32_e32 v120, v120, v122
	v_add_f32_e32 v121, v126, v127
	v_add_f32_e32 v122, v124, v125
	v_pk_mul_f32 v[80:81], v[112:113], v[112:113]
	v_pk_mul_f32 v[82:83], v[114:115], v[114:115]
	v_add_f32_e32 v121, v122, v121
	v_add_f32_e32 v118, v118, v119
	v_add_f32_e32 v116, v116, v117
	v_add_f32_e32 v120, v121, v120
	v_add_f32_e32 v116, v116, v118
	v_add_f32_e32 v82, v82, v83
	v_add_f32_e32 v80, v80, v81
	v_add_f32_e32 v116, v116, v120
	v_add_f32_e32 v80, v80, v82
	v_add_f32_e32 v80, v80, v116
	s_nop 1
	v_mov_b32_dpp v81, v80 quad_perm:[1,0,3,2] row_mask:0xf bank_mask:0xf
	global_store_dwordx4 v[168:169], v[92:95], off
	global_store_dwordx4 v[168:169], v[88:91], off offset:64
	global_store_dwordx4 v[168:169], v[84:87], off offset:512
	global_store_dwordx4 v[168:169], v[112:115], off offset:576
	s_waitcnt lgkmcnt(0)
	v_add_f32_e32 v80, v80, v81
	s_nop 1
	v_mov_b32_dpp v81, v80 quad_perm:[2,3,0,1] row_mask:0xf bank_mask:0xf
	s_mov_b32 vcc_lo, 0x11111111
	s_mov_b32 vcc_hi, 0x11111111
	s_and_saveexec_b64 s[26:27], vcc
	s_cbranch_execz .LBB0_2127
	v_lshl_add_u64 v[82:83], v[166:167], 2, s[10:11]
	s_waitcnt lgkmcnt(0)
	v_add_f32_e32 v80, v80, v81
	global_atomic_add_f32 v[82:83], v80, off
.LBB0_2127:
	s_or_b64 exec, exec, s[26:27]
	s_waitcnt vmcnt(4)
	v_fmamk_f32 v80, v140, 0x3a800000, v193
	s_waitcnt lgkmcnt(0)
	v_mul_f32_e32 v81, 0x4b800000, v80
	v_cmp_gt_f32_e32 vcc, s55, v80
	v_add_u32_e32 v112, 0x80, v160
	v_ashrrev_i32_e32 v113, 31, v112
	v_cndmask_b32_e32 v80, v80, v81, vcc
	v_rsq_f32_e32 v80, v80
	v_lshlrev_b64 v[82:83], 11, v[112:113]
	v_lshl_add_u64 v[82:83], s[6:7], 0, v[82:83]
	v_mul_f32_e32 v81, 0x45800000, v80
	v_cndmask_b32_e32 v126, v80, v81, vcc
	v_lshlrev_b64 v[80:81], 12, v[112:113]
	v_lshl_add_u64 v[80:81], s[4:5], 0, v[80:81]
	v_lshl_add_u64 v[114:115], v[156:157], 2, v[80:81]
	v_lshl_add_u64 v[116:117], v[156:157], 1, v[82:83]
	global_load_dwordx4 v[92:95], v[114:115], off
	global_load_dwordx4 v[88:91], v[114:115], off offset:64
	global_load_dwordx4 v[84:87], v[114:115], off offset:512
	global_load_dwordx4 v[80:83], v[114:115], off offset:576
	global_load_dwordx2 v[122:123], v[116:117], off
	global_load_dwordx2 v[120:121], v[116:117], off offset:32
	global_load_dwordx2 v[118:119], v[116:117], off offset:256
	s_nop 0
	global_load_dwordx2 v[116:117], v[116:117], off offset:288
	s_nop 0
	global_load_dword v124, v[158:159], off offset:512
	v_pk_mul_f32 v[76:77], v[76:77], v[126:127] op_sel_hi:[1,0]
	v_lshlrev_b32_e32 v140, 16, v138
	v_mul_f32_e32 v76, 0xbfb8aa3b, v76
	v_exp_f32_e32 v125, v76
	v_mul_f32_e32 v76, 0xbfb8aa3b, v77
	v_exp_f32_e32 v127, v76
	v_and_b32_e32 v141, 0xffff0000, v138
	v_lshlrev_b32_e32 v138, 16, v136
	v_pk_mul_f32 v[72:73], v[72:73], v[126:127] op_sel_hi:[1,0]
	v_pk_mul_f32 v[76:77], v[78:79], v[126:127] op_sel_hi:[1,0]
	v_mul_f32_e32 v72, 0xbfb8aa3b, v72
	v_add_f32_e32 v78, 1.0, v125
	v_exp_f32_e32 v125, v72
	v_mul_f32_e32 v72, 0xbfb8aa3b, v73
	v_add_f32_e32 v79, 1.0, v127
	v_exp_f32_e32 v127, v72
	v_mul_f32_e32 v76, 0xbfb8aa3b, v76
	v_exp_f32_e32 v76, v76
	v_mul_f32_e32 v77, 0xbfb8aa3b, v77
	v_pk_mul_f32 v[68:69], v[68:69], v[126:127] op_sel_hi:[1,0]
	v_pk_mul_f32 v[72:73], v[74:75], v[126:127] op_sel_hi:[1,0]
	v_mul_f32_e32 v68, 0xbfb8aa3b, v68
	v_add_f32_e32 v74, 1.0, v125
	v_exp_f32_e32 v125, v68
	v_mul_f32_e32 v68, 0xbfb8aa3b, v69
	v_add_f32_e32 v75, 1.0, v127
	v_exp_f32_e32 v127, v68
	v_mul_f32_e32 v72, 0xbfb8aa3b, v72
	v_exp_f32_e32 v77, v77
	v_exp_f32_e32 v72, v72
	v_pk_mul_f32 v[64:65], v[64:65], v[126:127] op_sel_hi:[1,0]
	v_pk_mul_f32 v[68:69], v[70:71], v[126:127] op_sel_hi:[1,0]
	v_mul_f32_e32 v64, 0xbfb8aa3b, v64
	v_add_f32_e32 v70, 1.0, v125
	v_exp_f32_e32 v125, v64
	v_mul_f32_e32 v64, 0xbfb8aa3b, v65
	v_add_f32_e32 v71, 1.0, v127
	v_exp_f32_e32 v127, v64
	v_mul_f32_e32 v73, 0xbfb8aa3b, v73
	v_rcp_f32_e32 v78, v78
	v_rcp_f32_e32 v79, v79
	v_exp_f32_e32 v73, v73
	v_mul_f32_e32 v68, 0xbfb8aa3b, v68
	v_exp_f32_e32 v68, v68
	v_mul_f32_e32 v69, 0xbfb8aa3b, v69
	v_pk_mul_f32 v[64:65], v[66:67], v[126:127] op_sel_hi:[1,0]
	v_add_f32_e32 v76, 1.0, v76
	v_rcp_f32_e32 v74, v74
	v_rcp_f32_e32 v75, v75
	v_exp_f32_e32 v69, v69
	v_mul_f32_e32 v64, 0xbfb8aa3b, v64
	v_mul_f32_e32 v65, 0xbfb8aa3b, v65
	v_rcp_f32_e32 v142, v76
	v_add_f32_e32 v76, 1.0, v77
	v_add_f32_e32 v72, 1.0, v72
	v_exp_f32_e32 v64, v64
	v_exp_f32_e32 v65, v65
	v_rcp_f32_e32 v143, v76
	v_pk_fma_f32 v[76:77], v[78:79], v[140:141], v[108:109]
	v_rcp_f32_e32 v140, v72
	v_add_f32_e32 v72, 1.0, v73
	v_lshlrev_b32_e32 v78, 16, v139
	v_and_b32_e32 v79, 0xffff0000, v139
	v_and_b32_e32 v139, 0xffff0000, v136
	v_rcp_f32_e32 v141, v72
	v_add_f32_e32 v68, 1.0, v68
	v_pk_fma_f32 v[72:73], v[74:75], v[138:139], v[104:105]
	v_rcp_f32_e32 v70, v70
	v_rcp_f32_e32 v71, v71
	v_rcp_f32_e32 v138, v68
	v_add_f32_e32 v68, 1.0, v69
	v_add_f32_e32 v66, 1.0, v125
	v_add_f32_e32 v67, 1.0, v127
	v_rcp_f32_e32 v139, v68
	v_rcp_f32_e32 v66, v66
	v_rcp_f32_e32 v67, v67
	v_add_f32_e32 v64, 1.0, v64
	v_add_f32_e32 v65, 1.0, v65
	v_lshlrev_b32_e32 v74, 16, v137
	v_and_b32_e32 v75, 0xffff0000, v137
	v_rcp_f32_e32 v64, v64
	v_rcp_f32_e32 v65, v65
	v_pk_fma_f32 v[74:75], v[140:141], v[74:75], v[106:107]
	v_lshlrev_b32_e32 v136, 16, v134
	v_and_b32_e32 v137, 0xffff0000, v134
	v_pk_fma_f32 v[78:79], v[142:143], v[78:79], v[110:111]
	v_pk_mul_f32 v[104:105], v[72:73], v[72:73]
	v_pk_mul_f32 v[106:107], v[74:75], v[74:75]
	v_pk_fma_f32 v[68:69], v[70:71], v[136:137], v[100:101]
	v_lshlrev_b32_e32 v70, 16, v135
	v_and_b32_e32 v71, 0xffff0000, v135
	v_lshlrev_b32_e32 v126, 16, v132
	v_and_b32_e32 v127, 0xffff0000, v132
	v_pk_mul_f32 v[108:109], v[76:77], v[76:77]
	v_pk_mul_f32 v[110:111], v[78:79], v[78:79]
	v_pk_fma_f32 v[70:71], v[138:139], v[70:71], v[102:103]
	v_pk_fma_f32 v[96:97], v[66:67], v[126:127], v[96:97]
	v_lshlrev_b32_e32 v66, 16, v133
	v_and_b32_e32 v67, 0xffff0000, v133
	v_add_f32_e32 v106, v106, v107
	v_add_f32_e32 v104, v104, v105
	v_pk_mul_f32 v[100:101], v[68:69], v[68:69]
	v_pk_mul_f32 v[102:103], v[70:71], v[70:71]
	v_pk_fma_f32 v[98:99], v[64:65], v[66:67], v[98:99]
	v_add_f32_e32 v104, v104, v106
	v_add_f32_e32 v105, v110, v111
	v_add_f32_e32 v106, v108, v109
	v_pk_mul_f32 v[64:65], v[96:97], v[96:97]
	v_pk_mul_f32 v[66:67], v[98:99], v[98:99]
	v_add_f32_e32 v105, v106, v105
	v_add_f32_e32 v102, v102, v103
	v_add_f32_e32 v100, v100, v101
	v_add_f32_e32 v104, v105, v104
	v_add_f32_e32 v100, v100, v102
	v_add_f32_e32 v66, v66, v67
	v_add_f32_e32 v64, v64, v65
	v_add_f32_e32 v100, v100, v104
	v_add_f32_e32 v64, v64, v66
	v_add_f32_e32 v64, v64, v100
	s_nop 1
	v_mov_b32_dpp v65, v64 quad_perm:[1,0,3,2] row_mask:0xf bank_mask:0xf
	global_store_dwordx4 v[130:131], v[76:79], off
	global_store_dwordx4 v[130:131], v[72:75], off offset:64
	global_store_dwordx4 v[130:131], v[68:71], off offset:512
	global_store_dwordx4 v[130:131], v[96:99], off offset:576
	s_waitcnt lgkmcnt(0)
	v_add_f32_e32 v64, v64, v65
	s_nop 1
	v_mov_b32_dpp v65, v64 quad_perm:[2,3,0,1] row_mask:0xf bank_mask:0xf
	s_mov_b32 vcc_lo, 0x11111111
	s_mov_b32 vcc_hi, 0x11111111
	s_and_saveexec_b64 s[26:27], vcc
	s_cbranch_execz .LBB0_2129
	v_lshl_add_u64 v[66:67], v[128:129], 2, s[10:11]
	s_waitcnt lgkmcnt(0)
	v_add_f32_e32 v64, v64, v65
	global_atomic_add_f32 v[66:67], v64, off
.LBB0_2129:
	s_or_b64 exec, exec, s[26:27]
	s_waitcnt vmcnt(4)
	v_fmamk_f32 v64, v124, 0x3a800000, v193
	s_waitcnt lgkmcnt(0)
	v_mul_f32_e32 v65, 0x4b800000, v64
	v_cmp_gt_f32_e32 vcc, s55, v64
	v_or_b32_e32 v96, 16, v112
	v_ashrrev_i32_e32 v97, 31, v96
	v_cndmask_b32_e32 v64, v64, v65, vcc
	v_rsq_f32_e32 v64, v64
	v_lshlrev_b64 v[66:67], 11, v[96:97]
	v_lshl_add_u64 v[66:67], s[6:7], 0, v[66:67]
	v_mul_f32_e32 v65, 0x45800000, v64
	v_cndmask_b32_e32 v110, v64, v65, vcc
	v_lshlrev_b64 v[64:65], 12, v[96:97]
	v_lshl_add_u64 v[64:65], s[4:5], 0, v[64:65]
	v_lshl_add_u64 v[98:99], v[156:157], 2, v[64:65]
	v_lshl_add_u64 v[100:101], v[156:157], 1, v[66:67]
	global_load_dwordx4 v[76:79], v[98:99], off
	global_load_dwordx4 v[72:75], v[98:99], off offset:64
	global_load_dwordx4 v[68:71], v[98:99], off offset:512
	global_load_dwordx4 v[64:67], v[98:99], off offset:576
	global_load_dwordx2 v[106:107], v[100:101], off
	global_load_dwordx2 v[104:105], v[100:101], off offset:32
	global_load_dwordx2 v[102:103], v[100:101], off offset:256
	s_nop 0
	global_load_dwordx2 v[100:101], v[100:101], off offset:288
	v_lshl_add_u64 v[108:109], v[96:97], 2, s[12:13]
	global_load_dword v108, v[108:109], off
	v_pk_mul_f32 v[60:61], v[60:61], v[110:111] op_sel_hi:[1,0]
	v_lshlrev_b32_e32 v124, 16, v122
	v_mul_f32_e32 v60, 0xbfb8aa3b, v60
	v_exp_f32_e32 v109, v60
	v_mul_f32_e32 v60, 0xbfb8aa3b, v61
	v_exp_f32_e32 v111, v60
	v_and_b32_e32 v125, 0xffff0000, v122
	v_lshlrev_b32_e32 v122, 16, v120
	v_pk_mul_f32 v[56:57], v[56:57], v[110:111] op_sel_hi:[1,0]
	v_pk_mul_f32 v[60:61], v[62:63], v[110:111] op_sel_hi:[1,0]
	v_mul_f32_e32 v56, 0xbfb8aa3b, v56
	v_add_f32_e32 v62, 1.0, v109
	v_exp_f32_e32 v109, v56
	v_mul_f32_e32 v56, 0xbfb8aa3b, v57
	v_add_f32_e32 v63, 1.0, v111
	v_exp_f32_e32 v111, v56
	v_mul_f32_e32 v60, 0xbfb8aa3b, v60
	v_exp_f32_e32 v60, v60
	v_mul_f32_e32 v61, 0xbfb8aa3b, v61
	v_pk_mul_f32 v[52:53], v[52:53], v[110:111] op_sel_hi:[1,0]
	v_pk_mul_f32 v[56:57], v[58:59], v[110:111] op_sel_hi:[1,0]
	v_mul_f32_e32 v52, 0xbfb8aa3b, v52
	v_add_f32_e32 v58, 1.0, v109
	v_exp_f32_e32 v109, v52
	v_mul_f32_e32 v52, 0xbfb8aa3b, v53
	v_add_f32_e32 v59, 1.0, v111
	v_exp_f32_e32 v111, v52
	v_mul_f32_e32 v56, 0xbfb8aa3b, v56
	v_exp_f32_e32 v61, v61
	v_exp_f32_e32 v56, v56
	v_pk_mul_f32 v[48:49], v[48:49], v[110:111] op_sel_hi:[1,0]
	v_pk_mul_f32 v[52:53], v[54:55], v[110:111] op_sel_hi:[1,0]
	v_mul_f32_e32 v48, 0xbfb8aa3b, v48
	v_add_f32_e32 v54, 1.0, v109
	v_exp_f32_e32 v109, v48
	v_mul_f32_e32 v48, 0xbfb8aa3b, v49
	v_add_f32_e32 v55, 1.0, v111
	v_exp_f32_e32 v111, v48
	v_mul_f32_e32 v57, 0xbfb8aa3b, v57
	v_rcp_f32_e32 v62, v62
	v_rcp_f32_e32 v63, v63
	v_exp_f32_e32 v57, v57
	v_mul_f32_e32 v52, 0xbfb8aa3b, v52
	v_exp_f32_e32 v52, v52
	v_mul_f32_e32 v53, 0xbfb8aa3b, v53
	v_pk_mul_f32 v[48:49], v[50:51], v[110:111] op_sel_hi:[1,0]
	v_add_f32_e32 v60, 1.0, v60
	v_rcp_f32_e32 v58, v58
	v_rcp_f32_e32 v59, v59
	v_exp_f32_e32 v53, v53
	v_mul_f32_e32 v48, 0xbfb8aa3b, v48
	v_mul_f32_e32 v49, 0xbfb8aa3b, v49
	v_rcp_f32_e32 v126, v60
	v_add_f32_e32 v60, 1.0, v61
	v_add_f32_e32 v56, 1.0, v56
	v_exp_f32_e32 v48, v48
	v_exp_f32_e32 v49, v49
	v_rcp_f32_e32 v127, v60
	v_pk_fma_f32 v[60:61], v[62:63], v[124:125], v[92:93]
	v_rcp_f32_e32 v124, v56
	v_add_f32_e32 v56, 1.0, v57
	v_lshlrev_b32_e32 v62, 16, v123
	v_and_b32_e32 v63, 0xffff0000, v123
	v_and_b32_e32 v123, 0xffff0000, v120
	v_rcp_f32_e32 v125, v56
	v_add_f32_e32 v52, 1.0, v52
	v_pk_fma_f32 v[56:57], v[58:59], v[122:123], v[88:89]
	v_rcp_f32_e32 v54, v54
	v_rcp_f32_e32 v55, v55
	v_rcp_f32_e32 v122, v52
	v_add_f32_e32 v52, 1.0, v53
	v_add_f32_e32 v50, 1.0, v109
	v_add_f32_e32 v51, 1.0, v111
	v_rcp_f32_e32 v123, v52
	v_rcp_f32_e32 v50, v50
	v_rcp_f32_e32 v51, v51
	v_add_f32_e32 v48, 1.0, v48
	v_add_f32_e32 v49, 1.0, v49
	v_lshlrev_b32_e32 v58, 16, v121
	v_and_b32_e32 v59, 0xffff0000, v121
	v_rcp_f32_e32 v48, v48
	v_rcp_f32_e32 v49, v49
	v_pk_fma_f32 v[58:59], v[124:125], v[58:59], v[90:91]
	v_lshlrev_b32_e32 v120, 16, v118
	v_and_b32_e32 v121, 0xffff0000, v118
	v_pk_fma_f32 v[62:63], v[126:127], v[62:63], v[94:95]
	v_pk_mul_f32 v[88:89], v[56:57], v[56:57]
	v_pk_mul_f32 v[90:91], v[58:59], v[58:59]
	v_pk_fma_f32 v[52:53], v[54:55], v[120:121], v[84:85]
	v_lshlrev_b32_e32 v54, 16, v119
	v_and_b32_e32 v55, 0xffff0000, v119
	v_lshlrev_b32_e32 v110, 16, v116
	v_and_b32_e32 v111, 0xffff0000, v116
	v_pk_mul_f32 v[92:93], v[60:61], v[60:61]
	v_pk_mul_f32 v[94:95], v[62:63], v[62:63]
	v_pk_fma_f32 v[54:55], v[122:123], v[54:55], v[86:87]
	v_pk_fma_f32 v[80:81], v[50:51], v[110:111], v[80:81]
	v_lshlrev_b32_e32 v50, 16, v117
	v_and_b32_e32 v51, 0xffff0000, v117
	v_add_f32_e32 v90, v90, v91
	v_add_f32_e32 v88, v88, v89
	v_pk_mul_f32 v[84:85], v[52:53], v[52:53]
	v_pk_mul_f32 v[86:87], v[54:55], v[54:55]
	v_pk_fma_f32 v[82:83], v[48:49], v[50:51], v[82:83]
	v_add_f32_e32 v88, v88, v90
	v_add_f32_e32 v89, v94, v95
	v_add_f32_e32 v90, v92, v93
	v_pk_mul_f32 v[48:49], v[80:81], v[80:81]
	v_pk_mul_f32 v[50:51], v[82:83], v[82:83]
	v_add_f32_e32 v89, v90, v89
	v_add_f32_e32 v86, v86, v87
	v_add_f32_e32 v84, v84, v85
	v_add_f32_e32 v88, v89, v88
	v_add_f32_e32 v84, v84, v86
	v_add_f32_e32 v50, v50, v51
	v_add_f32_e32 v48, v48, v49
	v_add_f32_e32 v84, v84, v88
	v_add_f32_e32 v48, v48, v50
	v_add_f32_e32 v48, v48, v84
	s_nop 1
	v_mov_b32_dpp v49, v48 quad_perm:[1,0,3,2] row_mask:0xf bank_mask:0xf
	global_store_dwordx4 v[114:115], v[60:63], off
	global_store_dwordx4 v[114:115], v[56:59], off offset:64
	global_store_dwordx4 v[114:115], v[52:55], off offset:512
	global_store_dwordx4 v[114:115], v[80:83], off offset:576
	s_waitcnt lgkmcnt(0)
	v_add_f32_e32 v48, v48, v49
	s_nop 1
	v_mov_b32_dpp v49, v48 quad_perm:[2,3,0,1] row_mask:0xf bank_mask:0xf
	s_mov_b32 vcc_lo, 0x11111111
	s_mov_b32 vcc_hi, 0x11111111
	s_and_saveexec_b64 s[26:27], vcc
	s_cbranch_execz .LBB0_2131
	v_lshl_add_u64 v[50:51], v[112:113], 2, s[10:11]
	s_waitcnt lgkmcnt(0)
	v_add_f32_e32 v48, v48, v49
	global_atomic_add_f32 v[50:51], v48, off
.LBB0_2131:
	s_or_b64 exec, exec, s[26:27]
	s_waitcnt vmcnt(4)
	v_fmamk_f32 v48, v108, 0x3a800000, v193
	s_waitcnt lgkmcnt(0)
	v_mul_f32_e32 v49, 0x4b800000, v48
	v_cmp_gt_f32_e32 vcc, s55, v48
	v_or_b32_e32 v80, 32, v112
	v_ashrrev_i32_e32 v81, 31, v80
	v_cndmask_b32_e32 v48, v48, v49, vcc
	v_rsq_f32_e32 v48, v48
	v_lshlrev_b64 v[50:51], 11, v[80:81]
	v_lshl_add_u64 v[50:51], s[6:7], 0, v[50:51]
	v_mul_f32_e32 v49, 0x45800000, v48
	v_cndmask_b32_e32 v94, v48, v49, vcc
	v_lshlrev_b64 v[48:49], 12, v[80:81]
	v_lshl_add_u64 v[48:49], s[4:5], 0, v[48:49]
	v_lshl_add_u64 v[82:83], v[156:157], 2, v[48:49]
	v_lshl_add_u64 v[84:85], v[156:157], 1, v[50:51]
	global_load_dwordx4 v[60:63], v[82:83], off
	global_load_dwordx4 v[56:59], v[82:83], off offset:64
	global_load_dwordx4 v[52:55], v[82:83], off offset:512
	global_load_dwordx4 v[48:51], v[82:83], off offset:576
	global_load_dwordx2 v[90:91], v[84:85], off
	global_load_dwordx2 v[88:89], v[84:85], off offset:32
	global_load_dwordx2 v[86:87], v[84:85], off offset:256
	s_nop 0
	global_load_dwordx2 v[84:85], v[84:85], off offset:288
	v_lshl_add_u64 v[92:93], v[80:81], 2, s[12:13]
	global_load_dword v92, v[92:93], off
	v_pk_mul_f32 v[44:45], v[44:45], v[94:95] op_sel_hi:[1,0]
	v_lshlrev_b32_e32 v108, 16, v106
	v_mul_f32_e32 v44, 0xbfb8aa3b, v44
	v_exp_f32_e32 v93, v44
	v_mul_f32_e32 v44, 0xbfb8aa3b, v45
	v_exp_f32_e32 v95, v44
	v_and_b32_e32 v109, 0xffff0000, v106
	v_lshlrev_b32_e32 v106, 16, v104
	v_pk_mul_f32 v[40:41], v[40:41], v[94:95] op_sel_hi:[1,0]
	v_pk_mul_f32 v[44:45], v[46:47], v[94:95] op_sel_hi:[1,0]
	v_mul_f32_e32 v40, 0xbfb8aa3b, v40
	v_add_f32_e32 v46, 1.0, v93
	v_exp_f32_e32 v93, v40
	v_mul_f32_e32 v40, 0xbfb8aa3b, v41
	v_add_f32_e32 v47, 1.0, v95
	v_exp_f32_e32 v95, v40
	v_mul_f32_e32 v44, 0xbfb8aa3b, v44
	v_exp_f32_e32 v44, v44
	v_mul_f32_e32 v45, 0xbfb8aa3b, v45
	v_pk_mul_f32 v[36:37], v[36:37], v[94:95] op_sel_hi:[1,0]
	v_pk_mul_f32 v[40:41], v[42:43], v[94:95] op_sel_hi:[1,0]
	v_mul_f32_e32 v36, 0xbfb8aa3b, v36
	v_add_f32_e32 v42, 1.0, v93
	v_exp_f32_e32 v93, v36
	v_mul_f32_e32 v36, 0xbfb8aa3b, v37
	v_add_f32_e32 v43, 1.0, v95
	v_exp_f32_e32 v95, v36
	v_mul_f32_e32 v40, 0xbfb8aa3b, v40
	v_exp_f32_e32 v45, v45
	v_exp_f32_e32 v40, v40
	v_pk_mul_f32 v[32:33], v[32:33], v[94:95] op_sel_hi:[1,0]
	v_pk_mul_f32 v[36:37], v[38:39], v[94:95] op_sel_hi:[1,0]
	v_mul_f32_e32 v32, 0xbfb8aa3b, v32
	v_add_f32_e32 v38, 1.0, v93
	v_exp_f32_e32 v93, v32
	v_mul_f32_e32 v32, 0xbfb8aa3b, v33
	v_add_f32_e32 v39, 1.0, v95
	v_exp_f32_e32 v95, v32
	v_mul_f32_e32 v41, 0xbfb8aa3b, v41
	v_rcp_f32_e32 v46, v46
	v_rcp_f32_e32 v47, v47
	v_exp_f32_e32 v41, v41
	v_mul_f32_e32 v36, 0xbfb8aa3b, v36
	v_exp_f32_e32 v36, v36
	v_mul_f32_e32 v37, 0xbfb8aa3b, v37
	v_pk_mul_f32 v[32:33], v[34:35], v[94:95] op_sel_hi:[1,0]
	v_add_f32_e32 v44, 1.0, v44
	v_rcp_f32_e32 v42, v42
	v_rcp_f32_e32 v43, v43
	v_exp_f32_e32 v37, v37
	v_mul_f32_e32 v32, 0xbfb8aa3b, v32
	v_mul_f32_e32 v33, 0xbfb8aa3b, v33
	v_rcp_f32_e32 v110, v44
	v_add_f32_e32 v44, 1.0, v45
	v_add_f32_e32 v40, 1.0, v40
	v_exp_f32_e32 v32, v32
	v_exp_f32_e32 v33, v33
	v_rcp_f32_e32 v111, v44
	v_pk_fma_f32 v[44:45], v[46:47], v[108:109], v[76:77]
	v_rcp_f32_e32 v108, v40
	v_add_f32_e32 v40, 1.0, v41
	v_lshlrev_b32_e32 v46, 16, v107
	v_and_b32_e32 v47, 0xffff0000, v107
	v_and_b32_e32 v107, 0xffff0000, v104
	v_rcp_f32_e32 v109, v40
	v_add_f32_e32 v36, 1.0, v36
	v_pk_fma_f32 v[40:41], v[42:43], v[106:107], v[72:73]
	v_rcp_f32_e32 v38, v38
	v_rcp_f32_e32 v39, v39
	v_rcp_f32_e32 v106, v36
	v_add_f32_e32 v36, 1.0, v37
	v_add_f32_e32 v34, 1.0, v93
	v_add_f32_e32 v35, 1.0, v95
	v_rcp_f32_e32 v107, v36
	v_rcp_f32_e32 v34, v34
	v_rcp_f32_e32 v35, v35
	v_add_f32_e32 v32, 1.0, v32
	v_add_f32_e32 v33, 1.0, v33
	v_lshlrev_b32_e32 v42, 16, v105
	v_and_b32_e32 v43, 0xffff0000, v105
	v_rcp_f32_e32 v32, v32
	v_rcp_f32_e32 v33, v33
	v_pk_fma_f32 v[42:43], v[108:109], v[42:43], v[74:75]
	v_lshlrev_b32_e32 v104, 16, v102
	v_and_b32_e32 v105, 0xffff0000, v102
	v_pk_fma_f32 v[46:47], v[110:111], v[46:47], v[78:79]
	v_pk_mul_f32 v[72:73], v[40:41], v[40:41]
	v_pk_mul_f32 v[74:75], v[42:43], v[42:43]
	v_pk_fma_f32 v[36:37], v[38:39], v[104:105], v[68:69]
	v_lshlrev_b32_e32 v38, 16, v103
	v_and_b32_e32 v39, 0xffff0000, v103
	v_lshlrev_b32_e32 v94, 16, v100
	v_and_b32_e32 v95, 0xffff0000, v100
	v_pk_mul_f32 v[76:77], v[44:45], v[44:45]
	v_pk_mul_f32 v[78:79], v[46:47], v[46:47]
	v_pk_fma_f32 v[38:39], v[106:107], v[38:39], v[70:71]
	v_pk_fma_f32 v[64:65], v[34:35], v[94:95], v[64:65]
	v_lshlrev_b32_e32 v34, 16, v101
	v_and_b32_e32 v35, 0xffff0000, v101
	v_add_f32_e32 v74, v74, v75
	v_add_f32_e32 v72, v72, v73
	v_pk_mul_f32 v[68:69], v[36:37], v[36:37]
	v_pk_mul_f32 v[70:71], v[38:39], v[38:39]
	v_pk_fma_f32 v[66:67], v[32:33], v[34:35], v[66:67]
	v_add_f32_e32 v72, v72, v74
	v_add_f32_e32 v73, v78, v79
	v_add_f32_e32 v74, v76, v77
	v_pk_mul_f32 v[32:33], v[64:65], v[64:65]
	v_pk_mul_f32 v[34:35], v[66:67], v[66:67]
	v_add_f32_e32 v73, v74, v73
	v_add_f32_e32 v70, v70, v71
	v_add_f32_e32 v68, v68, v69
	v_add_f32_e32 v72, v73, v72
	v_add_f32_e32 v68, v68, v70
	v_add_f32_e32 v34, v34, v35
	v_add_f32_e32 v32, v32, v33
	v_add_f32_e32 v68, v68, v72
	v_add_f32_e32 v32, v32, v34
	v_add_f32_e32 v32, v32, v68
	s_nop 1
	v_mov_b32_dpp v33, v32 quad_perm:[1,0,3,2] row_mask:0xf bank_mask:0xf
	global_store_dwordx4 v[98:99], v[44:47], off
	global_store_dwordx4 v[98:99], v[40:43], off offset:64
	global_store_dwordx4 v[98:99], v[36:39], off offset:512
	global_store_dwordx4 v[98:99], v[64:67], off offset:576
	s_waitcnt lgkmcnt(0)
	v_add_f32_e32 v32, v32, v33
	s_nop 1
	v_mov_b32_dpp v33, v32 quad_perm:[2,3,0,1] row_mask:0xf bank_mask:0xf
	s_mov_b32 vcc_lo, 0x11111111
	s_mov_b32 vcc_hi, 0x11111111
	s_and_saveexec_b64 s[26:27], vcc
	s_cbranch_execz .LBB0_2133
	v_lshl_add_u64 v[34:35], v[96:97], 2, s[10:11]
	s_waitcnt lgkmcnt(0)
	v_add_f32_e32 v32, v32, v33
	global_atomic_add_f32 v[34:35], v32, off
.LBB0_2133:
	s_or_b64 exec, exec, s[26:27]
	s_waitcnt vmcnt(4)
	v_fmamk_f32 v32, v92, 0x3a800000, v193
	s_waitcnt lgkmcnt(0)
	v_mul_f32_e32 v33, 0x4b800000, v32
	v_cmp_gt_f32_e32 vcc, s55, v32
	v_or_b32_e32 v64, 48, v112
	v_ashrrev_i32_e32 v65, 31, v64
	v_cndmask_b32_e32 v32, v32, v33, vcc
	v_rsq_f32_e32 v32, v32
	v_lshlrev_b64 v[34:35], 11, v[64:65]
	v_lshl_add_u64 v[34:35], s[6:7], 0, v[34:35]
	v_mul_f32_e32 v33, 0x45800000, v32
	v_cndmask_b32_e32 v78, v32, v33, vcc
	v_lshlrev_b64 v[32:33], 12, v[64:65]
	v_lshl_add_u64 v[32:33], s[4:5], 0, v[32:33]
	v_lshl_add_u64 v[66:67], v[156:157], 2, v[32:33]
	v_lshl_add_u64 v[68:69], v[156:157], 1, v[34:35]
	global_load_dwordx4 v[44:47], v[66:67], off
	global_load_dwordx4 v[40:43], v[66:67], off offset:64
	global_load_dwordx4 v[36:39], v[66:67], off offset:512
	global_load_dwordx4 v[32:35], v[66:67], off offset:576
	global_load_dwordx2 v[74:75], v[68:69], off
	global_load_dwordx2 v[72:73], v[68:69], off offset:32
	global_load_dwordx2 v[70:71], v[68:69], off offset:256
	s_nop 0
	global_load_dwordx2 v[68:69], v[68:69], off offset:288
	v_lshl_add_u64 v[76:77], v[64:65], 2, s[12:13]
	global_load_dword v76, v[76:77], off
	v_pk_mul_f32 v[28:29], v[28:29], v[78:79] op_sel_hi:[1,0]
	v_lshlrev_b32_e32 v92, 16, v90
	v_mul_f32_e32 v28, 0xbfb8aa3b, v28
	v_exp_f32_e32 v77, v28
	v_mul_f32_e32 v28, 0xbfb8aa3b, v29
	v_exp_f32_e32 v79, v28
	v_and_b32_e32 v93, 0xffff0000, v90
	v_lshlrev_b32_e32 v90, 16, v88
	v_pk_mul_f32 v[24:25], v[24:25], v[78:79] op_sel_hi:[1,0]
	v_pk_mul_f32 v[28:29], v[30:31], v[78:79] op_sel_hi:[1,0]
	v_mul_f32_e32 v24, 0xbfb8aa3b, v24
	v_add_f32_e32 v30, 1.0, v77
	v_exp_f32_e32 v77, v24
	v_mul_f32_e32 v24, 0xbfb8aa3b, v25
	v_add_f32_e32 v31, 1.0, v79
	v_exp_f32_e32 v79, v24
	v_mul_f32_e32 v28, 0xbfb8aa3b, v28
	v_exp_f32_e32 v28, v28
	v_mul_f32_e32 v29, 0xbfb8aa3b, v29
	v_pk_mul_f32 v[20:21], v[20:21], v[78:79] op_sel_hi:[1,0]
	v_pk_mul_f32 v[24:25], v[26:27], v[78:79] op_sel_hi:[1,0]
	v_mul_f32_e32 v20, 0xbfb8aa3b, v20
	v_add_f32_e32 v26, 1.0, v77
	v_exp_f32_e32 v77, v20
	v_mul_f32_e32 v20, 0xbfb8aa3b, v21
	v_add_f32_e32 v27, 1.0, v79
	v_exp_f32_e32 v79, v20
	v_mul_f32_e32 v24, 0xbfb8aa3b, v24
	v_exp_f32_e32 v29, v29
	v_exp_f32_e32 v24, v24
	v_pk_mul_f32 v[16:17], v[16:17], v[78:79] op_sel_hi:[1,0]
	v_pk_mul_f32 v[20:21], v[22:23], v[78:79] op_sel_hi:[1,0]
	v_mul_f32_e32 v16, 0xbfb8aa3b, v16
	v_add_f32_e32 v22, 1.0, v77
	v_exp_f32_e32 v77, v16
	v_mul_f32_e32 v16, 0xbfb8aa3b, v17
	v_add_f32_e32 v23, 1.0, v79
	v_exp_f32_e32 v79, v16
	v_mul_f32_e32 v25, 0xbfb8aa3b, v25
	v_rcp_f32_e32 v30, v30
	v_rcp_f32_e32 v31, v31
	v_exp_f32_e32 v25, v25
	v_mul_f32_e32 v20, 0xbfb8aa3b, v20
	v_exp_f32_e32 v20, v20
	v_mul_f32_e32 v21, 0xbfb8aa3b, v21
	v_pk_mul_f32 v[16:17], v[18:19], v[78:79] op_sel_hi:[1,0]
	v_add_f32_e32 v28, 1.0, v28
	v_rcp_f32_e32 v26, v26
	v_rcp_f32_e32 v27, v27
	v_exp_f32_e32 v21, v21
	v_mul_f32_e32 v16, 0xbfb8aa3b, v16
	v_mul_f32_e32 v17, 0xbfb8aa3b, v17
	v_rcp_f32_e32 v94, v28
	v_add_f32_e32 v28, 1.0, v29
	v_add_f32_e32 v24, 1.0, v24
	v_exp_f32_e32 v16, v16
	v_exp_f32_e32 v17, v17
	v_rcp_f32_e32 v95, v28
	v_pk_fma_f32 v[28:29], v[30:31], v[92:93], v[60:61]
	v_rcp_f32_e32 v92, v24
	v_add_f32_e32 v24, 1.0, v25
	v_lshlrev_b32_e32 v30, 16, v91
	v_and_b32_e32 v31, 0xffff0000, v91
	v_and_b32_e32 v91, 0xffff0000, v88
	v_rcp_f32_e32 v93, v24
	v_add_f32_e32 v20, 1.0, v20
	v_pk_fma_f32 v[24:25], v[26:27], v[90:91], v[56:57]
	v_rcp_f32_e32 v22, v22
	v_rcp_f32_e32 v23, v23
	v_rcp_f32_e32 v90, v20
	v_add_f32_e32 v20, 1.0, v21
	v_add_f32_e32 v18, 1.0, v77
	v_add_f32_e32 v19, 1.0, v79
	v_rcp_f32_e32 v91, v20
	v_rcp_f32_e32 v18, v18
	v_rcp_f32_e32 v19, v19
	v_add_f32_e32 v16, 1.0, v16
	v_add_f32_e32 v17, 1.0, v17
	v_lshlrev_b32_e32 v26, 16, v89
	v_and_b32_e32 v27, 0xffff0000, v89
	v_rcp_f32_e32 v16, v16
	v_rcp_f32_e32 v17, v17
	v_pk_fma_f32 v[26:27], v[92:93], v[26:27], v[58:59]
	v_lshlrev_b32_e32 v88, 16, v86
	v_and_b32_e32 v89, 0xffff0000, v86
	v_pk_fma_f32 v[30:31], v[94:95], v[30:31], v[62:63]
	v_pk_mul_f32 v[56:57], v[24:25], v[24:25]
	v_pk_mul_f32 v[58:59], v[26:27], v[26:27]
	v_pk_fma_f32 v[20:21], v[22:23], v[88:89], v[52:53]
	v_lshlrev_b32_e32 v22, 16, v87
	v_and_b32_e32 v23, 0xffff0000, v87
	v_lshlrev_b32_e32 v78, 16, v84
	v_and_b32_e32 v79, 0xffff0000, v84
	v_pk_mul_f32 v[60:61], v[28:29], v[28:29]
	v_pk_mul_f32 v[62:63], v[30:31], v[30:31]
	v_pk_fma_f32 v[22:23], v[90:91], v[22:23], v[54:55]
	v_pk_fma_f32 v[48:49], v[18:19], v[78:79], v[48:49]
	v_lshlrev_b32_e32 v18, 16, v85
	v_and_b32_e32 v19, 0xffff0000, v85
	v_add_f32_e32 v58, v58, v59
	v_add_f32_e32 v56, v56, v57
	v_pk_mul_f32 v[52:53], v[20:21], v[20:21]
	v_pk_mul_f32 v[54:55], v[22:23], v[22:23]
	v_pk_fma_f32 v[50:51], v[16:17], v[18:19], v[50:51]
	v_add_f32_e32 v56, v56, v58
	v_add_f32_e32 v57, v62, v63
	v_add_f32_e32 v58, v60, v61
	v_pk_mul_f32 v[16:17], v[48:49], v[48:49]
	v_pk_mul_f32 v[18:19], v[50:51], v[50:51]
	v_add_f32_e32 v57, v58, v57
	v_add_f32_e32 v54, v54, v55
	v_add_f32_e32 v52, v52, v53
	v_add_f32_e32 v56, v57, v56
	v_add_f32_e32 v52, v52, v54
	v_add_f32_e32 v18, v18, v19
	v_add_f32_e32 v16, v16, v17
	v_add_f32_e32 v52, v52, v56
	v_add_f32_e32 v16, v16, v18
	v_add_f32_e32 v16, v16, v52
	s_nop 1
	v_mov_b32_dpp v17, v16 quad_perm:[1,0,3,2] row_mask:0xf bank_mask:0xf
	global_store_dwordx4 v[82:83], v[28:31], off
	global_store_dwordx4 v[82:83], v[24:27], off offset:64
	global_store_dwordx4 v[82:83], v[20:23], off offset:512
	global_store_dwordx4 v[82:83], v[48:51], off offset:576
	s_waitcnt lgkmcnt(0)
	v_add_f32_e32 v16, v16, v17
	s_nop 1
	v_mov_b32_dpp v17, v16 quad_perm:[2,3,0,1] row_mask:0xf bank_mask:0xf
	s_mov_b32 vcc_lo, 0x11111111
	s_mov_b32 vcc_hi, 0x11111111
	s_and_saveexec_b64 s[26:27], vcc
	s_cbranch_execz .LBB0_2135
	v_lshl_add_u64 v[18:19], v[80:81], 2, s[10:11]
	s_waitcnt lgkmcnt(0)
	v_add_f32_e32 v16, v16, v17
	global_atomic_add_f32 v[18:19], v16, off
.LBB0_2135:
	s_or_b64 exec, exec, s[26:27]
	s_waitcnt vmcnt(4)
	v_fmamk_f32 v16, v76, 0x3a800000, v193
	s_waitcnt lgkmcnt(0)
	v_mul_f32_e32 v17, 0x4b800000, v16
	v_cmp_gt_f32_e32 vcc, s55, v16
	v_and_b32_e32 v19, 0xffff0000, v74
	s_nop 0
	v_cndmask_b32_e32 v16, v16, v17, vcc
	v_rsq_f32_e32 v16, v16
	s_nop 0
	v_mul_f32_e32 v17, 0x45800000, v16
	v_cndmask_b32_e32 v16, v16, v17, vcc
	v_pk_mul_f32 v[12:13], v[12:13], v[16:17] op_sel_hi:[1,0]
	s_nop 0
	v_mul_f32_e32 v12, 0xbfb8aa3b, v12
	v_exp_f32_e32 v17, v12
	v_mul_f32_e32 v13, 0xbfb8aa3b, v13
	v_exp_f32_e32 v18, v13
	v_pk_mul_f32 v[12:13], v[14:15], v[16:17] op_sel_hi:[1,0]
	s_nop 0
	v_mul_f32_e32 v12, 0xbfb8aa3b, v12
	v_exp_f32_e32 v12, v12
	v_mul_f32_e32 v13, 0xbfb8aa3b, v13
	v_add_f32_e32 v14, 1.0, v17
	v_add_f32_e32 v15, 1.0, v18
	v_exp_f32_e32 v13, v13
	v_pk_mul_f32 v[8:9], v[8:9], v[16:17] op_sel_hi:[1,0]
	v_rcp_f32_e32 v14, v14
	v_rcp_f32_e32 v15, v15
	v_mul_f32_e32 v8, 0xbfb8aa3b, v8
	v_exp_f32_e32 v17, v8
	v_add_f32_e32 v12, 1.0, v12
	v_lshlrev_b32_e32 v18, 16, v74
	v_rcp_f32_e32 v20, v12
	v_add_f32_e32 v12, 1.0, v13
	v_mul_f32_e32 v8, 0xbfb8aa3b, v9
	v_rcp_f32_e32 v21, v12
	v_pk_fma_f32 v[12:13], v[14:15], v[18:19], v[44:45]
	v_exp_f32_e32 v18, v8
	v_pk_mul_f32 v[8:9], v[10:11], v[16:17] op_sel_hi:[1,0]
	v_add_f32_e32 v10, 1.0, v17
	v_mul_f32_e32 v8, 0xbfb8aa3b, v8
	v_exp_f32_e32 v8, v8
	v_mul_f32_e32 v9, 0xbfb8aa3b, v9
	v_add_f32_e32 v11, 1.0, v18
	v_exp_f32_e32 v9, v9
	v_pk_mul_f32 v[4:5], v[4:5], v[16:17] op_sel_hi:[1,0]
	v_rcp_f32_e32 v10, v10
	v_rcp_f32_e32 v11, v11
	v_mul_f32_e32 v4, 0xbfb8aa3b, v4
	v_exp_f32_e32 v17, v4
	v_add_f32_e32 v8, 1.0, v8
	v_lshlrev_b32_e32 v18, 16, v72
	v_and_b32_e32 v19, 0xffff0000, v72
	v_rcp_f32_e32 v24, v8
	v_add_f32_e32 v8, 1.0, v9
	v_mul_f32_e32 v4, 0xbfb8aa3b, v5
	v_rcp_f32_e32 v25, v8
	v_pk_fma_f32 v[8:9], v[10:11], v[18:19], v[40:41]
	v_exp_f32_e32 v18, v4
	v_pk_mul_f32 v[4:5], v[6:7], v[16:17] op_sel_hi:[1,0]
	v_pk_mul_f32 v[0:1], v[0:1], v[16:17] op_sel_hi:[1,0]
	v_mul_f32_e32 v4, 0xbfb8aa3b, v4
	v_exp_f32_e32 v4, v4
	v_mul_f32_e32 v5, 0xbfb8aa3b, v5
	v_add_f32_e32 v6, 1.0, v17
	v_add_f32_e32 v7, 1.0, v18
	v_exp_f32_e32 v5, v5
	v_mul_f32_e32 v0, 0xbfb8aa3b, v0
	v_rcp_f32_e32 v6, v6
	v_rcp_f32_e32 v7, v7
	v_exp_f32_e32 v17, v0
	v_add_f32_e32 v4, 1.0, v4
	v_lshlrev_b32_e32 v18, 16, v70
	v_and_b32_e32 v19, 0xffff0000, v70
	v_rcp_f32_e32 v28, v4
	v_add_f32_e32 v4, 1.0, v5
	v_mul_f32_e32 v0, 0xbfb8aa3b, v1
	v_rcp_f32_e32 v29, v4
	v_pk_fma_f32 v[4:5], v[6:7], v[18:19], v[36:37]
	v_exp_f32_e32 v18, v0
	v_pk_mul_f32 v[0:1], v[2:3], v[16:17] op_sel_hi:[1,0]
	v_add_f32_e32 v2, 1.0, v17
	v_mul_f32_e32 v0, 0xbfb8aa3b, v0
	v_mul_f32_e32 v1, 0xbfb8aa3b, v1
	v_exp_f32_e32 v0, v0
	v_exp_f32_e32 v1, v1
	v_add_f32_e32 v3, 1.0, v18
	v_rcp_f32_e32 v2, v2
	v_rcp_f32_e32 v3, v3
	v_add_f32_e32 v0, 1.0, v0
	v_add_f32_e32 v1, 1.0, v1
	v_rcp_f32_e32 v0, v0
	v_rcp_f32_e32 v1, v1
	v_lshlrev_b32_e32 v14, 16, v75
	v_and_b32_e32 v15, 0xffff0000, v75
	v_lshlrev_b32_e32 v10, 16, v73
	v_and_b32_e32 v11, 0xffff0000, v73
	v_pk_fma_f32 v[14:15], v[20:21], v[14:15], v[46:47]
	v_pk_fma_f32 v[10:11], v[24:25], v[10:11], v[42:43]
	v_lshlrev_b32_e32 v6, 16, v71
	v_and_b32_e32 v7, 0xffff0000, v71
	v_lshlrev_b32_e32 v16, 16, v68
	v_and_b32_e32 v17, 0xffff0000, v68
	v_pk_mul_f32 v[20:21], v[12:13], v[12:13]
	v_pk_mul_f32 v[22:23], v[14:15], v[14:15]
	v_pk_mul_f32 v[24:25], v[8:9], v[8:9]
	v_pk_mul_f32 v[26:27], v[10:11], v[10:11]
	v_pk_fma_f32 v[6:7], v[28:29], v[6:7], v[38:39]
	v_pk_fma_f32 v[16:17], v[2:3], v[16:17], v[32:33]
	v_lshlrev_b32_e32 v2, 16, v69
	v_and_b32_e32 v3, 0xffff0000, v69
	v_pk_mul_f32 v[28:29], v[4:5], v[4:5]
	v_pk_mul_f32 v[30:31], v[6:7], v[6:7]
	v_pk_fma_f32 v[18:19], v[0:1], v[2:3], v[34:35]
	v_add_f32_e32 v26, v26, v27
	v_add_f32_e32 v24, v24, v25
	v_add_f32_e32 v22, v22, v23
	v_add_f32_e32 v20, v20, v21
	v_pk_mul_f32 v[0:1], v[16:17], v[16:17]
	v_pk_mul_f32 v[2:3], v[18:19], v[18:19]
	v_add_f32_e32 v24, v24, v26
	v_add_f32_e32 v20, v20, v22
	v_add_f32_e32 v21, v30, v31
	v_add_f32_e32 v22, v28, v29
	v_add_f32_e32 v20, v20, v24
	v_add_f32_e32 v21, v22, v21
	v_add_f32_e32 v2, v2, v3
	v_add_f32_e32 v0, v0, v1
	v_add_f32_e32 v20, v21, v20
	v_add_f32_e32 v0, v0, v2
	v_add_f32_e32 v0, v0, v20
	s_nop 1
	v_mov_b32_dpp v1, v0 quad_perm:[1,0,3,2] row_mask:0xf bank_mask:0xf
	global_store_dwordx4 v[66:67], v[12:15], off
	global_store_dwordx4 v[66:67], v[8:11], off offset:64
	global_store_dwordx4 v[66:67], v[4:7], off offset:512
	global_store_dwordx4 v[66:67], v[16:19], off offset:576
	s_waitcnt lgkmcnt(0)
	v_add_f32_e32 v0, v0, v1
	s_nop 1
	v_mov_b32_dpp v1, v0 quad_perm:[2,3,0,1] row_mask:0xf bank_mask:0xf
	s_mov_b32 vcc_lo, 0x11111111
	s_mov_b32 vcc_hi, 0x11111111
	s_and_saveexec_b64 s[26:27], vcc
	s_cbranch_execz .LBB0_2137
	v_lshl_add_u64 v[2:3], v[64:65], 2, s[10:11]
	s_waitcnt lgkmcnt(0)
	v_add_f32_e32 v0, v0, v1
	global_atomic_add_f32 v[2:3], v0, off
